# stack9: stack8 + every global store write-through (sc1), release write-back (buffer_wbl2) dropped from the counter grid barrier
# speedup vs baseline: 1.0306x; 1.0215x over previous
; DI unsigned pk2(float a, float b) { f32x2 v = {a, b}; bf2_t r = __builtin_convertvector(v, bf2_t); return __builtin_bit_cast(unsigned, r); }
; DI void phase1(const Params& p) {
;     ...
;     for (int row = gw; row < NTOK; row += nw) {
;         const float* src = row < NLAT ? p.x + (size_t)row * DM : p.ctx + (size_t)(row - NLAT) * DM;
;         const int cond = row < NLAT ? (row >> 12) : 4;
;         const float* mp = p.mod + ((size_t)cond) * 6144;
;         f32x4 v[4];
;         float ss = 0.f;
; #pragma unroll
;         for (int i = 0; i < 4; ++i) { v[i] = *(const f32x4*)(src + i * 256 + lane * 4); ss += v[i][0] * v[i][0] + v[i][1] * v[i][1] + v[i][2] * v[i][2] + v[i][3] * v[i][3]; }
; #pragma unroll
;         for (int o = 1; o < 64; o <<= 1) ss += __shfl_xor(ss, o);
;         if (lane < 16) p.ss[(size_t)row * 16 + lane] = lane == 0 ? ss : 0.f;
;         bf16_t* hp = p.H + (size_t)row * DM;
; #pragma unroll
;         for (int i = 0; i < 4; ++i) {
;             const int idx = i * 256 + lane * 4;
;             const f32x4 gg = *(const f32x4*)(p.norm1_g + idx), sc = *(const f32x4*)(mp + DM + idx);
;             f32x4 y;
; #pragma unroll
;             for (int j = 0; j < 4; ++j) y[j] = v[i][j] * gg[j] * (1.f + sc[j]);
;             u32x2 w; w[0] = pk2(y[0], y[1]); w[1] = pk2(y[2], y[3]);
;             *(u32x2*)(hp + idx) = w;
;         }
.LBB0_13:
	s_or_b64 exec, exec, s[6:7]
	s_waitcnt vmcnt(5) lgkmcnt(0)
	v_lshl_add_u64 v[30:31], v[30:31], 0, s[36:37]
	s_movk_i32 s6, 0x43ff
	v_cmp_lt_i32_e64 s[6:7], s6, v30
	v_lshl_add_u64 v[20:21], v[20:21], 0, s[38:39]
	s_or_b64 s[42:43], s[6:7], s[42:43]
	v_pk_mul_f32 v[10:11], v[10:11], v[66:67]
	v_pk_mul_f32 v[8:9], v[8:9], v[64:65]
	v_pk_add_f32 v[40:41], v[80:81], 1.0 op_sel_hi:[1,0]
	v_pk_add_f32 v[42:43], v[82:83], 1.0 op_sel_hi:[1,0]
	v_pk_mul_f32 v[8:9], v[8:9], v[40:41]
	v_pk_mul_f32 v[10:11], v[10:11], v[42:43]
	v_cvt_pk_bf16_f32 v8, v8, v9
	v_cvt_pk_bf16_f32 v9, v10, v11
	global_store_dwordx2 v[22:23], v[8:9], off sc1
	v_pk_mul_f32 v[6:7], v[6:7], v[70:71]
	v_pk_mul_f32 v[4:5], v[4:5], v[68:69]
	v_pk_add_f32 v[40:41], v[84:85], 1.0 op_sel_hi:[1,0]
	v_pk_add_f32 v[42:43], v[86:87], 1.0 op_sel_hi:[1,0]
	v_pk_mul_f32 v[4:5], v[4:5], v[40:41]
	v_pk_mul_f32 v[6:7], v[6:7], v[42:43]
	v_cvt_pk_bf16_f32 v4, v4, v5
	v_cvt_pk_bf16_f32 v5, v6, v7
	global_store_dwordx2 v[22:23], v[4:5], off offset:512 sc1
	v_pk_mul_f32 v[14:15], v[14:15], v[74:75]
	v_pk_mul_f32 v[12:13], v[12:13], v[72:73]
	v_pk_add_f32 v[40:41], v[88:89], 1.0 op_sel_hi:[1,0]
	v_pk_add_f32 v[42:43], v[90:91], 1.0 op_sel_hi:[1,0]
	v_pk_mul_f32 v[12:13], v[12:13], v[40:41]
	v_pk_mul_f32 v[14:15], v[14:15], v[42:43]
	v_cvt_pk_bf16_f32 v12, v12, v13
	v_cvt_pk_bf16_f32 v13, v14, v15
	global_store_dwordx2 v[22:23], v[12:13], off offset:1024 sc1
	v_pk_mul_f32 v[62:63], v[62:63], v[78:79]
	v_pk_mul_f32 v[60:61], v[60:61], v[76:77]
	v_pk_add_f32 v[40:41], v[92:93], 1.0 op_sel_hi:[1,0]
	v_pk_add_f32 v[42:43], v[94:95], 1.0 op_sel_hi:[1,0]
	v_pk_mul_f32 v[60:61], v[60:61], v[40:41]
	v_pk_mul_f32 v[62:63], v[62:63], v[42:43]
	v_cvt_pk_bf16_f32 v60, v60, v61
	v_cvt_pk_bf16_f32 v61, v62, v63
	global_store_dwordx2 v[22:23], v[60:61], off offset:1536 sc1
	v_lshl_add_u64 v[22:23], v[22:23], 0, s[40:41]
	s_andn2_b64 exec, exec, s[42:43]
	s_cbranch_execz .LBB0_16

; DI void phase1(const Params& p) {
;     ...
;     for (int row = gw; row < NTOK; row += nw) {
;         const float* src = row < NLAT ? p.x + (size_t)row * DM : p.ctx + (size_t)(row - NLAT) * DM;
;         const int cond = row < NLAT ? (row >> 12) : 4;
;         const float* mp = p.mod + ((size_t)cond) * 6144;
;         f32x4 v[4];
;         float ss = 0.f;
; #pragma unroll
;         for (int i = 0; i < 4; ++i) { v[i] = *(const f32x4*)(src + i * 256 + lane * 4); ss += v[i][0] * v[i][0] + v[i][1] * v[i][1] + v[i][2] * v[i][2] + v[i][3] * v[i][3]; }
; #pragma unroll
;         for (int o = 1; o < 64; o <<= 1) ss += __shfl_xor(ss, o);
;         if (lane < 16) p.ss[(size_t)row * 16 + lane] = lane == 0 ? ss : 0.f;
.Lph1a_entry:
	v_mov_b64_e32 v[8:9], v[136:137]
	v_mov_b64_e32 v[10:11], v[138:139]
	v_mov_b64_e32 v[4:5], v[140:141]
	v_mov_b64_e32 v[6:7], v[142:143]
	v_mov_b64_e32 v[12:13], v[144:145]
	v_mov_b64_e32 v[14:15], v[146:147]
	v_mov_b64_e32 v[60:61], v[148:149]
	v_mov_b64_e32 v[62:63], v[150:151]
	global_load_dwordx4 v[64:67], v[16:17], off
	global_load_dwordx4 v[68:71], v[16:17], off offset:1024
	global_load_dwordx4 v[72:75], v[16:17], off offset:2048
	global_load_dwordx4 v[76:79], v[16:17], off offset:3072
	v_min_i32_e32 v96, 0x4000, v30
	v_ashrrev_i32_e32 v96, 12, v96
	v_mul_hi_i32_i24_e32 v99, 0x6000, v96
	v_mul_i32_i24_e32 v98, 0x6000, v96
	v_lshl_add_u64 v[98:99], s[66:67], 0, v[98:99]
	s_mov_b64 s[6:7], 0x1000
	v_lshl_add_u64 v[98:99], v[98:99], 0, s[6:7]
	v_lshl_add_u64 v[100:101], v[98:99], 0, v[192:193]
	global_load_dwordx4 v[80:83], v[100:101], off
	v_lshl_add_u64 v[100:101], v[98:99], 0, v[24:25]
	global_load_dwordx4 v[84:87], v[100:101], off
	v_lshl_add_u64 v[100:101], v[98:99], 0, v[26:27]
	global_load_dwordx4 v[88:91], v[100:101], off
	v_lshl_add_u64 v[100:101], v[98:99], 0, v[28:29]
	global_load_dwordx4 v[92:95], v[100:101], off
	v_add_u32_e32 v154, s36, v30
	v_min_i32_e32 v154, 0x43ff, v154
	v_cmp_gt_i32_e64 s[6:7], s33, v154
	v_add_u32_e32 v152, 0xffffc000, v154
	v_mov_b32_e32 v155, s17
	v_mov_b32_e32 v156, s13
	v_cndmask_b32_e64 v152, v152, v154, s[6:7]
	v_mov_b32_e32 v153, 0
	v_cndmask_b32_e64 v157, v155, v156, s[6:7]
	v_mov_b32_e32 v155, s16
	v_mov_b32_e32 v156, s12
	v_cndmask_b32_e64 v156, v155, v156, s[6:7]
	v_lshlrev_b64 v[152:153], 12, v[152:153]
	v_lshl_add_u64 v[152:153], v[156:157], 0, v[152:153]
	v_lshl_add_u64 v[152:153], v[152:153], 0, v[192:193]
	global_load_dwordx4 v[136:139], v[152:153], off
	global_load_dwordx4 v[140:143], v[152:153], off offset:1024
	global_load_dwordx4 v[144:147], v[152:153], off offset:2048
	global_load_dwordx4 v[148:151], v[152:153], off offset:3072
	v_mul_f32_e32 v2, v9, v9
	v_mul_f32_e32 v3, v5, v5
	v_fmac_f32_e32 v2, v8, v8
	v_fmac_f32_e32 v3, v4, v4
	v_fmac_f32_e32 v2, v10, v10
	v_fmac_f32_e32 v3, v6, v6
	v_fmac_f32_e32 v2, v11, v11
	v_fmac_f32_e32 v3, v7, v7
	v_add_f32_e32 v2, v2, v3
	v_mul_f32_e32 v3, v13, v13
	v_fmac_f32_e32 v3, v12, v12
	v_fmac_f32_e32 v3, v14, v14
	v_fmac_f32_e32 v3, v15, v15
	v_add_f32_e32 v19, v2, v3
	v_mul_f32_e32 v40, v61, v61
	v_fmac_f32_e32 v40, v60, v60
	v_fmac_f32_e32 v40, v62, v62
	v_fmac_f32_e32 v40, v63, v63
	v_add_f32_e32 v19, v19, v40
	ds_bpermute_b32 v40, v34, v19
	s_waitcnt lgkmcnt(0)
	v_add_f32_e32 v19, v19, v40
	ds_bpermute_b32 v40, v35, v19
	s_waitcnt lgkmcnt(0)
	v_add_f32_e32 v19, v19, v40
	ds_bpermute_b32 v40, v36, v19
	s_waitcnt lgkmcnt(0)
	v_add_f32_e32 v19, v19, v40
	ds_bpermute_b32 v40, v37, v19
	s_waitcnt lgkmcnt(0)
	v_add_f32_e32 v19, v19, v40
	ds_bpermute_b32 v40, v38, v19
	s_waitcnt lgkmcnt(0)
	v_add_f32_e32 v19, v19, v40
	ds_bpermute_b32 v40, v39, v19
	s_and_saveexec_b64 s[6:7], vcc
	s_cbranch_execz .LBB0_13
	s_waitcnt lgkmcnt(0)
	v_add_f32_e32 v19, v19, v40
	v_cndmask_b32_e64 v19, 0, v19, s[4:5]
	global_store_dword v[20:21], v19, off sc1
	s_branch .LBB0_13

; DI void phase1(const Params& p) {
;     ...
;             const float r4 = __shfl(acc[0], fr + 16);
;             const float r5 = __shfl(acc[1], fr + 16), r6 = __shfl(acc[2], fr + 16), r7 = __shfl(acc[3], fr + 16);
;             const float r8 = __shfl(acc[0], fr + 32), r9 = __shfl(acc[1], fr + 32);
;             if (fq == 0) {
;                 dst[(size_t)0 * N + n0 + fr] = acc[0] + r5;
;                 dst[(size_t)1 * N + n0 + fr] = acc[1] + r6;
;                 dst[(size_t)2 * N + n0 + fr] = acc[2] + r7;
;                 dst[(size_t)3 * N + n0 + fr] = acc[3] + r8;
;                 dst[(size_t)4 * N + n0 + fr] = r4 + r9;
;             }
.LBB0_93:
	s_nop 2
	ds_bpermute_b32 v4, v21, v0
	ds_bpermute_b32 v9, v21, v1
	ds_bpermute_b32 v8, v21, v2
	ds_bpermute_b32 v7, v21, v3
	ds_bpermute_b32 v6, v38, v0
	ds_bpermute_b32 v5, v38, v1
	s_and_saveexec_b64 s[8:9], s[4:5]
	s_cbranch_execz .LBB0_18
	v_mov_b32_e32 v10, 0x1c00
	v_mov_b32_e32 v11, 0x4000
	v_ashrrev_i32_e32 v31, 31, v30
	v_cndmask_b32_e64 v192, v10, v11, s[6:7]
	v_lshlrev_b64 v[10:11], 2, v[30:31]
	v_lshl_add_u64 v[12:13], v[28:29], 0, v[10:11]
	v_mov_b32_e32 v27, v193
	s_waitcnt lgkmcnt(4)
	v_add_f32_e32 v0, v0, v9
	v_lshl_add_u64 v[12:13], v[12:13], 0, v[26:27]
	global_store_dword v[12:13], v0, off sc1
	s_waitcnt lgkmcnt(3)
	v_add_f32_e32 v12, v1, v8
	v_lshl_add_u64 v[0:1], v[28:29], 0, v[192:193]
	v_lshl_add_u64 v[8:9], v[0:1], 0, v[10:11]
	v_lshl_add_u64 v[8:9], v[8:9], 0, v[26:27]
	v_lshl_add_u64 v[0:1], v[0:1], 0, v[192:193]
	global_store_dword v[8:9], v12, off sc1
	v_lshl_add_u64 v[8:9], v[0:1], 0, v[10:11]
	s_waitcnt lgkmcnt(2)
	v_add_f32_e32 v2, v2, v7
	v_lshl_add_u64 v[8:9], v[8:9], 0, v[26:27]
	v_lshl_add_u64 v[0:1], v[0:1], 0, v[192:193]
	global_store_dword v[8:9], v2, off sc1
	s_waitcnt lgkmcnt(1)
	v_add_f32_e32 v6, v3, v6
	v_lshl_add_u64 v[2:3], v[0:1], 0, v[10:11]
	v_lshl_add_u64 v[0:1], v[0:1], 0, v[192:193]
	v_lshl_add_u64 v[2:3], v[2:3], 0, v[26:27]
	v_lshl_add_u64 v[0:1], v[0:1], 0, v[10:11]
	global_store_dword v[2:3], v6, off sc1
	s_waitcnt lgkmcnt(0)
	v_add_f32_e32 v2, v4, v5
	v_lshl_add_u64 v[0:1], v[0:1], 0, v[26:27]
	global_store_dword v[0:1], v2, off sc1
	s_branch .LBB0_18

; #define LDSP __attribute__((address_space(3)))
; #define WAIT_V0() asm volatile("s_waitcnt vmcnt(0)" ::: "memory")
; template <int EK, int TS, int KS>
; DI void ctx_tiles(const Params& p, int l, const bf16_t* __restrict__ A, const bf16_t* __restrict__ Bt, int N, int K, ldsp_t shm) {
;     ...
;     for (int u = blockIdx.x; u < ntiles; u += gridDim.x) {
;         const int tm = u / ntn, tn = u % ntn;
;         int tid = threadIdx.x;
;         asm volatile("" : "+v"(tid));
;         const int wid = tid >> 6, lane = tid & 63, wr = wid >> 2, wc = wid & 3, fr = lane & 15, fq = lane >> 4;
;         unsigned soff[PP];
; #pragma unroll
;         for (int i = 0; i < PP; ++i) { int sR, sC; stage_rc_ks<KS>((wid * PP + i) * 1024 + lane * 16, sR, sC); soff[i] = (unsigned)(sR * K + sC) * 2u; }
;         const bf16_t* Ab = A + (size_t)tm * TS * K;
;         const bf16_t* Bb = Bt + (size_t)tn * TS * K;
;     ...
;         f32x4 acc[MT][NT];
; #pragma unroll
;         for (int m = 0; m < MT; ++m)
; #pragma unroll
;             for (int n = 0; n < NT; ++n) acc[m][n] = (f32x4){0.f, 0.f, 0.f, 0.f};
;         const int aoff = lds_byte_ks<KS>(wr * WM + fr, fq * 8), boff = lds_byte_ks<KS>(wc * WN + fr, fq * 8);
;         C_STAGE(0, 0); WAIT_V0(); __syncthreads();
;         for (int t = 0; t < nt; ++t) {
;             const int cur = t & 1;
;             if (t + 1 < nt) C_STAGE(cur ^ 1, t + 1);
;             ldsp_t sa = shm + cur * 2 * TILE_A, sb = sa + TILE_A;
; #pragma unroll
;             for (int ks = 0; ks < KS; ++ks) {
;                 bf16x8 At[MT], Bf[NT];
; #pragma unroll
;                 for (int m = 0; m < MT; ++m) At[m] = *(const LDSP bf16x8*)(sa + aoff + m * (KS * 1024) + ks * 1024);
; #pragma unroll
;                 for (int n = 0; n < NT; ++n) Bf[n] = *(const LDSP bf16x8*)(sb + boff + n * (KS * 1024) + ks * 1024);
; #pragma unroll
;                 for (int m = 0; m < MT; ++m)
; #pragma unroll
;                     for (int n = 0; n < NT; ++n) acc[m][n] = __builtin_amdgcn_mfma_f32_16x16x32_bf16(Bf[n], At[m], acc[m][n], 0, 0, 0);
;             }
.LBB0_119:
	v_mov_b32_e32 v32, v252
	s_ashr_i32 s10, s31, 31
	v_ashrrev_i32_e32 v0, 6, v32
	v_lshlrev_b32_e32 v25, 12, v0
	v_lshlrev_b32_e32 v1, 4, v32
	v_and_b32_e32 v2, 32, v32
	v_bitop3_b32 v1, v1, v2, 48 bitop3:0x6c
	v_lshlrev_b32_e32 v2, 9, v32
	s_waitcnt lgkmcnt(5)
	v_or_b32_e32 v4, 0x400, v25
	v_and_or_b32 v1, v2, s20, v1
	v_ashrrev_i32_e32 v2, 10, v4
	v_ashrrev_i32_e32 v3, 31, v2
	v_lshrrev_b32_e32 v3, 30, v3
	v_add_u32_e32 v3, v2, v3
	s_waitcnt lgkmcnt(0)
	v_and_b32_e32 v5, 0x3fffffc, v3
	v_lshlrev_b32_e32 v3, 13, v3
	v_sub_u32_e32 v2, v2, v5
	v_and_or_b32 v3, v3, s90, v1
	v_or_b32_e32 v14, 0x800, v25
	v_lshl_add_u32 v8, v2, 6, v3
	v_ashrrev_i32_e32 v2, 10, v14
	v_ashrrev_i32_e32 v3, 31, v2
	v_lshrrev_b32_e32 v3, 30, v3
	s_lshr_b32 s10, s10, 27
	v_add_u32_e32 v3, v2, v3
	s_add_i32 s10, s31, s10
	v_and_b32_e32 v5, 0x3fffffc, v3
	v_lshlrev_b32_e32 v3, 13, v3
	s_ashr_i32 s34, s10, 5
	v_sub_u32_e32 v2, v2, v5
	v_and_or_b32 v3, v3, s90, v1
	v_or_b32_e32 v18, 0xc00, v25
	s_andn2_b32 s10, s10, 31
	v_lshl_add_u32 v12, v2, 6, v3
	v_ashrrev_i32_e32 v2, 10, v18
	s_sub_i32 s36, s31, s10
	v_ashrrev_i32_e32 v3, 31, v2
	s_ashr_i32 s35, s34, 31
	s_ashr_i32 s37, s36, 31
	v_lshrrev_b32_e32 v3, 30, v3
	s_lshl_b64 s[10:11], s[34:35], 18
	s_lshl_b64 s[38:39], s[36:37], 18
	v_add_u32_e32 v3, v2, v3
	s_add_u32 s40, s8, s10
	v_and_b32_e32 v5, 0x3fffffc, v3
	s_addc_u32 s41, s14, s11
	v_sub_u32_e32 v2, v2, v5
	s_add_u32 s38, s9, s38
	v_readfirstlane_b32 s11, v25
	v_add_u32_e32 v5, 0x8000, v25
	v_lshl_or_b32 v192, v0, 15, v1
	s_addc_u32 s39, s45, s39
	s_mov_b32 m0, s11
	v_readfirstlane_b32 s10, v5
	v_mov_b32_e32 v9, v193
	global_load_lds_dwordx4 v192, s[40:41]
	s_mov_b32 m0, s10
	v_lshl_add_u64 v[6:7], s[40:41], 0, v[8:9]
	v_readfirstlane_b32 s37, v4
	v_lshl_add_u64 v[4:5], s[38:39], 0, v[8:9]
	v_add_u32_e32 v9, 0x8400, v25
	global_load_lds_dwordx4 v192, s[38:39]
	s_mov_b32 m0, s37
	v_readfirstlane_b32 s35, v9
	global_load_lds_dwordx4 v8, s[40:41]
	s_mov_b32 m0, s35
	v_mov_b32_e32 v13, v193
	v_lshlrev_b32_e32 v3, 13, v3
	global_load_lds_dwordx4 v8, s[38:39]
	v_lshl_add_u64 v[10:11], s[40:41], 0, v[12:13]
	v_readfirstlane_b32 s43, v14
	v_lshl_add_u64 v[8:9], s[38:39], 0, v[12:13]
	v_add_u32_e32 v13, 0x8800, v25
	v_and_or_b32 v1, v3, s90, v1
	s_mov_b32 m0, s43
	v_readfirstlane_b32 s42, v13
	v_lshl_add_u32 v16, v2, 6, v1
	global_load_lds_dwordx4 v12, s[40:41]
	s_mov_b32 m0, s42
	v_mov_b32_e32 v17, v193
	v_readfirstlane_b32 s46, v18
	global_load_lds_dwordx4 v12, s[38:39]
	v_lshl_add_u64 v[14:15], s[40:41], 0, v[16:17]
	s_mov_b32 m0, s46
	v_lshl_add_u64 v[12:13], s[38:39], 0, v[16:17]
	v_add_u32_e32 v17, 0x8c00, v25
	v_ashrrev_i32_e32 v1, 2, v32
	v_lshl_add_u64 v[2:3], s[40:41], 0, v[192:193]
	global_load_lds_dwordx4 v16, s[40:41]
	v_readfirstlane_b32 s40, v17
	v_and_b32_e32 v33, 15, v32
	v_and_b32_e32 v19, 0xffffffc0, v1
	v_and_b32_e32 v1, 48, v32
	v_lshlrev_b32_e32 v20, 5, v0
	v_lshlrev_b32_e32 v0, 2, v32
	s_mov_b32 m0, s40
	v_add_u32_e32 v18, 0x10000, v25
	v_or_b32_e32 v34, v19, v33
	v_lshl_or_b32 v26, v33, 6, v1
	v_and_b32_e32 v27, 32, v0
	v_lshl_add_u64 v[0:1], s[38:39], 0, v[192:193]
	global_load_lds_dwordx4 v16, s[38:39]
	v_lshlrev_b32_e32 v28, 8, v19
	v_readfirstlane_b32 s38, v18
	v_add_u32_e32 v19, 0x18000, v25
	v_and_b32_e32 v35, 0x60, v20
	v_lshl_add_u64 v[16:17], v[2:3], 0, s[96:97]
	s_mov_b32 m0, s38
	v_readfirstlane_b32 s41, v19
	v_add_u32_e32 v20, 0x10400, v25
	s_waitcnt vmcnt(0)
	s_waitcnt vmcnt(0) lgkmcnt(0)
	s_barrier
	global_load_lds_dwordx4 v[16:17], off
	v_lshl_add_u64 v[16:17], v[0:1], 0, s[96:97]
	s_mov_b32 m0, s41
	v_readfirstlane_b32 s50, v20
	v_add_u32_e32 v21, 0x18400, v25
	global_load_lds_dwordx4 v[16:17], off
	v_lshl_add_u64 v[16:17], v[6:7], 0, s[96:97]
	s_mov_b32 m0, s50
	v_readfirstlane_b32 s47, v21
	v_add_u32_e32 v22, 0x10800, v25
	global_load_lds_dwordx4 v[16:17], off
	v_lshl_add_u64 v[16:17], v[4:5], 0, s[96:97]
	s_mov_b32 m0, s47
	v_readfirstlane_b32 s51, v22
	v_add_u32_e32 v23, 0x18800, v25
	global_load_lds_dwordx4 v[16:17], off
	v_lshl_add_u64 v[16:17], v[10:11], 0, s[96:97]
	s_mov_b32 m0, s51
	v_readfirstlane_b32 s85, v23
	v_add_u32_e32 v24, 0x10c00, v25
	global_load_lds_dwordx4 v[16:17], off
	v_lshl_add_u64 v[16:17], v[8:9], 0, s[96:97]
	s_mov_b32 m0, s85
	v_readfirstlane_b32 s84, v24
	v_add_u32_e32 v25, 0x18c00, v25
	global_load_lds_dwordx4 v[16:17], off
	v_lshl_add_u64 v[16:17], v[14:15], 0, s[96:97]
	s_mov_b32 m0, s84
	v_readfirstlane_b32 s39, v25
	global_load_lds_dwordx4 v[16:17], off
	v_lshl_add_u64 v[16:17], v[12:13], 0, s[96:97]
	s_mov_b32 m0, s39
	v_lshlrev_b32_e32 v29, 8, v35
	global_load_lds_dwordx4 v[16:17], off
	v_bitop3_b32 v16, v26, v28, v27 bitop3:0xde
	v_bitop3_b32 v17, v26, v29, v27 bitop3:0xde
	ds_read_b128 v[26:29], v16
	ds_read_b128 v[36:39], v16 offset:4096
	ds_read_b128 v[40:43], v16 offset:8192
	ds_read_b128 v[44:47], v16 offset:12288
	ds_read_b128 v[48:51], v17 offset:32768
	ds_read_b128 v[52:55], v17 offset:36864
	s_waitcnt lgkmcnt(0)
	v_mfma_f32_16x16x32_bf16 v[56:59], v[48:51], v[26:29], 0
	s_mov_b32 m0, s11
	v_or_b32_e32 v30, 0x19400, v17
	v_or_b32_e32 v31, 0x18800, v17
	v_mfma_f32_16x16x32_bf16 v[26:29], v[52:55], v[26:29], 0
	v_lshlrev_b32_e32 v34, 9, v34
	v_mfma_f32_16x16x32_bf16 v[60:63], v[48:51], v[36:39], 0
	v_mfma_f32_16x16x32_bf16 v[36:39], v[52:55], v[36:39], 0
	v_mfma_f32_16x16x32_bf16 v[64:67], v[48:51], v[40:43], 0
	v_mfma_f32_16x16x32_bf16 v[40:43], v[52:55], v[40:43], 0
	v_mfma_f32_16x16x32_bf16 v[48:51], v[48:51], v[44:47], 0
	v_mfma_f32_16x16x32_bf16 v[44:47], v[52:55], v[44:47], 0
	ds_read_b128 v[52:55], v16 offset:1024
	ds_read_b128 v[68:71], v16 offset:5120
	ds_read_b128 v[72:75], v16 offset:9216
	ds_read_b128 v[76:79], v16 offset:13312
	ds_read_b128 v[80:83], v17 offset:33792
	ds_read_b128 v[84:87], v17 offset:37888
	s_waitcnt lgkmcnt(0)
; #define LDSP __attribute__((address_space(3)))
; #define WAIT_V0() asm volatile("s_waitcnt vmcnt(0)" ::: "memory")
; template <int EK, int TS, int KS>
; DI void ctx_tiles(const Params& p, int l, const bf16_t* __restrict__ A, const bf16_t* __restrict__ Bt, int N, int K, ldsp_t shm) {
;     ...
;         for (int t = 0; t < nt; ++t) {
;             const int cur = t & 1;
;             if (t + 1 < nt) C_STAGE(cur ^ 1, t + 1);
;             ldsp_t sa = shm + cur * 2 * TILE_A, sb = sa + TILE_A;
; #pragma unroll
;             for (int ks = 0; ks < KS; ++ks) {
;                 bf16x8 At[MT], Bf[NT];
; #pragma unroll
;                 for (int m = 0; m < MT; ++m) At[m] = *(const LDSP bf16x8*)(sa + aoff + m * (KS * 1024) + ks * 1024);
; #pragma unroll
;                 for (int n = 0; n < NT; ++n) Bf[n] = *(const LDSP bf16x8*)(sb + boff + n * (KS * 1024) + ks * 1024);
; #pragma unroll
;                 for (int m = 0; m < MT; ++m)
; #pragma unroll
;                     for (int n = 0; n < NT; ++n) acc[m][n] = __builtin_amdgcn_mfma_f32_16x16x32_bf16(Bf[n], At[m], acc[m][n], 0, 0, 0);
;             }
;             WAIT_V0(); __syncthreads();
;         }
	v_mfma_f32_16x16x32_bf16 v[56:59], v[80:83], v[52:55], v[56:59]
	v_mfma_f32_16x16x32_bf16 v[26:29], v[84:87], v[52:55], v[26:29]
	v_mfma_f32_16x16x32_bf16 v[52:55], v[80:83], v[68:71], v[60:63]
	v_mfma_f32_16x16x32_bf16 v[36:39], v[84:87], v[68:71], v[36:39]
	v_mfma_f32_16x16x32_bf16 v[60:63], v[80:83], v[72:75], v[64:67]
	v_mfma_f32_16x16x32_bf16 v[40:43], v[84:87], v[72:75], v[40:43]
	v_mfma_f32_16x16x32_bf16 v[48:51], v[80:83], v[76:79], v[48:51]
	v_mfma_f32_16x16x32_bf16 v[44:47], v[84:87], v[76:79], v[44:47]
	ds_read_b128 v[64:67], v16 offset:2048
	ds_read_b128 v[68:71], v16 offset:6144
	ds_read_b128 v[72:75], v16 offset:10240
	ds_read_b128 v[76:79], v16 offset:14336
	ds_read_b128 v[80:83], v17 offset:34816
	ds_read_b128 v[84:87], v17 offset:38912
	s_waitcnt lgkmcnt(0)
	v_mfma_f32_16x16x32_bf16 v[56:59], v[80:83], v[64:67], v[56:59]
	v_mfma_f32_16x16x32_bf16 v[26:29], v[84:87], v[64:67], v[26:29]
	v_mfma_f32_16x16x32_bf16 v[52:55], v[80:83], v[68:71], v[52:55]
	v_mfma_f32_16x16x32_bf16 v[36:39], v[84:87], v[68:71], v[36:39]
	v_mfma_f32_16x16x32_bf16 v[60:63], v[80:83], v[72:75], v[60:63]
	v_mfma_f32_16x16x32_bf16 v[40:43], v[84:87], v[72:75], v[40:43]
	v_mfma_f32_16x16x32_bf16 v[48:51], v[80:83], v[76:79], v[48:51]
	v_mfma_f32_16x16x32_bf16 v[44:47], v[84:87], v[76:79], v[44:47]
	ds_read_b128 v[64:67], v16 offset:3072
	ds_read_b128 v[68:71], v16 offset:7168
	ds_read_b128 v[72:75], v16 offset:11264
	ds_read_b128 v[76:79], v16 offset:15360
	ds_read_b128 v[80:83], v17 offset:35840
	ds_read_b128 v[84:87], v17 offset:39936
	s_waitcnt vmcnt(0)
	s_waitcnt vmcnt(0) lgkmcnt(0)
	v_mfma_f32_16x16x32_bf16 v[56:59], v[80:83], v[64:67], v[56:59]
	s_barrier
	v_mfma_f32_16x16x32_bf16 v[64:67], v[84:87], v[64:67], v[26:29]
	s_nop 2
	v_lshl_add_u64 v[26:27], v[2:3], 0, s[2:3]
	global_load_lds_dwordx4 v[26:27], off
	v_lshl_add_u64 v[26:27], v[0:1], 0, s[2:3]
	s_mov_b32 m0, s10
	v_or_b32_e32 v28, 0x19000, v17
	global_load_lds_dwordx4 v[26:27], off
	v_lshl_add_u64 v[26:27], v[6:7], 0, s[2:3]
	s_mov_b32 m0, s37
	v_mfma_f32_16x16x32_bf16 v[52:55], v[80:83], v[68:71], v[52:55]
	global_load_lds_dwordx4 v[26:27], off
	v_lshl_add_u64 v[26:27], v[4:5], 0, s[2:3]
	s_mov_b32 m0, s35
	v_mfma_f32_16x16x32_bf16 v[36:39], v[84:87], v[68:71], v[36:39]
	global_load_lds_dwordx4 v[26:27], off
	v_lshl_add_u64 v[26:27], v[10:11], 0, s[2:3]
	s_mov_b32 m0, s43
	v_mfma_f32_16x16x32_bf16 v[60:63], v[80:83], v[72:75], v[60:63]
	global_load_lds_dwordx4 v[26:27], off
	v_lshl_add_u64 v[26:27], v[8:9], 0, s[2:3]
	s_mov_b32 m0, s42
	v_mfma_f32_16x16x32_bf16 v[40:43], v[84:87], v[72:75], v[40:43]
	global_load_lds_dwordx4 v[26:27], off
	v_lshl_add_u64 v[26:27], v[14:15], 0, s[2:3]
	s_mov_b32 m0, s46
	v_mfma_f32_16x16x32_bf16 v[48:51], v[80:83], v[76:79], v[48:51]
	global_load_lds_dwordx4 v[26:27], off
	v_lshl_add_u64 v[26:27], v[12:13], 0, s[2:3]
	s_mov_b32 m0, s40
	v_mfma_f32_16x16x32_bf16 v[44:47], v[84:87], v[76:79], v[44:47]
	global_load_lds_dwordx4 v[26:27], off
	v_add_u32_e32 v26, 0x10000, v16
	v_or_b32_e32 v27, 0x18000, v17
	ds_read_b128 v[68:71], v26
	ds_read_b128 v[72:75], v26 offset:4096
	ds_read_b128 v[76:79], v26 offset:8192
	ds_read_b128 v[80:83], v26 offset:12288
	ds_read_b128 v[84:87], v27
	ds_read_b128 v[88:91], v28
	v_or_b32_e32 v29, 0x18400, v17
	s_waitcnt lgkmcnt(0)
	v_mfma_f32_16x16x32_bf16 v[56:59], v[84:87], v[68:71], v[56:59]
	s_mov_b32 m0, s38
	v_mfma_f32_16x16x32_bf16 v[64:67], v[88:91], v[68:71], v[64:67]
	v_mfma_f32_16x16x32_bf16 v[52:55], v[84:87], v[72:75], v[52:55]
	v_mfma_f32_16x16x32_bf16 v[36:39], v[88:91], v[72:75], v[36:39]
	v_mfma_f32_16x16x32_bf16 v[60:63], v[84:87], v[76:79], v[60:63]
	v_mfma_f32_16x16x32_bf16 v[40:43], v[88:91], v[76:79], v[40:43]
	v_mfma_f32_16x16x32_bf16 v[48:51], v[84:87], v[80:83], v[48:51]
	v_mfma_f32_16x16x32_bf16 v[44:47], v[88:91], v[80:83], v[44:47]
	ds_read_b128 v[68:71], v26 offset:1024
	ds_read_b128 v[72:75], v26 offset:5120
	ds_read_b128 v[76:79], v26 offset:9216
	ds_read_b128 v[80:83], v26 offset:13312
	ds_read_b128 v[84:87], v29
	ds_read_b128 v[88:91], v30
	s_waitcnt lgkmcnt(0)
	v_mfma_f32_16x16x32_bf16 v[56:59], v[84:87], v[68:71], v[56:59]
	v_mfma_f32_16x16x32_bf16 v[64:67], v[88:91], v[68:71], v[64:67]
	v_mfma_f32_16x16x32_bf16 v[68:71], v[88:91], v[72:75], v[36:39]
	s_nop 2
	v_or_b32_e32 v36, 0x19800, v17
	v_mfma_f32_16x16x32_bf16 v[52:55], v[84:87], v[72:75], v[52:55]
	v_or_b32_e32 v37, 0x18c00, v17
	v_mfma_f32_16x16x32_bf16 v[60:63], v[84:87], v[76:79], v[60:63]
	v_mfma_f32_16x16x32_bf16 v[38:41], v[88:91], v[76:79], v[40:43]
	v_mfma_f32_16x16x32_bf16 v[48:51], v[84:87], v[80:83], v[48:51]
	v_mfma_f32_16x16x32_bf16 v[42:45], v[88:91], v[80:83], v[44:47]
	ds_read_b128 v[72:75], v26 offset:2048
	ds_read_b128 v[76:79], v26 offset:6144
	ds_read_b128 v[80:83], v26 offset:10240
	ds_read_b128 v[84:87], v26 offset:14336
	ds_read_b128 v[88:91], v31
	ds_read_b128 v[92:95], v36
	s_waitcnt lgkmcnt(0)
	v_mfma_f32_16x16x32_bf16 v[56:59], v[88:91], v[72:75], v[56:59]
	v_mfma_f32_16x16x32_bf16 v[64:67], v[92:95], v[72:75], v[64:67]
	v_mfma_f32_16x16x32_bf16 v[52:55], v[88:91], v[76:79], v[52:55]
	v_mfma_f32_16x16x32_bf16 v[68:71], v[92:95], v[76:79], v[68:71]
	v_mfma_f32_16x16x32_bf16 v[60:63], v[88:91], v[80:83], v[60:63]
	v_mfma_f32_16x16x32_bf16 v[72:75], v[92:95], v[80:83], v[38:41]
	v_mfma_f32_16x16x32_bf16 v[46:49], v[88:91], v[84:87], v[48:51]
	s_nop 1
	v_or_b32_e32 v38, 0x19c00, v17
	v_mfma_f32_16x16x32_bf16 v[40:43], v[92:95], v[84:87], v[42:45]
	ds_read_b128 v[76:79], v26 offset:3072
	ds_read_b128 v[80:83], v26 offset:7168
	ds_read_b128 v[84:87], v26 offset:11264
	ds_read_b128 v[88:91], v26 offset:15360
	ds_read_b128 v[92:95], v37
	ds_read_b128 v[96:99], v38
	s_waitcnt lgkmcnt(0)
	v_mfma_f32_16x16x32_bf16 v[44:47], v[92:95], v[88:91], v[46:49]
	s_nop 2
	v_lshl_add_u64 v[48:49], v[2:3], 0, s[22:23]
	s_waitcnt vmcnt(0)
	s_waitcnt vmcnt(0)
	s_barrier
; #define LDSP __attribute__((address_space(3)))
; #define WAIT_V0() asm volatile("s_waitcnt vmcnt(0)" ::: "memory")
; template <int EK, int TS, int KS>
; DI void ctx_tiles(const Params& p, int l, const bf16_t* __restrict__ A, const bf16_t* __restrict__ Bt, int N, int K, ldsp_t shm) {
;     ...
;         for (int t = 0; t < nt; ++t) {
;             const int cur = t & 1;
;             if (t + 1 < nt) C_STAGE(cur ^ 1, t + 1);
;             ldsp_t sa = shm + cur * 2 * TILE_A, sb = sa + TILE_A;
; #pragma unroll
;             for (int ks = 0; ks < KS; ++ks) {
;                 bf16x8 At[MT], Bf[NT];
; #pragma unroll
;                 for (int m = 0; m < MT; ++m) At[m] = *(const LDSP bf16x8*)(sa + aoff + m * (KS * 1024) + ks * 1024);
; #pragma unroll
;                 for (int n = 0; n < NT; ++n) Bf[n] = *(const LDSP bf16x8*)(sb + boff + n * (KS * 1024) + ks * 1024);
; #pragma unroll
;                 for (int m = 0; m < MT; ++m)
; #pragma unroll
;                     for (int n = 0; n < NT; ++n) acc[m][n] = __builtin_amdgcn_mfma_f32_16x16x32_bf16(Bf[n], At[m], acc[m][n], 0, 0, 0);
;             }
;             WAIT_V0(); __syncthreads();
;         }
	global_load_lds_dwordx4 v[48:49], off
	v_lshl_add_u64 v[48:49], v[0:1], 0, s[22:23]
	s_mov_b32 m0, s41
	v_mfma_f32_16x16x32_bf16 v[56:59], v[92:95], v[76:79], v[56:59]
	global_load_lds_dwordx4 v[48:49], off
	v_lshl_add_u64 v[48:49], v[6:7], 0, s[22:23]
	s_mov_b32 m0, s50
	v_mfma_f32_16x16x32_bf16 v[64:67], v[96:99], v[76:79], v[64:67]
	global_load_lds_dwordx4 v[48:49], off
	v_lshl_add_u64 v[48:49], v[4:5], 0, s[22:23]
	s_mov_b32 m0, s47
	v_mfma_f32_16x16x32_bf16 v[50:53], v[92:95], v[80:83], v[52:55]
	global_load_lds_dwordx4 v[48:49], off
	v_lshl_add_u64 v[48:49], v[10:11], 0, s[22:23]
	s_mov_b32 m0, s51
	v_mfma_f32_16x16x32_bf16 v[68:71], v[96:99], v[80:83], v[68:71]
	global_load_lds_dwordx4 v[48:49], off
	v_lshl_add_u64 v[48:49], v[8:9], 0, s[22:23]
	s_mov_b32 m0, s85
	v_mfma_f32_16x16x32_bf16 v[60:63], v[92:95], v[84:87], v[60:63]
	global_load_lds_dwordx4 v[48:49], off
	v_lshl_add_u64 v[48:49], v[14:15], 0, s[22:23]
	s_mov_b32 m0, s84
	v_mfma_f32_16x16x32_bf16 v[72:75], v[96:99], v[84:87], v[72:75]
	global_load_lds_dwordx4 v[48:49], off
	v_lshl_add_u64 v[48:49], v[12:13], 0, s[22:23]
	s_mov_b32 m0, s39
	v_mfma_f32_16x16x32_bf16 v[40:43], v[96:99], v[88:91], v[40:43]
	global_load_lds_dwordx4 v[48:49], off
	ds_read_b128 v[76:79], v16
	ds_read_b128 v[80:83], v16 offset:4096
	ds_read_b128 v[84:87], v16 offset:8192
	ds_read_b128 v[88:91], v16 offset:12288
	ds_read_b128 v[92:95], v17 offset:32768
	ds_read_b128 v[96:99], v17 offset:36864
	s_waitcnt lgkmcnt(0)
	v_mfma_f32_16x16x32_bf16 v[54:57], v[92:95], v[76:79], v[56:59]
	s_mov_b32 m0, s11
	v_mfma_f32_16x16x32_bf16 v[64:67], v[96:99], v[76:79], v[64:67]
	v_mfma_f32_16x16x32_bf16 v[48:51], v[92:95], v[80:83], v[50:53]
	v_mfma_f32_16x16x32_bf16 v[68:71], v[96:99], v[80:83], v[68:71]
	v_mfma_f32_16x16x32_bf16 v[58:61], v[92:95], v[84:87], v[60:63]
	v_mfma_f32_16x16x32_bf16 v[72:75], v[96:99], v[84:87], v[72:75]
	v_mfma_f32_16x16x32_bf16 v[44:47], v[92:95], v[88:91], v[44:47]
	v_mfma_f32_16x16x32_bf16 v[40:43], v[96:99], v[88:91], v[40:43]
	ds_read_b128 v[76:79], v16 offset:1024
	ds_read_b128 v[80:83], v16 offset:5120
	ds_read_b128 v[84:87], v16 offset:9216
	ds_read_b128 v[88:91], v16 offset:13312
	ds_read_b128 v[92:95], v17 offset:33792
	ds_read_b128 v[96:99], v17 offset:37888
	s_waitcnt lgkmcnt(0)
	v_mfma_f32_16x16x32_bf16 v[52:55], v[92:95], v[76:79], v[54:57]
	v_mfma_f32_16x16x32_bf16 v[62:65], v[96:99], v[76:79], v[64:67]
	v_mfma_f32_16x16x32_bf16 v[48:51], v[92:95], v[80:83], v[48:51]
	v_mfma_f32_16x16x32_bf16 v[66:69], v[96:99], v[80:83], v[68:71]
	v_mfma_f32_16x16x32_bf16 v[56:59], v[92:95], v[84:87], v[58:61]
	v_mfma_f32_16x16x32_bf16 v[70:73], v[96:99], v[84:87], v[72:75]
	v_mfma_f32_16x16x32_bf16 v[44:47], v[92:95], v[88:91], v[44:47]
	v_mfma_f32_16x16x32_bf16 v[40:43], v[96:99], v[88:91], v[40:43]
	s_nop 0
	ds_read_b128 v[74:77], v16 offset:2048
	ds_read_b128 v[78:81], v16 offset:6144
	ds_read_b128 v[82:85], v16 offset:10240
	ds_read_b128 v[86:89], v16 offset:14336
	ds_read_b128 v[90:93], v17 offset:34816
	ds_read_b128 v[94:97], v17 offset:38912
	s_waitcnt lgkmcnt(0)
	v_mfma_f32_16x16x32_bf16 v[52:55], v[90:93], v[74:77], v[52:55]
	v_mfma_f32_16x16x32_bf16 v[60:63], v[94:97], v[74:77], v[62:65]
	v_mfma_f32_16x16x32_bf16 v[48:51], v[90:93], v[78:81], v[48:51]
	v_mfma_f32_16x16x32_bf16 v[64:67], v[94:97], v[78:81], v[66:69]
	v_mfma_f32_16x16x32_bf16 v[56:59], v[90:93], v[82:85], v[56:59]
	v_mfma_f32_16x16x32_bf16 v[68:71], v[94:97], v[82:85], v[70:73]
	v_mfma_f32_16x16x32_bf16 v[44:47], v[90:93], v[86:89], v[44:47]
	v_mfma_f32_16x16x32_bf16 v[40:43], v[94:97], v[86:89], v[40:43]
	s_nop 0
	ds_read_b128 v[72:75], v16 offset:3072
	ds_read_b128 v[76:79], v16 offset:7168
	ds_read_b128 v[80:83], v16 offset:11264
	ds_read_b128 v[84:87], v16 offset:15360
	ds_read_b128 v[88:91], v17 offset:35840
	ds_read_b128 v[92:95], v17 offset:39936
	s_waitcnt vmcnt(0)
	s_waitcnt vmcnt(0) lgkmcnt(0)
	v_mfma_f32_16x16x32_bf16 v[52:55], v[88:91], v[72:75], v[52:55]
	s_barrier
	v_mfma_f32_16x16x32_bf16 v[60:63], v[92:95], v[72:75], v[60:63]
	v_lshl_add_u64 v[72:73], v[2:3], 0, s[18:19]
	global_load_lds_dwordx4 v[72:73], off
	v_lshl_add_u64 v[72:73], v[0:1], 0, s[18:19]
	s_mov_b32 m0, s10
	v_mfma_f32_16x16x32_bf16 v[48:51], v[88:91], v[76:79], v[48:51]
	global_load_lds_dwordx4 v[72:73], off
	v_lshl_add_u64 v[72:73], v[6:7], 0, s[18:19]
	s_mov_b32 m0, s37
	v_mfma_f32_16x16x32_bf16 v[64:67], v[92:95], v[76:79], v[64:67]
	global_load_lds_dwordx4 v[72:73], off
	v_lshl_add_u64 v[72:73], v[4:5], 0, s[18:19]
	s_mov_b32 m0, s35
	v_mfma_f32_16x16x32_bf16 v[56:59], v[88:91], v[80:83], v[56:59]
	global_load_lds_dwordx4 v[72:73], off
	v_lshl_add_u64 v[72:73], v[10:11], 0, s[18:19]
	s_mov_b32 m0, s43
	v_mfma_f32_16x16x32_bf16 v[68:71], v[92:95], v[80:83], v[68:71]
	global_load_lds_dwordx4 v[72:73], off
	v_lshl_add_u64 v[72:73], v[8:9], 0, s[18:19]
	s_mov_b32 m0, s42
	v_mfma_f32_16x16x32_bf16 v[44:47], v[88:91], v[84:87], v[44:47]
	global_load_lds_dwordx4 v[72:73], off
	v_lshl_add_u64 v[72:73], v[14:15], 0, s[18:19]
	s_mov_b32 m0, s46
	v_mfma_f32_16x16x32_bf16 v[40:43], v[92:95], v[84:87], v[40:43]
	global_load_lds_dwordx4 v[72:73], off
	v_lshl_add_u64 v[72:73], v[12:13], 0, s[18:19]
	s_mov_b32 m0, s40
	s_nop 0
	global_load_lds_dwordx4 v[72:73], off
	ds_read_b128 v[72:75], v26
	ds_read_b128 v[76:79], v26 offset:4096
	ds_read_b128 v[80:83], v26 offset:8192
	ds_read_b128 v[84:87], v26 offset:12288
	ds_read_b128 v[88:91], v27
	ds_read_b128 v[92:95], v28
	s_waitcnt lgkmcnt(0)
; #define LDSP __attribute__((address_space(3)))
; #define WAIT_V0() asm volatile("s_waitcnt vmcnt(0)" ::: "memory")
; template <int EK, int TS, int KS>
; DI void ctx_tiles(const Params& p, int l, const bf16_t* __restrict__ A, const bf16_t* __restrict__ Bt, int N, int K, ldsp_t shm) {
;     ...
;         for (int t = 0; t < nt; ++t) {
;             const int cur = t & 1;
;             if (t + 1 < nt) C_STAGE(cur ^ 1, t + 1);
;             ldsp_t sa = shm + cur * 2 * TILE_A, sb = sa + TILE_A;
; #pragma unroll
;             for (int ks = 0; ks < KS; ++ks) {
;                 bf16x8 At[MT], Bf[NT];
; #pragma unroll
;                 for (int m = 0; m < MT; ++m) At[m] = *(const LDSP bf16x8*)(sa + aoff + m * (KS * 1024) + ks * 1024);
; #pragma unroll
;                 for (int n = 0; n < NT; ++n) Bf[n] = *(const LDSP bf16x8*)(sb + boff + n * (KS * 1024) + ks * 1024);
; #pragma unroll
;                 for (int m = 0; m < MT; ++m)
; #pragma unroll
;                     for (int n = 0; n < NT; ++n) acc[m][n] = __builtin_amdgcn_mfma_f32_16x16x32_bf16(Bf[n], At[m], acc[m][n], 0, 0, 0);
;             }
;             WAIT_V0(); __syncthreads();
;         }
	v_mfma_f32_16x16x32_bf16 v[52:55], v[88:91], v[72:75], v[52:55]
	s_mov_b32 m0, s38
	v_mfma_f32_16x16x32_bf16 v[60:63], v[92:95], v[72:75], v[60:63]
	v_mfma_f32_16x16x32_bf16 v[48:51], v[88:91], v[76:79], v[48:51]
	v_mfma_f32_16x16x32_bf16 v[64:67], v[92:95], v[76:79], v[64:67]
	v_mfma_f32_16x16x32_bf16 v[56:59], v[88:91], v[80:83], v[56:59]
	v_mfma_f32_16x16x32_bf16 v[68:71], v[92:95], v[80:83], v[68:71]
	v_mfma_f32_16x16x32_bf16 v[44:47], v[88:91], v[84:87], v[44:47]
	v_mfma_f32_16x16x32_bf16 v[40:43], v[92:95], v[84:87], v[40:43]
	ds_read_b128 v[72:75], v26 offset:1024
	ds_read_b128 v[76:79], v26 offset:5120
	ds_read_b128 v[80:83], v26 offset:9216
	ds_read_b128 v[84:87], v26 offset:13312
	ds_read_b128 v[88:91], v29
	ds_read_b128 v[92:95], v30
	s_waitcnt lgkmcnt(0)
	v_mfma_f32_16x16x32_bf16 v[52:55], v[88:91], v[72:75], v[52:55]
	v_mfma_f32_16x16x32_bf16 v[60:63], v[92:95], v[72:75], v[60:63]
	v_mfma_f32_16x16x32_bf16 v[48:51], v[88:91], v[76:79], v[48:51]
	v_mfma_f32_16x16x32_bf16 v[64:67], v[92:95], v[76:79], v[64:67]
	v_mfma_f32_16x16x32_bf16 v[56:59], v[88:91], v[80:83], v[56:59]
	v_mfma_f32_16x16x32_bf16 v[68:71], v[92:95], v[80:83], v[68:71]
	v_mfma_f32_16x16x32_bf16 v[44:47], v[88:91], v[84:87], v[44:47]
	v_mfma_f32_16x16x32_bf16 v[40:43], v[92:95], v[84:87], v[40:43]
	ds_read_b128 v[72:75], v26 offset:2048
	ds_read_b128 v[76:79], v26 offset:6144
	ds_read_b128 v[80:83], v26 offset:10240
	ds_read_b128 v[84:87], v26 offset:14336
	ds_read_b128 v[88:91], v31
	ds_read_b128 v[92:95], v36
	s_waitcnt lgkmcnt(0)
	v_mfma_f32_16x16x32_bf16 v[52:55], v[88:91], v[72:75], v[52:55]
	v_mfma_f32_16x16x32_bf16 v[60:63], v[92:95], v[72:75], v[60:63]
	v_mfma_f32_16x16x32_bf16 v[48:51], v[88:91], v[76:79], v[48:51]
	v_mfma_f32_16x16x32_bf16 v[64:67], v[92:95], v[76:79], v[64:67]
	v_mfma_f32_16x16x32_bf16 v[56:59], v[88:91], v[80:83], v[56:59]
	v_mfma_f32_16x16x32_bf16 v[68:71], v[92:95], v[80:83], v[68:71]
	v_mfma_f32_16x16x32_bf16 v[44:47], v[88:91], v[84:87], v[44:47]
	v_mfma_f32_16x16x32_bf16 v[40:43], v[92:95], v[84:87], v[40:43]
	ds_read_b128 v[72:75], v26 offset:3072
	ds_read_b128 v[76:79], v26 offset:7168
	ds_read_b128 v[80:83], v26 offset:11264
	ds_read_b128 v[84:87], v26 offset:15360
	ds_read_b128 v[88:91], v37
	ds_read_b128 v[92:95], v38
	s_waitcnt vmcnt(0)
	s_waitcnt vmcnt(0) lgkmcnt(0)
	v_mfma_f32_16x16x32_bf16 v[52:55], v[88:91], v[72:75], v[52:55]
	s_barrier
	v_mfma_f32_16x16x32_bf16 v[60:63], v[92:95], v[72:75], v[60:63]
	v_lshl_add_u64 v[72:73], v[2:3], 0, s[24:25]
	global_load_lds_dwordx4 v[72:73], off
	v_lshl_add_u64 v[72:73], v[0:1], 0, s[24:25]
	s_mov_b32 m0, s41
	v_mfma_f32_16x16x32_bf16 v[48:51], v[88:91], v[76:79], v[48:51]
	global_load_lds_dwordx4 v[72:73], off
	v_lshl_add_u64 v[72:73], v[6:7], 0, s[24:25]
	s_mov_b32 m0, s50
	v_mfma_f32_16x16x32_bf16 v[64:67], v[92:95], v[76:79], v[64:67]
	global_load_lds_dwordx4 v[72:73], off
	v_lshl_add_u64 v[72:73], v[4:5], 0, s[24:25]
	s_mov_b32 m0, s47
	v_mfma_f32_16x16x32_bf16 v[56:59], v[88:91], v[80:83], v[56:59]
	global_load_lds_dwordx4 v[72:73], off
	v_lshl_add_u64 v[72:73], v[10:11], 0, s[24:25]
	s_mov_b32 m0, s51
	v_mfma_f32_16x16x32_bf16 v[68:71], v[92:95], v[80:83], v[68:71]
	global_load_lds_dwordx4 v[72:73], off
	v_lshl_add_u64 v[72:73], v[8:9], 0, s[24:25]
	s_mov_b32 m0, s85
	v_mfma_f32_16x16x32_bf16 v[44:47], v[88:91], v[84:87], v[44:47]
	global_load_lds_dwordx4 v[72:73], off
	v_lshl_add_u64 v[72:73], v[14:15], 0, s[24:25]
	s_mov_b32 m0, s84
	v_mfma_f32_16x16x32_bf16 v[40:43], v[92:95], v[84:87], v[40:43]
	global_load_lds_dwordx4 v[72:73], off
	v_lshl_add_u64 v[72:73], v[12:13], 0, s[24:25]
	s_mov_b32 m0, s39
	s_nop 0
	global_load_lds_dwordx4 v[72:73], off
	ds_read_b128 v[72:75], v16
	ds_read_b128 v[76:79], v16 offset:4096
	ds_read_b128 v[80:83], v16 offset:8192
	ds_read_b128 v[84:87], v16 offset:12288
	ds_read_b128 v[88:91], v17 offset:32768
	ds_read_b128 v[92:95], v17 offset:36864
	s_waitcnt lgkmcnt(0)
	v_mfma_f32_16x16x32_bf16 v[52:55], v[88:91], v[72:75], v[52:55]
	s_mov_b32 m0, s11
	s_lshl_b32 s11, s34, 7
	s_addk_i32 s11, 0x4000
	v_mfma_f32_16x16x32_bf16 v[60:63], v[92:95], v[72:75], v[60:63]
	v_mfma_f32_16x16x32_bf16 v[48:51], v[88:91], v[76:79], v[48:51]
	v_mfma_f32_16x16x32_bf16 v[64:67], v[92:95], v[76:79], v[64:67]
	v_mfma_f32_16x16x32_bf16 v[56:59], v[88:91], v[80:83], v[56:59]
	v_mfma_f32_16x16x32_bf16 v[68:71], v[92:95], v[80:83], v[68:71]
	v_mfma_f32_16x16x32_bf16 v[44:47], v[88:91], v[84:87], v[44:47]
	v_mfma_f32_16x16x32_bf16 v[40:43], v[92:95], v[84:87], v[40:43]
	ds_read_b128 v[72:75], v16 offset:1024
	ds_read_b128 v[76:79], v16 offset:5120
	ds_read_b128 v[80:83], v16 offset:9216
	ds_read_b128 v[84:87], v16 offset:13312
	ds_read_b128 v[88:91], v17 offset:33792
	ds_read_b128 v[92:95], v17 offset:37888
	s_waitcnt lgkmcnt(0)
	v_mfma_f32_16x16x32_bf16 v[52:55], v[88:91], v[72:75], v[52:55]
	v_mfma_f32_16x16x32_bf16 v[60:63], v[92:95], v[72:75], v[60:63]
	v_mfma_f32_16x16x32_bf16 v[48:51], v[88:91], v[76:79], v[48:51]
	v_mfma_f32_16x16x32_bf16 v[64:67], v[92:95], v[76:79], v[64:67]
	v_mfma_f32_16x16x32_bf16 v[56:59], v[88:91], v[80:83], v[56:59]
	v_mfma_f32_16x16x32_bf16 v[68:71], v[92:95], v[80:83], v[68:71]
	v_mfma_f32_16x16x32_bf16 v[44:47], v[88:91], v[84:87], v[44:47]
	v_mfma_f32_16x16x32_bf16 v[40:43], v[92:95], v[84:87], v[40:43]
	ds_read_b128 v[72:75], v16 offset:2048
	ds_read_b128 v[76:79], v16 offset:6144
	ds_read_b128 v[80:83], v16 offset:10240
	ds_read_b128 v[84:87], v16 offset:14336
	ds_read_b128 v[88:91], v17 offset:34816
	ds_read_b128 v[92:95], v17 offset:38912
	s_waitcnt lgkmcnt(0)
	v_mfma_f32_16x16x32_bf16 v[52:55], v[88:91], v[72:75], v[52:55]
	v_mfma_f32_16x16x32_bf16 v[60:63], v[92:95], v[72:75], v[60:63]
	v_mfma_f32_16x16x32_bf16 v[48:51], v[88:91], v[76:79], v[48:51]
	v_mfma_f32_16x16x32_bf16 v[64:67], v[92:95], v[76:79], v[64:67]
	v_mfma_f32_16x16x32_bf16 v[56:59], v[88:91], v[80:83], v[56:59]
	v_mfma_f32_16x16x32_bf16 v[68:71], v[92:95], v[80:83], v[68:71]
	v_mfma_f32_16x16x32_bf16 v[44:47], v[88:91], v[84:87], v[44:47]
	v_mfma_f32_16x16x32_bf16 v[40:43], v[92:95], v[84:87], v[40:43]
	ds_read_b128 v[72:75], v16 offset:3072
	ds_read_b128 v[76:79], v16 offset:7168
	ds_read_b128 v[80:83], v16 offset:11264
	ds_read_b128 v[84:87], v16 offset:15360
	ds_read_b128 v[88:91], v17 offset:35840
	ds_read_b128 v[92:95], v17 offset:39936
	s_waitcnt vmcnt(0)
	s_waitcnt vmcnt(0) lgkmcnt(0)
	v_mfma_f32_16x16x32_bf16 v[52:55], v[88:91], v[72:75], v[52:55]
	s_barrier
; #define LDSP __attribute__((address_space(3)))
; #define WAIT_V0() asm volatile("s_waitcnt vmcnt(0)" ::: "memory")
; template <int EK, int TS, int KS>
; DI void ctx_tiles(const Params& p, int l, const bf16_t* __restrict__ A, const bf16_t* __restrict__ Bt, int N, int K, ldsp_t shm) {
;     ...
;         for (int t = 0; t < nt; ++t) {
;             const int cur = t & 1;
;             if (t + 1 < nt) C_STAGE(cur ^ 1, t + 1);
;             ldsp_t sa = shm + cur * 2 * TILE_A, sb = sa + TILE_A;
; #pragma unroll
;             for (int ks = 0; ks < KS; ++ks) {
;                 bf16x8 At[MT], Bf[NT];
; #pragma unroll
;                 for (int m = 0; m < MT; ++m) At[m] = *(const LDSP bf16x8*)(sa + aoff + m * (KS * 1024) + ks * 1024);
; #pragma unroll
;                 for (int n = 0; n < NT; ++n) Bf[n] = *(const LDSP bf16x8*)(sb + boff + n * (KS * 1024) + ks * 1024);
; #pragma unroll
;                 for (int m = 0; m < MT; ++m)
; #pragma unroll
;                     for (int n = 0; n < NT; ++n) acc[m][n] = __builtin_amdgcn_mfma_f32_16x16x32_bf16(Bf[n], At[m], acc[m][n], 0, 0, 0);
;             }
;             WAIT_V0(); __syncthreads();
;         }
	v_mfma_f32_16x16x32_bf16 v[60:63], v[92:95], v[72:75], v[60:63]
	v_lshl_add_u64 v[72:73], v[2:3], 0, s[16:17]
	global_load_lds_dwordx4 v[72:73], off
	v_lshl_add_u64 v[72:73], v[0:1], 0, s[16:17]
	s_mov_b32 m0, s10
	v_mfma_f32_16x16x32_bf16 v[48:51], v[88:91], v[76:79], v[48:51]
	global_load_lds_dwordx4 v[72:73], off
	v_lshl_add_u64 v[72:73], v[6:7], 0, s[16:17]
	s_mov_b32 m0, s37
	v_mfma_f32_16x16x32_bf16 v[64:67], v[92:95], v[76:79], v[64:67]
	global_load_lds_dwordx4 v[72:73], off
	v_lshl_add_u64 v[72:73], v[4:5], 0, s[16:17]
	s_mov_b32 m0, s35
	v_mfma_f32_16x16x32_bf16 v[56:59], v[88:91], v[80:83], v[56:59]
	global_load_lds_dwordx4 v[72:73], off
	v_lshl_add_u64 v[72:73], v[10:11], 0, s[16:17]
	s_mov_b32 m0, s43
	v_mfma_f32_16x16x32_bf16 v[68:71], v[92:95], v[80:83], v[68:71]
	global_load_lds_dwordx4 v[72:73], off
	v_lshl_add_u64 v[72:73], v[8:9], 0, s[16:17]
	s_mov_b32 m0, s42
	v_mfma_f32_16x16x32_bf16 v[44:47], v[88:91], v[84:87], v[44:47]
	global_load_lds_dwordx4 v[72:73], off
	v_lshl_add_u64 v[72:73], v[14:15], 0, s[16:17]
	s_mov_b32 m0, s46
	v_mfma_f32_16x16x32_bf16 v[40:43], v[92:95], v[84:87], v[40:43]
	global_load_lds_dwordx4 v[72:73], off
	v_lshl_add_u64 v[72:73], v[12:13], 0, s[16:17]
	s_mov_b32 m0, s40
	v_readfirstlane_b32 s10, v18
	global_load_lds_dwordx4 v[72:73], off
	ds_read_b128 v[72:75], v26
	ds_read_b128 v[76:79], v26 offset:4096
	ds_read_b128 v[80:83], v26 offset:8192
	ds_read_b128 v[84:87], v26 offset:12288
	ds_read_b128 v[88:91], v27
	ds_read_b128 v[92:95], v28
	s_waitcnt lgkmcnt(0)
	v_mfma_f32_16x16x32_bf16 v[52:55], v[88:91], v[72:75], v[52:55]
	v_lshl_add_u64 v[2:3], v[2:3], 0, s[26:27]
	s_mov_b32 m0, s10
	v_readfirstlane_b32 s10, v19
	v_mfma_f32_16x16x32_bf16 v[60:63], v[92:95], v[72:75], v[60:63]
	v_lshl_add_u64 v[0:1], v[0:1], 0, s[26:27]
	v_mfma_f32_16x16x32_bf16 v[48:51], v[88:91], v[76:79], v[48:51]
	v_mfma_f32_16x16x32_bf16 v[64:67], v[92:95], v[76:79], v[64:67]
	v_mfma_f32_16x16x32_bf16 v[56:59], v[88:91], v[80:83], v[56:59]
	v_mfma_f32_16x16x32_bf16 v[68:71], v[92:95], v[80:83], v[68:71]
	v_mfma_f32_16x16x32_bf16 v[44:47], v[88:91], v[84:87], v[44:47]
	v_mfma_f32_16x16x32_bf16 v[40:43], v[92:95], v[84:87], v[40:43]
	ds_read_b128 v[72:75], v26 offset:1024
	ds_read_b128 v[76:79], v26 offset:5120
	ds_read_b128 v[80:83], v26 offset:9216
	ds_read_b128 v[84:87], v26 offset:13312
	ds_read_b128 v[88:91], v29
	ds_read_b128 v[92:95], v30
	s_waitcnt lgkmcnt(0)
	v_mfma_f32_16x16x32_bf16 v[52:55], v[88:91], v[72:75], v[52:55]
	v_mfma_f32_16x16x32_bf16 v[60:63], v[92:95], v[72:75], v[60:63]
	v_mfma_f32_16x16x32_bf16 v[48:51], v[88:91], v[76:79], v[48:51]
	v_mfma_f32_16x16x32_bf16 v[64:67], v[92:95], v[76:79], v[64:67]
	v_mfma_f32_16x16x32_bf16 v[56:59], v[88:91], v[80:83], v[56:59]
	v_mfma_f32_16x16x32_bf16 v[68:71], v[92:95], v[80:83], v[68:71]
	v_mfma_f32_16x16x32_bf16 v[44:47], v[88:91], v[84:87], v[44:47]
	v_mfma_f32_16x16x32_bf16 v[40:43], v[92:95], v[84:87], v[40:43]
	ds_read_b128 v[72:75], v26 offset:2048
	ds_read_b128 v[76:79], v26 offset:6144
	ds_read_b128 v[80:83], v26 offset:10240
	ds_read_b128 v[84:87], v26 offset:14336
	ds_read_b128 v[88:91], v31
	ds_read_b128 v[92:95], v36
	s_waitcnt lgkmcnt(0)
	v_mfma_f32_16x16x32_bf16 v[52:55], v[88:91], v[72:75], v[52:55]
	v_mfma_f32_16x16x32_bf16 v[60:63], v[92:95], v[72:75], v[60:63]
	v_mfma_f32_16x16x32_bf16 v[48:51], v[88:91], v[76:79], v[48:51]
	v_mfma_f32_16x16x32_bf16 v[64:67], v[92:95], v[76:79], v[64:67]
	v_mfma_f32_16x16x32_bf16 v[56:59], v[88:91], v[80:83], v[56:59]
	v_mfma_f32_16x16x32_bf16 v[68:71], v[92:95], v[80:83], v[68:71]
	v_mfma_f32_16x16x32_bf16 v[44:47], v[88:91], v[84:87], v[44:47]
	v_mfma_f32_16x16x32_bf16 v[40:43], v[92:95], v[84:87], v[40:43]
	ds_read_b128 v[72:75], v26 offset:3072
	ds_read_b128 v[76:79], v26 offset:7168
	ds_read_b128 v[80:83], v26 offset:11264
	ds_read_b128 v[84:87], v26 offset:15360
	ds_read_b128 v[88:91], v37
	ds_read_b128 v[92:95], v38
	s_waitcnt vmcnt(0)
	s_waitcnt vmcnt(0) lgkmcnt(0)
	s_barrier
	global_load_lds_dwordx4 v[2:3], off
	s_mov_b32 m0, s10
	v_readfirstlane_b32 s10, v20
	global_load_lds_dwordx4 v[0:1], off
	v_lshl_add_u64 v[0:1], v[6:7], 0, s[26:27]
	s_mov_b32 m0, s10
	v_readfirstlane_b32 s10, v21
	global_load_lds_dwordx4 v[0:1], off
	v_lshl_add_u64 v[0:1], v[4:5], 0, s[26:27]
	s_mov_b32 m0, s10
	v_readfirstlane_b32 s10, v22
	global_load_lds_dwordx4 v[0:1], off
	v_lshl_add_u64 v[0:1], v[10:11], 0, s[26:27]
	s_mov_b32 m0, s10
	v_readfirstlane_b32 s10, v23
	global_load_lds_dwordx4 v[0:1], off
	v_lshl_add_u64 v[0:1], v[8:9], 0, s[26:27]
	s_mov_b32 m0, s10
	v_readfirstlane_b32 s10, v24
	global_load_lds_dwordx4 v[0:1], off
	v_lshl_add_u64 v[0:1], v[14:15], 0, s[26:27]
	s_mov_b32 m0, s10
	v_readfirstlane_b32 s10, v25
	global_load_lds_dwordx4 v[0:1], off
	v_lshl_add_u64 v[0:1], v[12:13], 0, s[26:27]
	s_mov_b32 m0, s10
	v_mfma_f32_16x16x32_bf16 v[52:55], v[88:91], v[72:75], v[52:55]
	global_load_lds_dwordx4 v[0:1], off
	ds_read_b128 v[0:3], v16
	ds_read_b128 v[4:7], v16 offset:4096
	ds_read_b128 v[8:11], v16 offset:8192
	ds_read_b128 v[12:15], v16 offset:12288
	ds_read_b128 v[18:21], v17 offset:32768
	ds_read_b128 v[22:25], v17 offset:36864
	v_mfma_f32_16x16x32_bf16 v[60:63], v[92:95], v[72:75], v[60:63]
	s_lshl_b32 s10, s36, 7
	v_mfma_f32_16x16x32_bf16 v[48:51], v[88:91], v[76:79], v[48:51]
	v_mfma_f32_16x16x32_bf16 v[64:67], v[92:95], v[76:79], v[64:67]
	v_mfma_f32_16x16x32_bf16 v[56:59], v[88:91], v[80:83], v[56:59]
	v_mfma_f32_16x16x32_bf16 v[68:71], v[92:95], v[80:83], v[68:71]
	v_mfma_f32_16x16x32_bf16 v[44:47], v[88:91], v[84:87], v[44:47]
	v_mfma_f32_16x16x32_bf16 v[40:43], v[92:95], v[84:87], v[40:43]
	s_waitcnt lgkmcnt(0)
; #define LDSP __attribute__((address_space(3)))
; #define WAIT_V0() asm volatile("s_waitcnt vmcnt(0)" ::: "memory")
; template <int EK, int TS, int KS>
; DI void ctx_tiles(const Params& p, int l, const bf16_t* __restrict__ A, const bf16_t* __restrict__ Bt, int N, int K, ldsp_t shm) {
;     ...
;         for (int t = 0; t < nt; ++t) {
;             const int cur = t & 1;
;             if (t + 1 < nt) C_STAGE(cur ^ 1, t + 1);
;             ldsp_t sa = shm + cur * 2 * TILE_A, sb = sa + TILE_A;
; #pragma unroll
;             for (int ks = 0; ks < KS; ++ks) {
;                 bf16x8 At[MT], Bf[NT];
; #pragma unroll
;                 for (int m = 0; m < MT; ++m) At[m] = *(const LDSP bf16x8*)(sa + aoff + m * (KS * 1024) + ks * 1024);
; #pragma unroll
;                 for (int n = 0; n < NT; ++n) Bf[n] = *(const LDSP bf16x8*)(sb + boff + n * (KS * 1024) + ks * 1024);
; #pragma unroll
;                 for (int m = 0; m < MT; ++m)
; #pragma unroll
;                     for (int n = 0; n < NT; ++n) acc[m][n] = __builtin_amdgcn_mfma_f32_16x16x32_bf16(Bf[n], At[m], acc[m][n], 0, 0, 0);
;             }
;             WAIT_V0(); __syncthreads();
;         }
	v_mfma_f32_16x16x32_bf16 v[52:55], v[18:21], v[0:3], v[52:55]
	v_mfma_f32_16x16x32_bf16 v[0:3], v[22:25], v[0:3], v[60:63]
	v_mfma_f32_16x16x32_bf16 v[48:51], v[18:21], v[4:7], v[48:51]
	v_mfma_f32_16x16x32_bf16 v[4:7], v[22:25], v[4:7], v[64:67]
	v_mfma_f32_16x16x32_bf16 v[56:59], v[18:21], v[8:11], v[56:59]
	v_mfma_f32_16x16x32_bf16 v[8:11], v[22:25], v[8:11], v[68:71]
	v_mfma_f32_16x16x32_bf16 v[18:21], v[18:21], v[12:15], v[44:47]
	v_mfma_f32_16x16x32_bf16 v[12:15], v[22:25], v[12:15], v[40:43]
	ds_read_b128 v[22:25], v16 offset:1024
	s_nop 1
	ds_read_b128 v[40:43], v16 offset:5120
	ds_read_b128 v[44:47], v16 offset:9216
	ds_read_b128 v[60:63], v16 offset:13312
	ds_read_b128 v[64:67], v17 offset:33792
	ds_read_b128 v[68:71], v17 offset:37888
	s_waitcnt lgkmcnt(0)
	v_mfma_f32_16x16x32_bf16 v[52:55], v[64:67], v[22:25], v[52:55]
	v_mfma_f32_16x16x32_bf16 v[0:3], v[68:71], v[22:25], v[0:3]
	v_mfma_f32_16x16x32_bf16 v[22:25], v[64:67], v[40:43], v[48:51]
	v_mfma_f32_16x16x32_bf16 v[4:7], v[68:71], v[40:43], v[4:7]
	v_mfma_f32_16x16x32_bf16 v[40:43], v[64:67], v[44:47], v[56:59]
	v_mfma_f32_16x16x32_bf16 v[8:11], v[68:71], v[44:47], v[8:11]
	v_mfma_f32_16x16x32_bf16 v[18:21], v[64:67], v[60:63], v[18:21]
	v_mfma_f32_16x16x32_bf16 v[12:15], v[68:71], v[60:63], v[12:15]
	ds_read_b128 v[44:47], v16 offset:2048
	ds_read_b128 v[48:51], v16 offset:6144
	ds_read_b128 v[56:59], v16 offset:10240
	ds_read_b128 v[60:63], v16 offset:14336
	ds_read_b128 v[64:67], v17 offset:34816
	ds_read_b128 v[68:71], v17 offset:38912
	s_waitcnt lgkmcnt(0)
	v_mfma_f32_16x16x32_bf16 v[52:55], v[64:67], v[44:47], v[52:55]
	v_mfma_f32_16x16x32_bf16 v[0:3], v[68:71], v[44:47], v[0:3]
	v_mfma_f32_16x16x32_bf16 v[22:25], v[64:67], v[48:51], v[22:25]
	v_mfma_f32_16x16x32_bf16 v[4:7], v[68:71], v[48:51], v[4:7]
	v_mfma_f32_16x16x32_bf16 v[40:43], v[64:67], v[56:59], v[40:43]
	v_mfma_f32_16x16x32_bf16 v[8:11], v[68:71], v[56:59], v[8:11]
	v_mfma_f32_16x16x32_bf16 v[18:21], v[64:67], v[60:63], v[18:21]
	v_mfma_f32_16x16x32_bf16 v[12:15], v[68:71], v[60:63], v[12:15]
	ds_read_b128 v[44:47], v16 offset:3072
	ds_read_b128 v[48:51], v16 offset:7168
	ds_read_b128 v[56:59], v16 offset:11264
	ds_read_b128 v[60:63], v16 offset:15360
	ds_read_b128 v[64:67], v17 offset:35840
	ds_read_b128 v[68:71], v17 offset:39936
	s_waitcnt vmcnt(0)
	s_waitcnt vmcnt(0) lgkmcnt(0)
	v_mfma_f32_16x16x32_bf16 v[52:55], v[64:67], v[44:47], v[52:55]
	s_barrier
	v_mfma_f32_16x16x32_bf16 v[0:3], v[68:71], v[44:47], v[0:3]
	v_mfma_f32_16x16x32_bf16 v[22:25], v[64:67], v[48:51], v[22:25]
	v_mfma_f32_16x16x32_bf16 v[4:7], v[68:71], v[48:51], v[4:7]
	v_mfma_f32_16x16x32_bf16 v[40:43], v[64:67], v[56:59], v[40:43]
	v_mfma_f32_16x16x32_bf16 v[8:11], v[68:71], v[56:59], v[8:11]
	v_mfma_f32_16x16x32_bf16 v[16:19], v[64:67], v[60:63], v[18:21]
	v_mfma_f32_16x16x32_bf16 v[12:15], v[68:71], v[60:63], v[12:15]
	ds_read_b128 v[44:47], v28
	ds_read_b128 v[48:51], v27
	ds_read_b128 v[56:59], v26 offset:12288
	ds_read_b128 v[60:63], v26 offset:8192
	ds_read_b128 v[64:67], v26 offset:4096
	ds_read_b128 v[68:71], v26
	s_waitcnt lgkmcnt(0)
	v_mfma_f32_16x16x32_bf16 v[52:55], v[48:51], v[68:71], v[52:55]
	v_mfma_f32_16x16x32_bf16 v[0:3], v[44:47], v[68:71], v[0:3]
	v_mfma_f32_16x16x32_bf16 v[20:23], v[48:51], v[64:67], v[22:25]
	v_mfma_f32_16x16x32_bf16 v[4:7], v[44:47], v[64:67], v[4:7]
	v_mfma_f32_16x16x32_bf16 v[40:43], v[48:51], v[60:63], v[40:43]
	v_mfma_f32_16x16x32_bf16 v[8:11], v[44:47], v[60:63], v[8:11]
	v_mfma_f32_16x16x32_bf16 v[16:19], v[48:51], v[56:59], v[16:19]
	v_mfma_f32_16x16x32_bf16 v[12:15], v[44:47], v[56:59], v[12:15]
	ds_read_b128 v[44:47], v26 offset:1024
	ds_read_b128 v[48:51], v26 offset:5120
	ds_read_b128 v[56:59], v26 offset:9216
	ds_read_b128 v[60:63], v26 offset:13312
	ds_read_b128 v[64:67], v29
	ds_read_b128 v[68:71], v30
	s_waitcnt lgkmcnt(1)
	v_mfma_f32_16x16x32_bf16 v[52:55], v[64:67], v[44:47], v[52:55]
	s_waitcnt lgkmcnt(0)
	v_mfma_f32_16x16x32_bf16 v[0:3], v[68:71], v[44:47], v[0:3]
	v_mfma_f32_16x16x32_bf16 v[20:23], v[64:67], v[48:51], v[20:23]
	v_mfma_f32_16x16x32_bf16 v[4:7], v[68:71], v[48:51], v[4:7]
	v_mfma_f32_16x16x32_bf16 v[40:43], v[64:67], v[56:59], v[40:43]
	v_mfma_f32_16x16x32_bf16 v[8:11], v[68:71], v[56:59], v[8:11]
	v_mfma_f32_16x16x32_bf16 v[16:19], v[64:67], v[60:63], v[16:19]
	v_mfma_f32_16x16x32_bf16 v[12:15], v[68:71], v[60:63], v[12:15]
	ds_read_b128 v[44:47], v26 offset:2048
	ds_read_b128 v[48:51], v26 offset:6144
	ds_read_b128 v[56:59], v26 offset:10240
	ds_read_b128 v[60:63], v26 offset:14336
	ds_read_b128 v[28:31], v31
	ds_read_b128 v[64:67], v36
	s_waitcnt lgkmcnt(1)
	v_mfma_f32_16x16x32_bf16 v[52:55], v[28:31], v[44:47], v[52:55]
	s_waitcnt lgkmcnt(0)
	v_mfma_f32_16x16x32_bf16 v[0:3], v[64:67], v[44:47], v[0:3]
	v_mfma_f32_16x16x32_bf16 v[20:23], v[28:31], v[48:51], v[20:23]
	v_mfma_f32_16x16x32_bf16 v[44:47], v[64:67], v[48:51], v[4:7]
	v_mfma_f32_16x16x32_bf16 v[40:43], v[28:31], v[56:59], v[40:43]
	v_mfma_f32_16x16x32_bf16 v[48:51], v[64:67], v[56:59], v[8:11]
	v_mfma_f32_16x16x32_bf16 v[56:59], v[28:31], v[60:63], v[16:19]
	v_mfma_f32_16x16x32_bf16 v[60:63], v[64:67], v[60:63], v[12:15]
	ds_read_b128 v[4:7], v26 offset:3072
	ds_read_b128 v[8:11], v26 offset:7168
	ds_read_b128 v[16:19], v26 offset:11264
	ds_read_b128 v[24:27], v26 offset:15360
	ds_read_b128 v[64:67], v37
	ds_read_b128 v[36:39], v38
	s_waitcnt vmcnt(0)
	s_waitcnt lgkmcnt(0)
	v_mfma_f32_16x16x32_bf16 v[28:31], v[64:67], v[4:7], v[52:55]
	s_barrier
; #define LDSP __attribute__((address_space(3)))
; DI unsigned pk2(float a, float b) { f32x2 v = {a, b}; bf2_t r = __builtin_convertvector(v, bf2_t); return __builtin_bit_cast(unsigned, r); }
; template <int EK>
; DI void ctx_item(const Params& p, int l, int grow, int gcol, int slot, f32x4 s0, f32x4 s1, bool lead) {
;     if (EK == 2) {
;         const float* pp = p.ss + ((size_t)(l * 2 + 1) * NTOK + NLAT + grow) * 16;
;         const f32x4 q0 = *(const f32x4*)pp, q1 = *(const f32x4*)(pp + 4), q2 = *(const f32x4*)(pp + 8), q3 = *(const f32x4*)(pp + 12);
;         const f32x4 qs = q0 + q1 + q2 + q3;
;         const float rstd = rsqrtf((qs[0] + qs[1] + qs[2] + qs[3]) * (1.f / DM) + EPS);
;         const float* shw = p.shw_ff1 + ((size_t)l * 5 + 4) * FF + gcol;
;         const f32x4 h0 = *(const f32x4*)shw, h1 = *(const f32x4*)(shw + 4);
;         s0 = s0 * rstd + h0; s1 = s1 * rstd + h1;
; #pragma unroll
;         for (int j = 0; j < 4; ++j) { float r0 = fmaxf(s0[j], 0.f), r1 = fmaxf(s1[j], 0.f); s0[j] = r0 * r0; s1[j] = r1 * r1; }
;         u32x4 w; w[0] = pk2(s0[0], s0[1]); w[1] = pk2(s0[2], s0[3]); w[2] = pk2(s1[0], s1[1]); w[3] = pk2(s1[2], s1[3]);
;         *(u32x4*)(p.ACT + (size_t)(NLAT + grow) * FF + gcol) = w;
; template <int EK, int TS, int KS>
; DI void ctx_tiles(const Params& p, int l, const bf16_t* __restrict__ A, const bf16_t* __restrict__ Bt, int N, int K, ldsp_t shm) {
;     ...
; #pragma unroll
;         for (int m = 0; m < MT; ++m)
; #pragma unroll
;             for (int n = 0; n < NT; ++n) {
;                 const int row = wr * WM + m * 16 + fr, ch = (wc * WN + n * 16 + fq * 4) >> 2;
;                 *(LDSP f32x4*)(shm + row * (TS * 4) + ((ch ^ (row & 15)) << 4)) = acc[m][n];
;             }
;         __syncthreads();
; #pragma unroll
;         for (int it = 0; it < (TS * TS / 8) / 512; ++it) {
;             const int item = it * 512 + tid, row = item / (TS / 8), c8 = item % (TS / 8);
;             const f32x4 s0 = *(const LDSP f32x4*)(shm + row * (TS * 4) + (((2 * c8) ^ (row & 15)) << 4));
;             const f32x4 s1 = *(const LDSP f32x4*)(shm + row * (TS * 4) + (((2 * c8 + 1) ^ (row & 15)) << 4));
;             ctx_item<EK>(p, l, tm * TS + row, tn * TS + c8 * 8, tn, s0, s1, c8 == 0);
	v_mfma_f32_16x16x32_bf16 v[0:3], v[36:39], v[4:7], v[0:3]
	v_mfma_f32_16x16x32_bf16 v[4:7], v[64:67], v[8:11], v[20:23]
	v_mfma_f32_16x16x32_bf16 v[8:11], v[36:39], v[8:11], v[44:47]
	v_mfma_f32_16x16x32_bf16 v[12:15], v[64:67], v[16:19], v[40:43]
	v_mfma_f32_16x16x32_bf16 v[16:19], v[36:39], v[16:19], v[48:51]
	v_mfma_f32_16x16x32_bf16 v[20:23], v[64:67], v[24:27], v[56:59]
	v_mfma_f32_16x16x32_bf16 v[24:27], v[36:39], v[24:27], v[60:63]
	v_lshrrev_b32_e32 v36, 2, v32
	v_and_or_b32 v35, v36, 12, v35
	v_lshrrev_b32_e32 v35, 2, v35
	v_bitop3_b32 v36, v35, v32, 15 bitop3:0x78
	v_lshl_or_b32 v36, v36, 4, v34
	ds_write_b128 v36, v[28:31]
	v_bitop3_b32 v28, v35, v33, 4 bitop3:0x36
	v_lshl_or_b32 v28, v28, 4, v34
	ds_write_b128 v28, v[0:3]
	ds_write_b128 v36, v[4:7] offset:8192
	ds_write_b128 v28, v[8:11] offset:8192
	ds_write_b128 v36, v[12:15] offset:16384
	ds_write_b128 v28, v[16:19] offset:16384
	ds_write_b128 v36, v[20:23] offset:24576
	ds_write_b128 v28, v[24:27] offset:24576
	v_ashrrev_i32_e32 v0, 31, v32
	v_lshrrev_b32_e32 v0, 28, v0
	v_add_u32_e32 v0, v32, v0
	v_ashrrev_i32_e32 v8, 4, v0
	v_and_b32_e32 v0, -16, v0
	v_sub_u32_e32 v9, v32, v0
	v_add_u32_e32 v26, s11, v8
	v_lshlrev_b32_e32 v5, 1, v9
	v_ashrrev_i32_e32 v27, 31, v26
	v_lshlrev_b32_e32 v4, 9, v8
	v_and_b32_e32 v6, 15, v8
	v_bitop3_b32 v0, v5, v8, 15 bitop3:0x78
	v_lshl_add_u32 v24, v9, 3, s10
	v_lshl_add_u64 v[8:9], s[4:5], 0, v[26:27]
	v_bitop3_b32 v5, v5, v6, 1 bitop3:0x36
	v_lshlrev_b64 v[8:9], 6, v[8:9]
	v_lshl_add_u32 v0, v0, 4, v4
	v_lshl_add_u32 v4, v5, 4, v4
	v_lshl_add_u64 v[20:21], s[74:75], 0, v[8:9]
	s_waitcnt lgkmcnt(0)
	s_barrier
	ds_read_b128 v[0:3], v0
	ds_read_b128 v[4:7], v4
	global_load_dwordx4 v[8:11], v[20:21], off offset:48
	global_load_dwordx4 v[12:15], v[20:21], off offset:32
	global_load_dwordx4 v[16:19], v[20:21], off
	s_nop 0
	global_load_dwordx4 v[20:23], v[20:21], off offset:16
	v_ashrrev_i32_e32 v25, 31, v24
	s_waitcnt vmcnt(0)
	v_pk_add_f32 v[16:17], v[16:17], v[20:21]
	v_pk_add_f32 v[18:19], v[18:19], v[22:23]
	v_pk_add_f32 v[12:13], v[16:17], v[12:13]
	v_pk_add_f32 v[14:15], v[18:19], v[14:15]
	v_pk_add_f32 v[8:9], v[12:13], v[8:9]
	v_pk_add_f32 v[10:11], v[14:15], v[10:11]
	v_add_f32_e32 v8, v8, v9
	v_add_f32_e32 v8, v10, v8
	v_add_f32_e32 v8, v11, v8
	v_fmamk_f32 v8, v8, 0x3a800000, v208
	v_cmp_gt_f32_e32 vcc, s92, v8
	v_mul_f32_e32 v9, 0x4b800000, v8
	v_lshl_add_u64 v[12:13], v[24:25], 2, s[6:7]
	v_cndmask_b32_e32 v8, v8, v9, vcc
	v_rsq_f32_e32 v8, v8
	s_nop 0
	v_mul_f32_e32 v9, 0x45800000, v8
	v_cndmask_b32_e32 v16, v8, v9, vcc
	global_load_dwordx4 v[8:11], v[12:13], off offset:16
	s_nop 0
	global_load_dwordx4 v[12:15], v[12:13], off
	s_waitcnt vmcnt(1) lgkmcnt(0)
	v_pk_fma_f32 v[4:5], v[4:5], v[16:17], v[8:9] op_sel_hi:[1,0,1]
	s_waitcnt vmcnt(0)
	v_pk_fma_f32 v[2:3], v[2:3], v[16:17], v[14:15] op_sel_hi:[1,0,1]
	v_pk_fma_f32 v[0:1], v[0:1], v[16:17], v[12:13] op_sel_hi:[1,0,1]
	v_max_f32_e32 v4, 0, v4
	v_max_f32_e32 v0, 0, v0
	v_max_f32_e32 v1, 0, v1
	v_max_f32_e32 v5, 0, v5
	v_max_f32_e32 v2, 0, v2
	v_max_f32_e32 v3, 0, v3
	v_pk_fma_f32 v[6:7], v[6:7], v[16:17], v[10:11] op_sel_hi:[1,0,1]
	v_pk_mul_f32 v[0:1], v[0:1], v[0:1]
	v_pk_mul_f32 v[4:5], v[4:5], v[4:5]
	v_pk_mul_f32 v[2:3], v[2:3], v[2:3]
	v_max_f32_e32 v6, 0, v6
	v_max_f32_e32 v7, 0, v7
	v_cvt_pk_bf16_f32 v0, v0, v1
	v_cvt_pk_bf16_f32 v1, v2, v3
	v_cvt_pk_bf16_f32 v2, v4, v5
	v_lshlrev_b64 v[4:5], 13, v[26:27]
	v_pk_mul_f32 v[6:7], v[6:7], v[6:7]
	v_lshl_add_u64 v[4:5], s[12:13], 0, v[4:5]
	v_cvt_pk_bf16_f32 v3, v6, v7
	v_lshl_add_u64 v[4:5], v[24:25], 1, v[4:5]
	global_store_dwordx4 v[4:5], v[0:3], off sc1
	s_nop 1
	v_add_u32_e32 v0, 0x200, v32
	v_ashrrev_i32_e32 v1, 31, v0
	v_lshrrev_b32_e32 v1, 28, v1
	v_add_u32_e32 v1, v0, v1
	v_ashrrev_i32_e32 v8, 4, v1
	v_and_b32_e32 v1, -16, v1
	v_sub_u32_e32 v9, v0, v1
	v_add_u32_e32 v26, s11, v8
	v_lshlrev_b32_e32 v5, 1, v9
	v_ashrrev_i32_e32 v27, 31, v26
	v_lshlrev_b32_e32 v4, 9, v8
	v_and_b32_e32 v6, 15, v8
	v_bitop3_b32 v0, v5, v8, 15 bitop3:0x78
	v_lshl_add_u32 v24, v9, 3, s10
	v_lshl_add_u64 v[8:9], s[4:5], 0, v[26:27]
	v_bitop3_b32 v5, v5, v6, 1 bitop3:0x36
	v_lshlrev_b64 v[8:9], 6, v[8:9]
	v_lshl_add_u32 v0, v0, 4, v4
	v_lshl_add_u32 v4, v5, 4, v4
	v_lshl_add_u64 v[20:21], s[74:75], 0, v[8:9]
	ds_read_b128 v[0:3], v0
	ds_read_b128 v[4:7], v4
	global_load_dwordx4 v[8:11], v[20:21], off offset:48
	global_load_dwordx4 v[12:15], v[20:21], off offset:32
	global_load_dwordx4 v[16:19], v[20:21], off
	s_nop 0
	global_load_dwordx4 v[20:23], v[20:21], off offset:16
	v_ashrrev_i32_e32 v25, 31, v24
	s_waitcnt vmcnt(0)
	v_pk_add_f32 v[16:17], v[16:17], v[20:21]
	v_pk_add_f32 v[18:19], v[18:19], v[22:23]
	v_pk_add_f32 v[12:13], v[16:17], v[12:13]
	v_pk_add_f32 v[14:15], v[18:19], v[14:15]
	v_pk_add_f32 v[8:9], v[12:13], v[8:9]
	v_pk_add_f32 v[10:11], v[14:15], v[10:11]
	v_add_f32_e32 v8, v8, v9
	v_add_f32_e32 v8, v10, v8
	v_add_f32_e32 v8, v11, v8
	v_fmamk_f32 v8, v8, 0x3a800000, v208
	v_cmp_gt_f32_e32 vcc, s92, v8
	v_mul_f32_e32 v9, 0x4b800000, v8
	v_lshl_add_u64 v[12:13], v[24:25], 2, s[6:7]
	v_cndmask_b32_e32 v8, v8, v9, vcc
	v_rsq_f32_e32 v8, v8
	s_nop 0
	v_mul_f32_e32 v9, 0x45800000, v8
	v_cndmask_b32_e32 v16, v8, v9, vcc
	global_load_dwordx4 v[8:11], v[12:13], off offset:16
	s_nop 0
	global_load_dwordx4 v[12:15], v[12:13], off
	s_waitcnt vmcnt(1) lgkmcnt(0)
	v_pk_fma_f32 v[4:5], v[4:5], v[16:17], v[8:9] op_sel_hi:[1,0,1]
	s_waitcnt vmcnt(0)
; #define LDSP __attribute__((address_space(3)))
; DI unsigned pk2(float a, float b) { f32x2 v = {a, b}; bf2_t r = __builtin_convertvector(v, bf2_t); return __builtin_bit_cast(unsigned, r); }
; template <int EK>
; DI void ctx_item(const Params& p, int l, int grow, int gcol, int slot, f32x4 s0, f32x4 s1, bool lead) {
;     if (EK == 2) {
;         const float* pp = p.ss + ((size_t)(l * 2 + 1) * NTOK + NLAT + grow) * 16;
;         const f32x4 q0 = *(const f32x4*)pp, q1 = *(const f32x4*)(pp + 4), q2 = *(const f32x4*)(pp + 8), q3 = *(const f32x4*)(pp + 12);
;         const f32x4 qs = q0 + q1 + q2 + q3;
;         const float rstd = rsqrtf((qs[0] + qs[1] + qs[2] + qs[3]) * (1.f / DM) + EPS);
;         const float* shw = p.shw_ff1 + ((size_t)l * 5 + 4) * FF + gcol;
;         const f32x4 h0 = *(const f32x4*)shw, h1 = *(const f32x4*)(shw + 4);
;         s0 = s0 * rstd + h0; s1 = s1 * rstd + h1;
; #pragma unroll
;         for (int j = 0; j < 4; ++j) { float r0 = fmaxf(s0[j], 0.f), r1 = fmaxf(s1[j], 0.f); s0[j] = r0 * r0; s1[j] = r1 * r1; }
;         u32x4 w; w[0] = pk2(s0[0], s0[1]); w[1] = pk2(s0[2], s0[3]); w[2] = pk2(s1[0], s1[1]); w[3] = pk2(s1[2], s1[3]);
;         *(u32x4*)(p.ACT + (size_t)(NLAT + grow) * FF + gcol) = w;
; template <int EK, int TS, int KS>
; DI void ctx_tiles(const Params& p, int l, const bf16_t* __restrict__ A, const bf16_t* __restrict__ Bt, int N, int K, ldsp_t shm) {
;     ...
; #pragma unroll
;         for (int it = 0; it < (TS * TS / 8) / 512; ++it) {
;             const int item = it * 512 + tid, row = item / (TS / 8), c8 = item % (TS / 8);
;             const f32x4 s0 = *(const LDSP f32x4*)(shm + row * (TS * 4) + (((2 * c8) ^ (row & 15)) << 4));
;             const f32x4 s1 = *(const LDSP f32x4*)(shm + row * (TS * 4) + (((2 * c8 + 1) ^ (row & 15)) << 4));
;             ctx_item<EK>(p, l, tm * TS + row, tn * TS + c8 * 8, tn, s0, s1, c8 == 0);
;         }
;         __syncthreads();
;     }
	v_pk_fma_f32 v[2:3], v[2:3], v[16:17], v[14:15] op_sel_hi:[1,0,1]
	v_pk_fma_f32 v[0:1], v[0:1], v[16:17], v[12:13] op_sel_hi:[1,0,1]
	v_max_f32_e32 v4, 0, v4
	v_max_f32_e32 v0, 0, v0
	v_max_f32_e32 v1, 0, v1
	v_max_f32_e32 v5, 0, v5
	v_max_f32_e32 v2, 0, v2
	v_max_f32_e32 v3, 0, v3
	v_pk_fma_f32 v[6:7], v[6:7], v[16:17], v[10:11] op_sel_hi:[1,0,1]
	v_pk_mul_f32 v[0:1], v[0:1], v[0:1]
	v_pk_mul_f32 v[4:5], v[4:5], v[4:5]
	v_pk_mul_f32 v[2:3], v[2:3], v[2:3]
	v_max_f32_e32 v6, 0, v6
	v_max_f32_e32 v7, 0, v7
	v_cvt_pk_bf16_f32 v0, v0, v1
	v_cvt_pk_bf16_f32 v1, v2, v3
	v_cvt_pk_bf16_f32 v2, v4, v5
	v_lshlrev_b64 v[4:5], 13, v[26:27]
	v_pk_mul_f32 v[6:7], v[6:7], v[6:7]
	v_lshl_add_u64 v[4:5], s[12:13], 0, v[4:5]
	v_cvt_pk_bf16_f32 v3, v6, v7
	v_lshl_add_u64 v[4:5], v[24:25], 1, v[4:5]
	global_store_dwordx4 v[4:5], v[0:3], off sc1
	s_nop 1
	v_add_u32_e32 v0, 0x400, v32
	v_ashrrev_i32_e32 v1, 31, v0
	v_lshrrev_b32_e32 v1, 28, v1
	v_add_u32_e32 v1, v0, v1
	v_ashrrev_i32_e32 v8, 4, v1
	v_and_b32_e32 v1, -16, v1
	v_sub_u32_e32 v9, v0, v1
	v_add_u32_e32 v26, s11, v8
	v_lshlrev_b32_e32 v5, 1, v9
	v_ashrrev_i32_e32 v27, 31, v26
	v_lshlrev_b32_e32 v4, 9, v8
	v_and_b32_e32 v6, 15, v8
	v_bitop3_b32 v0, v5, v8, 15 bitop3:0x78
	v_lshl_add_u32 v24, v9, 3, s10
	v_lshl_add_u64 v[8:9], s[4:5], 0, v[26:27]
	v_bitop3_b32 v5, v5, v6, 1 bitop3:0x36
	v_lshlrev_b64 v[8:9], 6, v[8:9]
	v_lshl_add_u32 v0, v0, 4, v4
	v_lshl_add_u32 v4, v5, 4, v4
	v_lshl_add_u64 v[20:21], s[74:75], 0, v[8:9]
	ds_read_b128 v[0:3], v0
	ds_read_b128 v[4:7], v4
	global_load_dwordx4 v[8:11], v[20:21], off offset:48
	global_load_dwordx4 v[12:15], v[20:21], off offset:32
	global_load_dwordx4 v[16:19], v[20:21], off
	s_nop 0
	global_load_dwordx4 v[20:23], v[20:21], off offset:16
	v_ashrrev_i32_e32 v25, 31, v24
	s_waitcnt vmcnt(0)
	v_pk_add_f32 v[16:17], v[16:17], v[20:21]
	v_pk_add_f32 v[18:19], v[18:19], v[22:23]
	v_pk_add_f32 v[12:13], v[16:17], v[12:13]
	v_pk_add_f32 v[14:15], v[18:19], v[14:15]
	v_pk_add_f32 v[8:9], v[12:13], v[8:9]
	v_pk_add_f32 v[10:11], v[14:15], v[10:11]
	v_add_f32_e32 v8, v8, v9
	v_add_f32_e32 v8, v10, v8
	v_add_f32_e32 v8, v11, v8
	v_fmamk_f32 v8, v8, 0x3a800000, v208
	v_cmp_gt_f32_e32 vcc, s92, v8
	v_mul_f32_e32 v9, 0x4b800000, v8
	v_lshl_add_u64 v[12:13], v[24:25], 2, s[6:7]
	v_cndmask_b32_e32 v8, v8, v9, vcc
	v_rsq_f32_e32 v8, v8
	s_nop 0
	v_mul_f32_e32 v9, 0x45800000, v8
	v_cndmask_b32_e32 v16, v8, v9, vcc
	global_load_dwordx4 v[8:11], v[12:13], off offset:16
	s_nop 0
	global_load_dwordx4 v[12:15], v[12:13], off
	s_waitcnt vmcnt(1) lgkmcnt(0)
	v_pk_fma_f32 v[4:5], v[4:5], v[16:17], v[8:9] op_sel_hi:[1,0,1]
	s_waitcnt vmcnt(0)
	v_pk_fma_f32 v[2:3], v[2:3], v[16:17], v[14:15] op_sel_hi:[1,0,1]
	v_pk_fma_f32 v[0:1], v[0:1], v[16:17], v[12:13] op_sel_hi:[1,0,1]
	v_max_f32_e32 v4, 0, v4
	v_max_f32_e32 v0, 0, v0
	v_max_f32_e32 v1, 0, v1
	v_max_f32_e32 v5, 0, v5
	v_max_f32_e32 v2, 0, v2
	v_max_f32_e32 v3, 0, v3
	v_pk_fma_f32 v[6:7], v[6:7], v[16:17], v[10:11] op_sel_hi:[1,0,1]
	v_pk_mul_f32 v[0:1], v[0:1], v[0:1]
	v_pk_mul_f32 v[4:5], v[4:5], v[4:5]
	v_pk_mul_f32 v[2:3], v[2:3], v[2:3]
	v_max_f32_e32 v6, 0, v6
	v_max_f32_e32 v7, 0, v7
	v_cvt_pk_bf16_f32 v0, v0, v1
	v_cvt_pk_bf16_f32 v1, v2, v3
	v_cvt_pk_bf16_f32 v2, v4, v5
	v_lshlrev_b64 v[4:5], 13, v[26:27]
	v_pk_mul_f32 v[6:7], v[6:7], v[6:7]
	v_lshl_add_u64 v[4:5], s[12:13], 0, v[4:5]
	v_cvt_pk_bf16_f32 v3, v6, v7
	v_lshl_add_u64 v[4:5], v[24:25], 1, v[4:5]
	global_store_dwordx4 v[4:5], v[0:3], off sc1
	s_nop 1
	v_add_u32_e32 v0, 0x600, v32
	v_ashrrev_i32_e32 v1, 31, v0
	v_lshrrev_b32_e32 v1, 28, v1
	v_add_u32_e32 v1, v0, v1
	v_ashrrev_i32_e32 v9, 4, v1
	v_and_b32_e32 v1, -16, v1
	v_add_u32_e32 v10, s11, v9
	v_sub_u32_e32 v8, v0, v1
	v_ashrrev_i32_e32 v11, 31, v10
	v_lshlrev_b32_e32 v5, 1, v8
	v_and_b32_e32 v6, 15, v9
	v_lshl_add_u64 v[12:13], s[4:5], 0, v[10:11]
	v_lshlrev_b32_e32 v4, 9, v9
	v_bitop3_b32 v0, v5, v9, 15 bitop3:0x78
	v_bitop3_b32 v5, v5, v6, 1 bitop3:0x36
	v_lshlrev_b64 v[12:13], 6, v[12:13]
	v_lshl_add_u32 v0, v0, 4, v4
	v_lshl_add_u32 v4, v5, 4, v4
	v_lshl_add_u64 v[24:25], s[74:75], 0, v[12:13]
	ds_read_b128 v[0:3], v0
	ds_read_b128 v[4:7], v4
	global_load_dwordx4 v[12:15], v[24:25], off offset:48
	global_load_dwordx4 v[16:19], v[24:25], off offset:32
	global_load_dwordx4 v[20:23], v[24:25], off
	s_nop 0
	global_load_dwordx4 v[24:27], v[24:25], off offset:16
	v_lshl_add_u32 v8, v8, 3, s10
	s_waitcnt vmcnt(0)
	v_pk_add_f32 v[20:21], v[20:21], v[24:25]
	v_pk_add_f32 v[22:23], v[22:23], v[26:27]
	v_pk_add_f32 v[16:17], v[20:21], v[16:17]
	v_pk_add_f32 v[18:19], v[22:23], v[18:19]
	v_pk_add_f32 v[12:13], v[16:17], v[12:13]
	v_pk_add_f32 v[14:15], v[18:19], v[14:15]
	v_add_f32_e32 v9, v12, v13
	v_add_f32_e32 v9, v14, v9
	v_add_f32_e32 v9, v15, v9
	v_fmamk_f32 v9, v9, 0x3a800000, v208
	v_cmp_gt_f32_e32 vcc, s92, v9
	v_mul_f32_e32 v12, 0x4b800000, v9
	s_nop 0
	v_cndmask_b32_e32 v9, v9, v12, vcc
	v_rsq_f32_e32 v9, v9
	s_nop 0
	v_mul_f32_e32 v12, 0x45800000, v9
	v_cndmask_b32_e32 v20, v9, v12, vcc
	v_ashrrev_i32_e32 v9, 31, v8
	v_lshl_add_u64 v[16:17], v[8:9], 2, s[6:7]
	global_load_dwordx4 v[12:15], v[16:17], off offset:16
	s_nop 0
	global_load_dwordx4 v[16:19], v[16:17], off
	s_waitcnt vmcnt(1) lgkmcnt(0)
	v_pk_fma_f32 v[4:5], v[4:5], v[20:21], v[12:13] op_sel_hi:[1,0,1]
	s_waitcnt vmcnt(0)
	v_pk_fma_f32 v[2:3], v[2:3], v[20:21], v[18:19] op_sel_hi:[1,0,1]
	v_pk_fma_f32 v[0:1], v[0:1], v[20:21], v[16:17] op_sel_hi:[1,0,1]
	v_max_f32_e32 v4, 0, v4
	v_max_f32_e32 v0, 0, v0
	v_max_f32_e32 v1, 0, v1
	v_max_f32_e32 v5, 0, v5
	v_max_f32_e32 v2, 0, v2
	v_max_f32_e32 v3, 0, v3
	v_pk_fma_f32 v[6:7], v[6:7], v[20:21], v[14:15] op_sel_hi:[1,0,1]
	v_pk_mul_f32 v[0:1], v[0:1], v[0:1]
	v_pk_mul_f32 v[4:5], v[4:5], v[4:5]
	v_pk_mul_f32 v[2:3], v[2:3], v[2:3]
	v_max_f32_e32 v6, 0, v6
	v_max_f32_e32 v7, 0, v7
	v_cvt_pk_bf16_f32 v0, v0, v1
	v_cvt_pk_bf16_f32 v1, v2, v3
	v_cvt_pk_bf16_f32 v2, v4, v5
	v_lshlrev_b64 v[4:5], 13, v[10:11]
	v_pk_mul_f32 v[6:7], v[6:7], v[6:7]
	v_lshl_add_u64 v[4:5], s[12:13], 0, v[4:5]
	v_cvt_pk_bf16_f32 v3, v6, v7
	v_lshl_add_u64 v[4:5], v[8:9], 1, v[4:5]
	global_store_dwordx4 v[4:5], v[0:3], off sc1
	s_barrier
	s_load_dword s10, s[88:89], 0x0
	s_waitcnt lgkmcnt(0)
	s_add_i32 s31, s10, s31
	s_cmpk_gt_i32 s31, 0xff
	s_cbranch_scc0 .LBB0_119

; #define LDSP __attribute__((address_space(3)))
; DI void wave_rows_store(ldsp_t wb, int lane, bf16_t* dst0, size_t ld) {
; #pragma unroll
;     for (int i = 0; i < 8; ++i) {
;         const int row = i * 8 + (lane >> 3), ch = lane & 7;
;         const u32x4 v = *(const LDSP u32x4*)(wb + row * 128 + ((ch ^ (row & 7)) << 4));
;         *(u32x4*)(dst0 + (size_t)row * ld + ch * 8) = v;
;     }
; }
; template <int EK>
; DI void gemm_stream(const Params& p, int l, const bf16_t* __restrict__ A, const bf16_t* __restrict__ Bt, int M, int N, int K, ldsp_t shm) {
;     ...
;         }
;         __syncthreads();
;         if (!has_next) break;
;         L = Ln; pm = pm2; pn = pn2; Ab = Ab2; Bb = Bb2;
.LBB0_124:
	s_or_b64 exec, exec, s[6:7]
	v_ashrrev_i32_e32 v99, 31, v98
	s_waitcnt lgkmcnt(0)
	v_lshlrev_b64 v[0:1], 11, v[98:99]
	v_lshl_add_u64 v[0:1], s[82:83], 0, v[0:1]
	v_lshl_add_u64 v[0:1], s[38:39], 1, v[0:1]
	v_mov_b32_e32 v89, v193
	v_lshl_add_u64 v[0:1], v[0:1], 0, v[88:89]
	v_mov_b32_e32 v97, v193
	v_lshl_add_u64 v[4:5], v[0:1], 0, v[96:97]
	ds_read_b128 v[0:3], v111
	v_lshl_add_u64 v[6:7], v[4:5], 0, v[192:193]
	s_andn2_b64 vcc, exec, s[36:37]
	s_mov_b32 s87, s42
	s_mov_b32 s88, s40
	s_waitcnt lgkmcnt(0)
	global_store_dwordx4 v[6:7], v[0:3], off sc1
	ds_read_b128 v[0:3], v110
	v_lshl_add_u64 v[6:7], v[4:5], 0, v[94:95]
	s_waitcnt lgkmcnt(0)
	global_store_dwordx4 v[6:7], v[0:3], off sc1
	ds_read_b128 v[0:3], v109
	v_lshl_add_u64 v[6:7], v[4:5], 0, v[92:93]
	s_waitcnt lgkmcnt(0)
	global_store_dwordx4 v[6:7], v[0:3], off sc1
	ds_read_b128 v[0:3], v108
	v_lshl_add_u64 v[6:7], v[4:5], 0, v[90:91]
	s_waitcnt lgkmcnt(0)
	global_store_dwordx4 v[6:7], v[0:3], off sc1
	ds_read_b128 v[0:3], v104
	v_lshl_add_u64 v[6:7], v[4:5], 0, v[82:83]
	s_waitcnt lgkmcnt(0)
	global_store_dwordx4 v[6:7], v[0:3], off sc1
	ds_read_b128 v[0:3], v105
	v_lshl_add_u64 v[6:7], v[4:5], 0, v[86:87]
	s_waitcnt lgkmcnt(0)
	global_store_dwordx4 v[6:7], v[0:3], off sc1
	ds_read_b128 v[0:3], v106
	v_lshl_add_u64 v[6:7], v[4:5], 0, v[84:85]
	v_lshl_add_u64 v[4:5], v[4:5], 0, v[80:81]
	s_waitcnt lgkmcnt(0)
	global_store_dwordx4 v[6:7], v[0:3], off sc1
	ds_read_b128 v[0:3], v107
	s_waitcnt lgkmcnt(0)
	global_store_dwordx4 v[4:5], v[0:3], off sc1
	s_barrier
	s_cbranch_vccz .LBB0_153

; #define WAIT_V0() asm volatile("s_waitcnt vmcnt(0)" ::: "memory")
; #define G_STAGE_A(Ap, buf, kt) do { const char* ab_ = (const char*)(Ap) + (size_t)(kt) * 128; \
;       _Pragma("unroll") for (int i = 0; i < 4; ++i) \
;         __builtin_amdgcn_global_load_lds((const unsigned*)(ab_ + soff[i]), (LDSP unsigned*)(G_SA(buf) + wid * 1024 + i * 8192), 16, 0, 0); } while (0)
; #define G_STAGE_B(Bp, buf, kt) do { const char* bb_ = (const char*)(Bp) + (size_t)(kt) * 128; \
;       _Pragma("unroll") for (int i = 0; i < 4; ++i) \
;         __builtin_amdgcn_global_load_lds((const unsigned*)(bb_ + soff[i]), (LDSP unsigned*)(G_SB(buf) + wid * 1024 + i * 8192), 16, 0, 0); } while (0)
; #define G_RDA(AF, buf, ks, mh) do { _Pragma("unroll") for (int m = 0; m < 4; ++m) AF[m] = *(const LDSP bf16x8*)(G_SA(buf) + aoff + ((mh) * 4 + m) * 2048 + (ks) * 1024); } while (0)
; #define G_RDB(BF, buf, ks) do { _Pragma("unroll") for (int n = 0; n < 4; ++n) BF[n] = *(const LDSP bf16x8*)(G_SB(buf) + boff + n * 2048 + (ks) * 1024); } while (0)
; #define G_MMA(AF, BF, mh) do { __builtin_amdgcn_s_setprio(1); \
;             _Pragma("unroll") for (int m = 0; m < 4; ++m) _Pragma("unroll") for (int n = 0; n < 4; ++n) \
;                 acc[(mh) * 4 + m][n] = __builtin_amdgcn_mfma_f32_16x16x32_bf16(BF[n], AF[m], acc[(mh) * 4 + m][n], 0, 0, 0); \
;             __builtin_amdgcn_s_setprio(0); } while (0)
; template <int EK>
; DI void gemm_stream(const Params& p, int l, const bf16_t* __restrict__ A, const bf16_t* __restrict__ Bt, int M, int N, int K, ldsp_t shm) {
;     ...
;         for (int t = 0; t < nt; ++t) {
;             const int cur = t & 1;
;             G_RDA(Aa, cur, 0, 0); G_RDB(Bk0, cur, 0);
;             if (t + 1 < nt) G_STAGE_B(Bb, cur ^ 1, t + 1);
;             else if (has_next) G_STAGE_B(Bb2, cur ^ 1, 0);
;             G_SB0();
;             if (t > 0) G_MMA(Ab_, Bk1, 1);
;             G_SB0();
;             if (t + 1 < nt) G_STAGE_A(Ab, cur ^ 1, t + 1);
;             else if (has_next) G_STAGE_A(Ab2, cur ^ 1, 0);
;             G_RDA(Ab_, cur, 0, 1);
;             G_MMA(Aa, Bk0, 0); G_SB0();
;             G_RDA(Aa, cur, 1, 0); G_RDB(Bk1, cur, 1);
;             G_MMA(Ab_, Bk0, 1); G_SB0();
;             G_RDA(Ab_, cur, 1, 1);
;             G_MMA(Aa, Bk1, 0); G_SB0();
;             asm volatile("s_waitcnt lgkmcnt(0)" ::: "memory");
;             WAIT_V0(); __syncthreads();
;         }
.LBB0_137:
	v_add_u32_e32 v80, 0x12000, v218
	v_add_u32_e32 v84, 0x12800, v218
	v_add_u32_e32 v88, 0x13000, v218
	v_add_u32_e32 v92, 0x13800, v218
	ds_read_b128 v[80:83], v80
	ds_read_b128 v[84:87], v84
	ds_read_b128 v[88:91], v88
	ds_read_b128 v[92:95], v92
	s_setprio 1
	s_waitcnt lgkmcnt(0)
	v_mfma_f32_16x16x32_bf16 v[0:3], v[160:163], v[188:191], v[0:3]
	v_mfma_f32_16x16x32_bf16 v[4:7], v[164:167], v[188:191], v[4:7]
	v_mfma_f32_16x16x32_bf16 v[8:11], v[168:171], v[188:191], v[8:11]
	v_mfma_f32_16x16x32_bf16 v[12:15], v[172:175], v[188:191], v[12:15]
	v_mfma_f32_16x16x32_bf16 v[16:19], v[160:163], v[180:183], v[16:19]
	v_mfma_f32_16x16x32_bf16 v[20:23], v[164:167], v[180:183], v[20:23]
	v_mfma_f32_16x16x32_bf16 v[24:27], v[168:171], v[180:183], v[24:27]
	v_mfma_f32_16x16x32_bf16 v[28:31], v[172:175], v[180:183], v[28:31]
	v_mfma_f32_16x16x32_bf16 v[32:35], v[160:163], v[184:187], v[32:35]
	v_mfma_f32_16x16x32_bf16 v[36:39], v[164:167], v[184:187], v[36:39]
	v_mfma_f32_16x16x32_bf16 v[40:43], v[168:171], v[184:187], v[40:43]
	v_mfma_f32_16x16x32_bf16 v[44:47], v[172:175], v[184:187], v[44:47]
	v_mfma_f32_16x16x32_bf16 v[48:51], v[160:163], v[176:179], v[48:51]
	v_mfma_f32_16x16x32_bf16 v[52:55], v[164:167], v[176:179], v[52:55]
	v_mfma_f32_16x16x32_bf16 v[56:59], v[168:171], v[176:179], v[56:59]
	v_mfma_f32_16x16x32_bf16 v[60:63], v[172:175], v[176:179], v[60:63]
	s_setprio 0
	v_add_u32_e32 v144, 0x10400, v218
	v_add_u32_e32 v148, 0x10c00, v218
	v_add_u32_e32 v152, 0x11400, v218
	v_add_u32_e32 v156, 0x11c00, v218
	v_add_u32_e32 v176, 0x18400, v219
	v_add_u32_e32 v180, 0x18c00, v219
	v_add_u32_e32 v184, 0x19400, v219
	v_add_u32_e32 v188, 0x19c00, v219
	ds_read_b128 v[144:147], v144
	ds_read_b128 v[148:151], v148
	ds_read_b128 v[152:155], v152
	ds_read_b128 v[156:159], v156
	ds_read_b128 v[176:179], v176
	ds_read_b128 v[180:183], v180
	ds_read_b128 v[184:187], v184
	ds_read_b128 v[188:191], v188
	s_setprio 1
	v_mfma_f32_16x16x32_bf16 v[194:197], v[160:163], v[80:83], v[140:143]
	v_mfma_f32_16x16x32_bf16 v[198:201], v[164:167], v[80:83], v[136:139]
	v_mfma_f32_16x16x32_bf16 v[204:207], v[168:171], v[80:83], v[132:135]
	v_mfma_f32_16x16x32_bf16 v[210:213], v[172:175], v[80:83], v[128:131]
	v_mfma_f32_16x16x32_bf16 v[214:217], v[160:163], v[84:87], v[124:127]
	v_mfma_f32_16x16x32_bf16 v[220:223], v[164:167], v[84:87], v[120:123]
	v_mfma_f32_16x16x32_bf16 v[224:227], v[168:171], v[84:87], v[116:119]
	v_mfma_f32_16x16x32_bf16 v[228:231], v[172:175], v[84:87], v[112:115]
	v_mfma_f32_16x16x32_bf16 v[232:235], v[160:163], v[88:91], v[108:111]
	v_mfma_f32_16x16x32_bf16 v[236:239], v[164:167], v[88:91], v[104:107]
	v_mfma_f32_16x16x32_bf16 v[240:243], v[168:171], v[88:91], v[100:103]
	v_mfma_f32_16x16x32_bf16 v[244:247], v[172:175], v[88:91], v[96:99]
	v_mfma_f32_16x16x32_bf16 v[160:163], v[160:163], v[92:95], v[64:67]
	v_mfma_f32_16x16x32_bf16 v[164:167], v[164:167], v[92:95], v[68:71]
	v_mfma_f32_16x16x32_bf16 v[168:171], v[168:171], v[92:95], v[72:75]
	v_mfma_f32_16x16x32_bf16 v[172:175], v[172:175], v[92:95], v[76:79]
	s_setprio 0
	v_add_u32_e32 v64, 0x12400, v218
	v_add_u32_e32 v68, 0x12c00, v218
	ds_read_b128 v[64:67], v64
	ds_read_b128 v[248:251], v68
	v_add_u32_e32 v68, 0x13400, v218
	v_add_u32_e32 v72, 0x13c00, v218
	ds_read_b128 v[68:71], v68
	ds_read_b128 v[72:75], v72
	s_setprio 1
	s_waitcnt lgkmcnt(0)
	v_mfma_f32_16x16x32_bf16 v[140:143], v[176:179], v[144:147], v[0:3]
	v_mfma_f32_16x16x32_bf16 v[136:139], v[180:183], v[144:147], v[4:7]
	v_mfma_f32_16x16x32_bf16 v[132:135], v[184:187], v[144:147], v[8:11]
	v_mfma_f32_16x16x32_bf16 v[128:131], v[188:191], v[144:147], v[12:15]
	v_mfma_f32_16x16x32_bf16 v[124:127], v[176:179], v[148:151], v[16:19]
	v_mfma_f32_16x16x32_bf16 v[120:123], v[180:183], v[148:151], v[20:23]
	v_mfma_f32_16x16x32_bf16 v[116:119], v[184:187], v[148:151], v[24:27]
	v_mfma_f32_16x16x32_bf16 v[112:115], v[188:191], v[148:151], v[28:31]
	v_mfma_f32_16x16x32_bf16 v[108:111], v[176:179], v[152:155], v[32:35]
	v_mfma_f32_16x16x32_bf16 v[104:107], v[180:183], v[152:155], v[36:39]
	v_mfma_f32_16x16x32_bf16 v[100:103], v[184:187], v[152:155], v[40:43]
	v_mfma_f32_16x16x32_bf16 v[96:99], v[188:191], v[152:155], v[44:47]
	v_mfma_f32_16x16x32_bf16 v[92:95], v[176:179], v[156:159], v[48:51]
	v_mfma_f32_16x16x32_bf16 v[88:91], v[180:183], v[156:159], v[52:55]
	v_mfma_f32_16x16x32_bf16 v[84:87], v[184:187], v[156:159], v[56:59]
	v_mfma_f32_16x16x32_bf16 v[80:83], v[188:191], v[156:159], v[60:63]
	s_setprio 0
	s_waitcnt lgkmcnt(0)
	s_waitcnt vmcnt(0)
	s_waitcnt vmcnt(0)
	s_barrier
;     static DI void run(const f32x4 (&acc)[8][4], const TileCtx& tc, const Params& p, ldsp_t wb) {
;     ...
;         const int cond = tc.brow < NLAT ? (tc.brow >> 12) : 4;
;         const float* gate = p.mod + ((size_t)tc.l * 5 + cond) * 6144 + GI * DM;
;         const int col0 = tc.bcol + tc.wc * 64 + tc.fq * 4;
;         const bool has_next = EK == 1 || tc.l + 1 < DEPTH;
;         const int ln = EK == 1 ? tc.l : (has_next ? tc.l + 1 : tc.l);
;         const float* gnx = (EK == 1 ? p.norm2_g : p.norm1_g) + (size_t)ln * DM + col0;
;         const float* scn = p.mod + ((size_t)ln * 5 + cond) * 6144 + (EK == 1 ? 4 : 1) * DM + col0;
;         float* ssp = p.ss + (size_t)(ln * 2 + (EK == 1 ? 1 : 0)) * NTOK * 16 + (tc.bcol >> 8) * 4 + tc.wc;
;         f32x4 gv[4], av[4];
; #pragma unroll
;         for (int n = 0; n < 4; ++n) {
;             gv[n] = *(const f32x4*)(gate + col0 + n * 16);
;             const f32x4 g1 = *(const f32x4*)(gnx + n * 16), s1 = *(const f32x4*)(scn + n * 16);
;             av[n] = g1 * (1.f + s1);
;         }
; #pragma unroll
;         for (int h = 0; h < 2; ++h) {
; #pragma unroll
;             for (int mm = 0; mm < 4; ++mm) { __builtin_amdgcn_sched_barrier(0);
;                 const int m = h * 4 + mm;
;                 const int row = tc.brow + tc.wr * 128 + m * 16 + tc.fr;
;                 float* xr = xrow_ptr(p, row) + col0;
;                 const float* xs = (EK == 1 && tc.l == 0) ? p.x + (size_t)row * DM + col0 : xr;
;                 float part = 0.f;
; #pragma unroll
;                 for (int n = 0; n < 4; ++n) {
;                     f32x4 xv = *(const f32x4*)(xs + n * 16);
;                     xv += gv[n] * acc[m][n];
	s_setprio 1
	v_mfma_f32_16x16x32_bf16 v[76:79], v[176:179], v[64:67], v[194:197]
	v_mfma_f32_16x16x32_bf16 v[198:201], v[180:183], v[64:67], v[198:201]
	v_mfma_f32_16x16x32_bf16 v[194:197], v[184:187], v[64:67], v[204:207]
	v_mfma_f32_16x16x32_bf16 v[64:67], v[188:191], v[64:67], v[210:213]
	v_mfma_f32_16x16x32_bf16 v[60:63], v[176:179], v[248:251], v[214:217]
	v_mfma_f32_16x16x32_bf16 v[56:59], v[180:183], v[248:251], v[220:223]
	v_mfma_f32_16x16x32_bf16 v[52:55], v[184:187], v[248:251], v[224:227]
	v_mfma_f32_16x16x32_bf16 v[48:51], v[188:191], v[248:251], v[228:231]
	v_mfma_f32_16x16x32_bf16 v[44:47], v[176:179], v[68:71], v[232:235]
	v_mfma_f32_16x16x32_bf16 v[40:43], v[180:183], v[68:71], v[236:239]
	v_mfma_f32_16x16x32_bf16 v[36:39], v[184:187], v[68:71], v[240:243]
	v_mfma_f32_16x16x32_bf16 v[32:35], v[188:191], v[68:71], v[244:247]
	v_mfma_f32_16x16x32_bf16 v[16:19], v[176:179], v[72:75], v[160:163]
	v_mfma_f32_16x16x32_bf16 v[12:15], v[180:183], v[72:75], v[164:167]
	v_mfma_f32_16x16x32_bf16 v[8:11], v[184:187], v[72:75], v[168:171]
	v_mfma_f32_16x16x32_bf16 v[0:3], v[188:191], v[72:75], v[172:175]
	s_setprio 0
	v_mov_b32_e32 v177, v252
	s_lshl_b32 s41, s88, 8
	s_min_i32 s6, s41, 0x4000
	s_ashr_i32 s6, s6, 12
	v_readlane_b32 s8, v255, 10
	s_lshl_b32 s38, s87, 8
	s_ashr_i32 s7, s6, 31
	s_mul_i32 s39, s8, 5
	s_add_u32 s6, s39, s6
	s_mul_hi_i32 s39, s8, 5
	v_ashrrev_i32_e32 v144, 6, v177
	s_addc_u32 s7, s39, s7
	v_mov_b64_e32 v[4:5], s[66:67]
	v_mov_b32_e32 v6, 0x6000
	v_and_b32_e32 v145, 3, v144
	s_mul_i32 s39, s7, 0x6000
	v_mad_u64_u32 v[4:5], s[6:7], s6, v6, v[4:5]
	v_lshrrev_b32_e32 v6, 2, v177
	v_lshlrev_b32_e32 v172, 6, v145
	v_and_b32_e32 v6, 12, v6
	v_or3_b32 v6, v6, s38, v172
	v_ashrrev_i32_e32 v7, 31, v6
	v_add_u32_e32 v5, s39, v5
	v_lshlrev_b64 v[150:151], 2, v[6:7]
	v_lshl_add_u64 v[4:5], v[4:5], 0, v[150:151]
	v_add_co_u32_e32 v20, vcc, s33, v4
	s_mov_b64 s[6:7], 0x4000
	s_nop 0
	v_addc_co_u32_e32 v21, vcc, 0, v5, vcc
	global_load_dwordx4 v[68:71], v[20:21], off
	v_lshl_add_u64 v[20:21], v[4:5], 0, s[6:7]
	s_movk_i32 s6, 0x2000
	v_lshl_add_u64 v[6:7], s[34:35], 0, v[150:151]
	global_load_dwordx4 v[72:75], v[20:21], off offset:64
	global_load_dwordx4 v[146:149], v[6:7], off
	global_load_dwordx4 v[152:155], v[20:21], off offset:128
	global_load_dwordx4 v[156:159], v[20:21], off offset:192
	v_add_co_u32_e32 v20, vcc, s6, v4
	s_mov_b64 s[6:7], 0x2000
	s_nop 0
	v_addc_co_u32_e32 v21, vcc, 0, v5, vcc
	global_load_dwordx4 v[164:167], v[6:7], off offset:64
	global_load_dwordx4 v[28:31], v[20:21], off
	global_load_dwordx4 v[178:181], v[6:7], off offset:128
	v_lshl_add_u64 v[4:5], v[4:5], 0, s[6:7]
	global_load_dwordx4 v[182:185], v[6:7], off offset:192
	global_load_dwordx4 v[24:27], v[4:5], off offset:64
	global_load_dwordx4 v[20:23], v[4:5], off offset:128
	s_nop 0
	global_load_dwordx4 v[4:7], v[4:5], off offset:192
	s_lshl_b32 s6, s87, 2
	v_xor_b32_e32 v230, 16, v202
	s_ashr_i32 s7, s6, 31
	v_cmp_lt_i32_e32 vcc, v230, v203
	s_lshl_b64 s[6:7], s[6:7], 2
	s_add_u32 s6, s31, s6
	v_cndmask_b32_e32 v160, v202, v230, vcc
	v_cmp_lt_i32_e32 vcc, v209, v203
	v_lshlrev_b32_e32 v170, 2, v160
	v_mov_b32_e32 v160, 0x10000
	v_cndmask_b32_e32 v171, v202, v209, vcc
	v_lshlrev_b32_e32 v192, 2, v145
	s_addc_u32 s7, s45, s7
	v_and_b32_e32 v175, 63, v177
	v_and_b32_e32 v173, 15, v177
	v_lshl_add_u32 v176, v144, 13, v160
	v_lshl_add_u64 v[144:145], s[6:7], 0, v[192:193]
	v_lshlrev_b32_e32 v171, 2, v171
	v_readlane_b32 s9, v255, 11
	s_waitcnt vmcnt(11)
	v_pk_add_f32 v[70:71], v[70:71], 1.0 op_sel_hi:[1,0]
	v_pk_add_f32 v[68:69], v[68:69], 1.0 op_sel_hi:[1,0]
	s_waitcnt vmcnt(10)
	v_pk_add_f32 v[74:75], v[74:75], 1.0 op_sel_hi:[1,0]
	v_pk_add_f32 v[72:73], v[72:73], 1.0 op_sel_hi:[1,0]
	s_waitcnt vmcnt(8)
	v_pk_add_f32 v[154:155], v[154:155], 1.0 op_sel_hi:[1,0]
	v_pk_add_f32 v[168:169], v[152:153], 1.0 op_sel_hi:[1,0]
	s_waitcnt vmcnt(7)
	v_pk_add_f32 v[186:187], v[158:159], 1.0 op_sel_hi:[1,0]
	v_pk_add_f32 v[188:189], v[156:157], 1.0 op_sel_hi:[1,0]
	v_pk_mul_f32 v[160:161], v[148:149], v[70:71]
	v_pk_mul_f32 v[162:163], v[146:147], v[68:69]
	s_waitcnt vmcnt(6)
	v_pk_mul_f32 v[156:157], v[166:167], v[74:75]
	v_pk_mul_f32 v[158:159], v[164:165], v[72:73]
	s_waitcnt vmcnt(4)
	v_pk_mul_f32 v[152:153], v[180:181], v[154:155]
	v_pk_mul_f32 v[154:155], v[178:179], v[168:169]
	s_waitcnt vmcnt(3)
	v_pk_mul_f32 v[146:147], v[184:185], v[186:187]
	v_pk_mul_f32 v[148:149], v[182:183], v[188:189]
	v_ashrrev_i32_e32 v68, 1, v177
	v_and_b32_e32 v174, 0xffffff80, v68
	v_add_u32_e32 v164, s41, v174
	v_or_b32_e32 v166, v164, v173
	v_cmp_gt_i32_e32 vcc, s33, v166
	v_add_u32_e32 v68, 0xffffc000, v166
	v_ashrrev_i32_e32 v167, 31, v166
	v_mov_b32_e32 v70, s71
	v_mov_b32_e32 v71, s55
	v_cndmask_b32_e32 v69, 0, v167, vcc
	v_cndmask_b32_e32 v68, v68, v166, vcc
	v_cndmask_b32_e32 v71, v70, v71, vcc
	v_mov_b32_e32 v70, s70
	v_mov_b32_e32 v72, s54
	v_cndmask_b32_e32 v70, v70, v72, vcc
	v_lshlrev_b64 v[68:69], 12, v[68:69]
	v_readlane_b32 s8, v254, 50
	v_lshl_add_u64 v[68:69], v[70:71], 0, v[68:69]
	v_lshlrev_b64 v[70:71], 12, v[166:167]
	v_readlane_b32 s9, v254, 51
	v_lshl_add_u64 v[168:169], v[68:69], 0, v[150:151]
	v_bfe_u32 v75, v177, 5, 1
	v_lshl_add_u64 v[70:71], s[8:9], 0, v[70:71]
	v_cndmask_b32_e64 v69, v69, v71, s[4:5]
	v_cndmask_b32_e64 v68, v68, v70, s[4:5]
	v_lshl_add_u64 v[72:73], v[68:69], 0, v[150:151]
	global_load_dwordx4 v[68:71], v[72:73], off
	global_load_dwordx4 v[232:235], v[72:73], off offset:64
	global_load_dwordx4 v[236:239], v[72:73], off offset:128
	global_load_dwordx4 v[240:243], v[72:73], off offset:192
	v_cmp_gt_u32_e32 vcc, 16, v175
	v_readlane_b32 s10, v254, 52
	v_readlane_b32 s11, v254, 53
	v_readlane_b32 s12, v254, 54
	v_readlane_b32 s13, v254, 55
	v_readlane_b32 s14, v254, 56
	v_readlane_b32 s15, v254, 57
	v_readlane_b32 s16, v254, 58
	v_readlane_b32 s17, v254, 59
	v_readlane_b32 s18, v254, 60
	v_readlane_b32 s19, v254, 61
	v_readlane_b32 s20, v254, 62
	v_readlane_b32 s21, v254, 63
	v_readlane_b32 s22, v255, 0
	v_readlane_b32 s23, v255, 1
	s_waitcnt vmcnt(3)
; DI unsigned pk2(float a, float b) { f32x2 v = {a, b}; bf2_t r = __builtin_convertvector(v, bf2_t); return __builtin_bit_cast(unsigned, r); }
;     static DI void run(const f32x4 (&acc)[8][4], const TileCtx& tc, const Params& p, ldsp_t wb) {
;     ...
;             for (int mm = 0; mm < 4; ++mm) { __builtin_amdgcn_sched_barrier(0);
;                 const int m = h * 4 + mm;
;                 const int row = tc.brow + tc.wr * 128 + m * 16 + tc.fr;
;                 float* xr = xrow_ptr(p, row) + col0;
;                 const float* xs = (EK == 1 && tc.l == 0) ? p.x + (size_t)row * DM + col0 : xr;
;                 float part = 0.f;
; #pragma unroll
;                 for (int n = 0; n < 4; ++n) {
;                     f32x4 xv = *(const f32x4*)(xs + n * 16);
;                     xv += gv[n] * acc[m][n];
;                     *(f32x4*)(xr + n * 16) = xv;
;                     if (has_next) {
;                         part += xv[0] * xv[0] + xv[1] * xv[1] + xv[2] * xv[2] + xv[3] * xv[3];
;                         const f32x4 hv = xv * av[n];
;                         u32x2 w; w[0] = pk2(hv[0], hv[1]); w[1] = pk2(hv[2], hv[3]);
;                         wave_put(wb, mm * 16 + tc.fr, n, tc.fq, w);
;                     }
;                 }
;                 if (has_next) {
;                     part += __shfl_xor(part, 16);
;                     part += __shfl_xor(part, 32);
;                     if (tc.fq == 0) ssp[(size_t)row * 16] = part;
;                 }
	v_pk_fma_f32 v[68:69], v[140:141], v[28:29], v[68:69]
	s_nop 0
	v_mul_f32_e32 v74, v69, v69
	v_pk_fma_f32 v[70:71], v[142:143], v[30:31], v[70:71]
	v_fmac_f32_e32 v74, v68, v68
	v_fmac_f32_e32 v74, v70, v70
	global_store_dwordx4 v[168:169], v[68:71], off sc1
	v_fmac_f32_e32 v74, v71, v71
	v_lshl_or_b32 v142, v173, 7, v176
	v_pk_mul_f32 v[70:71], v[160:161], v[70:71]
	v_pk_mul_f32 v[68:69], v[162:163], v[68:69]
	v_and_b32_e32 v143, 7, v177
	v_cvt_pk_bf16_f32 v68, v68, v69
	v_cvt_pk_bf16_f32 v69, v70, v71
	v_bitop3_b32 v70, v75, v177, 7 bitop3:0x78
	v_lshl_or_b32 v141, v70, 4, v142
	v_lshrrev_b32_e32 v70, 1, v177
	v_and_b32_e32 v140, 8, v70
	v_or_b32_e32 v70, v141, v140
	ds_write_b64 v70, v[68:69]
	s_nop 1
	s_waitcnt vmcnt(3)
	v_pk_fma_f32 v[68:69], v[136:137], v[24:25], v[232:233]
	s_nop 0
	v_mul_f32_e32 v136, v69, v69
	v_pk_fma_f32 v[70:71], v[138:139], v[26:27], v[234:235]
	v_fmac_f32_e32 v136, v68, v68
	v_fmac_f32_e32 v136, v70, v70
	global_store_dwordx4 v[168:169], v[68:71], off offset:64 sc1
	v_fmac_f32_e32 v136, v71, v71
	v_add_f32_e32 v74, v74, v136
	v_pk_mul_f32 v[70:71], v[156:157], v[70:71]
	v_pk_mul_f32 v[68:69], v[158:159], v[68:69]
	s_nop 0
	v_cvt_pk_bf16_f32 v68, v68, v69
	v_cvt_pk_bf16_f32 v69, v70, v71
	v_bitop3_b32 v70, v75, v143, 2 bitop3:0x36
	v_lshl_or_b32 v136, v70, 4, v142
	v_or_b32_e32 v70, v136, v140
	ds_write_b64 v70, v[68:69]
	s_nop 1
	s_waitcnt vmcnt(3)
	v_pk_fma_f32 v[68:69], v[132:133], v[20:21], v[236:237]
	s_nop 0
	v_mul_f32_e32 v132, v69, v69
	v_pk_fma_f32 v[70:71], v[134:135], v[22:23], v[238:239]
	v_fmac_f32_e32 v132, v68, v68
	v_fmac_f32_e32 v132, v70, v70
	global_store_dwordx4 v[168:169], v[68:71], off offset:128 sc1
	v_fmac_f32_e32 v132, v71, v71
	v_add_f32_e32 v74, v74, v132
	v_pk_mul_f32 v[70:71], v[152:153], v[70:71]
	v_pk_mul_f32 v[68:69], v[154:155], v[68:69]
	s_nop 0
	v_cvt_pk_bf16_f32 v68, v68, v69
	v_cvt_pk_bf16_f32 v69, v70, v71
	v_bitop3_b32 v70, v75, v143, 4 bitop3:0x36
	v_lshl_or_b32 v133, v70, 4, v142
	v_or_b32_e32 v70, v133, v140
	ds_write_b64 v70, v[68:69]
	s_nop 1
	s_waitcnt vmcnt(3)
	v_pk_fma_f32 v[68:69], v[128:129], v[4:5], v[240:241]
	s_nop 0
	v_mul_f32_e32 v72, v69, v69
	v_pk_fma_f32 v[70:71], v[130:131], v[6:7], v[242:243]
	v_fmac_f32_e32 v72, v68, v68
	v_fmac_f32_e32 v72, v70, v70
	global_store_dwordx4 v[168:169], v[68:71], off offset:192 sc1
	v_fmac_f32_e32 v72, v71, v71
	v_add_f32_e32 v72, v74, v72
	v_pk_mul_f32 v[70:71], v[146:147], v[70:71]
	v_pk_mul_f32 v[68:69], v[148:149], v[68:69]
	s_nop 0
	v_cvt_pk_bf16_f32 v68, v68, v69
	v_cvt_pk_bf16_f32 v69, v70, v71
	v_bitop3_b32 v70, v75, v143, 6 bitop3:0x36
	v_lshl_or_b32 v134, v70, 4, v142
	v_or_b32_e32 v70, v134, v140
	ds_write_b64 v70, v[68:69]
	ds_bpermute_b32 v68, v170, v72
	s_waitcnt lgkmcnt(0)
	v_add_f32_e32 v128, v72, v68
	ds_bpermute_b32 v129, v171, v128
	s_and_saveexec_b64 s[6:7], vcc
	s_cbranch_execz .LBB0_139
	v_lshlrev_b64 v[68:69], 6, v[166:167]
	s_waitcnt lgkmcnt(0)
	v_add_f32_e32 v70, v128, v129
	v_lshl_add_u64 v[68:69], v[144:145], 0, v[68:69]
	global_store_dword v[68:69], v70, off sc1
.LBB0_139:
	s_or_b64 exec, exec, s[6:7]
	v_or_b32_e32 v68, s41, v173
	v_add_u32_e32 v132, v174, v68
	v_add_u32_e32 v128, 16, v132
	v_cmp_gt_i32_e64 s[6:7], s33, v128
	v_add_u32_e32 v68, 0xffffc010, v132
	s_waitcnt lgkmcnt(0)
	v_ashrrev_i32_e32 v129, 31, v128
	v_mov_b32_e32 v70, s71
	v_mov_b32_e32 v71, s55
	v_cndmask_b32_e64 v69, 0, v129, s[6:7]
	v_cndmask_b32_e64 v68, v68, v128, s[6:7]
	v_cndmask_b32_e64 v71, v70, v71, s[6:7]
	v_mov_b32_e32 v70, s70
	v_mov_b32_e32 v72, s54
	v_cndmask_b32_e64 v70, v70, v72, s[6:7]
	v_lshlrev_b64 v[68:69], 12, v[68:69]
	v_readlane_b32 s8, v254, 50
	v_lshl_add_u64 v[68:69], v[70:71], 0, v[68:69]
	v_lshlrev_b64 v[70:71], 12, v[128:129]
	v_readlane_b32 s9, v254, 51
	v_lshl_add_u64 v[130:131], v[68:69], 0, v[150:151]
	v_readlane_b32 s10, v254, 52
	v_lshl_add_u64 v[70:71], s[8:9], 0, v[70:71]
	v_cndmask_b32_e64 v69, v69, v71, s[4:5]
	v_cndmask_b32_e64 v68, v68, v70, s[4:5]
	v_lshl_add_u64 v[72:73], v[68:69], 0, v[150:151]
	global_load_dwordx4 v[68:71], v[72:73], off
	global_load_dwordx4 v[232:235], v[72:73], off offset:64
	global_load_dwordx4 v[236:239], v[72:73], off offset:128
	global_load_dwordx4 v[240:243], v[72:73], off offset:192
	v_readlane_b32 s11, v254, 53
	v_readlane_b32 s12, v254, 54
	v_readlane_b32 s13, v254, 55
	v_readlane_b32 s14, v254, 56
	v_readlane_b32 s15, v254, 57
	v_readlane_b32 s16, v254, 58
	v_readlane_b32 s17, v254, 59
	v_readlane_b32 s18, v254, 60
	v_readlane_b32 s19, v254, 61
	v_readlane_b32 s20, v254, 62
	v_readlane_b32 s21, v254, 63
	v_readlane_b32 s22, v255, 0
	v_readlane_b32 s23, v255, 1
	s_waitcnt vmcnt(3)
	v_pk_fma_f32 v[68:69], v[124:125], v[28:29], v[68:69]
	s_nop 0
	v_mul_f32_e32 v74, v69, v69
	v_pk_fma_f32 v[70:71], v[126:127], v[30:31], v[70:71]
	v_fmac_f32_e32 v74, v68, v68
	v_fmac_f32_e32 v74, v70, v70
	global_store_dwordx4 v[130:131], v[68:71], off sc1
	v_fmac_f32_e32 v74, v71, v71
	v_add_u32_e32 v124, v141, v140
	v_pk_mul_f32 v[70:71], v[160:161], v[70:71]
	v_pk_mul_f32 v[68:69], v[162:163], v[68:69]
	s_nop 0
	v_cvt_pk_bf16_f32 v68, v68, v69
	v_cvt_pk_bf16_f32 v69, v70, v71
	ds_write_b64 v124, v[68:69] offset:2048
	s_nop 1
	s_waitcnt vmcnt(3)
	v_pk_fma_f32 v[68:69], v[120:121], v[24:25], v[232:233]
	s_nop 0
	v_mul_f32_e32 v75, v69, v69
	v_pk_fma_f32 v[70:71], v[122:123], v[26:27], v[234:235]
	v_fmac_f32_e32 v75, v68, v68
	v_fmac_f32_e32 v75, v70, v70
	global_store_dwordx4 v[130:131], v[68:71], off offset:64 sc1
	v_fmac_f32_e32 v75, v71, v71
	v_add_u32_e32 v120, v136, v140
	v_pk_mul_f32 v[70:71], v[156:157], v[70:71]
	v_pk_mul_f32 v[68:69], v[158:159], v[68:69]
	v_add_f32_e32 v74, v74, v75
	v_cvt_pk_bf16_f32 v68, v68, v69
	v_cvt_pk_bf16_f32 v69, v70, v71
	ds_write_b64 v120, v[68:69] offset:2048
	s_nop 1
	s_waitcnt vmcnt(3)
; DI unsigned pk2(float a, float b) { f32x2 v = {a, b}; bf2_t r = __builtin_convertvector(v, bf2_t); return __builtin_bit_cast(unsigned, r); }
;     static DI void run(const f32x4 (&acc)[8][4], const TileCtx& tc, const Params& p, ldsp_t wb) {
;     ...
;             for (int mm = 0; mm < 4; ++mm) { __builtin_amdgcn_sched_barrier(0);
;                 const int m = h * 4 + mm;
;                 const int row = tc.brow + tc.wr * 128 + m * 16 + tc.fr;
;                 float* xr = xrow_ptr(p, row) + col0;
;                 const float* xs = (EK == 1 && tc.l == 0) ? p.x + (size_t)row * DM + col0 : xr;
;                 float part = 0.f;
; #pragma unroll
;                 for (int n = 0; n < 4; ++n) {
;                     f32x4 xv = *(const f32x4*)(xs + n * 16);
;                     xv += gv[n] * acc[m][n];
;                     *(f32x4*)(xr + n * 16) = xv;
;                     if (has_next) {
;                         part += xv[0] * xv[0] + xv[1] * xv[1] + xv[2] * xv[2] + xv[3] * xv[3];
;                         const f32x4 hv = xv * av[n];
;                         u32x2 w; w[0] = pk2(hv[0], hv[1]); w[1] = pk2(hv[2], hv[3]);
;                         wave_put(wb, mm * 16 + tc.fr, n, tc.fq, w);
;                     }
;                 }
;                 if (has_next) {
;                     part += __shfl_xor(part, 16);
;                     part += __shfl_xor(part, 32);
;                     if (tc.fq == 0) ssp[(size_t)row * 16] = part;
;                 }
	v_pk_fma_f32 v[68:69], v[116:117], v[20:21], v[236:237]
	s_nop 0
	v_mul_f32_e32 v75, v69, v69
	v_pk_fma_f32 v[70:71], v[118:119], v[22:23], v[238:239]
	v_fmac_f32_e32 v75, v68, v68
	v_fmac_f32_e32 v75, v70, v70
	global_store_dwordx4 v[130:131], v[68:71], off offset:128 sc1
	v_fmac_f32_e32 v75, v71, v71
	v_add_u32_e32 v116, v133, v140
	v_pk_mul_f32 v[70:71], v[152:153], v[70:71]
	v_pk_mul_f32 v[68:69], v[154:155], v[68:69]
	v_add_f32_e32 v74, v74, v75
	v_cvt_pk_bf16_f32 v68, v68, v69
	v_cvt_pk_bf16_f32 v69, v70, v71
	ds_write_b64 v116, v[68:69] offset:2048
	s_nop 1
	v_add_u32_e32 v117, v134, v140
	s_waitcnt vmcnt(3)
	v_pk_fma_f32 v[68:69], v[112:113], v[4:5], v[240:241]
	s_nop 0
	v_mul_f32_e32 v72, v69, v69
	v_pk_fma_f32 v[70:71], v[114:115], v[6:7], v[242:243]
	v_fmac_f32_e32 v72, v68, v68
	v_fmac_f32_e32 v72, v70, v70
	global_store_dwordx4 v[130:131], v[68:71], off offset:192 sc1
	v_fmac_f32_e32 v72, v71, v71
	v_add_f32_e32 v72, v74, v72
	v_pk_mul_f32 v[70:71], v[146:147], v[70:71]
	v_pk_mul_f32 v[68:69], v[148:149], v[68:69]
	s_nop 0
	v_cvt_pk_bf16_f32 v68, v68, v69
	v_cvt_pk_bf16_f32 v69, v70, v71
	ds_write_b64 v117, v[68:69] offset:2048
	ds_bpermute_b32 v68, v170, v72
	s_waitcnt lgkmcnt(0)
	v_add_f32_e32 v112, v72, v68
	ds_bpermute_b32 v113, v171, v112
	s_and_saveexec_b64 s[6:7], vcc
	s_cbranch_execz .LBB0_141
	v_lshlrev_b64 v[68:69], 6, v[128:129]
	s_waitcnt lgkmcnt(0)
	v_add_f32_e32 v70, v112, v113
	v_lshl_add_u64 v[68:69], v[144:145], 0, v[68:69]
	global_store_dword v[68:69], v70, off sc1
.LBB0_141:
	s_or_b64 exec, exec, s[6:7]
	v_add_u32_e32 v112, 32, v132
	v_cmp_gt_i32_e64 s[6:7], s33, v112
	v_add_u32_e32 v68, 0xffffc020, v132
	s_waitcnt lgkmcnt(0)
	v_ashrrev_i32_e32 v113, 31, v112
	v_mov_b32_e32 v70, s71
	v_mov_b32_e32 v71, s55
	v_cndmask_b32_e64 v69, 0, v113, s[6:7]
	v_cndmask_b32_e64 v68, v68, v112, s[6:7]
	v_cndmask_b32_e64 v71, v70, v71, s[6:7]
	v_mov_b32_e32 v70, s70
	v_mov_b32_e32 v72, s54
	v_cndmask_b32_e64 v70, v70, v72, s[6:7]
	v_lshlrev_b64 v[68:69], 12, v[68:69]
	v_readlane_b32 s8, v254, 50
	v_lshl_add_u64 v[68:69], v[70:71], 0, v[68:69]
	v_lshlrev_b64 v[70:71], 12, v[112:113]
	v_readlane_b32 s9, v254, 51
	v_lshl_add_u64 v[114:115], v[68:69], 0, v[150:151]
	v_readlane_b32 s10, v254, 52
	v_lshl_add_u64 v[70:71], s[8:9], 0, v[70:71]
	v_cndmask_b32_e64 v69, v69, v71, s[4:5]
	v_cndmask_b32_e64 v68, v68, v70, s[4:5]
	v_lshl_add_u64 v[72:73], v[68:69], 0, v[150:151]
	global_load_dwordx4 v[68:71], v[72:73], off
	global_load_dwordx4 v[232:235], v[72:73], off offset:64
	global_load_dwordx4 v[236:239], v[72:73], off offset:128
	global_load_dwordx4 v[240:243], v[72:73], off offset:192
	v_readlane_b32 s11, v254, 53
	v_readlane_b32 s12, v254, 54
	v_readlane_b32 s13, v254, 55
	v_readlane_b32 s14, v254, 56
	v_readlane_b32 s15, v254, 57
	v_readlane_b32 s16, v254, 58
	v_readlane_b32 s17, v254, 59
	v_readlane_b32 s18, v254, 60
	v_readlane_b32 s19, v254, 61
	v_readlane_b32 s20, v254, 62
	v_readlane_b32 s21, v254, 63
	v_readlane_b32 s22, v255, 0
	v_readlane_b32 s23, v255, 1
	s_waitcnt vmcnt(3)
	v_pk_fma_f32 v[68:69], v[108:109], v[28:29], v[68:69]
	s_nop 0
	v_mul_f32_e32 v74, v69, v69
	v_pk_fma_f32 v[70:71], v[110:111], v[30:31], v[70:71]
	v_fmac_f32_e32 v74, v68, v68
	v_fmac_f32_e32 v74, v70, v70
	global_store_dwordx4 v[114:115], v[68:71], off sc1
	v_fmac_f32_e32 v74, v71, v71
	s_nop 0
	v_pk_mul_f32 v[70:71], v[160:161], v[70:71]
	v_pk_mul_f32 v[68:69], v[162:163], v[68:69]
	s_nop 0
	v_cvt_pk_bf16_f32 v68, v68, v69
	v_cvt_pk_bf16_f32 v69, v70, v71
	ds_write_b64 v124, v[68:69] offset:4096
	s_nop 1
	s_waitcnt vmcnt(3)
	v_pk_fma_f32 v[68:69], v[104:105], v[24:25], v[232:233]
	s_nop 0
	v_mul_f32_e32 v75, v69, v69
	v_pk_fma_f32 v[70:71], v[106:107], v[26:27], v[234:235]
	v_fmac_f32_e32 v75, v68, v68
	v_fmac_f32_e32 v75, v70, v70
	global_store_dwordx4 v[114:115], v[68:71], off offset:64 sc1
	v_fmac_f32_e32 v75, v71, v71
	v_add_f32_e32 v74, v74, v75
	v_pk_mul_f32 v[70:71], v[156:157], v[70:71]
	v_pk_mul_f32 v[68:69], v[158:159], v[68:69]
	s_nop 0
	v_cvt_pk_bf16_f32 v68, v68, v69
	v_cvt_pk_bf16_f32 v69, v70, v71
	ds_write_b64 v120, v[68:69] offset:4096
	s_nop 1
	s_waitcnt vmcnt(3)
	v_pk_fma_f32 v[68:69], v[100:101], v[20:21], v[236:237]
	s_nop 0
	v_mul_f32_e32 v75, v69, v69
	v_pk_fma_f32 v[70:71], v[102:103], v[22:23], v[238:239]
	v_fmac_f32_e32 v75, v68, v68
	v_fmac_f32_e32 v75, v70, v70
	global_store_dwordx4 v[114:115], v[68:71], off offset:128 sc1
	v_fmac_f32_e32 v75, v71, v71
	v_add_f32_e32 v74, v74, v75
	v_pk_mul_f32 v[70:71], v[152:153], v[70:71]
	v_pk_mul_f32 v[68:69], v[154:155], v[68:69]
	s_nop 0
	v_cvt_pk_bf16_f32 v68, v68, v69
	v_cvt_pk_bf16_f32 v69, v70, v71
	ds_write_b64 v116, v[68:69] offset:4096
	s_nop 1
	s_waitcnt vmcnt(3)
	v_pk_fma_f32 v[68:69], v[96:97], v[4:5], v[240:241]
	s_nop 0
	v_mul_f32_e32 v72, v69, v69
	v_pk_fma_f32 v[70:71], v[98:99], v[6:7], v[242:243]
	v_fmac_f32_e32 v72, v68, v68
	v_fmac_f32_e32 v72, v70, v70
	global_store_dwordx4 v[114:115], v[68:71], off offset:192 sc1
	v_fmac_f32_e32 v72, v71, v71
	v_add_f32_e32 v72, v74, v72
	v_pk_mul_f32 v[70:71], v[146:147], v[70:71]
	v_pk_mul_f32 v[68:69], v[148:149], v[68:69]
	s_nop 0
	v_cvt_pk_bf16_f32 v68, v68, v69
	v_cvt_pk_bf16_f32 v69, v70, v71
	ds_write_b64 v117, v[68:69] offset:4096
	ds_bpermute_b32 v68, v170, v72
	s_waitcnt lgkmcnt(0)
	v_add_f32_e32 v96, v72, v68
	ds_bpermute_b32 v97, v171, v96
	s_and_saveexec_b64 s[6:7], vcc
	s_cbranch_execz .LBB0_143
	v_lshlrev_b64 v[68:69], 6, v[112:113]
	s_waitcnt lgkmcnt(0)
	v_add_f32_e32 v70, v96, v97
	v_lshl_add_u64 v[68:69], v[144:145], 0, v[68:69]
	global_store_dword v[68:69], v70, off sc1
; #define LDSP __attribute__((address_space(3)))
; DI unsigned pk2(float a, float b) { f32x2 v = {a, b}; bf2_t r = __builtin_convertvector(v, bf2_t); return __builtin_bit_cast(unsigned, r); }
; DI void wave_rows_store(ldsp_t wb, int lane, bf16_t* dst0, size_t ld) {
; #pragma unroll
;     for (int i = 0; i < 8; ++i) {
;         const int row = i * 8 + (lane >> 3), ch = lane & 7;
;         const u32x4 v = *(const LDSP u32x4*)(wb + row * 128 + ((ch ^ (row & 7)) << 4));
;         *(u32x4*)(dst0 + (size_t)row * ld + ch * 8) = v;
;     }
;     static DI void run(const f32x4 (&acc)[8][4], const TileCtx& tc, const Params& p, ldsp_t wb) {
;     ...
;             for (int mm = 0; mm < 4; ++mm) { __builtin_amdgcn_sched_barrier(0);
;                 const int m = h * 4 + mm;
;                 const int row = tc.brow + tc.wr * 128 + m * 16 + tc.fr;
;                 float* xr = xrow_ptr(p, row) + col0;
;                 const float* xs = (EK == 1 && tc.l == 0) ? p.x + (size_t)row * DM + col0 : xr;
;                 float part = 0.f;
; #pragma unroll
;                 for (int n = 0; n < 4; ++n) {
;                     f32x4 xv = *(const f32x4*)(xs + n * 16);
;                     xv += gv[n] * acc[m][n];
;                     *(f32x4*)(xr + n * 16) = xv;
;                     if (has_next) {
;                         part += xv[0] * xv[0] + xv[1] * xv[1] + xv[2] * xv[2] + xv[3] * xv[3];
;                         const f32x4 hv = xv * av[n];
;                         u32x2 w; w[0] = pk2(hv[0], hv[1]); w[1] = pk2(hv[2], hv[3]);
;                         wave_put(wb, mm * 16 + tc.fr, n, tc.fq, w);
;                     }
;                 }
;                 if (has_next) {
;                     part += __shfl_xor(part, 16);
;                     part += __shfl_xor(part, 32);
;                     if (tc.fq == 0) ssp[(size_t)row * 16] = part;
;                 }
.LBB0_143:
	s_or_b64 exec, exec, s[6:7]
	v_add_u32_e32 v96, 48, v132
	v_cmp_gt_i32_e64 s[6:7], s33, v96
	v_add_u32_e32 v68, 0xffffc030, v132
	s_waitcnt lgkmcnt(0)
	v_ashrrev_i32_e32 v97, 31, v96
	v_mov_b32_e32 v70, s71
	v_mov_b32_e32 v71, s55
	v_cndmask_b32_e64 v69, 0, v97, s[6:7]
	v_cndmask_b32_e64 v68, v68, v96, s[6:7]
	v_cndmask_b32_e64 v71, v70, v71, s[6:7]
	v_mov_b32_e32 v70, s70
	v_mov_b32_e32 v72, s54
	v_cndmask_b32_e64 v70, v70, v72, s[6:7]
	v_lshlrev_b64 v[68:69], 12, v[68:69]
	v_readlane_b32 s8, v254, 50
	v_lshl_add_u64 v[68:69], v[70:71], 0, v[68:69]
	v_lshlrev_b64 v[70:71], 12, v[96:97]
	v_readlane_b32 s9, v254, 51
	v_lshl_add_u64 v[98:99], v[68:69], 0, v[150:151]
	v_readlane_b32 s10, v254, 52
	v_lshl_add_u64 v[70:71], s[8:9], 0, v[70:71]
	v_cndmask_b32_e64 v69, v69, v71, s[4:5]
	v_cndmask_b32_e64 v68, v68, v70, s[4:5]
	v_lshl_add_u64 v[72:73], v[68:69], 0, v[150:151]
	global_load_dwordx4 v[68:71], v[72:73], off
	global_load_dwordx4 v[232:235], v[72:73], off offset:64
	global_load_dwordx4 v[236:239], v[72:73], off offset:128
	global_load_dwordx4 v[240:243], v[72:73], off offset:192
	v_readlane_b32 s11, v254, 53
	v_readlane_b32 s12, v254, 54
	v_readlane_b32 s13, v254, 55
	v_readlane_b32 s14, v254, 56
	v_readlane_b32 s15, v254, 57
	v_readlane_b32 s16, v254, 58
	v_readlane_b32 s17, v254, 59
	v_readlane_b32 s18, v254, 60
	v_readlane_b32 s19, v254, 61
	v_readlane_b32 s20, v254, 62
	v_readlane_b32 s21, v254, 63
	v_readlane_b32 s22, v255, 0
	v_readlane_b32 s23, v255, 1
	s_waitcnt vmcnt(3)
	v_pk_fma_f32 v[68:69], v[92:93], v[28:29], v[68:69]
	s_nop 0
	v_mul_f32_e32 v74, v69, v69
	v_pk_fma_f32 v[70:71], v[94:95], v[30:31], v[70:71]
	v_fmac_f32_e32 v74, v68, v68
	v_fmac_f32_e32 v74, v70, v70
	global_store_dwordx4 v[98:99], v[68:71], off sc1
	v_fmac_f32_e32 v74, v71, v71
	s_nop 0
	v_pk_mul_f32 v[70:71], v[160:161], v[70:71]
	v_pk_mul_f32 v[68:69], v[162:163], v[68:69]
	s_nop 0
	v_cvt_pk_bf16_f32 v68, v68, v69
	v_cvt_pk_bf16_f32 v69, v70, v71
	ds_write_b64 v124, v[68:69] offset:6144
	s_nop 1
	s_waitcnt vmcnt(3)
	v_pk_fma_f32 v[68:69], v[88:89], v[24:25], v[232:233]
	s_nop 0
	v_mul_f32_e32 v75, v69, v69
	v_pk_fma_f32 v[70:71], v[90:91], v[26:27], v[234:235]
	v_fmac_f32_e32 v75, v68, v68
	v_fmac_f32_e32 v75, v70, v70
	global_store_dwordx4 v[98:99], v[68:71], off offset:64 sc1
	v_fmac_f32_e32 v75, v71, v71
	v_add_f32_e32 v74, v74, v75
	v_pk_mul_f32 v[70:71], v[156:157], v[70:71]
	v_pk_mul_f32 v[68:69], v[158:159], v[68:69]
	s_nop 0
	v_cvt_pk_bf16_f32 v68, v68, v69
	v_cvt_pk_bf16_f32 v69, v70, v71
	ds_write_b64 v120, v[68:69] offset:6144
	s_nop 1
	s_waitcnt vmcnt(3)
	v_pk_fma_f32 v[68:69], v[84:85], v[20:21], v[236:237]
	s_nop 0
	v_mul_f32_e32 v75, v69, v69
	v_pk_fma_f32 v[70:71], v[86:87], v[22:23], v[238:239]
	v_fmac_f32_e32 v75, v68, v68
	v_fmac_f32_e32 v75, v70, v70
	global_store_dwordx4 v[98:99], v[68:71], off offset:128 sc1
	v_fmac_f32_e32 v75, v71, v71
	v_add_f32_e32 v74, v74, v75
	v_pk_mul_f32 v[70:71], v[152:153], v[70:71]
	v_pk_mul_f32 v[68:69], v[154:155], v[68:69]
	s_nop 0
	v_cvt_pk_bf16_f32 v68, v68, v69
	v_cvt_pk_bf16_f32 v69, v70, v71
	ds_write_b64 v116, v[68:69] offset:6144
	s_nop 1
	s_waitcnt vmcnt(3)
	v_pk_fma_f32 v[68:69], v[80:81], v[4:5], v[240:241]
	s_nop 0
	v_mul_f32_e32 v72, v69, v69
	v_pk_fma_f32 v[70:71], v[82:83], v[6:7], v[242:243]
	v_fmac_f32_e32 v72, v68, v68
	v_fmac_f32_e32 v72, v70, v70
	global_store_dwordx4 v[98:99], v[68:71], off offset:192 sc1
	v_fmac_f32_e32 v72, v71, v71
	v_add_f32_e32 v72, v74, v72
	v_pk_mul_f32 v[70:71], v[146:147], v[70:71]
	v_pk_mul_f32 v[68:69], v[148:149], v[68:69]
	s_nop 0
	v_cvt_pk_bf16_f32 v68, v68, v69
	v_cvt_pk_bf16_f32 v69, v70, v71
	ds_write_b64 v117, v[68:69] offset:6144
	ds_bpermute_b32 v68, v170, v72
	s_waitcnt lgkmcnt(0)
	v_add_f32_e32 v80, v72, v68
	ds_bpermute_b32 v81, v171, v80
	s_and_saveexec_b64 s[6:7], vcc
	s_cbranch_execz .LBB0_145
	v_lshlrev_b64 v[68:69], 6, v[96:97]
	s_waitcnt lgkmcnt(0)
	v_add_f32_e32 v70, v80, v81
	v_lshl_add_u64 v[68:69], v[144:145], 0, v[68:69]
	global_store_dword v[68:69], v70, off sc1
.LBB0_145:
	s_or_b64 exec, exec, s[6:7]
	v_lshrrev_b32_e32 v80, 3, v175
	v_xor_b32_e32 v70, v80, v175
	v_ashrrev_i32_e32 v165, 31, v164
	v_lshlrev_b32_e32 v70, 4, v70
	v_lshlrev_b64 v[68:69], 11, v[164:165]
	v_and_b32_e32 v70, 0x70, v70
	v_lshl_add_u64 v[68:69], s[82:83], 0, v[68:69]
	s_ashr_i32 s39, s38, 31
	s_waitcnt lgkmcnt(0)
	v_add_u32_e32 v81, v176, v70
	v_lshlrev_b32_e32 v70, 3, v175
	v_lshl_add_u64 v[68:69], s[38:39], 1, v[68:69]
	v_lshlrev_b32_e32 v88, 1, v172
	v_mov_b32_e32 v89, v193
	v_and_b32_e32 v70, 56, v70
	v_lshl_add_u64 v[68:69], v[68:69], 0, v[88:89]
	v_lshlrev_b32_e32 v96, 1, v70
	v_mov_b32_e32 v97, v193
	v_lshl_add_u64 v[72:73], v[68:69], 0, v[96:97]
	v_lshlrev_b32_e32 v68, 7, v80
	v_add_u32_e32 v111, v81, v68
	ds_read_b128 v[68:71], v111
	v_lshlrev_b32_e32 v192, 11, v80
	v_lshl_add_u64 v[74:75], v[72:73], 0, v[192:193]
	v_mov_b32_e32 v95, v193
	v_mov_b32_e32 v93, v193
	s_waitcnt lgkmcnt(0)
	global_store_dwordx4 v[74:75], v[68:71], off sc1
	v_or_b32_e32 v74, 8, v80
	v_lshlrev_b32_e32 v94, 11, v74
	v_lshlrev_b32_e32 v68, 7, v74
	v_add_u32_e32 v110, v81, v68
	ds_read_b128 v[68:71], v110
	v_lshl_add_u64 v[74:75], v[72:73], 0, v[94:95]
	v_mov_b32_e32 v91, v193
	v_mov_b32_e32 v83, v193
	v_mov_b32_e32 v87, v193
	s_waitcnt lgkmcnt(0)
	global_store_dwordx4 v[74:75], v[68:71], off sc1
	v_or_b32_e32 v74, 16, v80
	v_lshlrev_b32_e32 v92, 11, v74
	v_lshlrev_b32_e32 v68, 7, v74
	v_add_u32_e32 v109, v81, v68
	ds_read_b128 v[68:71], v109
	v_lshl_add_u64 v[74:75], v[72:73], 0, v[92:93]
	v_mov_b32_e32 v85, v193
	s_waitcnt lgkmcnt(0)
; #define LDSP __attribute__((address_space(3)))
; DI unsigned pk2(float a, float b) { f32x2 v = {a, b}; bf2_t r = __builtin_convertvector(v, bf2_t); return __builtin_bit_cast(unsigned, r); }
; DI void wave_rows_store(ldsp_t wb, int lane, bf16_t* dst0, size_t ld) {
; #pragma unroll
;     for (int i = 0; i < 8; ++i) {
;         const int row = i * 8 + (lane >> 3), ch = lane & 7;
;         const u32x4 v = *(const LDSP u32x4*)(wb + row * 128 + ((ch ^ (row & 7)) << 4));
;         *(u32x4*)(dst0 + (size_t)row * ld + ch * 8) = v;
;     }
;     static DI void run(const f32x4 (&acc)[8][4], const TileCtx& tc, const Params& p, ldsp_t wb) {
;     ...
;             for (int mm = 0; mm < 4; ++mm) { __builtin_amdgcn_sched_barrier(0);
;                 const int m = h * 4 + mm;
;                 const int row = tc.brow + tc.wr * 128 + m * 16 + tc.fr;
;                 float* xr = xrow_ptr(p, row) + col0;
;                 const float* xs = (EK == 1 && tc.l == 0) ? p.x + (size_t)row * DM + col0 : xr;
;                 float part = 0.f;
; #pragma unroll
;                 for (int n = 0; n < 4; ++n) {
;                     f32x4 xv = *(const f32x4*)(xs + n * 16);
;                     xv += gv[n] * acc[m][n];
;                     *(f32x4*)(xr + n * 16) = xv;
;                     if (has_next) {
;                         part += xv[0] * xv[0] + xv[1] * xv[1] + xv[2] * xv[2] + xv[3] * xv[3];
;                         const f32x4 hv = xv * av[n];
;                         u32x2 w; w[0] = pk2(hv[0], hv[1]); w[1] = pk2(hv[2], hv[3]);
;                         wave_put(wb, mm * 16 + tc.fr, n, tc.fq, w);
;                     }
;                 }
;                 if (has_next) {
;                     part += __shfl_xor(part, 16);
;                     part += __shfl_xor(part, 32);
;                     if (tc.fq == 0) ssp[(size_t)row * 16] = part;
;                 }
	global_store_dwordx4 v[74:75], v[68:71], off sc1
	v_or_b32_e32 v74, 24, v80
	s_nop 0
	v_lshlrev_b32_e32 v68, 7, v74
	v_add_u32_e32 v108, v81, v68
	ds_read_b128 v[68:71], v108
	v_lshlrev_b32_e32 v90, 11, v74
	v_lshl_add_u64 v[74:75], v[72:73], 0, v[90:91]
	s_waitcnt lgkmcnt(0)
	global_store_dwordx4 v[74:75], v[68:71], off sc1
	v_or_b32_e32 v74, 32, v80
	s_nop 0
	v_lshlrev_b32_e32 v68, 7, v74
	v_add_u32_e32 v104, v81, v68
	ds_read_b128 v[68:71], v104
	v_lshlrev_b32_e32 v82, 11, v74
	v_lshl_add_u64 v[74:75], v[72:73], 0, v[82:83]
	s_waitcnt lgkmcnt(0)
	global_store_dwordx4 v[74:75], v[68:71], off sc1
	v_or_b32_e32 v74, 40, v80
	s_nop 0
	v_lshlrev_b32_e32 v68, 7, v74
	v_add_u32_e32 v105, v81, v68
	ds_read_b128 v[68:71], v105
	v_lshlrev_b32_e32 v86, 11, v74
	v_lshl_add_u64 v[74:75], v[72:73], 0, v[86:87]
	s_waitcnt lgkmcnt(0)
	global_store_dwordx4 v[74:75], v[68:71], off sc1
	v_or_b32_e32 v74, 48, v80
	s_nop 0
	v_lshlrev_b32_e32 v68, 7, v74
	v_add_u32_e32 v106, v81, v68
	ds_read_b128 v[68:71], v106
	v_lshlrev_b32_e32 v84, 11, v74
	v_lshl_add_u64 v[74:75], v[72:73], 0, v[84:85]
	s_waitcnt lgkmcnt(0)
	global_store_dwordx4 v[74:75], v[68:71], off sc1
	v_or_b32_e32 v74, 56, v80
	s_nop 0
	v_lshlrev_b32_e32 v68, 7, v74
	v_add_u32_e32 v107, v81, v68
	ds_read_b128 v[68:71], v107
	v_lshlrev_b32_e32 v80, 11, v74
	v_mov_b32_e32 v81, v193
	v_lshl_add_u64 v[72:73], v[72:73], 0, v[80:81]
	s_waitcnt lgkmcnt(0)
	global_store_dwordx4 v[72:73], v[68:71], off sc1
	v_add3_u32 v98, v174, s41, 64
	v_or_b32_e32 v100, v98, v173
	v_cmp_gt_i32_e64 s[6:7], s33, v100
	v_add_u32_e32 v68, 0xffffc000, v100
	v_ashrrev_i32_e32 v101, 31, v100
	v_mov_b32_e32 v70, s71
	v_mov_b32_e32 v71, s55
	v_cndmask_b32_e64 v69, 0, v101, s[6:7]
	v_cndmask_b32_e64 v68, v68, v100, s[6:7]
	v_cndmask_b32_e64 v71, v70, v71, s[6:7]
	v_mov_b32_e32 v70, s70
	v_mov_b32_e32 v72, s54
	v_cndmask_b32_e64 v70, v70, v72, s[6:7]
	v_lshlrev_b64 v[68:69], 12, v[68:69]
	v_readlane_b32 s8, v254, 50
	v_lshl_add_u64 v[68:69], v[70:71], 0, v[68:69]
	v_lshlrev_b64 v[70:71], 12, v[100:101]
	v_readlane_b32 s9, v254, 51
	v_lshl_add_u64 v[102:103], v[68:69], 0, v[150:151]
	v_readlane_b32 s10, v254, 52
	v_lshl_add_u64 v[70:71], s[8:9], 0, v[70:71]
	v_cndmask_b32_e64 v69, v69, v71, s[4:5]
	v_cndmask_b32_e64 v68, v68, v70, s[4:5]
	v_lshl_add_u64 v[72:73], v[68:69], 0, v[150:151]
	global_load_dwordx4 v[68:71], v[72:73], off
	global_load_dwordx4 v[232:235], v[72:73], off offset:64
	global_load_dwordx4 v[236:239], v[72:73], off offset:128
	global_load_dwordx4 v[240:243], v[72:73], off offset:192
	v_readlane_b32 s11, v254, 53
	v_readlane_b32 s12, v254, 54
	v_readlane_b32 s13, v254, 55
	v_readlane_b32 s14, v254, 56
	v_readlane_b32 s15, v254, 57
	v_readlane_b32 s16, v254, 58
	v_readlane_b32 s17, v254, 59
	v_readlane_b32 s18, v254, 60
	v_readlane_b32 s19, v254, 61
	v_readlane_b32 s20, v254, 62
	v_readlane_b32 s21, v254, 63
	v_readlane_b32 s22, v255, 0
	v_readlane_b32 s23, v255, 1
	s_waitcnt vmcnt(3)
	v_pk_fma_f32 v[68:69], v[76:77], v[28:29], v[68:69]
	s_nop 0
	v_mul_f32_e32 v74, v69, v69
	v_pk_fma_f32 v[70:71], v[78:79], v[30:31], v[70:71]
	v_fmac_f32_e32 v74, v68, v68
	v_fmac_f32_e32 v74, v70, v70
	global_store_dwordx4 v[102:103], v[68:71], off sc1
	v_fmac_f32_e32 v74, v71, v71
	s_nop 0
	v_pk_mul_f32 v[70:71], v[160:161], v[70:71]
	v_pk_mul_f32 v[68:69], v[162:163], v[68:69]
	s_nop 0
	v_cvt_pk_bf16_f32 v68, v68, v69
	v_cvt_pk_bf16_f32 v69, v70, v71
	ds_write_b64 v124, v[68:69]
	s_nop 1
	s_waitcnt vmcnt(3)
	v_pk_fma_f32 v[68:69], v[198:199], v[24:25], v[232:233]
	s_nop 0
	v_mul_f32_e32 v75, v69, v69
	v_pk_fma_f32 v[70:71], v[200:201], v[26:27], v[234:235]
	v_fmac_f32_e32 v75, v68, v68
	v_fmac_f32_e32 v75, v70, v70
	global_store_dwordx4 v[102:103], v[68:71], off offset:64 sc1
	v_fmac_f32_e32 v75, v71, v71
	v_add_f32_e32 v74, v74, v75
	v_pk_mul_f32 v[70:71], v[156:157], v[70:71]
	v_pk_mul_f32 v[68:69], v[158:159], v[68:69]
	s_nop 0
	v_cvt_pk_bf16_f32 v68, v68, v69
	v_cvt_pk_bf16_f32 v69, v70, v71
	ds_write_b64 v120, v[68:69]
	s_nop 1
	s_waitcnt vmcnt(3)
	v_pk_fma_f32 v[68:69], v[194:195], v[20:21], v[236:237]
	s_nop 0
	v_mul_f32_e32 v75, v69, v69
	v_pk_fma_f32 v[70:71], v[196:197], v[22:23], v[238:239]
	v_fmac_f32_e32 v75, v68, v68
	v_fmac_f32_e32 v75, v70, v70
	global_store_dwordx4 v[102:103], v[68:71], off offset:128 sc1
	v_fmac_f32_e32 v75, v71, v71
	v_add_f32_e32 v74, v74, v75
	v_pk_mul_f32 v[70:71], v[152:153], v[70:71]
	v_pk_mul_f32 v[68:69], v[154:155], v[68:69]
	s_nop 0
	v_cvt_pk_bf16_f32 v68, v68, v69
	v_cvt_pk_bf16_f32 v69, v70, v71
	ds_write_b64 v116, v[68:69]
	s_nop 1
	s_waitcnt vmcnt(3)
	v_pk_fma_f32 v[64:65], v[64:65], v[4:5], v[240:241]
	s_nop 0
	v_mul_f32_e32 v68, v65, v65
	v_pk_fma_f32 v[66:67], v[66:67], v[6:7], v[242:243]
	v_fmac_f32_e32 v68, v64, v64
	v_fmac_f32_e32 v68, v66, v66
	global_store_dwordx4 v[102:103], v[64:67], off offset:192 sc1
	v_fmac_f32_e32 v68, v67, v67
	v_add_f32_e32 v68, v74, v68
	v_pk_mul_f32 v[66:67], v[146:147], v[66:67]
	v_pk_mul_f32 v[64:65], v[148:149], v[64:65]
	s_nop 0
	v_cvt_pk_bf16_f32 v64, v64, v65
	v_cvt_pk_bf16_f32 v65, v66, v67
	ds_write_b64 v117, v[64:65]
	ds_bpermute_b32 v64, v170, v68
	s_waitcnt lgkmcnt(0)
	v_add_f32_e32 v64, v68, v64
	ds_bpermute_b32 v65, v171, v64
	s_and_saveexec_b64 s[6:7], vcc
	s_cbranch_execz .LBB0_147
	s_waitcnt lgkmcnt(0)
	v_add_f32_e32 v66, v64, v65
	v_lshlrev_b64 v[64:65], 6, v[100:101]
	v_lshl_add_u64 v[64:65], v[144:145], 0, v[64:65]
	global_store_dword v[64:65], v66, off sc1
; DI unsigned pk2(float a, float b) { f32x2 v = {a, b}; bf2_t r = __builtin_convertvector(v, bf2_t); return __builtin_bit_cast(unsigned, r); }
;     static DI void run(const f32x4 (&acc)[8][4], const TileCtx& tc, const Params& p, ldsp_t wb) {
;     ...
;             for (int mm = 0; mm < 4; ++mm) { __builtin_amdgcn_sched_barrier(0);
;                 const int m = h * 4 + mm;
;                 const int row = tc.brow + tc.wr * 128 + m * 16 + tc.fr;
;                 float* xr = xrow_ptr(p, row) + col0;
;                 const float* xs = (EK == 1 && tc.l == 0) ? p.x + (size_t)row * DM + col0 : xr;
;                 float part = 0.f;
; #pragma unroll
;                 for (int n = 0; n < 4; ++n) {
;                     f32x4 xv = *(const f32x4*)(xs + n * 16);
;                     xv += gv[n] * acc[m][n];
;                     *(f32x4*)(xr + n * 16) = xv;
;                     if (has_next) {
;                         part += xv[0] * xv[0] + xv[1] * xv[1] + xv[2] * xv[2] + xv[3] * xv[3];
;                         const f32x4 hv = xv * av[n];
;                         u32x2 w; w[0] = pk2(hv[0], hv[1]); w[1] = pk2(hv[2], hv[3]);
;                         wave_put(wb, mm * 16 + tc.fr, n, tc.fq, w);
;                     }
;                 }
;                 if (has_next) {
;                     part += __shfl_xor(part, 16);
;                     part += __shfl_xor(part, 32);
;                     if (tc.fq == 0) ssp[(size_t)row * 16] = part;
;                 }
.LBB0_147:
	s_or_b64 exec, exec, s[6:7]
	v_add_u32_e32 v64, 0x50, v132
	v_cmp_gt_i32_e64 s[6:7], s33, v64
	v_add_u32_e32 v66, 0xffffc050, v132
	s_waitcnt lgkmcnt(0)
	v_ashrrev_i32_e32 v65, 31, v64
	v_mov_b32_e32 v68, s71
	v_mov_b32_e32 v69, s55
	v_cndmask_b32_e64 v67, 0, v65, s[6:7]
	v_cndmask_b32_e64 v66, v66, v64, s[6:7]
	v_cndmask_b32_e64 v69, v68, v69, s[6:7]
	v_mov_b32_e32 v68, s70
	v_mov_b32_e32 v70, s54
	v_readlane_b32 s8, v254, 50
	v_cndmask_b32_e64 v68, v68, v70, s[6:7]
	v_lshlrev_b64 v[66:67], 12, v[66:67]
	v_lshlrev_b64 v[70:71], 12, v[64:65]
	v_readlane_b32 s9, v254, 51
	v_lshl_add_u64 v[68:69], v[68:69], 0, v[66:67]
	v_lshl_add_u64 v[66:67], v[68:69], 0, v[150:151]
	v_lshl_add_u64 v[70:71], s[8:9], 0, v[70:71]
	v_cndmask_b32_e64 v69, v69, v71, s[4:5]
	v_cndmask_b32_e64 v68, v68, v70, s[4:5]
	v_lshl_add_u64 v[72:73], v[68:69], 0, v[150:151]
	global_load_dwordx4 v[68:71], v[72:73], off
	global_load_dwordx4 v[232:235], v[72:73], off offset:64
	global_load_dwordx4 v[236:239], v[72:73], off offset:128
	global_load_dwordx4 v[240:243], v[72:73], off offset:192
	v_readlane_b32 s10, v254, 52
	v_readlane_b32 s11, v254, 53
	v_readlane_b32 s12, v254, 54
	v_readlane_b32 s13, v254, 55
	v_readlane_b32 s14, v254, 56
	v_readlane_b32 s15, v254, 57
	v_readlane_b32 s16, v254, 58
	v_readlane_b32 s17, v254, 59
	v_readlane_b32 s18, v254, 60
	v_readlane_b32 s19, v254, 61
	v_readlane_b32 s20, v254, 62
	v_readlane_b32 s21, v254, 63
	v_readlane_b32 s22, v255, 0
	v_readlane_b32 s23, v255, 1
	s_waitcnt vmcnt(3)
	v_pk_fma_f32 v[60:61], v[60:61], v[28:29], v[68:69]
	s_nop 0
	v_mul_f32_e32 v68, v61, v61
	v_pk_fma_f32 v[62:63], v[62:63], v[30:31], v[70:71]
	v_fmac_f32_e32 v68, v60, v60
	v_fmac_f32_e32 v68, v62, v62
	global_store_dwordx4 v[66:67], v[60:63], off sc1
	v_fmac_f32_e32 v68, v63, v63
	s_nop 0
	v_pk_mul_f32 v[62:63], v[160:161], v[62:63]
	v_pk_mul_f32 v[60:61], v[162:163], v[60:61]
	s_nop 0
	v_cvt_pk_bf16_f32 v60, v60, v61
	v_cvt_pk_bf16_f32 v61, v62, v63
	ds_write_b64 v124, v[60:61] offset:2048
	s_nop 1
	s_waitcnt vmcnt(3)
	v_pk_fma_f32 v[56:57], v[56:57], v[24:25], v[232:233]
	s_nop 0
	v_mul_f32_e32 v60, v57, v57
	v_pk_fma_f32 v[58:59], v[58:59], v[26:27], v[234:235]
	v_fmac_f32_e32 v60, v56, v56
	v_fmac_f32_e32 v60, v58, v58
	global_store_dwordx4 v[66:67], v[56:59], off offset:64 sc1
	v_fmac_f32_e32 v60, v59, v59
	v_add_f32_e32 v60, v68, v60
	v_pk_mul_f32 v[58:59], v[156:157], v[58:59]
	v_pk_mul_f32 v[56:57], v[158:159], v[56:57]
	s_nop 0
	v_cvt_pk_bf16_f32 v56, v56, v57
	v_cvt_pk_bf16_f32 v57, v58, v59
	ds_write_b64 v120, v[56:57] offset:2048
	s_nop 1
	s_waitcnt vmcnt(3)
	v_pk_fma_f32 v[52:53], v[52:53], v[20:21], v[236:237]
	s_nop 0
	v_mul_f32_e32 v56, v53, v53
	v_pk_fma_f32 v[54:55], v[54:55], v[22:23], v[238:239]
	v_fmac_f32_e32 v56, v52, v52
	v_fmac_f32_e32 v56, v54, v54
	global_store_dwordx4 v[66:67], v[52:55], off offset:128 sc1
	v_fmac_f32_e32 v56, v55, v55
	v_add_f32_e32 v56, v60, v56
	v_pk_mul_f32 v[54:55], v[152:153], v[54:55]
	v_pk_mul_f32 v[52:53], v[154:155], v[52:53]
	s_nop 0
	v_cvt_pk_bf16_f32 v52, v52, v53
	v_cvt_pk_bf16_f32 v53, v54, v55
	ds_write_b64 v116, v[52:53] offset:2048
	s_nop 1
	s_waitcnt vmcnt(3)
	v_pk_fma_f32 v[48:49], v[48:49], v[4:5], v[240:241]
	s_nop 0
	v_mul_f32_e32 v52, v49, v49
	v_pk_fma_f32 v[50:51], v[50:51], v[6:7], v[242:243]
	v_fmac_f32_e32 v52, v48, v48
	v_fmac_f32_e32 v52, v50, v50
	global_store_dwordx4 v[66:67], v[48:51], off offset:192 sc1
	v_fmac_f32_e32 v52, v51, v51
	v_add_f32_e32 v52, v56, v52
	v_pk_mul_f32 v[50:51], v[146:147], v[50:51]
	v_pk_mul_f32 v[48:49], v[148:149], v[48:49]
	s_nop 0
	v_cvt_pk_bf16_f32 v48, v48, v49
	v_cvt_pk_bf16_f32 v49, v50, v51
	ds_write_b64 v117, v[48:49] offset:2048
	ds_bpermute_b32 v48, v170, v52
	s_waitcnt lgkmcnt(0)
	v_add_f32_e32 v48, v52, v48
	ds_bpermute_b32 v49, v171, v48
	s_and_saveexec_b64 s[6:7], vcc
	s_cbranch_execz .LBB0_149
	s_waitcnt lgkmcnt(0)
	v_add_f32_e32 v50, v48, v49
	v_lshlrev_b64 v[48:49], 6, v[64:65]
	v_lshl_add_u64 v[48:49], v[144:145], 0, v[48:49]
	global_store_dword v[48:49], v50, off sc1
.LBB0_149:
	s_or_b64 exec, exec, s[6:7]
	v_add_u32_e32 v48, 0x60, v132
	v_cmp_gt_i32_e64 s[6:7], s33, v48
	v_add_u32_e32 v50, 0xffffc060, v132
	s_waitcnt lgkmcnt(0)
	v_ashrrev_i32_e32 v49, 31, v48
	v_mov_b32_e32 v52, s71
	v_mov_b32_e32 v53, s55
	v_cndmask_b32_e64 v51, 0, v49, s[6:7]
	v_cndmask_b32_e64 v50, v50, v48, s[6:7]
	v_cndmask_b32_e64 v53, v52, v53, s[6:7]
	v_mov_b32_e32 v52, s70
	v_mov_b32_e32 v54, s54
	v_readlane_b32 s8, v254, 50
	v_cndmask_b32_e64 v52, v52, v54, s[6:7]
	v_lshlrev_b64 v[50:51], 12, v[50:51]
	v_lshlrev_b64 v[54:55], 12, v[48:49]
	v_readlane_b32 s9, v254, 51
	v_lshl_add_u64 v[52:53], v[52:53], 0, v[50:51]
	v_lshl_add_u64 v[50:51], v[52:53], 0, v[150:151]
	v_lshl_add_u64 v[54:55], s[8:9], 0, v[54:55]
	v_cndmask_b32_e64 v53, v53, v55, s[4:5]
	v_cndmask_b32_e64 v52, v52, v54, s[4:5]
	v_lshl_add_u64 v[56:57], v[52:53], 0, v[150:151]
	global_load_dwordx4 v[52:55], v[56:57], off
	global_load_dwordx4 v[232:235], v[56:57], off offset:64
	global_load_dwordx4 v[236:239], v[56:57], off offset:128
	global_load_dwordx4 v[240:243], v[56:57], off offset:192
	v_readlane_b32 s10, v254, 52
	v_readlane_b32 s11, v254, 53
	v_readlane_b32 s12, v254, 54
	v_readlane_b32 s13, v254, 55
	v_readlane_b32 s14, v254, 56
	v_readlane_b32 s15, v254, 57
	v_readlane_b32 s16, v254, 58
	v_readlane_b32 s17, v254, 59
	v_readlane_b32 s18, v254, 60
	v_readlane_b32 s19, v254, 61
	v_readlane_b32 s20, v254, 62
	v_readlane_b32 s21, v254, 63
	v_readlane_b32 s22, v255, 0
	v_readlane_b32 s23, v255, 1
	s_waitcnt vmcnt(3)
; DI unsigned pk2(float a, float b) { f32x2 v = {a, b}; bf2_t r = __builtin_convertvector(v, bf2_t); return __builtin_bit_cast(unsigned, r); }
;     static DI void run(const f32x4 (&acc)[8][4], const TileCtx& tc, const Params& p, ldsp_t wb) {
;     ...
;             for (int mm = 0; mm < 4; ++mm) { __builtin_amdgcn_sched_barrier(0);
;                 const int m = h * 4 + mm;
;                 const int row = tc.brow + tc.wr * 128 + m * 16 + tc.fr;
;                 float* xr = xrow_ptr(p, row) + col0;
;                 const float* xs = (EK == 1 && tc.l == 0) ? p.x + (size_t)row * DM + col0 : xr;
;                 float part = 0.f;
; #pragma unroll
;                 for (int n = 0; n < 4; ++n) {
;                     f32x4 xv = *(const f32x4*)(xs + n * 16);
;                     xv += gv[n] * acc[m][n];
;                     *(f32x4*)(xr + n * 16) = xv;
;                     if (has_next) {
;                         part += xv[0] * xv[0] + xv[1] * xv[1] + xv[2] * xv[2] + xv[3] * xv[3];
;                         const f32x4 hv = xv * av[n];
;                         u32x2 w; w[0] = pk2(hv[0], hv[1]); w[1] = pk2(hv[2], hv[3]);
;                         wave_put(wb, mm * 16 + tc.fr, n, tc.fq, w);
;                     }
;                 }
;                 if (has_next) {
;                     part += __shfl_xor(part, 16);
;                     part += __shfl_xor(part, 32);
;                     if (tc.fq == 0) ssp[(size_t)row * 16] = part;
;                 }
	v_pk_fma_f32 v[44:45], v[44:45], v[28:29], v[52:53]
	s_nop 0
	v_mul_f32_e32 v52, v45, v45
	v_pk_fma_f32 v[46:47], v[46:47], v[30:31], v[54:55]
	v_fmac_f32_e32 v52, v44, v44
	v_fmac_f32_e32 v52, v46, v46
	global_store_dwordx4 v[50:51], v[44:47], off sc1
	v_fmac_f32_e32 v52, v47, v47
	s_nop 0
	v_pk_mul_f32 v[46:47], v[160:161], v[46:47]
	v_pk_mul_f32 v[44:45], v[162:163], v[44:45]
	s_nop 0
	v_cvt_pk_bf16_f32 v44, v44, v45
	v_cvt_pk_bf16_f32 v45, v46, v47
	ds_write_b64 v124, v[44:45] offset:4096
	s_nop 1
	s_waitcnt vmcnt(3)
	v_pk_fma_f32 v[40:41], v[40:41], v[24:25], v[232:233]
	s_nop 0
	v_mul_f32_e32 v44, v41, v41
	v_pk_fma_f32 v[42:43], v[42:43], v[26:27], v[234:235]
	v_fmac_f32_e32 v44, v40, v40
	v_fmac_f32_e32 v44, v42, v42
	global_store_dwordx4 v[50:51], v[40:43], off offset:64 sc1
	v_fmac_f32_e32 v44, v43, v43
	v_add_f32_e32 v44, v52, v44
	v_pk_mul_f32 v[42:43], v[156:157], v[42:43]
	v_pk_mul_f32 v[40:41], v[158:159], v[40:41]
	s_nop 0
	v_cvt_pk_bf16_f32 v40, v40, v41
	v_cvt_pk_bf16_f32 v41, v42, v43
	ds_write_b64 v120, v[40:41] offset:4096
	s_nop 1
	s_waitcnt vmcnt(3)
	v_pk_fma_f32 v[36:37], v[36:37], v[20:21], v[236:237]
	s_nop 0
	v_mul_f32_e32 v40, v37, v37
	v_pk_fma_f32 v[38:39], v[38:39], v[22:23], v[238:239]
	v_fmac_f32_e32 v40, v36, v36
	v_fmac_f32_e32 v40, v38, v38
	global_store_dwordx4 v[50:51], v[36:39], off offset:128 sc1
	v_fmac_f32_e32 v40, v39, v39
	v_add_f32_e32 v40, v44, v40
	v_pk_mul_f32 v[38:39], v[152:153], v[38:39]
	v_pk_mul_f32 v[36:37], v[154:155], v[36:37]
	s_nop 0
	v_cvt_pk_bf16_f32 v36, v36, v37
	v_cvt_pk_bf16_f32 v37, v38, v39
	ds_write_b64 v116, v[36:37] offset:4096
	s_nop 1
	s_waitcnt vmcnt(3)
	v_pk_fma_f32 v[32:33], v[32:33], v[4:5], v[240:241]
	s_nop 0
	v_mul_f32_e32 v36, v33, v33
	v_pk_fma_f32 v[34:35], v[34:35], v[6:7], v[242:243]
	v_fmac_f32_e32 v36, v32, v32
	v_fmac_f32_e32 v36, v34, v34
	global_store_dwordx4 v[50:51], v[32:35], off offset:192 sc1
	v_fmac_f32_e32 v36, v35, v35
	v_add_f32_e32 v36, v40, v36
	v_pk_mul_f32 v[34:35], v[146:147], v[34:35]
	v_pk_mul_f32 v[32:33], v[148:149], v[32:33]
	s_nop 0
	v_cvt_pk_bf16_f32 v32, v32, v33
	v_cvt_pk_bf16_f32 v33, v34, v35
	ds_write_b64 v117, v[32:33] offset:4096
	ds_bpermute_b32 v32, v170, v36
	s_waitcnt lgkmcnt(0)
	v_add_f32_e32 v32, v36, v32
	ds_bpermute_b32 v33, v171, v32
	s_and_saveexec_b64 s[6:7], vcc
	s_cbranch_execz .LBB0_151
	s_waitcnt lgkmcnt(0)
	v_add_f32_e32 v34, v32, v33
	v_lshlrev_b64 v[32:33], 6, v[48:49]
	v_lshl_add_u64 v[32:33], v[144:145], 0, v[32:33]
	global_store_dword v[32:33], v34, off sc1
.LBB0_151:
	s_or_b64 exec, exec, s[6:7]
	v_add_u32_e32 v32, 0x70, v132
	v_cmp_gt_i32_e64 s[6:7], s33, v32
	v_add_u32_e32 v34, 0xffffc070, v132
	s_waitcnt lgkmcnt(0)
	v_ashrrev_i32_e32 v33, 31, v32
	v_mov_b32_e32 v36, s71
	v_mov_b32_e32 v37, s55
	v_cndmask_b32_e64 v35, 0, v33, s[6:7]
	v_cndmask_b32_e64 v34, v34, v32, s[6:7]
	v_cndmask_b32_e64 v37, v36, v37, s[6:7]
	v_mov_b32_e32 v36, s70
	v_mov_b32_e32 v38, s54
	v_readlane_b32 s8, v254, 50
	v_cndmask_b32_e64 v36, v36, v38, s[6:7]
	v_lshlrev_b64 v[34:35], 12, v[34:35]
	v_lshlrev_b64 v[38:39], 12, v[32:33]
	v_readlane_b32 s9, v254, 51
	v_lshl_add_u64 v[36:37], v[36:37], 0, v[34:35]
	v_lshl_add_u64 v[34:35], v[36:37], 0, v[150:151]
	v_lshl_add_u64 v[38:39], s[8:9], 0, v[38:39]
	v_cndmask_b32_e64 v37, v37, v39, s[4:5]
	v_cndmask_b32_e64 v36, v36, v38, s[4:5]
	v_lshl_add_u64 v[40:41], v[36:37], 0, v[150:151]
	global_load_dwordx4 v[36:39], v[40:41], off
	global_load_dwordx4 v[232:235], v[40:41], off offset:64
	global_load_dwordx4 v[236:239], v[40:41], off offset:128
	global_load_dwordx4 v[240:243], v[40:41], off offset:192
	v_readlane_b32 s10, v254, 52
	v_readlane_b32 s11, v254, 53
	v_readlane_b32 s12, v254, 54
	v_readlane_b32 s13, v254, 55
	v_readlane_b32 s14, v254, 56
	v_readlane_b32 s15, v254, 57
	v_readlane_b32 s16, v254, 58
	v_readlane_b32 s17, v254, 59
	v_readlane_b32 s18, v254, 60
	v_readlane_b32 s19, v254, 61
	v_readlane_b32 s20, v254, 62
	v_readlane_b32 s21, v254, 63
	v_readlane_b32 s22, v255, 0
	v_readlane_b32 s23, v255, 1
	s_waitcnt vmcnt(3)
	v_pk_fma_f32 v[16:17], v[16:17], v[28:29], v[36:37]
	s_nop 0
	v_mul_f32_e32 v28, v17, v17
	v_pk_fma_f32 v[18:19], v[18:19], v[30:31], v[38:39]
	v_fmac_f32_e32 v28, v16, v16
	v_fmac_f32_e32 v28, v18, v18
	global_store_dwordx4 v[34:35], v[16:19], off sc1
	v_fmac_f32_e32 v28, v19, v19
	s_nop 0
	v_pk_mul_f32 v[18:19], v[160:161], v[18:19]
	v_pk_mul_f32 v[16:17], v[162:163], v[16:17]
	s_nop 0
	v_cvt_pk_bf16_f32 v16, v16, v17
	v_cvt_pk_bf16_f32 v17, v18, v19
	ds_write_b64 v124, v[16:17] offset:6144
	s_nop 1
	s_waitcnt vmcnt(3)
	v_pk_fma_f32 v[12:13], v[12:13], v[24:25], v[232:233]
	s_nop 0
	v_mul_f32_e32 v16, v13, v13
	v_pk_fma_f32 v[14:15], v[14:15], v[26:27], v[234:235]
	v_fmac_f32_e32 v16, v12, v12
	v_fmac_f32_e32 v16, v14, v14
	global_store_dwordx4 v[34:35], v[12:15], off offset:64 sc1
	v_fmac_f32_e32 v16, v15, v15
	v_add_f32_e32 v16, v28, v16
	v_pk_mul_f32 v[14:15], v[156:157], v[14:15]
	v_pk_mul_f32 v[12:13], v[158:159], v[12:13]
	s_nop 0
	v_cvt_pk_bf16_f32 v12, v12, v13
	v_cvt_pk_bf16_f32 v13, v14, v15
	ds_write_b64 v120, v[12:13] offset:6144
	s_nop 1
	s_waitcnt vmcnt(3)
	v_pk_fma_f32 v[8:9], v[8:9], v[20:21], v[236:237]
	s_nop 0
	v_mul_f32_e32 v12, v9, v9
	v_pk_fma_f32 v[10:11], v[10:11], v[22:23], v[238:239]
	v_fmac_f32_e32 v12, v8, v8
	v_fmac_f32_e32 v12, v10, v10
	global_store_dwordx4 v[34:35], v[8:11], off offset:128 sc1
	v_fmac_f32_e32 v12, v11, v11
	v_add_f32_e32 v12, v16, v12
	v_pk_mul_f32 v[10:11], v[152:153], v[10:11]
	v_pk_mul_f32 v[8:9], v[154:155], v[8:9]
	s_nop 0
	v_cvt_pk_bf16_f32 v8, v8, v9
	v_cvt_pk_bf16_f32 v9, v10, v11
	ds_write_b64 v116, v[8:9] offset:6144
	s_nop 1
	s_waitcnt vmcnt(3)
	v_pk_fma_f32 v[0:1], v[0:1], v[4:5], v[240:241]
	s_nop 0
	v_mul_f32_e32 v4, v1, v1
	v_pk_fma_f32 v[2:3], v[2:3], v[6:7], v[242:243]
	v_fmac_f32_e32 v4, v0, v0
	v_fmac_f32_e32 v4, v2, v2
	global_store_dwordx4 v[34:35], v[0:3], off offset:192 sc1
	v_fmac_f32_e32 v4, v3, v3
	v_add_f32_e32 v4, v12, v4
	v_pk_mul_f32 v[2:3], v[146:147], v[2:3]
	v_pk_mul_f32 v[0:1], v[148:149], v[0:1]
	s_nop 0
	v_cvt_pk_bf16_f32 v0, v0, v1
	v_cvt_pk_bf16_f32 v1, v2, v3
	ds_write_b64 v117, v[0:1] offset:6144
	ds_bpermute_b32 v0, v170, v4
	s_waitcnt lgkmcnt(0)
	v_add_f32_e32 v0, v4, v0
	ds_bpermute_b32 v1, v171, v0
	s_and_saveexec_b64 s[6:7], vcc
	s_cbranch_execz .LBB0_124
	s_waitcnt lgkmcnt(0)
	v_add_f32_e32 v2, v0, v1
	v_lshlrev_b64 v[0:1], 6, v[32:33]
	v_lshl_add_u64 v[0:1], v[144:145], 0, v[0:1]
	global_store_dword v[0:1], v2, off sc1
	s_branch .LBB0_124

; #define WAIT_V0() asm volatile("s_waitcnt vmcnt(0)" ::: "memory")
; template <int EK, int TS, int KS>
; DI void ctx_tiles(const Params& p, int l, const bf16_t* __restrict__ A, const bf16_t* __restrict__ Bt, int N, int K, ldsp_t shm) {
;     ...
;     for (int u = blockIdx.x; u < ntiles; u += gridDim.x) {
;         const int tm = u / ntn, tn = u % ntn;
;         int tid = threadIdx.x;
;         asm volatile("" : "+v"(tid));
;         const int wid = tid >> 6, lane = tid & 63, wr = wid >> 2, wc = wid & 3, fr = lane & 15, fq = lane >> 4;
;         unsigned soff[PP];
; #pragma unroll
;         for (int i = 0; i < PP; ++i) { int sR, sC; stage_rc_ks<KS>((wid * PP + i) * 1024 + lane * 16, sR, sC); soff[i] = (unsigned)(sR * K + sC) * 2u; }
;         const bf16_t* Ab = A + (size_t)tm * TS * K;
;         const bf16_t* Bb = Bt + (size_t)tn * TS * K;
;     ...
;         f32x4 acc[MT][NT];
; #pragma unroll
;         for (int m = 0; m < MT; ++m)
; #pragma unroll
;             for (int n = 0; n < NT; ++n) acc[m][n] = (f32x4){0.f, 0.f, 0.f, 0.f};
;         const int aoff = lds_byte_ks<KS>(wr * WM + fr, fq * 8), boff = lds_byte_ks<KS>(wc * WN + fr, fq * 8);
;         C_STAGE(0, 0); WAIT_V0(); __syncthreads();
;         for (int t = 0; t < nt; ++t) {
;             const int cur = t & 1;
;             if (t + 1 < nt) C_STAGE(cur ^ 1, t + 1);
.LBB0_156:
	v_mov_b32_e32 v16, v252
	s_movk_i32 s6, 0x7800
	v_ashrrev_i32_e32 v0, 6, v16
	v_lshlrev_b32_e32 v1, 4, v16
	v_and_b32_e32 v2, 32, v16
	v_lshlrev_b32_e32 v22, 12, v0
	v_bitop3_b32 v1, v1, v2, 48 bitop3:0x6c
	v_lshlrev_b32_e32 v2, 9, v16
	v_and_or_b32 v1, v2, s6, v1
	v_ashrrev_i32_e32 v2, 10, v22
	v_ashrrev_i32_e32 v3, 31, v2
	v_lshrrev_b32_e32 v3, 29, v3
	v_add_u32_e32 v3, v2, v3
	s_waitcnt lgkmcnt(5)
	v_and_b32_e32 v4, 0x3fffff8, v3
	v_lshlrev_b32_e32 v3, 12, v3
	v_sub_u32_e32 v2, v2, v4
	v_and_or_b32 v3, v3, s90, v1
	s_waitcnt lgkmcnt(1)
	v_or_b32_e32 v6, 0x400, v22
	v_lshl_add_u32 v192, v2, 6, v3
	v_ashrrev_i32_e32 v2, 10, v6
	v_ashrrev_i32_e32 v3, 31, v2
	v_lshrrev_b32_e32 v3, 29, v3
	v_add_u32_e32 v3, v2, v3
	v_and_b32_e32 v4, 0x3fffff8, v3
	v_lshlrev_b32_e32 v3, 12, v3
	v_sub_u32_e32 v2, v2, v4
	v_and_or_b32 v3, v3, s90, v1
	v_or_b32_e32 v10, 0x800, v22
	v_lshl_add_u32 v8, v2, 6, v3
	v_ashrrev_i32_e32 v2, 10, v10
	v_ashrrev_i32_e32 v3, 31, v2
	s_ashr_i32 s4, s9, 31
	v_lshrrev_b32_e32 v3, 29, v3
	s_lshr_b32 s4, s4, 28
	v_add_u32_e32 v3, v2, v3
	s_add_i32 s5, s9, s4
	v_and_b32_e32 v4, 0x3fffff8, v3
	v_lshlrev_b32_e32 v3, 12, v3
	s_ashr_i32 s4, s5, 4
	v_sub_u32_e32 v2, v2, v4
	v_and_or_b32 v3, v3, s90, v1
	v_or_b32_e32 v14, 0xc00, v22
	s_and_b32 s5, s5, -16
	v_lshl_add_u32 v12, v2, 6, v3
	v_ashrrev_i32_e32 v2, 10, v14
	s_sub_i32 s42, s9, s5
	v_ashrrev_i32_e32 v3, 31, v2
	s_ashr_i32 s5, s4, 31
	s_ashr_i32 s43, s42, 31
	v_lshrrev_b32_e32 v3, 29, v3
	s_lshl_b64 s[6:7], s[4:5], 17
	s_lshl_b64 s[46:47], s[42:43], 17
	v_readlane_b32 s5, v253, 30
	v_add_u32_e32 v3, v2, v3
	s_add_u32 s6, s5, s6
	v_readlane_b32 s5, v253, 31
	v_and_b32_e32 v4, 0x3fffff8, v3
	s_addc_u32 s7, s5, s7
	v_sub_u32_e32 v2, v2, v4
	s_add_u32 s46, s93, s46
	v_readfirstlane_b32 s51, v22
	v_add_u32_e32 v4, 0x8000, v22
	s_addc_u32 s47, s98, s47
	s_mov_b32 m0, s51
	v_readfirstlane_b32 s84, v4
	v_mov_b32_e32 v9, v193
	global_load_lds_dwordx4 v192, s[6:7]
	s_mov_b32 m0, s84
	s_waitcnt lgkmcnt(0)
	v_lshl_add_u64 v[4:5], s[6:7], 0, v[8:9]
	v_readfirstlane_b32 s85, v6
	v_lshl_add_u64 v[6:7], s[46:47], 0, v[8:9]
	v_add_u32_e32 v9, 0x8400, v22
	global_load_lds_dwordx4 v192, s[46:47]
	s_mov_b32 m0, s85
	v_readfirstlane_b32 s86, v9
	global_load_lds_dwordx4 v8, s[6:7]
	s_mov_b32 m0, s86
	v_mov_b32_e32 v13, v193
	v_lshlrev_b32_e32 v3, 12, v3
	global_load_lds_dwordx4 v8, s[46:47]
	v_lshl_add_u64 v[8:9], s[6:7], 0, v[12:13]
	v_readfirstlane_b32 s87, v10
	v_lshl_add_u64 v[10:11], s[46:47], 0, v[12:13]
	v_add_u32_e32 v13, 0x8800, v22
	v_and_or_b32 v1, v3, s90, v1
	s_mov_b32 m0, s87
	v_readfirstlane_b32 s88, v13
	v_lshl_add_u32 v20, v2, 6, v1
	global_load_lds_dwordx4 v12, s[6:7]
	s_mov_b32 m0, s88
	v_mov_b32_e32 v21, v193
	v_ashrrev_i32_e32 v1, 3, v16
	global_load_lds_dwordx4 v12, s[46:47]
	v_lshl_add_u64 v[12:13], s[6:7], 0, v[20:21]
	v_readfirstlane_b32 s89, v14
	v_lshl_add_u64 v[14:15], s[46:47], 0, v[20:21]
	v_add_u32_e32 v21, 0x8c00, v22
	v_and_b32_e32 v17, 15, v16
	v_and_b32_e32 v19, 0xffffffe0, v1
	v_and_b32_e32 v1, 48, v16
	v_lshlrev_b32_e32 v23, 4, v0
	v_lshlrev_b32_e32 v0, 2, v16
	s_mov_b32 m0, s89
	v_readfirstlane_b32 s90, v21
	v_add_u32_e32 v27, 0x10000, v22
	v_lshl_or_b32 v24, v17, 6, v1
	v_and_b32_e32 v25, 32, v0
	v_lshl_add_u64 v[0:1], s[6:7], 0, v[192:193]
	global_load_lds_dwordx4 v20, s[6:7]
	s_mov_b32 m0, s90
	v_readfirstlane_b32 s5, v27
	v_add_u32_e32 v27, 0x18000, v22
	v_lshl_add_u64 v[2:3], s[46:47], 0, v[192:193]
	global_load_lds_dwordx4 v20, s[46:47]
	v_lshl_add_u64 v[20:21], v[0:1], 0, s[2:3]
	s_mov_b32 m0, s5
	v_readfirstlane_b32 s6, v27
	v_add_u32_e32 v27, 0x10400, v22
	s_waitcnt vmcnt(0)
	s_waitcnt vmcnt(0) lgkmcnt(0)
	s_barrier
	global_load_lds_dwordx4 v[20:21], off
	v_lshl_add_u64 v[20:21], v[2:3], 0, s[2:3]
	s_mov_b32 m0, s6
	v_readfirstlane_b32 s7, v27
	v_add_u32_e32 v27, 0x18400, v22
	global_load_lds_dwordx4 v[20:21], off
	v_lshl_add_u64 v[20:21], v[4:5], 0, s[2:3]
	s_mov_b32 m0, s7
	v_readfirstlane_b32 s31, v27
	v_add_u32_e32 v27, 0x10800, v22
	global_load_lds_dwordx4 v[20:21], off
	v_lshl_add_u64 v[20:21], v[6:7], 0, s[2:3]
	s_mov_b32 m0, s31
	v_readfirstlane_b32 s45, v27
	v_add_u32_e32 v27, 0x18800, v22
	global_load_lds_dwordx4 v[20:21], off
	v_lshl_add_u64 v[20:21], v[8:9], 0, s[2:3]
	s_mov_b32 m0, s45
	v_readfirstlane_b32 s46, v27
	v_add_u32_e32 v27, 0x10c00, v22
	global_load_lds_dwordx4 v[20:21], off
	v_lshl_add_u64 v[20:21], v[10:11], 0, s[2:3]
	s_mov_b32 m0, s46
	v_readfirstlane_b32 s47, v27
	v_add_u32_e32 v22, 0x18c00, v22
	global_load_lds_dwordx4 v[20:21], off
	v_lshl_add_u64 v[20:21], v[12:13], 0, s[2:3]
	s_mov_b32 m0, s47
	v_readfirstlane_b32 s50, v22
	v_or_b32_e32 v18, v19, v17
	v_lshlrev_b32_e32 v26, 9, v19
	v_and_b32_e32 v19, 48, v23
	global_load_lds_dwordx4 v[20:21], off
	v_lshl_add_u64 v[20:21], v[14:15], 0, s[2:3]
	s_mov_b32 m0, s50
	v_lshlrev_b32_e32 v23, 9, v19
	global_load_lds_dwordx4 v[20:21], off
	v_bitop3_b32 v21, v24, v26, v25 bitop3:0xde
	v_bitop3_b32 v20, v24, v23, v25 bitop3:0xde
	ds_read_b128 v[22:25], v21
	ds_read_b128 v[26:29], v21 offset:8192
	ds_read_b128 v[30:33], v20 offset:32768
	s_waitcnt lgkmcnt(0)
	v_mfma_f32_16x16x32_bf16 v[22:25], v[30:33], v[22:25], 0
	s_mov_b32 m0, s51
	v_or_b32_e32 v46, 0x18c00, v20
	v_or_b32_e32 v47, 0x19000, v20
	v_mfma_f32_16x16x32_bf16 v[26:29], v[30:33], v[26:29], 0
	ds_read_b128 v[30:33], v21 offset:1024
	ds_read_b128 v[34:37], v21 offset:9216
	ds_read_b128 v[38:41], v20 offset:33792
	v_or_b32_e32 v48, 0x19400, v20
	v_or_b32_e32 v49, 0x19800, v20
	s_waitcnt lgkmcnt(0)
; #define LDSP __attribute__((address_space(3)))
; #define WAIT_V0() asm volatile("s_waitcnt vmcnt(0)" ::: "memory")
; template <int EK, int TS, int KS>
; DI void ctx_tiles(const Params& p, int l, const bf16_t* __restrict__ A, const bf16_t* __restrict__ Bt, int N, int K, ldsp_t shm) {
;     ...
;         for (int t = 0; t < nt; ++t) {
;             const int cur = t & 1;
;             if (t + 1 < nt) C_STAGE(cur ^ 1, t + 1);
;             ldsp_t sa = shm + cur * 2 * TILE_A, sb = sa + TILE_A;
; #pragma unroll
;             for (int ks = 0; ks < KS; ++ks) {
;                 bf16x8 At[MT], Bf[NT];
; #pragma unroll
;                 for (int m = 0; m < MT; ++m) At[m] = *(const LDSP bf16x8*)(sa + aoff + m * (KS * 1024) + ks * 1024);
; #pragma unroll
;                 for (int n = 0; n < NT; ++n) Bf[n] = *(const LDSP bf16x8*)(sb + boff + n * (KS * 1024) + ks * 1024);
; #pragma unroll
;                 for (int m = 0; m < MT; ++m)
; #pragma unroll
;                     for (int n = 0; n < NT; ++n) acc[m][n] = __builtin_amdgcn_mfma_f32_16x16x32_bf16(Bf[n], At[m], acc[m][n], 0, 0, 0);
;             }
;             WAIT_V0(); __syncthreads();
;         }
	v_mfma_f32_16x16x32_bf16 v[22:25], v[38:41], v[30:33], v[22:25]
	s_mov_b64 s[10:11], 0x600
	v_or_b32_e32 v50, 0x19c00, v20
	v_mfma_f32_16x16x32_bf16 v[26:29], v[38:41], v[34:37], v[26:29]
	ds_read_b128 v[30:33], v21 offset:2048
	ds_read_b128 v[34:37], v21 offset:10240
	ds_read_b128 v[38:41], v20 offset:34816
	s_waitcnt lgkmcnt(0)
	v_mfma_f32_16x16x32_bf16 v[22:25], v[38:41], v[30:33], v[22:25]
	v_mfma_f32_16x16x32_bf16 v[26:29], v[38:41], v[34:37], v[26:29]
	ds_read_b128 v[30:33], v21 offset:3072
	ds_read_b128 v[34:37], v21 offset:11264
	ds_read_b128 v[38:41], v20 offset:35840
	s_waitcnt lgkmcnt(0)
	v_mfma_f32_16x16x32_bf16 v[22:25], v[38:41], v[30:33], v[22:25]
	v_mfma_f32_16x16x32_bf16 v[26:29], v[38:41], v[34:37], v[26:29]
	ds_read_b128 v[30:33], v21 offset:4096
	ds_read_b128 v[34:37], v21 offset:12288
	ds_read_b128 v[38:41], v20 offset:36864
	s_waitcnt lgkmcnt(0)
	v_mfma_f32_16x16x32_bf16 v[22:25], v[38:41], v[30:33], v[22:25]
	v_mfma_f32_16x16x32_bf16 v[26:29], v[38:41], v[34:37], v[26:29]
	ds_read_b128 v[30:33], v21 offset:5120
	ds_read_b128 v[34:37], v21 offset:13312
	ds_read_b128 v[38:41], v20 offset:37888
	s_waitcnt lgkmcnt(0)
	v_mfma_f32_16x16x32_bf16 v[22:25], v[38:41], v[30:33], v[22:25]
	v_mfma_f32_16x16x32_bf16 v[26:29], v[38:41], v[34:37], v[26:29]
	ds_read_b128 v[30:33], v21 offset:6144
	ds_read_b128 v[34:37], v21 offset:14336
	ds_read_b128 v[38:41], v20 offset:38912
	s_waitcnt lgkmcnt(0)
	v_mfma_f32_16x16x32_bf16 v[22:25], v[38:41], v[30:33], v[22:25]
	v_mfma_f32_16x16x32_bf16 v[26:29], v[38:41], v[34:37], v[26:29]
	ds_read_b128 v[30:33], v21 offset:7168
	ds_read_b128 v[34:37], v21 offset:15360
	ds_read_b128 v[38:41], v20 offset:39936
	s_waitcnt vmcnt(0)
	s_waitcnt vmcnt(0) lgkmcnt(0)
	v_mfma_f32_16x16x32_bf16 v[30:33], v[38:41], v[30:33], v[22:25]
	s_barrier
	s_nop 1
	v_lshl_add_u64 v[22:23], v[0:1], 0, s[24:25]
	global_load_lds_dwordx4 v[22:23], off
	v_lshl_add_u64 v[22:23], v[2:3], 0, s[24:25]
	s_mov_b32 m0, s84
	v_mfma_f32_16x16x32_bf16 v[24:27], v[38:41], v[34:37], v[26:29]
	global_load_lds_dwordx4 v[22:23], off
	v_lshl_add_u64 v[22:23], v[4:5], 0, s[24:25]
	s_mov_b32 m0, s85
	v_lshl_add_u64 v[0:1], v[0:1], 0, s[10:11]
	global_load_lds_dwordx4 v[22:23], off
	v_lshl_add_u64 v[22:23], v[6:7], 0, s[24:25]
	s_mov_b32 m0, s86
	s_nop 0
	global_load_lds_dwordx4 v[22:23], off
	v_lshl_add_u64 v[22:23], v[8:9], 0, s[24:25]
	s_mov_b32 m0, s87
	s_nop 0
	global_load_lds_dwordx4 v[22:23], off
	v_lshl_add_u64 v[22:23], v[10:11], 0, s[24:25]
	s_mov_b32 m0, s88
	s_nop 0
	global_load_lds_dwordx4 v[22:23], off
	v_lshl_add_u64 v[22:23], v[12:13], 0, s[24:25]
	s_mov_b32 m0, s89
	s_nop 0
	global_load_lds_dwordx4 v[22:23], off
	v_lshl_add_u64 v[22:23], v[14:15], 0, s[24:25]
	s_mov_b32 m0, s90
	v_readlane_b32 s12, v254, 50
	global_load_lds_dwordx4 v[22:23], off
	v_add_u32_e32 v22, 0x10000, v21
	v_or_b32_e32 v23, 0x18000, v20
	ds_read_b128 v[34:37], v22
	ds_read_b128 v[38:41], v22 offset:8192
	ds_read_b128 v[42:45], v23
	s_waitcnt lgkmcnt(0)
	v_mfma_f32_16x16x32_bf16 v[28:31], v[42:45], v[34:37], v[30:33]
	s_mov_b32 m0, s5
	v_readlane_b32 s16, v254, 54
	v_readlane_b32 s17, v254, 55
	v_mfma_f32_16x16x32_bf16 v[24:27], v[42:45], v[38:41], v[24:27]
	v_or_b32_e32 v44, 0x18400, v20
	ds_read_b128 v[32:35], v22 offset:1024
	ds_read_b128 v[36:39], v22 offset:9216
	ds_read_b128 v[40:43], v44
	v_or_b32_e32 v45, 0x18800, v20
	s_waitcnt lgkmcnt(0)
	v_mfma_f32_16x16x32_bf16 v[28:31], v[40:43], v[32:35], v[28:31]
	v_readlane_b32 s13, v254, 51
	v_readlane_b32 s14, v254, 52
	v_readlane_b32 s15, v254, 53
	v_mfma_f32_16x16x32_bf16 v[24:27], v[40:43], v[36:39], v[24:27]
	ds_read_b128 v[32:35], v22 offset:2048
	ds_read_b128 v[36:39], v22 offset:10240
	ds_read_b128 v[40:43], v45
	v_readlane_b32 s18, v254, 56
	s_waitcnt lgkmcnt(0)
	v_mfma_f32_16x16x32_bf16 v[28:31], v[40:43], v[32:35], v[28:31]
	v_readlane_b32 s19, v254, 57
	v_readlane_b32 s20, v254, 58
	v_readlane_b32 s21, v254, 59
	v_mfma_f32_16x16x32_bf16 v[24:27], v[40:43], v[36:39], v[24:27]
	ds_read_b128 v[32:35], v22 offset:3072
	ds_read_b128 v[36:39], v22 offset:11264
	ds_read_b128 v[40:43], v46
	v_readlane_b32 s22, v254, 60
	s_waitcnt lgkmcnt(0)
	v_mfma_f32_16x16x32_bf16 v[28:31], v[40:43], v[32:35], v[28:31]
	v_readlane_b32 s23, v254, 61
	v_readlane_b32 s24, v254, 62
	v_readlane_b32 s25, v254, 63
	v_mfma_f32_16x16x32_bf16 v[24:27], v[40:43], v[36:39], v[24:27]
	ds_read_b128 v[32:35], v22 offset:4096
	ds_read_b128 v[36:39], v22 offset:12288
	ds_read_b128 v[40:43], v47
	v_readlane_b32 s26, v255, 0
	s_waitcnt lgkmcnt(0)
	v_mfma_f32_16x16x32_bf16 v[28:31], v[40:43], v[32:35], v[28:31]
	v_readlane_b32 s27, v255, 1
	v_mfma_f32_16x16x32_bf16 v[24:27], v[40:43], v[36:39], v[24:27]
	ds_read_b128 v[32:35], v22 offset:5120
	ds_read_b128 v[36:39], v22 offset:13312
	ds_read_b128 v[40:43], v48
	s_waitcnt lgkmcnt(0)
	v_mfma_f32_16x16x32_bf16 v[28:31], v[40:43], v[32:35], v[28:31]
	v_mfma_f32_16x16x32_bf16 v[24:27], v[40:43], v[36:39], v[24:27]
	ds_read_b128 v[32:35], v22 offset:6144
	ds_read_b128 v[36:39], v22 offset:14336
	ds_read_b128 v[40:43], v49
	s_waitcnt lgkmcnt(0)
	v_mfma_f32_16x16x32_bf16 v[28:31], v[40:43], v[32:35], v[28:31]
	v_mfma_f32_16x16x32_bf16 v[24:27], v[40:43], v[36:39], v[24:27]
	ds_read_b128 v[32:35], v22 offset:7168
	ds_read_b128 v[36:39], v22 offset:15360
	ds_read_b128 v[40:43], v50
	s_waitcnt vmcnt(0)
	s_waitcnt vmcnt(0) lgkmcnt(0)
	s_barrier
; #define LDSP __attribute__((address_space(3)))
; #define WAIT_V0() asm volatile("s_waitcnt vmcnt(0)" ::: "memory")
; template <int EK, int TS, int KS>
; DI void ctx_tiles(const Params& p, int l, const bf16_t* __restrict__ A, const bf16_t* __restrict__ Bt, int N, int K, ldsp_t shm) {
;     ...
;         for (int t = 0; t < nt; ++t) {
;             const int cur = t & 1;
;             if (t + 1 < nt) C_STAGE(cur ^ 1, t + 1);
;             ldsp_t sa = shm + cur * 2 * TILE_A, sb = sa + TILE_A;
; #pragma unroll
;             for (int ks = 0; ks < KS; ++ks) {
;                 bf16x8 At[MT], Bf[NT];
; #pragma unroll
;                 for (int m = 0; m < MT; ++m) At[m] = *(const LDSP bf16x8*)(sa + aoff + m * (KS * 1024) + ks * 1024);
; #pragma unroll
;                 for (int n = 0; n < NT; ++n) Bf[n] = *(const LDSP bf16x8*)(sb + boff + n * (KS * 1024) + ks * 1024);
; #pragma unroll
;                 for (int m = 0; m < MT; ++m)
; #pragma unroll
;                     for (int n = 0; n < NT; ++n) acc[m][n] = __builtin_amdgcn_mfma_f32_16x16x32_bf16(Bf[n], At[m], acc[m][n], 0, 0, 0);
;             }
;             WAIT_V0(); __syncthreads();
;         }
	global_load_lds_dwordx4 v[0:1], off
	v_lshl_add_u64 v[0:1], v[2:3], 0, s[10:11]
	s_mov_b32 m0, s6
	v_mfma_f32_16x16x32_bf16 v[28:31], v[40:43], v[32:35], v[28:31]
	global_load_lds_dwordx4 v[0:1], off
	v_lshl_add_u64 v[0:1], v[4:5], 0, s[10:11]
	s_mov_b32 m0, s7
	v_mfma_f32_16x16x32_bf16 v[24:27], v[40:43], v[36:39], v[24:27]
	global_load_lds_dwordx4 v[0:1], off
	v_lshl_add_u64 v[0:1], v[6:7], 0, s[10:11]
	s_mov_b32 m0, s31
	v_cmp_lt_i32_e64 s[6:7], v134, v203
	global_load_lds_dwordx4 v[0:1], off
	v_lshl_add_u64 v[0:1], v[8:9], 0, s[10:11]
	s_mov_b32 m0, s45
	s_nop 0
	global_load_lds_dwordx4 v[0:1], off
	v_lshl_add_u64 v[0:1], v[10:11], 0, s[10:11]
	s_mov_b32 m0, s46
	s_nop 0
	global_load_lds_dwordx4 v[0:1], off
	v_lshl_add_u64 v[0:1], v[12:13], 0, s[10:11]
	s_mov_b32 m0, s47
	s_nop 0
	global_load_lds_dwordx4 v[0:1], off
	v_lshl_add_u64 v[0:1], v[14:15], 0, s[10:11]
	s_mov_b32 m0, s50
	s_nop 0
	global_load_lds_dwordx4 v[0:1], off
	ds_read_b128 v[0:3], v21
	ds_read_b128 v[4:7], v21 offset:8192
	ds_read_b128 v[8:11], v20 offset:32768
	s_waitcnt lgkmcnt(0)
	v_mfma_f32_16x16x32_bf16 v[0:3], v[8:11], v[0:3], v[28:31]
	v_mfma_f32_16x16x32_bf16 v[4:7], v[8:11], v[4:7], v[24:27]
	ds_read_b128 v[8:11], v21 offset:1024
	ds_read_b128 v[12:15], v21 offset:9216
	s_nop 0
	ds_read_b128 v[24:27], v20 offset:33792
	s_waitcnt lgkmcnt(0)
	v_mfma_f32_16x16x32_bf16 v[0:3], v[24:27], v[8:11], v[0:3]
	v_mfma_f32_16x16x32_bf16 v[4:7], v[24:27], v[12:15], v[4:7]
	ds_read_b128 v[8:11], v21 offset:2048
	ds_read_b128 v[12:15], v21 offset:10240
	ds_read_b128 v[24:27], v20 offset:34816
	s_waitcnt lgkmcnt(0)
	v_mfma_f32_16x16x32_bf16 v[0:3], v[24:27], v[8:11], v[0:3]
	v_mfma_f32_16x16x32_bf16 v[4:7], v[24:27], v[12:15], v[4:7]
	ds_read_b128 v[8:11], v21 offset:3072
	ds_read_b128 v[12:15], v21 offset:11264
	ds_read_b128 v[24:27], v20 offset:35840
	s_waitcnt lgkmcnt(0)
	v_mfma_f32_16x16x32_bf16 v[0:3], v[24:27], v[8:11], v[0:3]
	v_mfma_f32_16x16x32_bf16 v[4:7], v[24:27], v[12:15], v[4:7]
	ds_read_b128 v[8:11], v21 offset:4096
	ds_read_b128 v[12:15], v21 offset:12288
	ds_read_b128 v[24:27], v20 offset:36864
	s_waitcnt lgkmcnt(0)
	v_mfma_f32_16x16x32_bf16 v[0:3], v[24:27], v[8:11], v[0:3]
	v_mfma_f32_16x16x32_bf16 v[4:7], v[24:27], v[12:15], v[4:7]
	ds_read_b128 v[8:11], v21 offset:5120
	ds_read_b128 v[12:15], v21 offset:13312
	ds_read_b128 v[24:27], v20 offset:37888
	s_waitcnt lgkmcnt(0)
	v_mfma_f32_16x16x32_bf16 v[0:3], v[24:27], v[8:11], v[0:3]
	v_mfma_f32_16x16x32_bf16 v[4:7], v[24:27], v[12:15], v[4:7]
	ds_read_b128 v[8:11], v21 offset:6144
	ds_read_b128 v[12:15], v21 offset:14336
	ds_read_b128 v[24:27], v20 offset:38912
	s_waitcnt lgkmcnt(0)
	v_mfma_f32_16x16x32_bf16 v[0:3], v[24:27], v[8:11], v[0:3]
	v_mfma_f32_16x16x32_bf16 v[4:7], v[24:27], v[12:15], v[4:7]
	ds_read_b128 v[8:11], v21 offset:7168
	ds_read_b128 v[12:15], v21 offset:15360
	ds_read_b128 v[24:27], v20 offset:39936
	s_waitcnt vmcnt(0)
	s_waitcnt vmcnt(0) lgkmcnt(0)
	v_mfma_f32_16x16x32_bf16 v[0:3], v[24:27], v[8:11], v[0:3]
	s_barrier
	v_mfma_f32_16x16x32_bf16 v[4:7], v[24:27], v[12:15], v[4:7]
	ds_read_b128 v[8:11], v22 offset:1024
	ds_read_b128 v[12:15], v23
	ds_read_b128 v[24:27], v22 offset:8192
	ds_read_b128 v[28:31], v22
	s_waitcnt lgkmcnt(0)
	v_mfma_f32_16x16x32_bf16 v[0:3], v[12:15], v[28:31], v[0:3]
	v_mfma_f32_16x16x32_bf16 v[4:7], v[12:15], v[24:27], v[4:7]
	ds_read_b128 v[12:15], v22 offset:9216
	ds_read_b128 v[24:27], v44
	s_waitcnt lgkmcnt(0)
	v_mfma_f32_16x16x32_bf16 v[0:3], v[24:27], v[8:11], v[0:3]
	v_mfma_f32_16x16x32_bf16 v[4:7], v[24:27], v[12:15], v[4:7]
	ds_read_b128 v[8:11], v22 offset:2048
	ds_read_b128 v[12:15], v22 offset:10240
	ds_read_b128 v[24:27], v45
	s_waitcnt lgkmcnt(0)
	v_mfma_f32_16x16x32_bf16 v[0:3], v[24:27], v[8:11], v[0:3]
	v_mfma_f32_16x16x32_bf16 v[4:7], v[24:27], v[12:15], v[4:7]
	ds_read_b128 v[8:11], v22 offset:3072
	ds_read_b128 v[12:15], v22 offset:11264
	ds_read_b128 v[24:27], v46
	s_waitcnt lgkmcnt(0)
	v_mfma_f32_16x16x32_bf16 v[0:3], v[24:27], v[8:11], v[0:3]
	v_mfma_f32_16x16x32_bf16 v[4:7], v[24:27], v[12:15], v[4:7]
	ds_read_b128 v[8:11], v22 offset:4096
	ds_read_b128 v[12:15], v22 offset:12288
	ds_read_b128 v[24:27], v47
	s_waitcnt lgkmcnt(0)
	v_mfma_f32_16x16x32_bf16 v[0:3], v[24:27], v[8:11], v[0:3]
	v_mfma_f32_16x16x32_bf16 v[4:7], v[24:27], v[12:15], v[4:7]
	ds_read_b128 v[8:11], v22 offset:5120
	ds_read_b128 v[12:15], v22 offset:13312
	ds_read_b128 v[24:27], v48
	s_waitcnt lgkmcnt(0)
	v_mfma_f32_16x16x32_bf16 v[0:3], v[24:27], v[8:11], v[0:3]
	v_mfma_f32_16x16x32_bf16 v[4:7], v[24:27], v[12:15], v[4:7]
	ds_read_b128 v[8:11], v22 offset:6144
	ds_read_b128 v[12:15], v22 offset:14336
	ds_read_b128 v[24:27], v49
	s_waitcnt lgkmcnt(0)
	v_mfma_f32_16x16x32_bf16 v[0:3], v[24:27], v[8:11], v[0:3]
	v_mfma_f32_16x16x32_bf16 v[4:7], v[24:27], v[12:15], v[4:7]
	ds_read_b128 v[8:11], v22 offset:7168
	ds_read_b128 v[12:15], v22 offset:15360
	ds_read_b128 v[20:23], v50
	s_waitcnt vmcnt(0)
	s_waitcnt lgkmcnt(0)
	v_mfma_f32_16x16x32_bf16 v[0:3], v[20:23], v[8:11], v[0:3]
	v_bfe_u32 v8, v16, 4, 2
	v_lshrrev_b32_e32 v9, 2, v19
	v_bitop3_b32 v8, v9, v17, v8 bitop3:0x36
	v_mfma_f32_16x16x32_bf16 v[4:7], v[20:23], v[12:15], v[4:7]
	v_lshlrev_b32_e32 v9, 8, v18
	v_lshl_or_b32 v8, v8, 4, v9
	s_barrier
; template <int EK>
; DI void ctx_item(const Params& p, int l, int grow, int gcol, int slot, f32x4 s0, f32x4 s1, bool lead) {
;     ...
;         const float* gate = p.mod + ((size_t)l * 5 + 4) * 6144 + (EK == 1 ? 2 : 5) * DM + gcol;
;         float* xr = p.xc + (size_t)grow * DM + gcol;
;         const float* xs = (EK == 1 && l == 0) ? p.ctx + (size_t)grow * DM + gcol : xr;
;         const f32x4 g0 = *(const f32x4*)gate, g1 = *(const f32x4*)(gate + 4);
;         f32x4 x0 = *(const f32x4*)xs, x1 = *(const f32x4*)(xs + 4);
;         x0 += g0 * s0; x1 += g1 * s1;
;         *(f32x4*)xr = x0; *(f32x4*)(xr + 4) = x1;
;         const int ln = EK == 1 ? l : l + 1;
;         const float* gnx = (EK == 1 ? p.norm2_g : p.norm1_g) + (size_t)ln * DM + gcol;
;         const float* scn = p.mod + ((size_t)ln * 5 + 4) * 6144 + (EK == 1 ? 4 : 1) * DM + gcol;
;         const f32x4 a0 = *(const f32x4*)gnx * (1.f + *(const f32x4*)scn), a1 = *(const f32x4*)(gnx + 4) * (1.f + *(const f32x4*)(scn + 4));
;         const f32x4 y0 = x0 * a0, y1 = x1 * a1;
;         u32x4 w; w[0] = pk2(y0[0], y0[1]); w[1] = pk2(y0[2], y0[3]); w[2] = pk2(y1[0], y1[1]); w[3] = pk2(y1[2], y1[3]);
;         *(u32x4*)(p.H + (size_t)(NLAT + grow) * DM + gcol) = w;
;         float part = x0[0] * x0[0] + x0[1] * x0[1] + x0[2] * x0[2] + x0[3] * x0[3] + x1[0] * x1[0] + x1[1] * x1[1] + x1[2] * x1[2] + x1[3] * x1[3];
; template <int EK, int TS, int KS>
; DI void ctx_tiles(const Params& p, int l, const bf16_t* __restrict__ A, const bf16_t* __restrict__ Bt, int N, int K, ldsp_t shm) {
;     ...
; #pragma unroll
;         for (int m = 0; m < MT; ++m)
; #pragma unroll
;             for (int n = 0; n < NT; ++n) {
;                 const int row = wr * WM + m * 16 + fr, ch = (wc * WN + n * 16 + fq * 4) >> 2;
;                 *(LDSP f32x4*)(shm + row * (TS * 4) + ((ch ^ (row & 15)) << 4)) = acc[m][n];
;             }
;         __syncthreads();
; #pragma unroll
;         for (int it = 0; it < (TS * TS / 8) / 512; ++it) {
;             const int item = it * 512 + tid, row = item / (TS / 8), c8 = item % (TS / 8);
;             const f32x4 s0 = *(const LDSP f32x4*)(shm + row * (TS * 4) + (((2 * c8) ^ (row & 15)) << 4));
;             const f32x4 s1 = *(const LDSP f32x4*)(shm + row * (TS * 4) + (((2 * c8 + 1) ^ (row & 15)) << 4));
;             ctx_item<EK>(p, l, tm * TS + row, tn * TS + c8 * 8, tn, s0, s1, c8 == 0);
;         }
	s_nop 0
	ds_write_b128 v8, v[0:3]
	s_nop 2
	ds_write_b128 v8, v[4:7] offset:4096
	v_ashrrev_i32_e32 v0, 31, v16
	v_lshrrev_b32_e32 v0, 29, v0
	v_add_u32_e32 v0, v16, v0
	v_ashrrev_i32_e32 v1, 3, v0
	v_and_b32_e32 v0, -8, v0
	v_sub_u32_e32 v2, v16, v0
	v_lshlrev_b32_e32 v3, 1, v2
	v_and_b32_e32 v4, 15, v1
	v_lshlrev_b32_e32 v0, 8, v1
	v_bitop3_b32 v5, v3, v1, 15 bitop3:0x78
	v_bitop3_b32 v3, v3, v4, 1 bitop3:0x36
	v_lshl_add_u32 v5, v5, 4, v0
	v_lshl_add_u32 v6, v3, 4, v0
	v_lshl_add_u32 v0, s4, 6, v1
	s_lshl_b32 s4, s42, 6
	v_lshl_add_u32 v26, v2, 3, s4
	v_cmp_eq_u32_e64 s[4:5], 0, v2
	v_ashrrev_i32_e32 v1, 31, v0
	v_cndmask_b32_e64 v2, v202, v134, s[6:7]
	v_cmp_lt_i32_e64 s[6:7], v135, v203
	v_ashrrev_i32_e32 v27, 31, v26
	v_lshlrev_b32_e32 v34, 2, v2
	v_cndmask_b32_e64 v2, v202, v135, s[6:7]
	v_lshlrev_b64 v[10:11], 12, v[0:1]
	v_lshlrev_b32_e32 v35, 2, v2
	v_xor_b32_e32 v2, 4, v202
	v_lshlrev_b64 v[30:31], 2, v[26:27]
	v_lshl_add_u64 v[12:13], s[70:71], 0, v[10:11]
	v_lshl_add_u64 v[10:11], s[16:17], 0, v[10:11]
	v_cmp_lt_i32_e64 s[6:7], v2, v203
	v_lshl_add_u64 v[32:33], v[12:13], 0, v[30:31]
	v_lshl_add_u64 v[10:11], v[10:11], 0, v[30:31]
	v_cndmask_b32_e64 v2, v202, v2, s[6:7]
	v_lshl_add_u64 v[14:15], s[36:37], 0, v[30:31]
	v_cndmask_b32_e32 v23, v33, v11, vcc
	v_cndmask_b32_e32 v22, v32, v10, vcc
	s_waitcnt lgkmcnt(0)
	s_barrier
	v_lshlrev_b32_e32 v36, 2, v2
	ds_read_b128 v[2:5], v5
	ds_read_b128 v[6:9], v6
	global_load_dwordx4 v[10:13], v[14:15], off offset:16
	s_nop 0
	global_load_dwordx4 v[14:17], v[14:15], off
	s_nop 0
	global_load_dwordx4 v[18:21], v[22:23], off offset:16
	s_nop 0
	global_load_dwordx4 v[22:25], v[22:23], off
	v_lshlrev_b64 v[28:29], 11, v[0:1]
	s_brev_b32 s6, 64
	s_waitcnt vmcnt(1) lgkmcnt(0)
	v_pk_fma_f32 v[8:9], v[8:9], v[12:13], v[20:21]
	s_waitcnt vmcnt(0)
	v_pk_fma_f32 v[4:5], v[4:5], v[16:17], v[24:25]
	v_pk_fma_f32 v[2:3], v[2:3], v[14:15], v[22:23]
	v_pk_fma_f32 v[6:7], v[6:7], v[10:11], v[18:19]
	global_store_dwordx4 v[32:33], v[2:5], off sc1
	global_store_dwordx4 v[32:33], v[6:9], off offset:16 sc1
	v_lshl_add_u64 v[14:15], s[38:39], 0, v[30:31]
	v_lshl_add_u64 v[22:23], s[40:41], 0, v[30:31]
	global_load_dwordx4 v[10:13], v[14:15], off offset:16
	s_nop 0
	global_load_dwordx4 v[14:17], v[14:15], off
	s_nop 0
	global_load_dwordx4 v[18:21], v[22:23], off offset:16
	s_nop 0
	global_load_dwordx4 v[22:25], v[22:23], off
	s_waitcnt vmcnt(1)
	v_pk_add_f32 v[20:21], v[20:21], 1.0 op_sel_hi:[1,0]
	s_waitcnt vmcnt(0)
	v_pk_add_f32 v[22:23], v[22:23], 1.0 op_sel_hi:[1,0]
	v_pk_add_f32 v[18:19], v[18:19], 1.0 op_sel_hi:[1,0]
	v_pk_mul_f32 v[14:15], v[14:15], v[22:23]
	v_pk_mul_f32 v[12:13], v[12:13], v[20:21]
	v_pk_mul_f32 v[14:15], v[2:3], v[14:15]
	v_mul_f32_e32 v3, v3, v3
	v_fmac_f32_e32 v3, v2, v2
	v_fmac_f32_e32 v3, v4, v4
	v_fmac_f32_e32 v3, v5, v5
	v_fmac_f32_e32 v3, v6, v6
	v_fmac_f32_e32 v3, v7, v7
	v_fmac_f32_e32 v3, v8, v8
	v_fmac_f32_e32 v3, v9, v9
	ds_bpermute_b32 v2, v34, v3
	v_pk_mul_f32 v[10:11], v[10:11], v[18:19]
	v_pk_add_f32 v[24:25], v[24:25], 1.0 op_sel_hi:[1,0]
	v_pk_mul_f32 v[18:19], v[8:9], v[12:13]
	v_pk_mul_f32 v[12:13], v[6:7], v[10:11]
	s_waitcnt lgkmcnt(0)
	v_add_f32_e32 v2, v3, v2
	ds_bpermute_b32 v3, v35, v2
	v_cvt_pk_bf16_f32 v10, v14, v15
	v_lshl_add_u64 v[14:15], s[82:83], 0, v[28:29]
	v_pk_mul_f32 v[16:17], v[16:17], v[24:25]
	v_lshl_add_u64 v[14:15], v[26:27], 1, v[14:15]
	s_waitcnt lgkmcnt(0)
	v_add_f32_e32 v2, v2, v3
	ds_bpermute_b32 v3, v36, v2
	v_pk_mul_f32 v[16:17], v[4:5], v[16:17]
	v_add_co_u32_e64 v14, s[6:7], s6, v14
	v_cvt_pk_bf16_f32 v11, v16, v17
	v_cvt_pk_bf16_f32 v12, v12, v13
	v_cvt_pk_bf16_f32 v13, v18, v19
	v_addc_co_u32_e64 v15, s[6:7], 0, v15, s[6:7]
	global_store_dwordx4 v[14:15], v[10:13], off sc1
	s_and_saveexec_b64 s[6:7], s[4:5]
	s_cbranch_execz .LBB0_155
	v_lshl_add_u64 v[0:1], s[34:35], 0, v[0:1]
	v_lshlrev_b64 v[0:1], 6, v[0:1]
	v_lshl_add_u64 v[0:1], s[74:75], 0, v[0:1]
	v_lshl_add_u64 v[0:1], s[42:43], 2, v[0:1]
	s_waitcnt lgkmcnt(0)
	v_add_f32_e32 v2, v2, v3
	global_store_dword v[0:1], v2, off sc1
	s_branch .LBB0_155

; DI void attn_unit(const Params& p, int l, int b, int kvh, int qb, bool isctx, ldsp_t smem) {
;     ...
;     for (int t = 0; t < ntile; t += 2) {
;         ATT_STEP(t, sA, sB);
;         ATT_STEP(t + 1, sB, sA);
;     }
.LBB0_164:
	s_add_i32 s10, s9, 4
	s_min_u32 s10, s10, 0x43
	s_lshl_b32 s98, s10, 13
	v_lshl_add_u64 v[80:81], v[146:147], 0, s[98:99]
	s_waitcnt lgkmcnt(0)
	s_barrier
	global_load_dwordx4 v[132:135], v[80:81], off
	global_load_dwordx4 v[128:131], v[150:151], off
	v_add_u32_e32 v171, v192, v167
	v_add_u32_e32 v172, v192, v168
	v_add_u32_e32 v142, v192, v169
	v_add_u32_e32 v143, v192, v170
	ds_read_b128 v[80:83], v171 offset:8192
	ds_read_b128 v[138:141], v171 offset:12288
	ds_read_b128 v[152:155], v172 offset:8192
	ds_read_b128 v[156:159], v172 offset:12288
	ds_read_b128 v[160:163], v142 offset:8192
	ds_read_b128 v[174:177], v142 offset:12288
	ds_read_b128 v[178:181], v143 offset:8192
	ds_read_b128 v[182:185], v143 offset:12288
	ds_read_b128 v[186:189], v171 offset:16384
	ds_read_b128 v[194:197], v171 offset:20480
	ds_read_b128 v[198:201], v172 offset:16384
	ds_read_b128 v[204:207], v172 offset:20480
	s_add_i32 s9, s9, 2
	s_waitcnt lgkmcnt(11)
	v_mfma_f32_32x32x16_bf16 v[96:111], v[80:83], v[112:115], v[32:47]
	v_exp_f32_e32 v64, v64
	v_exp_f32_e32 v65, v65
	v_exp_f32_e32 v66, v66
	v_exp_f32_e32 v67, v67
	v_exp_f32_e32 v68, v68
	v_exp_f32_e32 v69, v69
	v_exp_f32_e32 v74, v74
	s_waitcnt lgkmcnt(10)
	v_mfma_f32_32x32x16_bf16 v[80:95], v[138:141], v[112:115], v[32:47]
	v_exp_f32_e32 v138, v70
	v_exp_f32_e32 v139, v71
	v_exp_f32_e32 v140, v72
	v_exp_f32_e32 v141, v73
	v_exp_f32_e32 v75, v75
	v_exp_f32_e32 v70, v76
	v_exp_f32_e32 v71, v77
	s_waitcnt lgkmcnt(9)
	v_mfma_f32_32x32x16_bf16 v[96:111], v[152:155], v[116:119], v[96:111]
	v_exp_f32_e32 v152, v54
	v_exp_f32_e32 v153, v55
	v_cvt_pk_bf16_f32 v54, v68, v69
	v_cvt_pk_bf16_f32 v55, v138, v139
	v_exp_f32_e32 v72, v78
	v_exp_f32_e32 v73, v79
	v_exp_f32_e32 v48, v48
	s_waitcnt lgkmcnt(8)
	v_mfma_f32_32x32x16_bf16 v[80:95], v[156:159], v[116:119], v[80:95]
	v_exp_f32_e32 v158, v52
	v_exp_f32_e32 v159, v53
	v_cvt_pk_bf16_f32 v52, v64, v65
	v_cvt_pk_bf16_f32 v53, v66, v67
	v_exp_f32_e32 v49, v49
	v_exp_f32_e32 v50, v50
	v_exp_f32_e32 v51, v51
	s_waitcnt lgkmcnt(3)
	v_mfma_f32_32x32x16_bf16 v[16:31], v[186:189], v[52:55], v[16:31]
	v_exp_f32_e32 v154, v56
	v_exp_f32_e32 v155, v57
	v_exp_f32_e32 v156, v58
	v_exp_f32_e32 v157, v59
	s_min_u32 s11, s9, 64
	s_lshl_b32 s98, s11, 13
	v_pk_add_f32 v[56:57], v[136:137], v[64:65]
	s_waitcnt lgkmcnt(2)
	v_mfma_f32_32x32x16_bf16 v[0:15], v[194:197], v[52:55], v[0:15]
	v_cvt_pk_bf16_f32 v52, v140, v141
	v_cvt_pk_bf16_f32 v53, v74, v75
	v_cvt_pk_bf16_f32 v54, v70, v71
	v_cvt_pk_bf16_f32 v55, v72, v73
	v_add_f32_e64 v56, v66, v56
	v_add_f32_e64 v57, v67, v57
	v_pk_add_f32 v[56:57], v[68:69], v[56:57]
	v_mfma_f32_32x32x16_bf16 v[96:111], v[160:163], v[120:123], v[96:111]
	v_exp_f32_e32 v160, v60
	v_exp_f32_e32 v161, v61
	v_exp_f32_e32 v162, v62
	v_exp_f32_e32 v163, v63
	v_pk_add_f32 v[56:57], v[138:139], v[56:57]
	s_nop 0
	v_pk_add_f32 v[56:57], v[140:141], v[56:57]
	v_mfma_f32_32x32x16_bf16 v[80:95], v[174:177], v[120:123], v[80:95]
	v_add_f32_e64 v56, v74, v56
	v_add_f32_e64 v57, v75, v57
	v_add_f32_e64 v56, v70, v56
	v_add_f32_e64 v57, v71, v57
	v_add_f32_e64 v56, v72, v56
	v_add_f32_e64 v57, v73, v57
	s_waitcnt lgkmcnt(1)
	v_mfma_f32_32x32x16_bf16 v[16:31], v[198:201], v[52:55], v[16:31]
	s_waitcnt lgkmcnt(0)
	v_mfma_f32_32x32x16_bf16 v[0:15], v[204:207], v[52:55], v[0:15]
	v_cvt_pk_bf16_f32 v52, v48, v49
	v_cvt_pk_bf16_f32 v53, v50, v51
	v_cvt_pk_bf16_f32 v54, v158, v159
	v_cvt_pk_bf16_f32 v55, v152, v153
	v_add_f32_e64 v48, v48, v56
	v_add_f32_e64 v49, v49, v57
	v_pk_add_f32 v[190:191], v[50:51], v[48:49]
	v_mfma_f32_32x32x16_bf16 v[96:111], v[178:181], v[124:127], v[96:111]
	v_mfma_f32_32x32x16_bf16 v[80:95], v[182:185], v[124:127], v[80:95]
	ds_read_b128 v[174:177], v142 offset:16384
	ds_read_b128 v[178:181], v142 offset:20480
	ds_read_b128 v[182:185], v143 offset:16384
	ds_read_b128 v[210:213], v143 offset:20480
	s_waitcnt vmcnt(1)
	ds_write_b128 v145, v[132:135]
	s_waitcnt vmcnt(0)
	ds_write_b128 v145, v[128:131] offset:24576
	s_waitcnt lgkmcnt(0)
	s_barrier
	v_mfma_f32_32x32x16_bf16 v[16:31], v[174:177], v[52:55], v[16:31]
	v_mfma_f32_32x32x16_bf16 v[0:15], v[178:181], v[52:55], v[0:15]
	v_cvt_pk_bf16_f32 v52, v154, v155
	v_cvt_pk_bf16_f32 v53, v156, v157
	v_cvt_pk_bf16_f32 v54, v160, v161
	v_cvt_pk_bf16_f32 v55, v162, v163
	s_nop 1
	v_mfma_f32_32x32x16_bf16 v[16:31], v[182:185], v[52:55], v[16:31]
	v_mfma_f32_32x32x16_bf16 v[0:15], v[210:213], v[52:55], v[0:15]
	v_lshl_add_u64 v[52:53], v[146:147], 0, s[98:99]
	v_add_co_u32_e32 v52, vcc, s28, v52
	s_lshl_b32 s98, s10, 7
	s_nop 0
	v_addc_co_u32_e32 v53, vcc, 0, v53, vcc
	global_load_dwordx4 v[128:131], v[52:53], off
	v_lshl_add_u64 v[52:53], v[148:149], 0, s[98:99]
	global_load_dwordx4 v[132:135], v[52:53], off
	ds_read_b128 v[52:55], v171
	ds_read_b128 v[174:177], v172
	ds_read_b128 v[178:181], v142
	ds_read_b128 v[182:185], v143
	ds_read_b128 v[186:189], v171 offset:4096
	ds_read_b128 v[194:197], v172 offset:4096
	ds_read_b128 v[198:201], v142 offset:4096
	ds_read_b128 v[204:207], v143 offset:4096
	ds_read_b128 v[210:213], v171 offset:24576
	ds_read_b128 v[214:217], v171 offset:28672
	ds_read_b128 v[218:221], v172 offset:24576
	ds_read_b128 v[222:225], v172 offset:28672
	v_exp_f32_e32 v96, v96
	v_exp_f32_e32 v97, v97
	v_exp_f32_e32 v98, v98
	v_exp_f32_e32 v99, v99
	v_exp_f32_e32 v100, v100
	v_exp_f32_e32 v101, v101
	v_exp_f32_e32 v102, v102
	v_exp_f32_e32 v103, v103
	v_pk_add_f32 v[158:159], v[158:159], v[190:191]
	s_waitcnt lgkmcnt(11)
; DI void attn_unit(const Params& p, int l, int b, int kvh, int qb, bool isctx, ldsp_t smem) {
;     ...
;     for (int t = 0; t < ntile; t += 2) {
;         ATT_STEP(t, sA, sB);
;         ATT_STEP(t + 1, sB, sA);
;     }
	v_mfma_f32_32x32x16_bf16 v[64:79], v[52:55], v[112:115], v[32:47]
	v_add_f32_e64 v152, v152, v158
	v_add_f32_e64 v153, v153, v159
	v_exp_f32_e32 v104, v104
	v_pk_add_f32 v[152:153], v[154:155], v[152:153]
	v_exp_f32_e32 v154, v80
	v_pk_add_f32 v[152:153], v[156:157], v[152:153]
	v_exp_f32_e32 v155, v81
	v_exp_f32_e32 v156, v82
	v_exp_f32_e32 v157, v83
	v_cvt_pk_bf16_f32 v80, v96, v97
	v_cvt_pk_bf16_f32 v81, v98, v99
	v_cvt_pk_bf16_f32 v82, v100, v101
	v_cvt_pk_bf16_f32 v83, v102, v103
	s_waitcnt lgkmcnt(7)
	v_mfma_f32_32x32x16_bf16 v[48:63], v[186:189], v[112:115], v[32:47]
	v_exp_f32_e32 v105, v105
	v_exp_f32_e32 v106, v106
	v_exp_f32_e32 v107, v107
	v_exp_f32_e32 v108, v108
	v_exp_f32_e32 v109, v109
	v_exp_f32_e32 v110, v110
	v_exp_f32_e32 v111, v111
	s_waitcnt lgkmcnt(3)
	v_mfma_f32_32x32x16_bf16 v[16:31], v[210:213], v[80:83], v[16:31]
	v_exp_f32_e32 v84, v84
	v_exp_f32_e32 v85, v85
	v_exp_f32_e32 v86, v86
	v_exp_f32_e32 v87, v87
	v_pk_add_f32 v[152:153], v[160:161], v[152:153]
	v_exp_f32_e32 v88, v88
	v_pk_add_f32 v[152:153], v[162:163], v[152:153]
	s_waitcnt lgkmcnt(2)
	v_mfma_f32_32x32x16_bf16 v[0:15], v[214:217], v[80:83], v[0:15]
	v_cvt_pk_bf16_f32 v80, v104, v105
	v_cvt_pk_bf16_f32 v81, v106, v107
	v_cvt_pk_bf16_f32 v82, v108, v109
	v_cvt_pk_bf16_f32 v83, v110, v111
	v_add_f32_e64 v152, v152, v96
	v_add_f32_e64 v153, v153, v97
	v_exp_f32_e32 v89, v89
	v_exp_f32_e32 v90, v90
	v_mfma_f32_32x32x16_bf16 v[64:79], v[174:177], v[116:119], v[64:79]
	v_exp_f32_e32 v91, v91
	v_exp_f32_e32 v92, v92
	v_exp_f32_e32 v93, v93
	v_exp_f32_e32 v94, v94
	v_exp_f32_e32 v95, v95
	v_pk_add_f32 v[152:153], v[98:99], v[152:153]
	v_lshl_add_u64 v[150:151], v[150:151], 0, s[96:97]
	s_waitcnt lgkmcnt(1)
	v_mfma_f32_32x32x16_bf16 v[16:31], v[218:221], v[80:83], v[16:31]
	v_add_f32_e64 v152, v100, v152
	v_add_f32_e64 v153, v101, v153
	s_cmpk_lt_u32 s9, 0x42
	v_add_f32_e64 v152, v102, v152
	v_add_f32_e64 v153, v103, v153
	v_pk_add_f32 v[152:153], v[104:105], v[152:153]
	s_waitcnt lgkmcnt(0)
	v_mfma_f32_32x32x16_bf16 v[0:15], v[222:225], v[80:83], v[0:15]
	v_cvt_pk_bf16_f32 v80, v154, v155
	v_cvt_pk_bf16_f32 v81, v156, v157
	v_cvt_pk_bf16_f32 v82, v84, v85
	v_cvt_pk_bf16_f32 v83, v86, v87
	v_mfma_f32_32x32x16_bf16 v[48:63], v[194:197], v[116:119], v[48:63]
	v_mfma_f32_32x32x16_bf16 v[64:79], v[178:181], v[120:123], v[64:79]
	ds_read_b128 v[172:175], v142 offset:24576
	ds_read_b128 v[176:179], v142 offset:28672
	ds_read_b128 v[136:139], v143 offset:24576
	ds_read_b128 v[140:143], v143 offset:28672
	s_waitcnt vmcnt(1)
	ds_write_b128 v145, v[128:131] offset:8192
	s_waitcnt vmcnt(0)
	ds_write_b128 v145, v[132:135] offset:16384
	s_waitcnt lgkmcnt(5)
	v_mfma_f32_32x32x16_bf16 v[16:31], v[172:175], v[80:83], v[16:31]
	s_waitcnt lgkmcnt(4)
	v_mfma_f32_32x32x16_bf16 v[0:15], v[176:179], v[80:83], v[0:15]
	v_cvt_pk_bf16_f32 v80, v88, v89
	v_cvt_pk_bf16_f32 v81, v90, v91
	v_cvt_pk_bf16_f32 v82, v92, v93
	v_cvt_pk_bf16_f32 v83, v94, v95
	v_mfma_f32_32x32x16_bf16 v[48:63], v[198:201], v[120:123], v[48:63]
	s_waitcnt lgkmcnt(3)
	v_mfma_f32_32x32x16_bf16 v[16:31], v[136:139], v[80:83], v[16:31]
	s_waitcnt lgkmcnt(2)
	v_mfma_f32_32x32x16_bf16 v[0:15], v[140:143], v[80:83], v[0:15]
	v_add_f32_e64 v80, v106, v152
	v_add_f32_e64 v81, v107, v153
	v_add_f32_e64 v80, v108, v80
	v_add_f32_e64 v81, v109, v81
	v_add_f32_e64 v80, v110, v80
	v_add_f32_e64 v81, v111, v81
	v_pk_add_f32 v[80:81], v[154:155], v[80:81]
	v_mfma_f32_32x32x16_bf16 v[64:79], v[182:185], v[124:127], v[64:79]
	v_add_f32_e64 v80, v156, v80
	v_add_f32_e64 v81, v157, v81
	v_add_f32_e64 v80, v84, v80
	v_add_f32_e64 v81, v85, v81
	v_add_f32_e64 v80, v86, v80
	v_add_f32_e64 v81, v87, v81
	v_pk_add_f32 v[80:81], v[88:89], v[80:81]
	v_mfma_f32_32x32x16_bf16 v[48:63], v[204:207], v[124:127], v[48:63]
	v_add_f32_e64 v80, v90, v80
	v_add_f32_e64 v81, v91, v81
	v_add_f32_e64 v80, v92, v80
	v_add_f32_e64 v81, v93, v81
	v_add_f32_e64 v136, v94, v80
	v_add_f32_e64 v137, v95, v81
	s_cbranch_scc1 .LBB0_164
; DI unsigned pk2(float a, float b) { f32x2 v = {a, b}; bf2_t r = __builtin_convertvector(v, bf2_t); return __builtin_bit_cast(unsigned, r); }
; DI void attn_unit(const Params& p, int l, int b, int kvh, int qb, bool isctx, ldsp_t smem) {
;     ...
;     const float lrun = rs0 + rs1;
;     const float ltot = lrun + __shfl_xor(lrun, 32);
;     const float inv = 1.f / ltot;
; #pragma unroll
;     for (int dt = 0; dt < 2; ++dt)
; #pragma unroll
;         for (int g4 = 0; g4 < 4; ++g4) {
;             u32x2 w; w[0] = pk2(o[dt][4 * g4 + 0] * inv, o[dt][4 * g4 + 1] * inv); w[1] = pk2(o[dt][4 * g4 + 2] * inv, o[dt][4 * g4 + 3] * inv);
;             *(u32x2*)(Op + (size_t)r * DM + dt * 32 + 8 * g4 + 4 * hh) = w;
;         }
;     __syncthreads();
	v_lshrrev_b32_e32 v42, 6, v252
	v_mul_u32_u24_e32 v42, 0x1200, v42
	v_add_u32_e32 v42, 0x8000, v42
	v_and_b32_e32 v43, 31, v252
	v_mul_u32_u24_e32 v43, 0x90, v43
	v_bfe_u32 v40, v252, 5, 1
	v_lshl_add_u32 v40, v40, 3, v43
	v_add_u32_e32 v40, v42, v40
	v_bfe_u32 v43, v252, 3, 3
	v_mul_u32_u24_e32 v43, 0x90, v43
	v_and_b32_e32 v41, 7, v252
	v_lshl_add_u32 v41, v41, 4, v43
	v_add_u32_e32 v41, v42, v41
	v_lshl_add_u32 v32, s7, 12, v144
	v_ashrrev_i32_e32 v33, 31, v32
	v_lshlrev_b64 v[32:33], 11, v[32:33]
	v_lshlrev_b32_e32 v34, 6, v166
	v_lshl_add_u64 v[32:33], s[18:19], 0, v[32:33]
	v_ashrrev_i32_e32 v35, 31, v34
	v_cmp_lt_i32_e32 vcc, v209, v203
	v_lshl_add_u64 v[32:33], v[34:35], 1, v[32:33]
	v_add_f32_e32 v34, v137, v136
	v_cndmask_b32_e32 v35, v202, v209, vcc
	v_lshlrev_b32_e32 v35, 2, v35
	ds_bpermute_b32 v35, v35, v34
	v_bfe_u32 v192, v252, 3, 3
	v_lshlrev_b32_e32 v192, 11, v192
	v_lshl_add_u64 v[32:33], v[32:33], 0, v[192:193]
	v_and_b32_e32 v192, 7, v252
	v_lshlrev_b32_e32 v192, 4, v192
	v_lshl_add_u64 v[32:33], v[32:33], 0, v[192:193]
	s_waitcnt lgkmcnt(0)
	v_add_f32_e32 v34, v34, v35
	v_div_scale_f32 v35, s[10:11], v34, v34, 1.0
	v_rcp_f32_e32 v36, v35
	s_nop 0
	v_fma_f32 v37, -v35, v36, 1.0
	v_fmac_f32_e32 v36, v37, v36
	v_div_scale_f32 v37, vcc, 1.0, v34, 1.0
	v_mul_f32_e32 v38, v37, v36
	v_fma_f32 v39, -v35, v38, v37
	v_fmac_f32_e32 v38, v39, v36
	v_fma_f32 v35, -v35, v38, v37
	v_div_fmas_f32 v35, v35, v36, v38
	v_div_fixup_f32 v34, v35, v34, 1.0
	v_pk_mul_f32 v[16:17], v[16:17], v[34:35] op_sel_hi:[1,0]
	v_pk_mul_f32 v[18:19], v[18:19], v[34:35] op_sel_hi:[1,0]
	v_pk_mul_f32 v[0:1], v[0:1], v[34:35] op_sel_hi:[1,0]
	v_pk_mul_f32 v[2:3], v[2:3], v[34:35] op_sel_hi:[1,0]
	v_cvt_pk_bf16_f32 v16, v16, v17
	v_cvt_pk_bf16_f32 v17, v18, v19
	v_cvt_pk_bf16_f32 v0, v0, v1
	v_cvt_pk_bf16_f32 v1, v2, v3
	ds_write_b64 v40, v[16:17]
	v_pk_mul_f32 v[16:17], v[20:21], v[34:35] op_sel_hi:[1,0]
	v_pk_mul_f32 v[18:19], v[22:23], v[34:35] op_sel_hi:[1,0]
	ds_write_b64 v40, v[0:1] offset:64
	v_pk_mul_f32 v[0:1], v[4:5], v[34:35] op_sel_hi:[1,0]
	v_pk_mul_f32 v[2:3], v[6:7], v[34:35] op_sel_hi:[1,0]
	v_cvt_pk_bf16_f32 v16, v16, v17
	v_cvt_pk_bf16_f32 v17, v18, v19
	v_cvt_pk_bf16_f32 v0, v0, v1
	v_cvt_pk_bf16_f32 v1, v2, v3
	ds_write_b64 v40, v[16:17] offset:16
	v_pk_mul_f32 v[16:17], v[24:25], v[34:35] op_sel_hi:[1,0]
	v_pk_mul_f32 v[18:19], v[26:27], v[34:35] op_sel_hi:[1,0]
	ds_write_b64 v40, v[0:1] offset:80
	v_pk_mul_f32 v[0:1], v[8:9], v[34:35] op_sel_hi:[1,0]
	v_pk_mul_f32 v[2:3], v[10:11], v[34:35] op_sel_hi:[1,0]
	v_cvt_pk_bf16_f32 v16, v16, v17
	v_cvt_pk_bf16_f32 v17, v18, v19
	v_cvt_pk_bf16_f32 v0, v0, v1
	v_cvt_pk_bf16_f32 v1, v2, v3
	ds_write_b64 v40, v[16:17] offset:32
	v_pk_mul_f32 v[16:17], v[28:29], v[34:35] op_sel_hi:[1,0]
	v_pk_mul_f32 v[18:19], v[30:31], v[34:35] op_sel_hi:[1,0]
	ds_write_b64 v40, v[0:1] offset:96
	v_pk_mul_f32 v[0:1], v[12:13], v[34:35] op_sel_hi:[1,0]
	v_pk_mul_f32 v[2:3], v[14:15], v[34:35] op_sel_hi:[1,0]
	v_cvt_pk_bf16_f32 v16, v16, v17
	v_cvt_pk_bf16_f32 v17, v18, v19
	v_cvt_pk_bf16_f32 v0, v0, v1
	v_cvt_pk_bf16_f32 v1, v2, v3
	ds_write_b64 v40, v[16:17] offset:48
	ds_write_b64 v40, v[0:1] offset:112
	ds_read_b128 v[44:47], v41
	ds_read_b128 v[48:51], v41 offset:1152
	ds_read_b128 v[52:55], v41 offset:2304
	ds_read_b128 v[56:59], v41 offset:3456
	v_mov_b32_e32 v192, 0x4000
	v_lshl_add_u64 v[60:61], v[32:33], 0, v[192:193]
	v_lshl_add_u64 v[62:63], v[60:61], 0, v[192:193]
	v_lshl_add_u64 v[64:65], v[62:63], 0, v[192:193]
	s_waitcnt lgkmcnt(0)
	global_store_dwordx4 v[32:33], v[44:47], off sc1
	global_store_dwordx4 v[60:61], v[48:51], off sc1
	global_store_dwordx4 v[62:63], v[52:55], off sc1
	global_store_dwordx4 v[64:65], v[56:59], off sc1
	s_barrier
	s_load_dword s7, s[88:89], 0x0
	s_waitcnt lgkmcnt(0)
	s_add_i32 s6, s7, s6
	s_cmpk_gt_i32 s6, 0x1ff
	s_cbranch_scc0 .LBB0_163

; DI void attn_unit(const Params& p, int l, int b, int kvh, int qb, bool isctx, ldsp_t smem) {
;     ...
;     for (int t = 0; t < ntile; t += 2) {
;         ATT_STEP(t, sA, sB);
;         ATT_STEP(t + 1, sB, sA);
;     }
.LBB0_169:
	s_lshl_b32 s98, s11, 13
	v_lshl_add_u64 v[80:81], v[162:163], 0, s[98:99]
	s_waitcnt lgkmcnt(0)
	s_barrier
	global_load_dwordx4 v[128:131], v[80:81], off
	v_lshl_add_u64 v[80:81], s[34:35], 1, v[164:165]
	global_load_dwordx4 v[132:135], v[80:81], off offset:128
	v_add_u32_e32 v144, v192, v183
	v_add_u32_e32 v145, v192, v184
	v_add_u32_e32 v142, v192, v185
	v_add_u32_e32 v143, v192, v186
	ds_read_b128 v[80:83], v144 offset:8192
	ds_read_b128 v[138:141], v144 offset:12288
	ds_read_b128 v[146:149], v145 offset:8192
	ds_read_b128 v[150:153], v145 offset:12288
	ds_read_b128 v[154:157], v142 offset:8192
	ds_read_b128 v[168:171], v142 offset:12288
	ds_read_b128 v[172:175], v143 offset:8192
	ds_read_b128 v[176:179], v143 offset:12288
	ds_read_b128 v[188:191], v144 offset:16384
	ds_read_b128 v[194:197], v144 offset:20480
	ds_read_b128 v[198:201], v145 offset:16384
	ds_read_b128 v[204:207], v145 offset:20480
	s_waitcnt lgkmcnt(11)
	v_mfma_f32_32x32x16_bf16 v[96:111], v[80:83], v[112:115], v[16:31]
	v_exp_f32_e32 v64, v64
	v_exp_f32_e32 v65, v65
	v_exp_f32_e32 v66, v66
	v_exp_f32_e32 v67, v67
	v_exp_f32_e32 v68, v68
	v_exp_f32_e32 v69, v69
	v_exp_f32_e32 v74, v74
	s_waitcnt lgkmcnt(10)
	v_mfma_f32_32x32x16_bf16 v[80:95], v[138:141], v[112:115], v[16:31]
	v_exp_f32_e32 v138, v70
	v_exp_f32_e32 v139, v71
	v_exp_f32_e32 v140, v72
	v_exp_f32_e32 v141, v73
	v_exp_f32_e32 v75, v75
	v_exp_f32_e32 v70, v76
	v_exp_f32_e32 v71, v77
	s_waitcnt lgkmcnt(8)
	v_mfma_f32_32x32x16_bf16 v[80:95], v[150:153], v[116:119], v[80:95]
	v_exp_f32_e32 v72, v78
	v_exp_f32_e32 v73, v79
	v_exp_f32_e32 v48, v48
	v_exp_f32_e32 v49, v49
	v_exp_f32_e32 v50, v50
	v_exp_f32_e32 v51, v51
	s_lshl_b32 s98, s11, 7
	s_waitcnt lgkmcnt(6)
	v_mfma_f32_32x32x16_bf16 v[80:95], v[168:171], v[120:123], v[80:95]
	v_exp_f32_e32 v168, v52
	v_exp_f32_e32 v169, v53
	v_exp_f32_e32 v170, v54
	v_exp_f32_e32 v171, v55
	v_cvt_pk_bf16_f32 v52, v64, v65
	v_cvt_pk_bf16_f32 v53, v66, v67
	v_cvt_pk_bf16_f32 v54, v68, v69
	v_cvt_pk_bf16_f32 v55, v138, v139
	v_mfma_f32_32x32x16_bf16 v[96:111], v[146:149], v[116:119], v[96:111]
	s_waitcnt lgkmcnt(3)
	v_mfma_f32_32x32x16_bf16 v[0:15], v[188:191], v[52:55], v[0:15]
	s_waitcnt lgkmcnt(2)
	v_mfma_f32_32x32x16_bf16 v[32:47], v[194:197], v[52:55], v[32:47]
	v_cvt_pk_bf16_f32 v52, v140, v141
	v_cvt_pk_bf16_f32 v53, v74, v75
	v_cvt_pk_bf16_f32 v54, v70, v71
	v_cvt_pk_bf16_f32 v55, v72, v73
	s_waitcnt lgkmcnt(1)
	s_nop 0
	v_mfma_f32_32x32x16_bf16 v[0:15], v[198:201], v[52:55], v[0:15]
	s_waitcnt lgkmcnt(0)
	v_mfma_f32_32x32x16_bf16 v[32:47], v[204:207], v[52:55], v[32:47]
	v_cvt_pk_bf16_f32 v52, v48, v49
	v_cvt_pk_bf16_f32 v53, v50, v51
	v_cvt_pk_bf16_f32 v54, v168, v169
	v_cvt_pk_bf16_f32 v55, v170, v171
	v_mfma_f32_32x32x16_bf16 v[96:111], v[154:157], v[120:123], v[96:111]
	ds_read_b128 v[146:149], v142 offset:16384
	ds_read_b128 v[150:153], v142 offset:20480
	ds_read_b128 v[154:157], v143 offset:16384
	ds_read_b128 v[210:213], v143 offset:20480
	s_waitcnt vmcnt(1)
	ds_write_b128 v161, v[128:131]
	s_waitcnt vmcnt(0)
	ds_write_b128 v161, v[132:135] offset:24576
	s_waitcnt lgkmcnt(0)
	s_barrier
	global_load_dwordx4 v[128:131], v[166:167], off
	v_mfma_f32_32x32x16_bf16 v[0:15], v[146:149], v[52:55], v[0:15]
	v_mfma_f32_32x32x16_bf16 v[32:47], v[150:153], v[52:55], v[32:47]
	v_mfma_f32_32x32x16_bf16 v[96:111], v[172:175], v[124:127], v[96:111]
	v_exp_f32_e32 v172, v56
	v_exp_f32_e32 v173, v57
	v_exp_f32_e32 v174, v58
	v_exp_f32_e32 v175, v59
	v_pk_add_f32 v[56:57], v[136:137], v[64:65]
	v_cvt_pk_bf16_f32 v52, v172, v173
	v_pk_add_f32 v[56:57], v[66:67], v[56:57]
	v_mfma_f32_32x32x16_bf16 v[80:95], v[176:179], v[124:127], v[80:95]
	v_exp_f32_e32 v176, v60
	v_exp_f32_e32 v177, v61
	v_exp_f32_e32 v178, v62
	v_exp_f32_e32 v179, v63
	v_cvt_pk_bf16_f32 v53, v174, v175
	v_cvt_pk_bf16_f32 v54, v176, v177
	v_pk_add_f32 v[56:57], v[68:69], v[56:57]
	v_cvt_pk_bf16_f32 v55, v178, v179
	v_pk_add_f32 v[56:57], v[138:139], v[56:57]
	s_nop 0
	v_mfma_f32_32x32x16_bf16 v[0:15], v[154:157], v[52:55], v[0:15]
	v_add_f32_e64 v56, v140, v56
	v_add_f32_e64 v57, v141, v57
	v_add_f32_e64 v56, v74, v56
	v_add_f32_e64 v57, v75, v57
	v_add_f32_e64 v56, v70, v56
	v_add_f32_e64 v57, v71, v57
	v_pk_add_f32 v[56:57], v[72:73], v[56:57]
	v_mfma_f32_32x32x16_bf16 v[32:47], v[210:213], v[52:55], v[32:47]
	v_lshl_add_u64 v[52:53], v[164:165], 0, s[98:99]
	global_load_dwordx4 v[132:135], v[52:53], off
	ds_read_b128 v[52:55], v144
	ds_read_b128 v[146:149], v145
	ds_read_b128 v[188:191], v142
	ds_read_b128 v[194:197], v143
	ds_read_b128 v[198:201], v144 offset:4096
	ds_read_b128 v[204:207], v145 offset:4096
	ds_read_b128 v[210:213], v142 offset:4096
	ds_read_b128 v[214:217], v143 offset:4096
	ds_read_b128 v[218:221], v144 offset:24576
	ds_read_b128 v[222:225], v144 offset:28672
	ds_read_b128 v[156:159], v145 offset:24576
	ds_read_b128 v[152:155], v145 offset:28672
	v_pk_add_f32 v[48:49], v[48:49], v[56:57]
	s_nop 0
	v_pk_add_f32 v[226:227], v[50:51], v[48:49]
	s_waitcnt lgkmcnt(11)
	v_mfma_f32_32x32x16_bf16 v[64:79], v[52:55], v[112:115], v[16:31]
	v_exp_f32_e32 v80, v80
	v_exp_f32_e32 v81, v81
	v_exp_f32_e32 v82, v82
	v_exp_f32_e32 v83, v83
	v_exp_f32_e32 v84, v84
	v_exp_f32_e32 v85, v85
	v_exp_f32_e32 v86, v86
	s_waitcnt lgkmcnt(10)
	v_mfma_f32_32x32x16_bf16 v[64:79], v[146:149], v[116:119], v[64:79]
	v_exp_f32_e32 v87, v87
	ds_read_b128 v[148:151], v142 offset:24576
	ds_read_b128 v[144:147], v142 offset:28672
	ds_read_b128 v[136:139], v143 offset:24576
	ds_read_b128 v[140:143], v143 offset:28672
	v_exp_f32_e32 v88, v88
	v_exp_f32_e32 v89, v89
	v_exp_f32_e32 v90, v90
	v_exp_f32_e32 v91, v91
	v_exp_f32_e32 v92, v92
	s_waitcnt lgkmcnt(13)
; DI unsigned pk2(float a, float b) { f32x2 v = {a, b}; bf2_t r = __builtin_convertvector(v, bf2_t); return __builtin_bit_cast(unsigned, r); }
; DI void attn_unit(const Params& p, int l, int b, int kvh, int qb, bool isctx, ldsp_t smem) {
;     ...
;     for (int t = 0; t < ntile; t += 2) {
;         ATT_STEP(t, sA, sB);
;         ATT_STEP(t + 1, sB, sA);
;     }
;     const float lrun = rs0 + rs1;
;     const float ltot = lrun + __shfl_xor(lrun, 32);
;     const float inv = 1.f / ltot;
; #pragma unroll
;     for (int dt = 0; dt < 2; ++dt)
; #pragma unroll
;         for (int g4 = 0; g4 < 4; ++g4) {
;             u32x2 w; w[0] = pk2(o[dt][4 * g4 + 0] * inv, o[dt][4 * g4 + 1] * inv); w[1] = pk2(o[dt][4 * g4 + 2] * inv, o[dt][4 * g4 + 3] * inv);
;             *(u32x2*)(Op + (size_t)r * DM + dt * 32 + 8 * g4 + 4 * hh) = w;
;         }
;     __syncthreads();
	v_mfma_f32_32x32x16_bf16 v[64:79], v[188:191], v[120:123], v[64:79]
	v_exp_f32_e32 v188, v96
	v_exp_f32_e32 v189, v97
	v_exp_f32_e32 v190, v98
	v_exp_f32_e32 v191, v99
	v_exp_f32_e32 v98, v106
	v_exp_f32_e32 v99, v107
	v_pk_add_f32 v[96:97], v[168:169], v[226:227]
	s_waitcnt lgkmcnt(12)
	v_mfma_f32_32x32x16_bf16 v[64:79], v[194:197], v[124:127], v[64:79]
	v_exp_f32_e32 v194, v100
	v_exp_f32_e32 v195, v101
	v_exp_f32_e32 v196, v102
	v_exp_f32_e32 v197, v103
	v_exp_f32_e32 v100, v108
	v_cvt_pk_bf16_f32 v106, v194, v195
	v_exp_f32_e32 v101, v109
	s_waitcnt lgkmcnt(11)
	v_mfma_f32_32x32x16_bf16 v[48:63], v[198:201], v[112:115], v[16:31]
	v_exp_f32_e32 v198, v104
	v_exp_f32_e32 v199, v105
	v_cvt_pk_bf16_f32 v104, v188, v189
	v_cvt_pk_bf16_f32 v105, v190, v191
	v_cvt_pk_bf16_f32 v107, v196, v197
	v_exp_f32_e32 v102, v110
	v_exp_f32_e32 v103, v111
	s_waitcnt lgkmcnt(7)
	v_mfma_f32_32x32x16_bf16 v[0:15], v[218:221], v[104:107], v[0:15]
	v_add_f32_e64 v96, v170, v96
	v_add_f32_e64 v97, v171, v97
	v_exp_f32_e32 v93, v93
	v_pk_add_f32 v[96:97], v[172:173], v[96:97]
	v_exp_f32_e32 v94, v94
	v_pk_add_f32 v[96:97], v[174:175], v[96:97]
	v_exp_f32_e32 v95, v95
	v_pk_add_f32 v[96:97], v[176:177], v[96:97]
	s_waitcnt lgkmcnt(6)
	v_mfma_f32_32x32x16_bf16 v[32:47], v[222:225], v[104:107], v[32:47]
	v_cvt_pk_bf16_f32 v104, v198, v199
	v_cvt_pk_bf16_f32 v105, v98, v99
	v_cvt_pk_bf16_f32 v106, v100, v101
	v_cvt_pk_bf16_f32 v107, v102, v103
	v_add_f32_e64 v96, v178, v96
	v_add_f32_e64 v97, v179, v97
	s_mov_b64 s[34:35], 0x80
	v_pk_add_f32 v[96:97], v[96:97], v[188:189]
	v_mfma_f32_32x32x16_bf16 v[48:63], v[204:207], v[116:119], v[48:63]
	v_add_f32_e64 v96, v190, v96
	v_add_f32_e64 v97, v191, v97
	s_mov_b32 s11, 3
	v_add_f32_e64 v96, v194, v96
	v_add_f32_e64 v97, v195, v97
	s_and_b64 vcc, exec, s[6:7]
	v_pk_add_f32 v[96:97], v[196:197], v[96:97]
	s_mov_b64 s[6:7], 0
	v_pk_add_f32 v[96:97], v[198:199], v[96:97]
	s_waitcnt lgkmcnt(5)
	v_mfma_f32_32x32x16_bf16 v[0:15], v[156:159], v[104:107], v[0:15]
	v_add_f32_e64 v96, v98, v96
	v_add_f32_e64 v97, v99, v97
	s_waitcnt vmcnt(1)
	ds_write_b128 v161, v[128:131] offset:8192
	s_waitcnt vmcnt(0)
	ds_write_b128 v161, v[132:135] offset:16384
	v_pk_add_f32 v[96:97], v[100:101], v[96:97]
	s_nop 0
	v_pk_add_f32 v[96:97], v[102:103], v[96:97]
	s_waitcnt lgkmcnt(6)
	v_mfma_f32_32x32x16_bf16 v[32:47], v[152:155], v[104:107], v[32:47]
	v_cvt_pk_bf16_f32 v104, v80, v81
	v_cvt_pk_bf16_f32 v105, v82, v83
	v_cvt_pk_bf16_f32 v106, v84, v85
	v_cvt_pk_bf16_f32 v107, v86, v87
	v_add_f32_e64 v80, v80, v96
	v_add_f32_e64 v81, v81, v97
	v_pk_add_f32 v[80:81], v[82:83], v[80:81]
	v_mfma_f32_32x32x16_bf16 v[48:63], v[210:213], v[120:123], v[48:63]
	v_add_f32_e64 v80, v84, v80
	v_add_f32_e64 v81, v85, v81
	v_add_f32_e64 v80, v86, v80
	v_add_f32_e64 v81, v87, v81
	v_add_f32_e64 v80, v88, v80
	v_add_f32_e64 v81, v89, v81
	v_pk_add_f32 v[80:81], v[90:91], v[80:81]
	s_waitcnt lgkmcnt(5)
	v_mfma_f32_32x32x16_bf16 v[0:15], v[148:151], v[104:107], v[0:15]
	v_add_f32_e64 v80, v92, v80
	v_add_f32_e64 v81, v93, v81
	s_waitcnt lgkmcnt(4)
	v_mfma_f32_32x32x16_bf16 v[32:47], v[144:147], v[104:107], v[32:47]
	v_cvt_pk_bf16_f32 v104, v88, v89
	v_cvt_pk_bf16_f32 v105, v90, v91
	v_cvt_pk_bf16_f32 v106, v92, v93
	v_cvt_pk_bf16_f32 v107, v94, v95
	v_mfma_f32_32x32x16_bf16 v[48:63], v[214:217], v[124:127], v[48:63]
	s_waitcnt lgkmcnt(3)
	v_mfma_f32_32x32x16_bf16 v[0:15], v[136:139], v[104:107], v[0:15]
	v_add_f32_e64 v136, v94, v80
	v_add_f32_e64 v137, v95, v81
	s_waitcnt lgkmcnt(2)
	v_mfma_f32_32x32x16_bf16 v[32:47], v[140:143], v[104:107], v[32:47]
	s_cbranch_vccnz .LBB0_169
	v_lshl_add_u32 v16, s10, 8, v160
	v_add_u32_e32 v16, 0x4000, v16
	v_ashrrev_i32_e32 v17, 31, v16
	v_lshlrev_b64 v[16:17], 11, v[16:17]
	v_lshlrev_b32_e32 v18, 6, v182
	v_lshl_add_u64 v[16:17], s[18:19], 0, v[16:17]
	v_ashrrev_i32_e32 v19, 31, v18
	v_cmp_lt_i32_e32 vcc, v209, v203
	v_lshl_add_u64 v[16:17], v[18:19], 1, v[16:17]
	v_add_f32_e32 v18, v137, v136
	v_cndmask_b32_e32 v19, v202, v209, vcc
	v_lshlrev_b32_e32 v19, 2, v19
	ds_bpermute_b32 v19, v19, v18
	v_lshlrev_b32_e32 v192, 11, v181
	v_lshl_add_u64 v[16:17], v[16:17], 0, v[192:193]
	v_lshlrev_b32_e32 v192, 3, v180
	v_lshl_add_u64 v[16:17], v[16:17], 0, v[192:193]
	s_waitcnt lgkmcnt(0)
	v_add_f32_e32 v18, v18, v19
	v_div_scale_f32 v19, s[6:7], v18, v18, 1.0
	v_rcp_f32_e32 v20, v19
	s_nop 0
	v_fma_f32 v21, -v19, v20, 1.0
	v_fmac_f32_e32 v20, v21, v20
	v_div_scale_f32 v21, vcc, 1.0, v18, 1.0
	v_mul_f32_e32 v22, v21, v20
	v_fma_f32 v23, -v19, v22, v21
	v_fmac_f32_e32 v22, v23, v20
	v_fma_f32 v19, -v19, v22, v21
	v_div_fmas_f32 v19, v19, v20, v22
	v_div_fixup_f32 v18, v19, v18, 1.0
	v_pk_mul_f32 v[0:1], v[0:1], v[18:19] op_sel_hi:[1,0]
	v_pk_mul_f32 v[2:3], v[2:3], v[18:19] op_sel_hi:[1,0]
	v_cvt_pk_bf16_f32 v0, v0, v1
	v_cvt_pk_bf16_f32 v1, v2, v3
	global_store_dwordx2 v[16:17], v[0:1], off sc1
	v_pk_mul_f32 v[0:1], v[4:5], v[18:19] op_sel_hi:[1,0]
	v_pk_mul_f32 v[2:3], v[6:7], v[18:19] op_sel_hi:[1,0]
	v_cvt_pk_bf16_f32 v0, v0, v1
	v_cvt_pk_bf16_f32 v1, v2, v3
	global_store_dwordx2 v[16:17], v[0:1], off offset:16 sc1
	v_pk_mul_f32 v[0:1], v[8:9], v[18:19] op_sel_hi:[1,0]
	v_pk_mul_f32 v[2:3], v[10:11], v[18:19] op_sel_hi:[1,0]
	v_cvt_pk_bf16_f32 v0, v0, v1
	v_cvt_pk_bf16_f32 v1, v2, v3
	global_store_dwordx2 v[16:17], v[0:1], off offset:32 sc1
	v_pk_mul_f32 v[0:1], v[12:13], v[18:19] op_sel_hi:[1,0]
	v_pk_mul_f32 v[2:3], v[14:15], v[18:19] op_sel_hi:[1,0]
	v_cvt_pk_bf16_f32 v0, v0, v1
	v_cvt_pk_bf16_f32 v1, v2, v3
	global_store_dwordx2 v[16:17], v[0:1], off offset:48 sc1
	v_pk_mul_f32 v[0:1], v[32:33], v[18:19] op_sel_hi:[1,0]
	v_pk_mul_f32 v[2:3], v[34:35], v[18:19] op_sel_hi:[1,0]
	v_cvt_pk_bf16_f32 v0, v0, v1
	v_cvt_pk_bf16_f32 v1, v2, v3
	global_store_dwordx2 v[16:17], v[0:1], off offset:64 sc1
	v_pk_mul_f32 v[0:1], v[36:37], v[18:19] op_sel_hi:[1,0]
	v_pk_mul_f32 v[2:3], v[38:39], v[18:19] op_sel_hi:[1,0]
	v_cvt_pk_bf16_f32 v0, v0, v1
	v_cvt_pk_bf16_f32 v1, v2, v3
	global_store_dwordx2 v[16:17], v[0:1], off offset:80 sc1
	v_pk_mul_f32 v[0:1], v[40:41], v[18:19] op_sel_hi:[1,0]
	v_pk_mul_f32 v[2:3], v[42:43], v[18:19] op_sel_hi:[1,0]
	v_cvt_pk_bf16_f32 v0, v0, v1
	v_cvt_pk_bf16_f32 v1, v2, v3
	global_store_dwordx2 v[16:17], v[0:1], off offset:96 sc1
	v_pk_mul_f32 v[0:1], v[44:45], v[18:19] op_sel_hi:[1,0]
	v_pk_mul_f32 v[2:3], v[46:47], v[18:19] op_sel_hi:[1,0]
	v_cvt_pk_bf16_f32 v0, v0, v1
	v_cvt_pk_bf16_f32 v1, v2, v3
	global_store_dwordx2 v[16:17], v[0:1], off offset:112 sc1
	s_barrier
	s_load_dword s6, s[88:89], 0x0
	s_waitcnt lgkmcnt(0)
	s_add_i32 s9, s6, s9
	s_cmp_lt_i32 s9, 32
	s_cbranch_scc1 .LBB0_168
	s_movk_i32 s6, 0x220

; #define LDSP __attribute__((address_space(3)))
; DI void gmlp_unit(const Params& p, int l, int T, int g, ldsp_t smem) {
;     ...
;     {
;         const int q = tid >> 2, part = tid & 3;
;         const bf16_t* src = p.U + (size_t)(T * 128 + q) * 1024 + 512 + g * 128 + part * 32;
;         u32x4 raw[4];
; #pragma unroll
;         for (int i = 0; i < 4; ++i) raw[i] = *(const u32x4*)(src + i * 8);
;         float a = 0.f, b = 0.f;
; #pragma unroll
;         for (int i = 0; i < 4; ++i)
; #pragma unroll
;             for (int j = 0; j < 4; ++j) {
;                 const float lo = __uint_as_float(raw[i][j] << 16), hi = __uint_as_float(raw[i][j] & 0xffff0000u);
;                 a += lo + hi; b += lo * lo + hi * hi;
;             }
;         a += __shfl_xor(a, 1); a += __shfl_xor(a, 2);
;         b += __shfl_xor(b, 1); b += __shfl_xor(b, 2);
;         const float mean = a * (1.f / 128.f);
;         const float rstd = rsqrtf(fmaxf(b * (1.f / 128.f) - mean * mean, 0.f) + EPS);
;         const float* gn = p.gmlp_norm_g + l * 512 + g * 128 + part * 32;
;     ...
;     const bf16_t* wsp = p.ws_bf + ((size_t)(l * 4 + g) * 128 + prow) * 128 + fq * 8;
;     bf16x8 a[4];
; #pragma unroll
;     for (int ks = 0; ks < 4; ++ks) a[ks] = *(const bf16x8*)(wsp + ks * 32);
;     f32x4 acc[8];
; #pragma unroll
;     for (int n = 0; n < 8; ++n) {
;         acc[n] = (f32x4){0.f, 0.f, 0.f, 0.f};
;         const int c = n * 16 + fr;
; #pragma unroll
;         for (int ks = 0; ks < 4; ++ks) {
;             const bf16x8 bq = *(const LDSP bf16x8*)(smem + c * 256 + (((ks * 4 + fq) ^ (c & 15)) << 4));
;             acc[n] = __builtin_amdgcn_mfma_f32_16x16x32_bf16(bq, a[ks], acc[n], 0, 0, 0);
;         }
;     }
;     const float bs = p.b_spatial[(size_t)(l * 4 + g) * 128 + prow];
;     const int row = T * 128 + prow;
;     const bf16_t* up = p.U + (size_t)row * 1024 + g * 128 + fq * 4;
.LBB0_174:
	v_mov_b32_e32 v46, v252
	s_lshl_b32 s4, s11, 5
	s_and_b32 s31, s4, 0xffffff80
	v_ashrrev_i32_e32 v47, 2, v46
	v_add_u32_e32 v0, s31, v47
	v_ashrrev_i32_e32 v1, 31, v0
	s_and_b32 s34, s11, 3
	v_lshlrev_b64 v[0:1], 11, v[0:1]
	v_lshlrev_b32_e32 v2, 5, v46
	v_lshl_add_u64 v[0:1], s[16:17], 0, v[0:1]
	s_lshl_b32 s98, s34, 8
	v_and_b32_e32 v36, 0x60, v2
	v_lshl_add_u64 v[0:1], v[0:1], 0, s[98:99]
	v_lshlrev_b32_e32 v192, 1, v36
	s_waitcnt lgkmcnt(0)
	v_lshl_add_u64 v[4:5], v[0:1], 0, v[192:193]
	global_load_dwordx4 v[0:3], v[4:5], off offset:1072
	global_load_dwordx4 v[10:13], v[4:5], off offset:1056
	global_load_dwordx4 v[22:25], v[4:5], off offset:1040
	global_load_dwordx4 v[38:41], v[4:5], off offset:1024
	v_cmp_lt_i32_e32 vcc, v134, v203
	v_lshlrev_b32_e32 v64, 2, v36
	v_lshlrev_b32_e32 v57, 8, v36
	v_ashrrev_i32_e32 v36, 1, v46
	v_and_b32_e32 v58, -16, v36
	v_add_u32_e32 v36, v57, v58
	s_lshl_b32 s4, s34, 9
	s_add_u32 s4, s9, s4
	s_addc_u32 s5, s10, 0
	s_movk_i32 s35, 0x50
	s_brev_b32 s36, 60
	v_lshrrev_b32_e32 v44, 4, v46
	v_and_b32_e32 v45, 15, v46
	s_waitcnt vmcnt(3)
	v_lshlrev_b32_e32 v4, 16, v2
	v_and_b32_e32 v26, 0xffff0000, v2
	v_lshlrev_b32_e32 v5, 16, v3
	v_and_b32_e32 v27, 0xffff0000, v3
	v_mov_b32_e32 v28, v4
	v_mov_b32_e32 v29, v26
	v_mul_f32_e32 v2, v26, v26
	v_pk_fma_f32 v[30:31], v[28:29], v[28:29], v[2:3] op_sel_hi:[1,1,0]
	v_pk_add_f32 v[2:3], v[4:5], v[26:27]
	v_mov_b32_e32 v26, v5
	v_mul_f32_e32 v4, v27, v27
	v_pk_fma_f32 v[32:33], v[26:27], v[26:27], v[4:5] op_sel_hi:[1,1,0]
	v_cndmask_b32_e32 v4, v202, v134, vcc
	v_cmp_lt_i32_e32 vcc, v135, v203
	v_lshlrev_b32_e32 v62, 2, v4
	s_waitcnt vmcnt(0)
	v_and_b32_e32 v5, 0xffff0000, v38
	v_cndmask_b32_e32 v4, v202, v135, vcc
	v_lshlrev_b32_e32 v63, 2, v4
	v_lshlrev_b32_e32 v4, 1, v47
	v_and_b32_e32 v56, 14, v4
	v_or_b32_e32 v65, v36, v56
	v_xad_u32 v36, v58, 16, v57
	v_lshlrev_b32_e32 v34, 16, v38
	v_and_b32_e32 v4, s0, v38
	v_mov_b32_e32 v35, v5
	v_or_b32_e32 v66, v36, v56
	v_lshlrev_b32_e32 v36, 16, v39
	v_and_b32_e32 v37, 0xffff0000, v39
	v_pk_add_f32 v[42:43], v[34:35], v[4:5] op_sel_hi:[0,1]
	v_pk_mul_f32 v[38:39], v[36:37], v[36:37]
	v_pk_mul_f32 v[48:49], v[34:35], v[34:35]
	v_mov_b32_e32 v42, v38
	v_mov_b32_e32 v192, v39
	v_pk_add_f32 v[38:39], v[42:43], v[192:193]
	v_mov_b32_e32 v42, v48
	v_mov_b32_e32 v43, v36
	v_mov_b32_e32 v48, v49
	v_mov_b32_e32 v49, v37
	v_mov_b32_e32 v31, v2
	v_mov_b32_e32 v33, v3
	global_load_dwordx4 v[2:5], v64, s[4:5] offset:48
	global_load_dwordx4 v[6:9], v64, s[4:5] offset:32
	global_load_dwordx4 v[14:17], v64, s[4:5] offset:16
	global_load_dwordx4 v[18:21], v64, s[4:5]
	global_load_dwordx4 v[84:87], v64, s[4:5] offset:112
	global_load_dwordx4 v[88:91], v64, s[4:5] offset:96
	global_load_dwordx4 v[92:95], v64, s[4:5] offset:80
	global_load_dwordx4 v[96:99], v64, s[4:5] offset:64
	s_or_b32 s100, s34, s7
	s_lshl_b32 s100, s100, 7
	v_lshrrev_b32_e32 v116, 2, v252
	v_bfi_b32 v116, -16, v116, v252
	v_add_u32_e32 v117, s100, v116
	v_bfe_u32 v118, v252, 4, 2
	v_lshlrev_b32_e32 v119, 8, v117
	v_lshl_add_u32 v119, v118, 4, v119
	global_load_dwordx4 v[140:143], v119, s[64:65]
	global_load_dwordx4 v[144:147], v119, s[64:65] offset:64
	global_load_dwordx4 v[148:151], v119, s[64:65] offset:128
	global_load_dwordx4 v[152:155], v119, s[64:65] offset:192
	v_lshlrev_b32_e32 v117, 2, v117
	v_readlane_b32 s100, v253, 11
	v_readlane_b32 s101, v253, 12
	s_nop 4
	global_load_dword v156, v117, s[100:101]
	v_lshrrev_b32_e32 v120, 6, v252
	v_lshl_add_u32 v123, v120, 4, v118
	v_add_u32_e32 v123, s31, v123
	v_lshlrev_b32_e32 v123, 11, v123
	v_and_b32_e32 v128, 15, v252
	v_lshl_add_u32 v123, v128, 4, v123
	v_add_u32_e32 v124, s98, v123
	v_add_u32_e32 v125, 0x2000, v124
	v_add_u32_e32 v126, 0x4000, v124
	v_add_u32_e32 v127, 0x6000, v124
	global_load_dwordx4 v[168:171], v124, s[16:17]
	global_load_dwordx4 v[172:175], v125, s[16:17]
	global_load_dwordx4 v[176:179], v126, s[16:17]
	global_load_dwordx4 v[180:183], v127, s[16:17]
	v_mul_u32_u24_e32 v129, 0x1200, v120
	v_mul_u32_u24_e32 v130, 0x110, v118
	v_add_u32_e32 v121, v129, v130
	v_add_u32_e32 v121, 0x8000, v121
	v_lshl_add_u32 v121, v128, 4, v121
	v_mul_u32_u24_e32 v130, 0x110, v128
	v_add_u32_e32 v122, v129, v130
	v_add_u32_e32 v122, 0x8000, v122
	v_lshl_add_u32 v122, v118, 3, v122
	v_pk_add_f32 v[42:43], v[42:43], v[48:49]
	s_nop 0
	v_pk_add_f32 v[42:43], v[42:43], v[38:39]
	v_xad_u32 v38, v58, 32, v57
	v_or_b32_e32 v67, v38, v56
	v_xad_u32 v38, v58, 48, v57
	v_or_b32_e32 v68, v38, v56
	v_lshlrev_b32_e32 v38, 16, v40
	v_and_b32_e32 v39, 0xffff0000, v40
	v_pk_mul_f32 v[48:49], v[38:39], v[38:39]
	v_xad_u32 v40, v58, 64, v57
	v_mov_b32_e32 v50, v48
	v_mov_b32_e32 v51, v38
	v_mov_b32_e32 v48, v49
	v_mov_b32_e32 v49, v39
	v_or_b32_e32 v69, v40, v56
	v_xad_u32 v40, v58, s35, v57
	v_pk_add_f32 v[48:49], v[50:51], v[48:49]
	v_or_b32_e32 v70, v40, v56
	v_lshlrev_b32_e32 v40, 16, v41
	v_and_b32_e32 v41, 0xffff0000, v41
	v_pk_add_f32 v[42:43], v[48:49], v[42:43]
	v_pk_mul_f32 v[48:49], v[40:41], v[40:41]
	v_mov_b32_e32 v51, v40
	v_mov_b32_e32 v50, v48
	v_mov_b32_e32 v48, v49
	v_mov_b32_e32 v49, v41
	v_pk_add_f32 v[48:49], v[50:51], v[48:49]
	s_movk_i32 s35, 0x60
	v_pk_add_f32 v[48:49], v[48:49], v[42:43]
	v_xad_u32 v42, v58, s35, v57
	v_or_b32_e32 v71, v42, v56
	v_xad_u32 v42, v58, s14, v57
	v_or_b32_e32 v72, v42, v56
	v_lshlrev_b32_e32 v42, 16, v22
	v_and_b32_e32 v43, 0xffff0000, v22
	v_pk_mul_f32 v[50:51], v[42:43], v[42:43]
	v_xad_u32 v22, v58, s8, v57
	s_movk_i32 s35, 0x90
	v_mov_b32_e32 v52, v50
	v_mov_b32_e32 v53, v42
	v_mov_b32_e32 v50, v51
	v_mov_b32_e32 v51, v43
	v_or_b32_e32 v73, v22, v56
; DI void gmlp_unit(const Params& p, int l, int T, int g, ldsp_t smem) {
;     ...
;         float a = 0.f, b = 0.f;
; #pragma unroll
;         for (int i = 0; i < 4; ++i)
; #pragma unroll
;             for (int j = 0; j < 4; ++j) {
;                 const float lo = __uint_as_float(raw[i][j] << 16), hi = __uint_as_float(raw[i][j] & 0xffff0000u);
;                 a += lo + hi; b += lo * lo + hi * hi;
;             }
;         a += __shfl_xor(a, 1); a += __shfl_xor(a, 2);
;         b += __shfl_xor(b, 1); b += __shfl_xor(b, 2);
;         const float mean = a * (1.f / 128.f);
;         const float rstd = rsqrtf(fmaxf(b * (1.f / 128.f) - mean * mean, 0.f) + EPS);
	v_xad_u32 v22, v58, s35, v57
	v_pk_add_f32 v[50:51], v[52:53], v[50:51]
	v_or_b32_e32 v74, v22, v56
	v_lshlrev_b32_e32 v22, 16, v23
	v_and_b32_e32 v23, 0xffff0000, v23
	v_pk_add_f32 v[48:49], v[50:51], v[48:49]
	v_pk_mul_f32 v[50:51], v[22:23], v[22:23]
	v_mov_b32_e32 v53, v22
	v_mov_b32_e32 v52, v50
	v_mov_b32_e32 v50, v51
	v_mov_b32_e32 v51, v23
	v_pk_add_f32 v[50:51], v[52:53], v[50:51]
	s_movk_i32 s35, 0xa0
	v_pk_add_f32 v[48:49], v[50:51], v[48:49]
	v_xad_u32 v50, v58, s35, v57
	s_movk_i32 s35, 0xb0
	v_or_b32_e32 v75, v50, v56
	v_xad_u32 v50, v58, s35, v57
	v_or_b32_e32 v76, v50, v56
	v_lshlrev_b32_e32 v50, 16, v24
	v_and_b32_e32 v51, 0xffff0000, v24
	v_pk_mul_f32 v[52:53], v[50:51], v[50:51]
	v_xad_u32 v24, v58, s15, v57
	s_movk_i32 s35, 0xd0
	v_mov_b32_e32 v54, v52
	v_mov_b32_e32 v55, v50
	v_mov_b32_e32 v52, v53
	v_mov_b32_e32 v53, v51
	v_or_b32_e32 v77, v24, v56
	v_xad_u32 v24, v58, s35, v57
	v_pk_add_f32 v[52:53], v[54:55], v[52:53]
	v_or_b32_e32 v78, v24, v56
	v_lshlrev_b32_e32 v24, 16, v25
	v_and_b32_e32 v25, 0xffff0000, v25
	v_pk_add_f32 v[48:49], v[52:53], v[48:49]
	v_pk_mul_f32 v[52:53], v[24:25], v[24:25]
	v_mov_b32_e32 v55, v24
	v_mov_b32_e32 v54, v52
	v_mov_b32_e32 v52, v53
	v_mov_b32_e32 v53, v25
	v_pk_add_f32 v[52:53], v[54:55], v[52:53]
	s_movk_i32 s35, 0xe0
	v_pk_add_f32 v[48:49], v[52:53], v[48:49]
	v_xad_u32 v52, v58, s35, v57
	s_movk_i32 s35, 0xf0
	v_or_b32_e32 v79, v52, v56
	v_xad_u32 v52, v58, s35, v57
	v_or_b32_e32 v80, v52, v56
	v_lshlrev_b32_e32 v52, 16, v10
	v_and_b32_e32 v53, 0xffff0000, v10
	v_pk_mul_f32 v[54:55], v[52:53], v[52:53]
	v_mov_b32_e32 v57, v52
	v_mov_b32_e32 v56, v54
	v_mov_b32_e32 v54, v55
	v_mov_b32_e32 v55, v53
	v_pk_add_f32 v[54:55], v[56:57], v[54:55]
	s_nop 0
	v_pk_add_f32 v[48:49], v[54:55], v[48:49]
	v_lshlrev_b32_e32 v54, 16, v11
	v_and_b32_e32 v55, 0xffff0000, v11
	v_pk_mul_f32 v[10:11], v[54:55], v[54:55]
	v_mov_b32_e32 v57, v54
	v_mov_b32_e32 v56, v10
	v_mov_b32_e32 v10, v11
	v_mov_b32_e32 v11, v55
	v_pk_add_f32 v[10:11], v[56:57], v[10:11]
	s_nop 0
	v_pk_add_f32 v[10:11], v[10:11], v[48:49]
	v_lshlrev_b32_e32 v48, 16, v12
	v_and_b32_e32 v49, 0xffff0000, v12
	v_pk_mul_f32 v[56:57], v[48:49], v[48:49]
	v_mov_b32_e32 v59, v48
	v_mov_b32_e32 v58, v56
	v_mov_b32_e32 v56, v57
	v_mov_b32_e32 v57, v49
	v_pk_add_f32 v[56:57], v[58:59], v[56:57]
	s_nop 0
	v_pk_add_f32 v[10:11], v[56:57], v[10:11]
	v_lshlrev_b32_e32 v56, 16, v13
	v_and_b32_e32 v57, 0xffff0000, v13
	v_pk_mul_f32 v[12:13], v[56:57], v[56:57]
	v_mov_b32_e32 v59, v56
	v_mov_b32_e32 v58, v12
	v_mov_b32_e32 v12, v13
	v_mov_b32_e32 v13, v57
	v_pk_add_f32 v[12:13], v[58:59], v[12:13]
	v_lshlrev_b32_e32 v58, 16, v0
	v_and_b32_e32 v59, 0xffff0000, v0
	v_pk_add_f32 v[10:11], v[12:13], v[10:11]
	v_pk_mul_f32 v[12:13], v[58:59], v[58:59]
	v_mov_b32_e32 v61, v58
	v_mov_b32_e32 v60, v12
	v_mov_b32_e32 v12, v13
	v_mov_b32_e32 v13, v59
	v_pk_add_f32 v[12:13], v[60:61], v[12:13]
	v_lshlrev_b32_e32 v60, 16, v1
	v_and_b32_e32 v61, 0xffff0000, v1
	v_pk_mul_f32 v[0:1], v[60:61], v[60:61]
	v_pk_add_f32 v[10:11], v[12:13], v[10:11]
	v_mov_b32_e32 v12, v0
	v_mov_b32_e32 v13, v60
	v_mov_b32_e32 v0, v1
	v_mov_b32_e32 v1, v61
	v_pk_add_f32 v[0:1], v[12:13], v[0:1]
	s_nop 0
	v_pk_add_f32 v[0:1], v[0:1], v[10:11]
	s_nop 0
	v_pk_add_f32 v[0:1], v[30:31], v[0:1]
	s_nop 0
	v_pk_add_f32 v[0:1], v[32:33], v[0:1]
	ds_bpermute_b32 v11, v62, v1
	ds_bpermute_b32 v10, v62, v0
	s_waitcnt lgkmcnt(0)
	v_pk_add_f32 v[0:1], v[0:1], v[10:11]
	ds_bpermute_b32 v11, v63, v1
	ds_bpermute_b32 v10, v63, v0
	s_waitcnt lgkmcnt(0)
	v_pk_add_f32 v[0:1], v[0:1], v[10:11]
	s_nop 0
	v_pk_mul_f32 v[30:31], v[0:1], s[36:37] op_sel_hi:[1,0]
	v_readlane_b32 s36, v253, 3
	v_fma_f32 v0, -v31, v31, v30
	v_max_f32_e32 v0, 0, v0
	v_add_f32_e32 v0, 0x358637bd, v0
	v_cmp_gt_f32_e32 vcc, s92, v0
	v_mul_f32_e32 v1, 0x4b800000, v0
	v_readlane_b32 s44, v253, 11
	v_cndmask_b32_e32 v0, v0, v1, vcc
	v_rsq_f32_e32 v0, v0
	v_readlane_b32 s45, v253, 12
	v_readlane_b32 s37, v253, 4
	v_readlane_b32 s38, v253, 5
	v_mul_f32_e32 v1, 0x45800000, v0
	v_cndmask_b32_e32 v32, v0, v1, vcc
	v_pk_add_f32 v[0:1], v[34:35], v[30:31] op_sel:[0,1] neg_lo:[0,1] neg_hi:[0,1]
	v_bfi_b32 v34, -16, v47, v46
	v_pk_mul_f32 v[0:1], v[0:1], v[32:33] op_sel_hi:[1,0]
	v_ashrrev_i32_e32 v35, 31, v34
	s_waitcnt vmcnt(13)
; #define LDSP __attribute__((address_space(3)))
; DI unsigned pk2(float a, float b) { f32x2 v = {a, b}; bf2_t r = __builtin_convertvector(v, bf2_t); return __builtin_bit_cast(unsigned, r); }
; DI void gmlp_unit(const Params& p, int l, int T, int g, ldsp_t smem) {
;     ...
;         const float* gn = p.gmlp_norm_g + l * 512 + g * 128 + part * 32;
; #pragma unroll
;         for (int i = 0; i < 4; ++i)
; #pragma unroll
;             for (int j = 0; j < 4; ++j) {
;                 const int c0 = part * 32 + i * 8 + j * 2;
;                 const float lo = __uint_as_float(raw[i][j] << 16), hi = __uint_as_float(raw[i][j] & 0xffff0000u);
;                 const unsigned w = pk2((lo - mean) * rstd * gn[i * 8 + j * 2], (hi - mean) * rstd * gn[i * 8 + j * 2 + 1]);
;                 *(LDSP bf16_t*)(smem + c0 * 256 + (((q >> 3) ^ (c0 & 15)) << 4) + (q & 7) * 2) = (bf16_t)(w & 0xffffu);
;                 *(LDSP bf16_t*)(smem + (c0 + 1) * 256 + (((q >> 3) ^ ((c0 + 1) & 15)) << 4) + (q & 7) * 2) = (bf16_t)(w >> 16);
;             }
	v_pk_mul_f32 v[0:1], v[18:19], v[0:1]
	v_readlane_b32 s39, v253, 6
	v_cvt_pk_bf16_f32 v0, v0, v1
	ds_write_b16 v65, v0
	ds_write_b16_d16_hi v66, v0 offset:256
	v_pk_add_f32 v[0:1], v[36:37], v[30:31] op_sel:[0,1] neg_lo:[0,1] neg_hi:[0,1]
	v_readlane_b32 s40, v253, 7
	v_pk_mul_f32 v[0:1], v[0:1], v[32:33] op_sel_hi:[1,0]
	v_readlane_b32 s41, v253, 8
	v_pk_mul_f32 v[0:1], v[20:21], v[0:1]
	v_readlane_b32 s42, v253, 9
	v_cvt_pk_bf16_f32 v0, v0, v1
	ds_write_b16 v67, v0 offset:512
	ds_write_b16_d16_hi v68, v0 offset:768
	v_pk_add_f32 v[0:1], v[38:39], v[30:31] op_sel:[0,1] neg_lo:[0,1] neg_hi:[0,1]
	v_readlane_b32 s43, v253, 10
	v_pk_mul_f32 v[0:1], v[0:1], v[32:33] op_sel_hi:[1,0]
	v_readlane_b32 s46, v253, 13
	v_pk_mul_f32 v[0:1], v[14:15], v[0:1]
	v_readlane_b32 s47, v253, 14
	v_cvt_pk_bf16_f32 v0, v0, v1
	ds_write_b16 v69, v0 offset:1024
	ds_write_b16_d16_hi v70, v0 offset:1280
	v_pk_add_f32 v[0:1], v[40:41], v[30:31] op_sel:[0,1] neg_lo:[0,1] neg_hi:[0,1]
	v_readlane_b32 s48, v253, 15
	v_pk_mul_f32 v[0:1], v[0:1], v[32:33] op_sel_hi:[1,0]
	v_readlane_b32 s49, v253, 16
	v_pk_mul_f32 v[0:1], v[16:17], v[0:1]
	v_readlane_b32 s50, v253, 17
	v_cvt_pk_bf16_f32 v0, v0, v1
	ds_write_b16 v71, v0 offset:1536
	ds_write_b16_d16_hi v72, v0 offset:1792
	v_pk_add_f32 v[0:1], v[42:43], v[30:31] op_sel:[0,1] neg_lo:[0,1] neg_hi:[0,1]
	v_readlane_b32 s51, v253, 18
	v_pk_mul_f32 v[0:1], v[0:1], v[32:33] op_sel_hi:[1,0]
	s_nop 0
	v_pk_mul_f32 v[0:1], v[6:7], v[0:1]
	s_nop 0
	v_cvt_pk_bf16_f32 v0, v0, v1
	ds_write_b16 v73, v0 offset:2048
	ds_write_b16_d16_hi v74, v0 offset:2304
	v_pk_add_f32 v[0:1], v[22:23], v[30:31] op_sel:[0,1] neg_lo:[0,1] neg_hi:[0,1]
	s_nop 0
	v_pk_mul_f32 v[0:1], v[0:1], v[32:33] op_sel_hi:[1,0]
	s_nop 0
	v_pk_mul_f32 v[0:1], v[8:9], v[0:1]
	s_nop 0
	v_cvt_pk_bf16_f32 v0, v0, v1
	ds_write_b16 v75, v0 offset:2560
	ds_write_b16_d16_hi v76, v0 offset:2816
	v_pk_add_f32 v[0:1], v[50:51], v[30:31] op_sel:[0,1] neg_lo:[0,1] neg_hi:[0,1]
	s_nop 0
	v_pk_mul_f32 v[0:1], v[0:1], v[32:33] op_sel_hi:[1,0]
	s_nop 0
	v_pk_mul_f32 v[0:1], v[0:1], v[2:3]
	s_nop 0
	v_cvt_pk_bf16_f32 v0, v0, v1
	ds_write_b16 v77, v0 offset:3072
	ds_write_b16_d16_hi v78, v0 offset:3328
	v_pk_add_f32 v[0:1], v[24:25], v[30:31] op_sel:[0,1] neg_lo:[0,1] neg_hi:[0,1]
	s_nop 0
	v_pk_mul_f32 v[0:1], v[0:1], v[32:33] op_sel_hi:[1,0]
	s_nop 0
	v_pk_mul_f32 v[0:1], v[0:1], v[4:5]
	s_nop 0
	v_cvt_pk_bf16_f32 v0, v0, v1
	ds_write_b16 v79, v0 offset:3584
	ds_write_b16_d16_hi v80, v0 offset:3840
	v_pk_add_f32 v[0:1], v[52:53], v[30:31] op_sel:[0,1] neg_lo:[0,1] neg_hi:[0,1]
	s_nop 0
	v_pk_mul_f32 v[16:17], v[0:1], v[32:33] op_sel_hi:[1,0]
	s_nop 0
	s_nop 0
	s_nop 0
	s_nop 0
	s_or_b32 s4, s34, s7
	s_ashr_i32 s5, s4, 31
	s_lshl_b64 s[4:5], s[4:5], 7
	s_waitcnt vmcnt(9)
	v_pk_mul_f32 v[12:13], v[16:17], v[96:97]
	s_nop 0
	v_cvt_pk_bf16_f32 v12, v12, v13
	ds_write_b16 v65, v12 offset:4096
	ds_write_b16_d16_hi v66, v12 offset:4352
	v_pk_add_f32 v[12:13], v[54:55], v[30:31] op_sel:[0,1] neg_lo:[0,1] neg_hi:[0,1]
	s_nop 0
	v_pk_mul_f32 v[12:13], v[12:13], v[32:33] op_sel_hi:[1,0]
	s_nop 0
	v_pk_mul_f32 v[12:13], v[12:13], v[98:99]
	s_nop 0
	v_cvt_pk_bf16_f32 v12, v12, v13
	ds_write_b16 v67, v12 offset:4608
	ds_write_b16_d16_hi v68, v12 offset:4864
	v_pk_add_f32 v[12:13], v[48:49], v[30:31] op_sel:[0,1] neg_lo:[0,1] neg_hi:[0,1]
	s_nop 0
	v_pk_mul_f32 v[12:13], v[12:13], v[32:33] op_sel_hi:[1,0]
	s_nop 0
	v_pk_mul_f32 v[8:9], v[12:13], v[92:93]
	s_nop 0
	v_cvt_pk_bf16_f32 v8, v8, v9
	ds_write_b16 v69, v8 offset:5120
	ds_write_b16_d16_hi v70, v8 offset:5376
	v_pk_add_f32 v[8:9], v[56:57], v[30:31] op_sel:[0,1] neg_lo:[0,1] neg_hi:[0,1]
	s_nop 0
	v_pk_mul_f32 v[8:9], v[8:9], v[32:33] op_sel_hi:[1,0]
	s_nop 0
	v_pk_mul_f32 v[8:9], v[8:9], v[94:95]
	s_nop 0
	v_cvt_pk_bf16_f32 v8, v8, v9
	ds_write_b16 v71, v8 offset:5632
	ds_write_b16_d16_hi v72, v8 offset:5888
	v_pk_add_f32 v[8:9], v[58:59], v[30:31] op_sel:[0,1] neg_lo:[0,1] neg_hi:[0,1]
	s_nop 0
	v_pk_mul_f32 v[8:9], v[8:9], v[32:33] op_sel_hi:[1,0]
	s_nop 0
	v_pk_mul_f32 v[4:5], v[8:9], v[88:89]
	s_nop 0
	v_cvt_pk_bf16_f32 v4, v4, v5
	ds_write_b16 v73, v4 offset:6144
	ds_write_b16_d16_hi v74, v4 offset:6400
	v_pk_add_f32 v[4:5], v[60:61], v[30:31] op_sel:[0,1] neg_lo:[0,1] neg_hi:[0,1]
	s_nop 0
	v_pk_mul_f32 v[4:5], v[4:5], v[32:33] op_sel_hi:[1,0]
	s_nop 0
	v_pk_mul_f32 v[4:5], v[4:5], v[90:91]
	s_nop 0
	v_cvt_pk_bf16_f32 v4, v4, v5
	ds_write_b16 v75, v4 offset:6656
	ds_write_b16_d16_hi v76, v4 offset:6912
	v_pk_add_f32 v[4:5], v[28:29], v[30:31] op_sel:[0,1] neg_lo:[0,1] neg_hi:[0,1]
	s_nop 0
	v_pk_mul_f32 v[4:5], v[4:5], v[32:33] op_sel_hi:[1,0]
	s_nop 0
	v_pk_mul_f32 v[0:1], v[4:5], v[84:85]
	v_bfe_u32 v4, v46, 4, 2
	v_cvt_pk_bf16_f32 v0, v0, v1
	ds_write_b16 v77, v0 offset:7168
	ds_write_b16_d16_hi v78, v0 offset:7424
	v_pk_add_f32 v[0:1], v[26:27], v[30:31] op_sel:[0,1] neg_lo:[0,1] neg_hi:[0,1]
	v_lshlrev_b32_e32 v5, 8, v45
	v_pk_mul_f32 v[0:1], v[0:1], v[32:33] op_sel_hi:[1,0]
	v_lshl_add_u64 v[32:33], s[4:5], 0, v[34:35]
	v_pk_mul_f32 v[0:1], v[0:1], v[86:87]
	v_lshlrev_b32_e32 v2, 4, v4
	v_cvt_pk_bf16_f32 v0, v0, v1
	ds_write_b16 v79, v0 offset:7680
	ds_write_b16_d16_hi v80, v0 offset:7936
	v_lshlrev_b64 v[0:1], 8, v[32:33]
	v_lshl_add_u64 v[0:1], s[64:65], 0, v[0:1]
	v_mov_b32_e32 v3, v193
	v_lshl_add_u64 v[6:7], v[0:1], 0, v[2:3]
	s_waitcnt lgkmcnt(0)
	s_barrier
; #define LDSP __attribute__((address_space(3)))
; DI void gmlp_unit(const Params& p, int l, int T, int g, ldsp_t smem) {
;     ...
;     const int prow = wid * 16 + fr;
;     const bf16_t* wsp = p.ws_bf + ((size_t)(l * 4 + g) * 128 + prow) * 128 + fq * 8;
;     bf16x8 a[4];
; #pragma unroll
;     for (int ks = 0; ks < 4; ++ks) a[ks] = *(const bf16x8*)(wsp + ks * 32);
;     f32x4 acc[8];
; #pragma unroll
;     for (int n = 0; n < 8; ++n) {
;         acc[n] = (f32x4){0.f, 0.f, 0.f, 0.f};
;         const int c = n * 16 + fr;
; #pragma unroll
;         for (int ks = 0; ks < 4; ++ks) {
;             const bf16x8 bq = *(const LDSP bf16x8*)(smem + c * 256 + (((ks * 4 + fq) ^ (c & 15)) << 4));
;             acc[n] = __builtin_amdgcn_mfma_f32_16x16x32_bf16(bq, a[ks], acc[n], 0, 0, 0);
;         }
;     }
	s_nop 0
	s_nop 0
	s_nop 0
	s_nop 0
	v_bitop3_b32 v6, v44, v45, 3 bitop3:0x6c
	v_lshl_or_b32 v35, v6, 4, v5
	ds_read_b128 v[6:9], v35
	v_bitop3_b32 v10, v4, v45, 4 bitop3:0x36
	v_lshl_or_b32 v44, v10, 4, v5
	ds_read_b128 v[10:13], v44
	s_waitcnt vmcnt(8) lgkmcnt(1)
	v_mfma_f32_16x16x32_bf16 v[6:9], v[6:9], v[140:143], 0
	v_lshlrev_b32_e32 v192, 3, v4
	ds_read_b128 v[50:53], v44 offset:24576
	v_add_u32_e32 v34, s31, v34
	s_waitcnt vmcnt(7) lgkmcnt(1)
	v_mfma_f32_16x16x32_bf16 v[6:9], v[10:13], v[144:147], v[6:9]
	v_bitop3_b32 v10, v4, v45, 8 bitop3:0x36
	v_lshl_or_b32 v54, v10, 4, v5
	ds_read_b128 v[10:13], v54
	v_bitop3_b32 v4, v4, v45, 12 bitop3:0x36
	v_lshl_or_b32 v45, v4, 4, v5
	s_waitcnt vmcnt(5) lgkmcnt(0)
	v_mfma_f32_16x16x32_bf16 v[6:9], v[10:13], v[148:151], v[6:9]
	ds_read_b128 v[10:13], v45
	v_lshl_add_u64 v[32:33], v[32:33], 2, s[44:45]
	s_nop 0
	s_waitcnt vmcnt(5) lgkmcnt(0)
	v_mfma_f32_16x16x32_bf16 v[28:31], v[10:13], v[152:155], v[6:9]
	s_nop 2
	ds_read_b128 v[4:7], v35 offset:4096
	ds_read_b128 v[8:11], v44 offset:4096
	s_waitcnt vmcnt(4)
	v_mov_b32_e32 v32, v156
	s_nop 1
	v_pk_add_f32 v[28:29], v[28:29], v[32:33] op_sel_hi:[1,0]
	s_waitcnt lgkmcnt(1)
	v_mfma_f32_16x16x32_bf16 v[4:7], v[4:7], v[140:143], 0
	v_add_f32_e64 v30, v30, v32
	v_add_f32_e64 v31, v31, v32
	s_waitcnt lgkmcnt(0)
	v_mfma_f32_16x16x32_bf16 v[4:7], v[8:11], v[144:147], v[4:7]
	ds_read_b128 v[8:11], v54 offset:4096
	s_waitcnt lgkmcnt(0)
	v_mfma_f32_16x16x32_bf16 v[4:7], v[8:11], v[148:151], v[4:7]
	ds_read_b128 v[8:11], v45 offset:4096
	s_waitcnt lgkmcnt(0)
	v_mfma_f32_16x16x32_bf16 v[24:27], v[8:11], v[152:155], v[4:7]
	s_nop 4
	ds_read_b128 v[4:7], v35 offset:8192
	ds_read_b128 v[8:11], v44 offset:8192
	s_nop 0
	v_pk_add_f32 v[24:25], v[24:25], v[32:33] op_sel_hi:[1,0]
	s_waitcnt lgkmcnt(1)
	v_mfma_f32_16x16x32_bf16 v[4:7], v[4:7], v[140:143], 0
	v_add_f32_e64 v26, v26, v32
	v_add_f32_e64 v27, v27, v32
	s_waitcnt lgkmcnt(0)
	v_mfma_f32_16x16x32_bf16 v[4:7], v[8:11], v[144:147], v[4:7]
	ds_read_b128 v[8:11], v54 offset:8192
	s_waitcnt lgkmcnt(0)
	v_mfma_f32_16x16x32_bf16 v[4:7], v[8:11], v[148:151], v[4:7]
	ds_read_b128 v[8:11], v45 offset:8192
	s_waitcnt lgkmcnt(0)
	v_mfma_f32_16x16x32_bf16 v[20:23], v[8:11], v[152:155], v[4:7]
	s_nop 4
	ds_read_b128 v[4:7], v35 offset:12288
	ds_read_b128 v[8:11], v44 offset:12288
	s_nop 0
	v_pk_add_f32 v[20:21], v[20:21], v[32:33] op_sel_hi:[1,0]
	s_waitcnt lgkmcnt(1)
	v_mfma_f32_16x16x32_bf16 v[4:7], v[4:7], v[140:143], 0
	v_add_f32_e64 v22, v22, v32
	v_add_f32_e64 v23, v23, v32
	s_waitcnt lgkmcnt(0)
	v_mfma_f32_16x16x32_bf16 v[4:7], v[8:11], v[144:147], v[4:7]
	ds_read_b128 v[8:11], v54 offset:12288
	s_waitcnt lgkmcnt(0)
	v_mfma_f32_16x16x32_bf16 v[4:7], v[8:11], v[148:151], v[4:7]
	ds_read_b128 v[8:11], v45 offset:12288
	s_waitcnt lgkmcnt(0)
	v_mfma_f32_16x16x32_bf16 v[16:19], v[8:11], v[152:155], v[4:7]
	s_nop 4
	ds_read_b128 v[4:7], v35 offset:16384
	ds_read_b128 v[8:11], v44 offset:16384
	s_nop 0
	v_pk_add_f32 v[16:17], v[16:17], v[32:33] op_sel_hi:[1,0]
	s_waitcnt lgkmcnt(1)
	v_mfma_f32_16x16x32_bf16 v[4:7], v[4:7], v[140:143], 0
	v_add_f32_e64 v18, v18, v32
	v_add_f32_e64 v19, v19, v32
	s_waitcnt lgkmcnt(0)
	v_mfma_f32_16x16x32_bf16 v[4:7], v[8:11], v[144:147], v[4:7]
	ds_read_b128 v[8:11], v54 offset:16384
	s_waitcnt lgkmcnt(0)
	v_mfma_f32_16x16x32_bf16 v[4:7], v[8:11], v[148:151], v[4:7]
	ds_read_b128 v[8:11], v45 offset:16384
	s_waitcnt lgkmcnt(0)
	v_mfma_f32_16x16x32_bf16 v[12:15], v[8:11], v[152:155], v[4:7]
	s_nop 4
	ds_read_b128 v[4:7], v35 offset:20480
	ds_read_b128 v[8:11], v44 offset:20480
	s_nop 0
	v_pk_add_f32 v[12:13], v[12:13], v[32:33] op_sel_hi:[1,0]
	s_waitcnt lgkmcnt(1)
	v_mfma_f32_16x16x32_bf16 v[4:7], v[4:7], v[140:143], 0
	v_add_f32_e64 v14, v14, v32
	v_add_f32_e64 v15, v15, v32
	s_waitcnt lgkmcnt(0)
	v_mfma_f32_16x16x32_bf16 v[4:7], v[8:11], v[144:147], v[4:7]
	ds_read_b128 v[8:11], v54 offset:20480
	s_waitcnt lgkmcnt(0)
	v_mfma_f32_16x16x32_bf16 v[4:7], v[8:11], v[148:151], v[4:7]
	ds_read_b128 v[8:11], v45 offset:20480
	s_waitcnt lgkmcnt(0)
	v_mfma_f32_16x16x32_bf16 v[8:11], v[8:11], v[152:155], v[4:7]
	s_nop 4
	ds_read_b128 v[4:7], v35 offset:24576
	s_nop 1
	v_pk_add_f32 v[8:9], v[8:9], v[32:33] op_sel_hi:[1,0]
	s_waitcnt lgkmcnt(0)
	v_mfma_f32_16x16x32_bf16 v[4:7], v[4:7], v[140:143], 0
	v_add_f32_e64 v10, v10, v32
	v_add_f32_e64 v11, v11, v32
	v_mfma_f32_16x16x32_bf16 v[4:7], v[50:53], v[144:147], v[4:7]
	ds_read_b128 v[50:53], v54 offset:24576
	s_waitcnt lgkmcnt(0)
	v_mfma_f32_16x16x32_bf16 v[4:7], v[50:53], v[148:151], v[4:7]
	ds_read_b128 v[50:53], v45 offset:24576
	s_waitcnt lgkmcnt(0)
	v_mfma_f32_16x16x32_bf16 v[4:7], v[50:53], v[152:155], v[4:7]
	ds_read_b128 v[50:53], v35 offset:28672
	v_ashrrev_i32_e32 v35, 31, v34
	s_nop 5
	v_pk_add_f32 v[4:5], v[4:5], v[32:33] op_sel_hi:[1,0]
	s_waitcnt lgkmcnt(0)
; DI unsigned pk2(float a, float b) { f32x2 v = {a, b}; bf2_t r = __builtin_convertvector(v, bf2_t); return __builtin_bit_cast(unsigned, r); }
; DI void gmlp_unit(const Params& p, int l, int T, int g, ldsp_t smem) {
;     ...
;     const float bs = p.b_spatial[(size_t)(l * 4 + g) * 128 + prow];
;     const int row = T * 128 + prow;
;     const bf16_t* up = p.U + (size_t)row * 1024 + g * 128 + fq * 4;
;     bf16_t* mp = p.MIX + (size_t)row * DM + 512 + g * 128 + fq * 4;
; #pragma unroll
;     for (int n = 0; n < 8; ++n) {
;         const u32x2 uu = *(const u32x2*)(up + n * 16);
;         const float u0 = __uint_as_float(uu[0] << 16), u1 = __uint_as_float(uu[0] & 0xffff0000u), u2 = __uint_as_float(uu[1] << 16), u3 = __uint_as_float(uu[1] & 0xffff0000u);
;         u32x2 w; w[0] = pk2((acc[n][0] + bs) * u0, (acc[n][1] + bs) * u1); w[1] = pk2((acc[n][2] + bs) * u2, (acc[n][3] + bs) * u3);
;         *(u32x2*)(mp + n * 16) = w;
;     }
	v_mfma_f32_16x16x32_bf16 v[0:3], v[50:53], v[140:143], 0
	ds_read_b128 v[50:53], v44 offset:28672
	v_pk_add_f32 v[6:7], v[6:7], v[32:33] op_sel_hi:[1,0]
	s_waitcnt lgkmcnt(0)
	v_mfma_f32_16x16x32_bf16 v[0:3], v[50:53], v[144:147], v[0:3]
	ds_read_b128 v[36:39], v54 offset:28672
	s_waitcnt lgkmcnt(0)
	v_mfma_f32_16x16x32_bf16 v[0:3], v[36:39], v[148:151], v[0:3]
	ds_read_b128 v[36:39], v45 offset:28672
	s_waitcnt lgkmcnt(0)
	v_mfma_f32_16x16x32_bf16 v[0:3], v[36:39], v[152:155], v[0:3]
	v_lshlrev_b64 v[36:37], 11, v[34:35]
	v_lshl_add_u64 v[34:35], s[16:17], 0, v[36:37]
	v_lshl_add_u64 v[34:35], v[34:35], 0, s[98:99]
	v_lshl_add_u64 v[34:35], v[34:35], 0, v[192:193]
	s_nop 0
	v_lshl_add_u64 v[36:37], s[18:19], 0, v[36:37]
	v_lshl_add_u64 v[36:37], v[36:37], 0, s[98:99]
	v_lshl_add_u64 v[36:37], v[36:37], 0, v[192:193]
	v_pk_add_f32 v[0:1], v[0:1], v[32:33] op_sel_hi:[1,0]
	v_pk_add_f32 v[2:3], v[2:3], v[32:33] op_sel_hi:[1,0]
	s_waitcnt vmcnt(0)
	ds_write_b128 v121, v[168:171]
	ds_write_b128 v121, v[172:175] offset:1088
	ds_write_b128 v121, v[176:179] offset:2176
	ds_write_b128 v121, v[180:183] offset:3264
	ds_read_b64 v[100:101], v122
	ds_read_b64 v[102:103], v122 offset:32
	ds_read_b64 v[104:105], v122 offset:64
	ds_read_b64 v[106:107], v122 offset:96
	ds_read_b64 v[108:109], v122 offset:128
	ds_read_b64 v[110:111], v122 offset:160
	ds_read_b64 v[112:113], v122 offset:192
	ds_read_b64 v[114:115], v122 offset:224
	s_waitcnt lgkmcnt(0)
	v_lshlrev_b32_e32 v160, 16, v100
	v_and_b32_e32 v161, 0xffff0000, v100
	v_lshlrev_b32_e32 v162, 16, v101
	v_and_b32_e32 v163, 0xffff0000, v101
	v_pk_mul_f32 v[28:29], v[28:29], v[160:161]
	v_pk_mul_f32 v[30:31], v[30:31], v[162:163]
	v_cvt_pk_bf16_f32 v28, v28, v29
	v_cvt_pk_bf16_f32 v29, v30, v31
	ds_write_b64 v122, v[28:29]
	v_lshlrev_b32_e32 v160, 16, v102
	v_and_b32_e32 v161, 0xffff0000, v102
	v_lshlrev_b32_e32 v162, 16, v103
	v_and_b32_e32 v163, 0xffff0000, v103
	v_pk_mul_f32 v[24:25], v[24:25], v[160:161]
	v_pk_mul_f32 v[26:27], v[26:27], v[162:163]
	v_cvt_pk_bf16_f32 v24, v24, v25
	v_cvt_pk_bf16_f32 v25, v26, v27
	ds_write_b64 v122, v[24:25] offset:32
	v_lshlrev_b32_e32 v160, 16, v104
	v_and_b32_e32 v161, 0xffff0000, v104
	v_lshlrev_b32_e32 v162, 16, v105
	v_and_b32_e32 v163, 0xffff0000, v105
	v_pk_mul_f32 v[20:21], v[20:21], v[160:161]
	v_pk_mul_f32 v[22:23], v[22:23], v[162:163]
	v_cvt_pk_bf16_f32 v20, v20, v21
	v_cvt_pk_bf16_f32 v21, v22, v23
	ds_write_b64 v122, v[20:21] offset:64
	v_lshlrev_b32_e32 v160, 16, v106
	v_and_b32_e32 v161, 0xffff0000, v106
	v_lshlrev_b32_e32 v162, 16, v107
	v_and_b32_e32 v163, 0xffff0000, v107
	v_pk_mul_f32 v[16:17], v[16:17], v[160:161]
	v_pk_mul_f32 v[18:19], v[18:19], v[162:163]
	v_cvt_pk_bf16_f32 v16, v16, v17
	v_cvt_pk_bf16_f32 v17, v18, v19
	ds_write_b64 v122, v[16:17] offset:96
	v_lshlrev_b32_e32 v160, 16, v108
	v_and_b32_e32 v161, 0xffff0000, v108
	v_lshlrev_b32_e32 v162, 16, v109
	v_and_b32_e32 v163, 0xffff0000, v109
	v_pk_mul_f32 v[12:13], v[12:13], v[160:161]
	v_pk_mul_f32 v[14:15], v[14:15], v[162:163]
	v_cvt_pk_bf16_f32 v12, v12, v13
	v_cvt_pk_bf16_f32 v13, v14, v15
	ds_write_b64 v122, v[12:13] offset:128
	v_lshlrev_b32_e32 v160, 16, v110
	v_and_b32_e32 v161, 0xffff0000, v110
	v_lshlrev_b32_e32 v162, 16, v111
	v_and_b32_e32 v163, 0xffff0000, v111
	v_pk_mul_f32 v[8:9], v[8:9], v[160:161]
	v_pk_mul_f32 v[10:11], v[10:11], v[162:163]
	v_cvt_pk_bf16_f32 v8, v8, v9
	v_cvt_pk_bf16_f32 v9, v10, v11
	ds_write_b64 v122, v[8:9] offset:160
	v_lshlrev_b32_e32 v160, 16, v112
	v_and_b32_e32 v161, 0xffff0000, v112
	v_lshlrev_b32_e32 v162, 16, v113
	v_and_b32_e32 v163, 0xffff0000, v113
	v_pk_mul_f32 v[4:5], v[4:5], v[160:161]
	v_pk_mul_f32 v[6:7], v[6:7], v[162:163]
	v_cvt_pk_bf16_f32 v4, v4, v5
	v_cvt_pk_bf16_f32 v5, v6, v7
	ds_write_b64 v122, v[4:5] offset:192
	v_lshlrev_b32_e32 v160, 16, v114
	v_and_b32_e32 v161, 0xffff0000, v114
	v_lshlrev_b32_e32 v162, 16, v115
	v_and_b32_e32 v163, 0xffff0000, v115
	v_pk_mul_f32 v[0:1], v[0:1], v[160:161]
	v_pk_mul_f32 v[2:3], v[2:3], v[162:163]
	v_cvt_pk_bf16_f32 v0, v0, v1
	v_cvt_pk_bf16_f32 v1, v2, v3
	ds_write_b64 v122, v[0:1] offset:224
	ds_read_b128 v[204:207], v121
	ds_read_b128 v[210:213], v121 offset:1088
	ds_read_b128 v[214:217], v121 offset:2176
	ds_read_b128 v[220:223], v121 offset:3264
	s_waitcnt lgkmcnt(0)
	global_store_dwordx4 v124, v[204:207], s[18:19] offset:1024 sc1
	global_store_dwordx4 v125, v[210:213], s[18:19] offset:1024 sc1
	global_store_dwordx4 v126, v[214:217], s[18:19] offset:1024 sc1
	global_store_dwordx4 v127, v[220:223], s[18:19] offset:1024 sc1
	s_barrier
	s_load_dword s4, s[88:89], 0x0
	s_waitcnt lgkmcnt(0)
	s_add_i32 s11, s4, s11
	s_cmp_ge_i32 s11, s6
	s_cbranch_scc0 .LBB0_174

; #define LDSP __attribute__((address_space(3)))
; DI void wave_rows_store(ldsp_t wb, int lane, bf16_t* dst0, size_t ld) {
; #pragma unroll
;     for (int i = 0; i < 8; ++i) {
;         const int row = i * 8 + (lane >> 3), ch = lane & 7;
;         const u32x4 v = *(const LDSP u32x4*)(wb + row * 128 + ((ch ^ (row & 7)) << 4));
;         *(u32x4*)(dst0 + (size_t)row * ld + ch * 8) = v;
;     }
.LBB0_182:
	s_or_b64 exec, exec, s[4:5]
	v_lshrrev_b32_e32 v8, 3, v185
	v_ashrrev_i32_e32 v81, 31, v80
	v_xor_b32_e32 v2, v8, v185
	s_waitcnt lgkmcnt(0)
	v_lshlrev_b64 v[0:1], 11, v[80:81]
	v_lshlrev_b32_e32 v2, 4, v2
	v_lshl_add_u64 v[0:1], s[82:83], 0, v[0:1]
	s_ashr_i32 s35, s34, 31
	v_and_b32_e32 v2, 0x70, v2
	v_lshl_add_u64 v[0:1], s[34:35], 1, v[0:1]
	v_lshlrev_b32_e32 v192, 1, v184
	v_add_u32_e32 v9, v186, v2
	v_lshlrev_b32_e32 v2, 4, v185
	v_lshl_add_u64 v[0:1], v[0:1], 0, v[192:193]
	v_and_b32_e32 v192, 0x70, v2
	v_lshl_add_u64 v[4:5], v[0:1], 0, v[192:193]
	v_lshl_add_u32 v0, v8, 7, v9
	ds_read_b128 v[0:3], v0
	v_lshlrev_b32_e32 v192, 11, v8
	v_lshl_add_u64 v[6:7], v[4:5], 0, v[192:193]
	s_waitcnt lgkmcnt(0)
	global_store_dwordx4 v[6:7], v[0:3], off sc1
	v_or_b32_e32 v6, 8, v8
	s_nop 0
	v_lshl_add_u32 v0, v6, 7, v9
	ds_read_b128 v[0:3], v0
	v_lshlrev_b32_e32 v192, 11, v6
	v_lshl_add_u64 v[6:7], v[4:5], 0, v[192:193]
	s_waitcnt lgkmcnt(0)
	global_store_dwordx4 v[6:7], v[0:3], off sc1
	v_or_b32_e32 v6, 16, v8
	s_nop 0
	v_lshl_add_u32 v0, v6, 7, v9
	ds_read_b128 v[0:3], v0
	v_lshlrev_b32_e32 v192, 11, v6
	v_lshl_add_u64 v[6:7], v[4:5], 0, v[192:193]
	s_waitcnt lgkmcnt(0)
	global_store_dwordx4 v[6:7], v[0:3], off sc1
	v_or_b32_e32 v6, 24, v8
	s_nop 0
	v_lshl_add_u32 v0, v6, 7, v9
	ds_read_b128 v[0:3], v0
	v_lshlrev_b32_e32 v192, 11, v6
	v_lshl_add_u64 v[6:7], v[4:5], 0, v[192:193]
	s_waitcnt lgkmcnt(0)
	global_store_dwordx4 v[6:7], v[0:3], off sc1
	v_or_b32_e32 v6, 32, v8
	s_nop 0
	v_lshl_add_u32 v0, v6, 7, v9
	ds_read_b128 v[0:3], v0
	v_lshlrev_b32_e32 v192, 11, v6
	v_lshl_add_u64 v[6:7], v[4:5], 0, v[192:193]
	s_waitcnt lgkmcnt(0)
	global_store_dwordx4 v[6:7], v[0:3], off sc1
	v_or_b32_e32 v6, 40, v8
	s_nop 0
	v_lshl_add_u32 v0, v6, 7, v9
	ds_read_b128 v[0:3], v0
	v_lshlrev_b32_e32 v192, 11, v6
	v_lshl_add_u64 v[6:7], v[4:5], 0, v[192:193]
	s_waitcnt lgkmcnt(0)
	global_store_dwordx4 v[6:7], v[0:3], off sc1
	v_or_b32_e32 v6, 48, v8
	s_nop 0
	v_lshl_add_u32 v0, v6, 7, v9
	ds_read_b128 v[0:3], v0
	v_lshlrev_b32_e32 v192, 11, v6
	v_lshl_add_u64 v[6:7], v[4:5], 0, v[192:193]
	s_waitcnt lgkmcnt(0)
	global_store_dwordx4 v[6:7], v[0:3], off sc1
	v_or_b32_e32 v6, 56, v8
	s_nop 0
	v_lshl_add_u32 v0, v6, 7, v9
	ds_read_b128 v[0:3], v0
	v_lshlrev_b32_e32 v192, 11, v6
	v_lshl_add_u64 v[4:5], v[4:5], 0, v[192:193]
	s_waitcnt lgkmcnt(0)
	global_store_dwordx4 v[4:5], v[0:3], off sc1

; #define WAIT_V0() asm volatile("s_waitcnt vmcnt(0)" ::: "memory")
; #define G_STAGE_A(Ap, buf, kt) do { const char* ab_ = (const char*)(Ap) + (size_t)(kt) * 128; \
;       _Pragma("unroll") for (int i = 0; i < 4; ++i) \
;         __builtin_amdgcn_global_load_lds((const unsigned*)(ab_ + soff[i]), (LDSP unsigned*)(G_SA(buf) + wid * 1024 + i * 8192), 16, 0, 0); } while (0)
; #define G_STAGE_B(Bp, buf, kt) do { const char* bb_ = (const char*)(Bp) + (size_t)(kt) * 128; \
;       _Pragma("unroll") for (int i = 0; i < 4; ++i) \
;         __builtin_amdgcn_global_load_lds((const unsigned*)(bb_ + soff[i]), (LDSP unsigned*)(G_SB(buf) + wid * 1024 + i * 8192), 16, 0, 0); } while (0)
; #define G_RDA(AF, buf, ks, mh) do { _Pragma("unroll") for (int m = 0; m < 4; ++m) AF[m] = *(const LDSP bf16x8*)(G_SA(buf) + aoff + ((mh) * 4 + m) * 2048 + (ks) * 1024); } while (0)
; #define G_RDB(BF, buf, ks) do { _Pragma("unroll") for (int n = 0; n < 4; ++n) BF[n] = *(const LDSP bf16x8*)(G_SB(buf) + boff + n * 2048 + (ks) * 1024); } while (0)
; #define G_MMA(AF, BF, mh) do { __builtin_amdgcn_s_setprio(1); \
;             _Pragma("unroll") for (int m = 0; m < 4; ++m) _Pragma("unroll") for (int n = 0; n < 4; ++n) \
;                 acc[(mh) * 4 + m][n] = __builtin_amdgcn_mfma_f32_16x16x32_bf16(BF[n], AF[m], acc[(mh) * 4 + m][n], 0, 0, 0); \
;             __builtin_amdgcn_s_setprio(0); } while (0)
; template <int EK>
; DI void gemm_stream(const Params& p, int l, const bf16_t* __restrict__ A, const bf16_t* __restrict__ Bt, int M, int N, int K, ldsp_t shm) {
;     ...
;         for (int t = 0; t < nt; ++t) {
;             const int cur = t & 1;
;             G_RDA(Aa, cur, 0, 0); G_RDB(Bk0, cur, 0);
;             if (t + 1 < nt) G_STAGE_B(Bb, cur ^ 1, t + 1);
;             else if (has_next) G_STAGE_B(Bb2, cur ^ 1, 0);
;             G_SB0();
;             if (t > 0) G_MMA(Ab_, Bk1, 1);
;             G_SB0();
;             if (t + 1 < nt) G_STAGE_A(Ab, cur ^ 1, t + 1);
;             else if (has_next) G_STAGE_A(Ab2, cur ^ 1, 0);
;             G_RDA(Ab_, cur, 0, 1);
;             G_MMA(Aa, Bk0, 0); G_SB0();
;             G_RDA(Aa, cur, 1, 0); G_RDB(Bk1, cur, 1);
;             G_MMA(Ab_, Bk0, 1); G_SB0();
;             G_RDA(Ab_, cur, 1, 1);
;             G_MMA(Aa, Bk1, 0); G_SB0();
;             asm volatile("s_waitcnt lgkmcnt(0)" ::: "memory");
;             WAIT_V0(); __syncthreads();
;         }
.LBB0_196:
	v_add_u32_e32 v80, 0x12000, v218
	v_add_u32_e32 v84, 0x12800, v218
	v_add_u32_e32 v88, 0x13000, v218
	v_add_u32_e32 v92, 0x13800, v218
	ds_read_b128 v[80:83], v80
	ds_read_b128 v[84:87], v84
	ds_read_b128 v[88:91], v88
	ds_read_b128 v[92:95], v92
	s_setprio 1
	s_waitcnt lgkmcnt(0)
	v_mfma_f32_16x16x32_bf16 v[4:7], v[164:167], v[188:191], v[4:7]
	v_mfma_f32_16x16x32_bf16 v[8:11], v[168:171], v[188:191], v[8:11]
	v_mfma_f32_16x16x32_bf16 v[12:15], v[172:175], v[188:191], v[12:15]
	v_mfma_f32_16x16x32_bf16 v[16:19], v[160:163], v[180:183], v[16:19]
	v_mfma_f32_16x16x32_bf16 v[20:23], v[164:167], v[180:183], v[20:23]
	v_mfma_f32_16x16x32_bf16 v[24:27], v[168:171], v[180:183], v[24:27]
	v_mfma_f32_16x16x32_bf16 v[28:31], v[172:175], v[180:183], v[28:31]
	v_mfma_f32_16x16x32_bf16 v[32:35], v[160:163], v[184:187], v[32:35]
	v_mfma_f32_16x16x32_bf16 v[36:39], v[164:167], v[184:187], v[36:39]
	v_mfma_f32_16x16x32_bf16 v[40:43], v[168:171], v[184:187], v[40:43]
	v_mfma_f32_16x16x32_bf16 v[44:47], v[172:175], v[184:187], v[44:47]
	v_mfma_f32_16x16x32_bf16 v[48:51], v[160:163], v[176:179], v[48:51]
	v_mfma_f32_16x16x32_bf16 v[52:55], v[164:167], v[176:179], v[52:55]
	v_mfma_f32_16x16x32_bf16 v[56:59], v[168:171], v[176:179], v[56:59]
	v_mfma_f32_16x16x32_bf16 v[60:63], v[172:175], v[176:179], v[60:63]
	v_mfma_f32_16x16x32_bf16 v[0:3], v[160:163], v[188:191], v[0:3]
	s_setprio 0
	v_add_u32_e32 v144, 0x10400, v218
	v_add_u32_e32 v148, 0x10c00, v218
	v_add_u32_e32 v152, 0x11400, v218
	v_add_u32_e32 v156, 0x11c00, v218
	v_add_u32_e32 v176, 0x18400, v219
	v_add_u32_e32 v180, 0x18c00, v219
	v_add_u32_e32 v184, 0x19400, v219
	v_add_u32_e32 v188, 0x19c00, v219
	ds_read_b128 v[144:147], v144
	ds_read_b128 v[148:151], v148
	ds_read_b128 v[152:155], v152
	ds_read_b128 v[156:159], v156
	ds_read_b128 v[176:179], v176
	ds_read_b128 v[180:183], v180
	ds_read_b128 v[184:187], v184
	ds_read_b128 v[188:191], v188
	s_setprio 1
	v_mfma_f32_16x16x32_bf16 v[140:143], v[160:163], v[80:83], v[140:143]
	v_mfma_f32_16x16x32_bf16 v[194:197], v[164:167], v[80:83], v[136:139]
	v_mfma_f32_16x16x32_bf16 v[198:201], v[168:171], v[80:83], v[132:135]
	v_mfma_f32_16x16x32_bf16 v[204:207], v[172:175], v[80:83], v[128:131]
	v_mfma_f32_16x16x32_bf16 v[210:213], v[160:163], v[84:87], v[124:127]
	v_mfma_f32_16x16x32_bf16 v[214:217], v[164:167], v[84:87], v[120:123]
	v_mfma_f32_16x16x32_bf16 v[220:223], v[168:171], v[84:87], v[116:119]
	v_mfma_f32_16x16x32_bf16 v[224:227], v[172:175], v[84:87], v[112:115]
	v_mfma_f32_16x16x32_bf16 v[228:231], v[160:163], v[88:91], v[108:111]
	v_mfma_f32_16x16x32_bf16 v[232:235], v[164:167], v[88:91], v[104:107]
	v_mfma_f32_16x16x32_bf16 v[236:239], v[168:171], v[88:91], v[100:103]
	v_mfma_f32_16x16x32_bf16 v[240:243], v[172:175], v[88:91], v[96:99]
	v_mfma_f32_16x16x32_bf16 v[160:163], v[160:163], v[92:95], v[64:67]
	v_mfma_f32_16x16x32_bf16 v[164:167], v[164:167], v[92:95], v[68:71]
	v_mfma_f32_16x16x32_bf16 v[168:171], v[168:171], v[92:95], v[72:75]
	v_mfma_f32_16x16x32_bf16 v[172:175], v[172:175], v[92:95], v[76:79]
	s_setprio 0
	v_add_u32_e32 v64, 0x12400, v218
	v_add_u32_e32 v68, 0x12c00, v218
	ds_read_b128 v[64:67], v64
	ds_read_b128 v[244:247], v68
	v_add_u32_e32 v68, 0x13400, v218
	v_add_u32_e32 v69, 0x13c00, v218
	ds_read_b128 v[248:251], v68
	ds_read_b128 v[68:71], v69
	s_setprio 1
	s_waitcnt lgkmcnt(0)
	v_mfma_f32_16x16x32_bf16 v[136:139], v[180:183], v[144:147], v[4:7]
	v_mfma_f32_16x16x32_bf16 v[132:135], v[184:187], v[144:147], v[8:11]
	v_mfma_f32_16x16x32_bf16 v[128:131], v[188:191], v[144:147], v[12:15]
	v_mfma_f32_16x16x32_bf16 v[124:127], v[176:179], v[148:151], v[16:19]
	v_mfma_f32_16x16x32_bf16 v[120:123], v[180:183], v[148:151], v[20:23]
	v_mfma_f32_16x16x32_bf16 v[116:119], v[184:187], v[148:151], v[24:27]
	v_mfma_f32_16x16x32_bf16 v[112:115], v[188:191], v[148:151], v[28:31]
	v_mfma_f32_16x16x32_bf16 v[108:111], v[176:179], v[152:155], v[32:35]
	v_mfma_f32_16x16x32_bf16 v[104:107], v[180:183], v[152:155], v[36:39]
	v_mfma_f32_16x16x32_bf16 v[100:103], v[184:187], v[152:155], v[40:43]
	v_mfma_f32_16x16x32_bf16 v[96:99], v[188:191], v[152:155], v[44:47]
	v_mfma_f32_16x16x32_bf16 v[92:95], v[176:179], v[156:159], v[48:51]
	v_mfma_f32_16x16x32_bf16 v[88:91], v[180:183], v[156:159], v[52:55]
	v_mfma_f32_16x16x32_bf16 v[84:87], v[184:187], v[156:159], v[56:59]
	v_mfma_f32_16x16x32_bf16 v[80:83], v[188:191], v[156:159], v[60:63]
	v_mfma_f32_16x16x32_bf16 v[0:3], v[176:179], v[144:147], v[0:3]
	s_setprio 0
	s_waitcnt lgkmcnt(0)
	s_waitcnt vmcnt(0)
	s_waitcnt vmcnt(0)
	s_barrier
; #define G_MMA(AF, BF, mh) do { __builtin_amdgcn_s_setprio(1); \
;             _Pragma("unroll") for (int m = 0; m < 4; ++m) _Pragma("unroll") for (int n = 0; n < 4; ++n) \
;                 acc[(mh) * 4 + m][n] = __builtin_amdgcn_mfma_f32_16x16x32_bf16(BF[n], AF[m], acc[(mh) * 4 + m][n], 0, 0, 0); \
;             __builtin_amdgcn_s_setprio(0); } while (0)
;     static DI void run(const f32x4 (&acc)[8][4], const TileCtx& tc, const Params& p, ldsp_t wb) {
;         constexpr int GI = EK == 1 ? 2 : 5;
;         const int cond = tc.brow < NLAT ? (tc.brow >> 12) : 4;
;         const float* gate = p.mod + ((size_t)tc.l * 5 + cond) * 6144 + GI * DM;
;         const int col0 = tc.bcol + tc.wc * 64 + tc.fq * 4;
;         const bool has_next = EK == 1 || tc.l + 1 < DEPTH;
;         const int ln = EK == 1 ? tc.l : (has_next ? tc.l + 1 : tc.l);
;         const float* gnx = (EK == 1 ? p.norm2_g : p.norm1_g) + (size_t)ln * DM + col0;
;         const float* scn = p.mod + ((size_t)ln * 5 + cond) * 6144 + (EK == 1 ? 4 : 1) * DM + col0;
;         float* ssp = p.ss + (size_t)(ln * 2 + (EK == 1 ? 1 : 0)) * NTOK * 16 + (tc.bcol >> 8) * 4 + tc.wc;
;         f32x4 gv[4], av[4];
; #pragma unroll
;         for (int n = 0; n < 4; ++n) {
;             gv[n] = *(const f32x4*)(gate + col0 + n * 16);
;             const f32x4 g1 = *(const f32x4*)(gnx + n * 16), s1 = *(const f32x4*)(scn + n * 16);
;             av[n] = g1 * (1.f + s1);
;         }
; #pragma unroll
;         for (int h = 0; h < 2; ++h) {
; #pragma unroll
;             for (int mm = 0; mm < 4; ++mm) { __builtin_amdgcn_sched_barrier(0);
;                 const int m = h * 4 + mm;
;                 const int row = tc.brow + tc.wr * 128 + m * 16 + tc.fr;
;                 float* xr = xrow_ptr(p, row) + col0;
;                 const float* xs = (EK == 1 && tc.l == 0) ? p.x + (size_t)row * DM + col0 : xr;
;                 float part = 0.f;
; #pragma unroll
;                 for (int n = 0; n < 4; ++n) {
;                     f32x4 xv = *(const f32x4*)(xs + n * 16);
;                     xv += gv[n] * acc[m][n];
;                     *(f32x4*)(xr + n * 16) = xv;
; template <int EK>
; DI void gemm_stream(const Params& p, int l, const bf16_t* __restrict__ A, const bf16_t* __restrict__ Bt, int M, int N, int K, ldsp_t shm) {
;     ...
;         G_MMA(Ab_, Bk1, 1);
	s_setprio 1
	v_mfma_f32_16x16x32_bf16 v[76:79], v[176:179], v[64:67], v[140:143]
	v_mfma_f32_16x16x32_bf16 v[72:75], v[180:183], v[64:67], v[194:197]
	v_mfma_f32_16x16x32_bf16 v[194:197], v[184:187], v[64:67], v[198:201]
	v_mfma_f32_16x16x32_bf16 v[64:67], v[188:191], v[64:67], v[204:207]
	v_mfma_f32_16x16x32_bf16 v[60:63], v[176:179], v[244:247], v[210:213]
	v_mfma_f32_16x16x32_bf16 v[56:59], v[180:183], v[244:247], v[214:217]
	v_mfma_f32_16x16x32_bf16 v[52:55], v[184:187], v[244:247], v[220:223]
	v_mfma_f32_16x16x32_bf16 v[48:51], v[188:191], v[244:247], v[224:227]
	v_mfma_f32_16x16x32_bf16 v[44:47], v[176:179], v[248:251], v[228:231]
	v_mfma_f32_16x16x32_bf16 v[40:43], v[180:183], v[248:251], v[232:235]
	v_mfma_f32_16x16x32_bf16 v[36:39], v[184:187], v[248:251], v[236:239]
	v_mfma_f32_16x16x32_bf16 v[32:35], v[188:191], v[248:251], v[240:243]
	v_mfma_f32_16x16x32_bf16 v[24:27], v[176:179], v[68:71], v[160:163]
	v_mfma_f32_16x16x32_bf16 v[16:19], v[180:183], v[68:71], v[164:167]
	v_mfma_f32_16x16x32_bf16 v[8:11], v[184:187], v[68:71], v[168:171]
	v_mfma_f32_16x16x32_bf16 v[68:71], v[188:191], v[68:71], v[172:175]
	s_setprio 0
	v_mov_b32_e32 v179, v252
	s_lshl_b32 s43, s45, 8
	s_min_i32 s4, s43, 0x4000
	s_ashr_i32 s35, s4, 12
	s_lshl_b32 s34, s44, 8
	s_ashr_i32 s45, s35, 31
	s_mul_i32 s4, s48, 5
	s_add_u32 s4, s4, s35
	s_mul_hi_i32 s5, s48, 5
	v_ashrrev_i32_e32 v186, 6, v179
	s_addc_u32 s5, s5, s45
	v_mov_b64_e32 v[4:5], s[66:67]
	v_mov_b32_e32 v13, 0x6000
	v_and_b32_e32 v190, 3, v186
	v_bfe_u32 v189, v179, 4, 2
	s_mul_i32 s47, s5, 0x6000
	v_mad_u64_u32 v[6:7], s[4:5], s4, v13, v[4:5]
	v_lshlrev_b32_e32 v184, 6, v190
	v_lshlrev_b32_e32 v12, 2, v189
	s_add_u32 s4, s98, s35
	v_or3_b32 v176, v12, s34, v184
	s_addc_u32 s5, s93, s45
	v_ashrrev_i32_e32 v177, 31, v176
	s_mul_i32 s35, s5, 0x6000
	v_mad_u64_u32 v[4:5], s[4:5], s4, v13, v[4:5]
	v_lshlrev_b64 v[168:169], 2, v[176:177]
	v_add_u32_e32 v5, s35, v5
	v_add_u32_e32 v7, s47, v7
	v_lshl_add_u64 v[4:5], v[4:5], 0, v[168:169]
	s_mov_b64 s[4:5], 0x1000
	v_lshl_add_u64 v[144:145], v[4:5], 0, s[4:5]
	v_lshl_add_u64 v[6:7], v[6:7], 0, v[168:169]
	s_mov_b64 s[4:5], 0x5000
	v_lshl_add_u64 v[22:23], v[6:7], 0, s[4:5]
	s_movk_i32 s4, 0x5000
	v_add_co_u32_e32 v6, vcc, s4, v6
	v_lshl_add_u64 v[20:21], s[38:39], 0, v[168:169]
	s_nop 0
	v_addc_co_u32_e32 v7, vcc, 0, v7, vcc
	v_add_co_u32_e32 v4, vcc, s29, v4
	s_lshl_b32 s4, s44, 2
	s_nop 0
	v_addc_co_u32_e32 v5, vcc, 0, v5, vcc
	global_load_dwordx4 v[28:31], v[6:7], off
	global_load_dwordx4 v[172:175], v[4:5], off
	global_load_dwordx4 v[164:167], v[20:21], off
	global_load_dwordx4 v[156:159], v[20:21], off offset:64
	global_load_dwordx4 v[160:163], v[144:145], off offset:64
	global_load_dwordx4 v[152:155], v[144:145], off offset:128
	global_load_dwordx4 v[12:15], v[22:23], off offset:128
	global_load_dwordx4 v[4:7], v[22:23], off offset:192
	global_load_dwordx4 v[148:151], v[20:21], off offset:128
	global_load_dwordx4 v[140:143], v[20:21], off offset:192
	s_nop 0
	global_load_dwordx4 v[20:23], v[22:23], off offset:64
	s_nop 0
	global_load_dwordx4 v[144:147], v[144:145], off offset:192
	s_ashr_i32 s5, s4, 31
	s_lshl_b64 s[4:5], s[4:5], 2
	s_add_u32 s4, s10, s4
	v_and_b32_e32 v187, 15, v179
	s_addc_u32 s5, s11, s5
	v_ashrrev_i32_e32 v170, 1, v179
	v_and_b32_e32 v188, 0xffffff80, v170
	v_add_u32_e32 v178, s43, v188
	v_or_b32_e32 v180, v178, v187
	v_add_u32_e32 v170, 0xffffc000, v180
	v_ashrrev_i32_e32 v181, 31, v180
	v_cmp_gt_i32_e32 vcc, s33, v180
	v_mov_b32_e32 v182, s71
	v_mov_b32_e32 v183, s55
	v_cndmask_b32_e32 v171, 0, v181, vcc
	v_cndmask_b32_e32 v170, v170, v180, vcc
	v_cndmask_b32_e32 v183, v182, v183, vcc
	v_mov_b32_e32 v182, s70
	v_mov_b32_e32 v185, s54
	v_cndmask_b32_e32 v182, v182, v185, vcc
	v_lshlrev_b64 v[170:171], 12, v[170:171]
	v_lshl_add_u64 v[170:171], v[182:183], 0, v[170:171]
	v_lshl_add_u64 v[182:183], v[170:171], 0, v[168:169]
	global_load_dwordx4 v[168:171], v[182:183], off
	global_load_dwordx4 v[232:235], v[182:183], off offset:64
	global_load_dwordx4 v[236:239], v[182:183], off offset:128
	global_load_dwordx4 v[240:243], v[182:183], off offset:192
	s_mov_b64 s[44:45], -1
	s_and_b64 vcc, exec, s[36:37]
	s_waitcnt vmcnt(3)
	v_pk_fma_f32 v[170:171], v[2:3], v[30:31], v[170:171]
	v_pk_fma_f32 v[168:169], v[0:1], v[28:29], v[168:169]
	global_store_dwordx4 v[182:183], v[168:171], off sc1
	s_cbranch_vccz .LBB0_198
	s_nop 1
	s_mov_b64 s[44:45], 0
	s_waitcnt vmcnt(3)
	v_pk_fma_f32 v[2:3], v[138:139], v[22:23], v[234:235]
	v_pk_fma_f32 v[0:1], v[136:137], v[20:21], v[232:233]
	global_store_dwordx4 v[182:183], v[0:3], off offset:64 sc1
	s_nop 1
	s_waitcnt vmcnt(3)
	v_pk_fma_f32 v[2:3], v[134:135], v[14:15], v[238:239]
	v_pk_fma_f32 v[0:1], v[132:133], v[12:13], v[236:237]
	global_store_dwordx4 v[182:183], v[0:3], off offset:128 sc1
	s_nop 1
	s_waitcnt vmcnt(3)
	v_pk_fma_f32 v[2:3], v[130:131], v[6:7], v[242:243]
	v_pk_fma_f32 v[0:1], v[128:129], v[4:5], v[240:241]
	global_store_dwordx4 v[182:183], v[0:3], off offset:192 sc1
; DI unsigned pk2(float a, float b) { f32x2 v = {a, b}; bf2_t r = __builtin_convertvector(v, bf2_t); return __builtin_bit_cast(unsigned, r); }
;     static DI void run(const f32x4 (&acc)[8][4], const TileCtx& tc, const Params& p, ldsp_t wb) {
;     ...
;             const f32x4 g1 = *(const f32x4*)(gnx + n * 16), s1 = *(const f32x4*)(scn + n * 16);
;             av[n] = g1 * (1.f + s1);
;         }
; #pragma unroll
;         for (int h = 0; h < 2; ++h) {
; #pragma unroll
;             for (int mm = 0; mm < 4; ++mm) { __builtin_amdgcn_sched_barrier(0);
;                 const int m = h * 4 + mm;
;                 const int row = tc.brow + tc.wr * 128 + m * 16 + tc.fr;
;                 float* xr = xrow_ptr(p, row) + col0;
;                 const float* xs = (EK == 1 && tc.l == 0) ? p.x + (size_t)row * DM + col0 : xr;
;                 float part = 0.f;
; #pragma unroll
;                 for (int n = 0; n < 4; ++n) {
;                     f32x4 xv = *(const f32x4*)(xs + n * 16);
;                     xv += gv[n] * acc[m][n];
;                     *(f32x4*)(xr + n * 16) = xv;
;                     if (has_next) {
;                         part += xv[0] * xv[0] + xv[1] * xv[1] + xv[2] * xv[2] + xv[3] * xv[3];
;                         const f32x4 hv = xv * av[n];
;                         u32x2 w; w[0] = pk2(hv[0], hv[1]); w[1] = pk2(hv[2], hv[3]);
;                         wave_put(wb, mm * 16 + tc.fr, n, tc.fq, w);
;                     }
;                 }
;                 if (has_next) {
;                     part += __shfl_xor(part, 16);
;                     part += __shfl_xor(part, 32);
;                     if (tc.fq == 0) ssp[(size_t)row * 16] = part;
.LBB0_198:
	s_nop 1
	v_mov_b32_e32 v0, 0x10000
	v_lshl_add_u32 v186, v186, 13, v0
	v_pk_add_f32 v[0:1], v[174:175], 1.0 op_sel_hi:[1,0]
	v_pk_add_f32 v[2:3], v[172:173], 1.0 op_sel_hi:[1,0]
	v_pk_mul_f32 v[166:167], v[166:167], v[0:1]
	v_pk_mul_f32 v[164:165], v[164:165], v[2:3]
	v_pk_add_f32 v[0:1], v[162:163], 1.0 op_sel_hi:[1,0]
	v_pk_add_f32 v[2:3], v[160:161], 1.0 op_sel_hi:[1,0]
	v_pk_mul_f32 v[158:159], v[158:159], v[0:1]
	v_pk_mul_f32 v[156:157], v[156:157], v[2:3]
	v_pk_add_f32 v[0:1], v[154:155], 1.0 op_sel_hi:[1,0]
	v_pk_add_f32 v[2:3], v[152:153], 1.0 op_sel_hi:[1,0]
	v_and_b32_e32 v185, 63, v179
	v_pk_mul_f32 v[150:151], v[150:151], v[0:1]
	v_pk_mul_f32 v[148:149], v[148:149], v[2:3]
	v_pk_add_f32 v[0:1], v[146:147], 1.0 op_sel_hi:[1,0]
	v_pk_add_f32 v[2:3], v[144:145], 1.0 op_sel_hi:[1,0]
	v_pk_mul_f32 v[142:143], v[142:143], v[0:1]
	v_pk_mul_f32 v[144:145], v[140:141], v[2:3]
	v_lshlrev_b32_e32 v192, 2, v190
	v_lshrrev_b32_e32 v0, 5, v185
	v_and_b32_e32 v1, 7, v179
	v_lshlrev_b32_e32 v2, 3, v189
	v_lshl_add_u64 v[140:141], s[4:5], 0, v[192:193]
	s_andn2_b64 vcc, exec, s[44:45]
	v_lshl_add_u32 v146, v187, 7, v186
	v_cmp_gt_u32_e64 s[4:5], 16, v185
	v_bitop3_b32 v155, v0, v179, 7 bitop3:0x78
	v_and_b32_e32 v147, 8, v2
	v_bitop3_b32 v154, v0, v1, 2 bitop3:0x36
	v_bitop3_b32 v153, v0, v1, 4 bitop3:0x36
	v_bitop3_b32 v152, v0, v1, 6 bitop3:0x36
	v_xor_b32_e32 v230, 16, v202
	s_cbranch_vccnz .LBB0_202
	v_pk_mul_f32 v[0:1], v[166:167], v[170:171]
	v_pk_mul_f32 v[2:3], v[164:165], v[168:169]
	v_mul_f32_e32 v160, v169, v169
	v_cvt_pk_bf16_f32 v2, v2, v3
	v_cvt_pk_bf16_f32 v3, v0, v1
	v_lshlrev_b32_e32 v0, 4, v155
	v_add3_u32 v0, v146, v0, v147
	ds_write_b64 v0, v[2:3]
	s_nop 1
	v_fmac_f32_e32 v160, v168, v168
	v_fmac_f32_e32 v160, v170, v170
	v_fmac_f32_e32 v160, v171, v171
	v_cmp_lt_i32_e32 vcc, v230, v203
	s_waitcnt vmcnt(3)
	v_pk_fma_f32 v[0:1], v[136:137], v[20:21], v[232:233]
	s_nop 0
	v_mul_f32_e32 v136, v1, v1
	v_pk_fma_f32 v[2:3], v[138:139], v[22:23], v[234:235]
	v_fmac_f32_e32 v136, v0, v0
	v_fmac_f32_e32 v136, v2, v2
	global_store_dwordx4 v[182:183], v[0:3], off offset:64 sc1
	v_fmac_f32_e32 v136, v3, v3
	v_add_f32_e32 v136, v160, v136
	v_pk_mul_f32 v[2:3], v[158:159], v[2:3]
	v_pk_mul_f32 v[0:1], v[156:157], v[0:1]
	s_nop 0
	v_cvt_pk_bf16_f32 v0, v0, v1
	v_cvt_pk_bf16_f32 v1, v2, v3
	v_lshlrev_b32_e32 v2, 4, v154
	v_add3_u32 v2, v146, v2, v147
	ds_write_b64 v2, v[0:1]
	s_nop 1
	s_waitcnt vmcnt(3)
	v_pk_fma_f32 v[0:1], v[132:133], v[12:13], v[236:237]
	s_nop 0
	v_mul_f32_e32 v132, v1, v1
	v_pk_fma_f32 v[2:3], v[134:135], v[14:15], v[238:239]
	v_fmac_f32_e32 v132, v0, v0
	v_fmac_f32_e32 v132, v2, v2
	global_store_dwordx4 v[182:183], v[0:3], off offset:128 sc1
	v_fmac_f32_e32 v132, v3, v3
	v_add_f32_e32 v132, v136, v132
	v_pk_mul_f32 v[2:3], v[150:151], v[2:3]
	v_pk_mul_f32 v[0:1], v[148:149], v[0:1]
	s_nop 0
	v_cvt_pk_bf16_f32 v0, v0, v1
	v_cvt_pk_bf16_f32 v1, v2, v3
	v_lshlrev_b32_e32 v2, 4, v153
	v_add3_u32 v2, v146, v2, v147
	ds_write_b64 v2, v[0:1]
	s_nop 1
	s_waitcnt vmcnt(3)
	v_pk_fma_f32 v[0:1], v[128:129], v[4:5], v[240:241]
	s_nop 0
	v_mul_f32_e32 v128, v1, v1
	v_pk_fma_f32 v[2:3], v[130:131], v[6:7], v[242:243]
	v_fmac_f32_e32 v128, v0, v0
	v_fmac_f32_e32 v128, v2, v2
	global_store_dwordx4 v[182:183], v[0:3], off offset:192 sc1
	v_fmac_f32_e32 v128, v3, v3
	v_add_f32_e32 v128, v132, v128
	v_pk_mul_f32 v[2:3], v[142:143], v[2:3]
	v_pk_mul_f32 v[0:1], v[144:145], v[0:1]
	s_nop 0
	v_cvt_pk_bf16_f32 v0, v0, v1
	v_cvt_pk_bf16_f32 v1, v2, v3
	v_lshlrev_b32_e32 v2, 4, v152
	v_add3_u32 v2, v146, v2, v147
	ds_write_b64 v2, v[0:1]
	v_cndmask_b32_e32 v0, v202, v230, vcc
	v_lshlrev_b32_e32 v0, 2, v0
	ds_bpermute_b32 v0, v0, v128
	v_cmp_lt_i32_e32 vcc, v209, v203
	s_waitcnt lgkmcnt(0)
	v_add_f32_e32 v128, v128, v0
	v_cndmask_b32_e32 v0, v202, v209, vcc
	v_lshlrev_b32_e32 v0, 2, v0
	ds_bpermute_b32 v129, v0, v128
	s_and_saveexec_b64 s[44:45], s[4:5]
	s_cbranch_execz .LBB0_201
	v_lshlrev_b64 v[0:1], 6, v[180:181]
	s_waitcnt lgkmcnt(0)
	v_add_f32_e32 v2, v128, v129
	v_lshl_add_u64 v[0:1], v[140:141], 0, v[0:1]
	global_store_dword v[0:1], v2, off sc1

; DI unsigned pk2(float a, float b) { f32x2 v = {a, b}; bf2_t r = __builtin_convertvector(v, bf2_t); return __builtin_bit_cast(unsigned, r); }
;     static DI void run(const f32x4 (&acc)[8][4], const TileCtx& tc, const Params& p, ldsp_t wb) {
;     ...
;             for (int mm = 0; mm < 4; ++mm) { __builtin_amdgcn_sched_barrier(0);
;                 const int m = h * 4 + mm;
;                 const int row = tc.brow + tc.wr * 128 + m * 16 + tc.fr;
;                 float* xr = xrow_ptr(p, row) + col0;
;                 const float* xs = (EK == 1 && tc.l == 0) ? p.x + (size_t)row * DM + col0 : xr;
;                 float part = 0.f;
; #pragma unroll
;                 for (int n = 0; n < 4; ++n) {
;                     f32x4 xv = *(const f32x4*)(xs + n * 16);
;                     xv += gv[n] * acc[m][n];
;                     *(f32x4*)(xr + n * 16) = xv;
;                     if (has_next) {
;                         part += xv[0] * xv[0] + xv[1] * xv[1] + xv[2] * xv[2] + xv[3] * xv[3];
;                         const f32x4 hv = xv * av[n];
;                         u32x2 w; w[0] = pk2(hv[0], hv[1]); w[1] = pk2(hv[2], hv[3]);
;                         wave_put(wb, mm * 16 + tc.fr, n, tc.fq, w);
;                     }
;                 }
;                 if (has_next) {
;                     part += __shfl_xor(part, 16);
;                     part += __shfl_xor(part, 32);
;                     if (tc.fq == 0) ssp[(size_t)row * 16] = part;
.LBB0_202:
	v_or_b32_e32 v0, s43, v187
	v_add_u32_e32 v132, v188, v0
	v_add_u32_e32 v128, 16, v132
	v_add_u32_e32 v0, 0xffffc010, v132
	s_waitcnt lgkmcnt(0)
	v_ashrrev_i32_e32 v129, 31, v128
	v_cmp_gt_i32_e32 vcc, s33, v128
	v_mov_b32_e32 v2, s71
	v_mov_b32_e32 v3, s55
	v_cndmask_b32_e32 v1, 0, v129, vcc
	v_cndmask_b32_e32 v0, v0, v128, vcc
	v_cndmask_b32_e32 v3, v2, v3, vcc
	v_mov_b32_e32 v2, s70
	v_mov_b32_e32 v130, s54
	v_cndmask_b32_e32 v2, v2, v130, vcc
	v_lshlrev_b64 v[0:1], 12, v[0:1]
	v_lshl_add_u64 v[0:1], v[2:3], 0, v[0:1]
	v_lshl_add_u64 v[130:131], v[176:177], 2, v[0:1]
	global_load_dwordx4 v[0:3], v[130:131], off
	global_load_dwordx4 v[232:235], v[130:131], off offset:64
	global_load_dwordx4 v[236:239], v[130:131], off offset:128
	global_load_dwordx4 v[240:243], v[130:131], off offset:192
	s_mov_b64 s[4:5], -1
	s_and_b64 vcc, exec, s[36:37]
	s_waitcnt vmcnt(3)
	v_pk_fma_f32 v[126:127], v[126:127], v[30:31], v[2:3]
	v_pk_fma_f32 v[124:125], v[124:125], v[28:29], v[0:1]
	global_store_dwordx4 v[130:131], v[124:127], off sc1
	s_cbranch_vccz .LBB0_204
	s_nop 1
	s_mov_b64 s[4:5], 0
	s_waitcnt vmcnt(3)
	v_pk_fma_f32 v[2:3], v[122:123], v[22:23], v[234:235]
	v_pk_fma_f32 v[0:1], v[120:121], v[20:21], v[232:233]
	global_store_dwordx4 v[130:131], v[0:3], off offset:64 sc1
	s_nop 1
	s_waitcnt vmcnt(3)
	v_pk_fma_f32 v[2:3], v[118:119], v[14:15], v[238:239]
	v_pk_fma_f32 v[0:1], v[116:117], v[12:13], v[236:237]
	global_store_dwordx4 v[130:131], v[0:3], off offset:128 sc1
	s_nop 1
	s_waitcnt vmcnt(3)
	v_pk_fma_f32 v[2:3], v[114:115], v[6:7], v[242:243]
	v_pk_fma_f32 v[0:1], v[112:113], v[4:5], v[240:241]
	global_store_dwordx4 v[130:131], v[0:3], off offset:192 sc1
.LBB0_204:
	s_andn2_b64 vcc, exec, s[4:5]
	v_xor_b32_e32 v134, 1, v202
	v_xor_b32_e32 v135, 2, v202
	s_cbranch_vccnz .LBB0_208
	v_pk_mul_f32 v[0:1], v[166:167], v[126:127]
	v_pk_mul_f32 v[2:3], v[164:165], v[124:125]
	v_mul_f32_e32 v133, v125, v125
	v_cvt_pk_bf16_f32 v2, v2, v3
	v_cvt_pk_bf16_f32 v3, v0, v1
	v_lshlrev_b32_e32 v0, 4, v155
	v_add3_u32 v0, v146, v0, v147
	ds_write_b64 v0, v[2:3] offset:2048
	s_nop 1
	v_fmac_f32_e32 v133, v124, v124
	v_fmac_f32_e32 v133, v126, v126
	v_fmac_f32_e32 v133, v127, v127
	v_cmp_lt_i32_e32 vcc, v230, v203
	s_waitcnt vmcnt(3)
	v_pk_fma_f32 v[0:1], v[120:121], v[20:21], v[232:233]
	s_nop 0
	v_mul_f32_e32 v120, v1, v1
	v_pk_fma_f32 v[2:3], v[122:123], v[22:23], v[234:235]
	v_fmac_f32_e32 v120, v0, v0
	v_fmac_f32_e32 v120, v2, v2
	global_store_dwordx4 v[130:131], v[0:3], off offset:64 sc1
	v_fmac_f32_e32 v120, v3, v3
	v_add_f32_e32 v120, v133, v120
	v_pk_mul_f32 v[2:3], v[158:159], v[2:3]
	v_pk_mul_f32 v[0:1], v[156:157], v[0:1]
	s_nop 0
	v_cvt_pk_bf16_f32 v0, v0, v1
	v_cvt_pk_bf16_f32 v1, v2, v3
	v_lshlrev_b32_e32 v2, 4, v154
	v_add3_u32 v2, v146, v2, v147
	ds_write_b64 v2, v[0:1] offset:2048
	s_nop 1
	s_waitcnt vmcnt(3)
	v_pk_fma_f32 v[0:1], v[116:117], v[12:13], v[236:237]
	s_nop 0
	v_mul_f32_e32 v116, v1, v1
	v_pk_fma_f32 v[2:3], v[118:119], v[14:15], v[238:239]
	v_fmac_f32_e32 v116, v0, v0
	v_fmac_f32_e32 v116, v2, v2
	global_store_dwordx4 v[130:131], v[0:3], off offset:128 sc1
	v_fmac_f32_e32 v116, v3, v3
	v_add_f32_e32 v116, v120, v116
	v_pk_mul_f32 v[2:3], v[150:151], v[2:3]
	v_pk_mul_f32 v[0:1], v[148:149], v[0:1]
	s_nop 0
	v_cvt_pk_bf16_f32 v0, v0, v1
	v_cvt_pk_bf16_f32 v1, v2, v3
	v_lshlrev_b32_e32 v2, 4, v153
	v_add3_u32 v2, v146, v2, v147
	ds_write_b64 v2, v[0:1] offset:2048
	s_nop 1
	s_waitcnt vmcnt(3)
	v_pk_fma_f32 v[0:1], v[112:113], v[4:5], v[240:241]
	s_nop 0
	v_mul_f32_e32 v112, v1, v1
	v_pk_fma_f32 v[2:3], v[114:115], v[6:7], v[242:243]
	v_fmac_f32_e32 v112, v0, v0
	v_fmac_f32_e32 v112, v2, v2
	global_store_dwordx4 v[130:131], v[0:3], off offset:192 sc1
	v_fmac_f32_e32 v112, v3, v3
	v_add_f32_e32 v112, v116, v112
	v_pk_mul_f32 v[2:3], v[142:143], v[2:3]
	v_pk_mul_f32 v[0:1], v[144:145], v[0:1]
	s_nop 0
	v_cvt_pk_bf16_f32 v0, v0, v1
	v_cvt_pk_bf16_f32 v1, v2, v3
	v_lshlrev_b32_e32 v2, 4, v152
	v_add3_u32 v2, v146, v2, v147
	ds_write_b64 v2, v[0:1] offset:2048
	v_cndmask_b32_e32 v0, v202, v230, vcc
	v_lshlrev_b32_e32 v0, 2, v0
	ds_bpermute_b32 v0, v0, v112
	v_cmp_lt_i32_e32 vcc, v209, v203
	s_waitcnt lgkmcnt(0)
	v_add_f32_e32 v112, v112, v0
	v_cndmask_b32_e32 v0, v202, v209, vcc
	v_lshlrev_b32_e32 v0, 2, v0
	ds_bpermute_b32 v113, v0, v112
	v_cmp_gt_u32_e32 vcc, 16, v185
	s_and_saveexec_b64 s[4:5], vcc
	s_cbranch_execz .LBB0_207
	v_lshlrev_b64 v[0:1], 6, v[128:129]
	s_waitcnt lgkmcnt(0)
	v_add_f32_e32 v2, v112, v113
	v_lshl_add_u64 v[0:1], v[140:141], 0, v[0:1]
	global_store_dword v[0:1], v2, off sc1

; DI unsigned pk2(float a, float b) { f32x2 v = {a, b}; bf2_t r = __builtin_convertvector(v, bf2_t); return __builtin_bit_cast(unsigned, r); }
;     static DI void run(const f32x4 (&acc)[8][4], const TileCtx& tc, const Params& p, ldsp_t wb) {
;     ...
;             for (int mm = 0; mm < 4; ++mm) { __builtin_amdgcn_sched_barrier(0);
;                 const int m = h * 4 + mm;
;                 const int row = tc.brow + tc.wr * 128 + m * 16 + tc.fr;
;                 float* xr = xrow_ptr(p, row) + col0;
;                 const float* xs = (EK == 1 && tc.l == 0) ? p.x + (size_t)row * DM + col0 : xr;
;                 float part = 0.f;
; #pragma unroll
;                 for (int n = 0; n < 4; ++n) {
;                     f32x4 xv = *(const f32x4*)(xs + n * 16);
;                     xv += gv[n] * acc[m][n];
;                     *(f32x4*)(xr + n * 16) = xv;
;                     if (has_next) {
;                         part += xv[0] * xv[0] + xv[1] * xv[1] + xv[2] * xv[2] + xv[3] * xv[3];
;                         const f32x4 hv = xv * av[n];
;                         u32x2 w; w[0] = pk2(hv[0], hv[1]); w[1] = pk2(hv[2], hv[3]);
;                         wave_put(wb, mm * 16 + tc.fr, n, tc.fq, w);
;                     }
;                 }
;                 if (has_next) {
;                     part += __shfl_xor(part, 16);
;                     part += __shfl_xor(part, 32);
;                     if (tc.fq == 0) ssp[(size_t)row * 16] = part;
;                 }
.LBB0_208:
	v_add_u32_e32 v112, 32, v132
	v_add_u32_e32 v0, 0xffffc020, v132
	s_waitcnt lgkmcnt(0)
	v_ashrrev_i32_e32 v113, 31, v112
	v_cmp_gt_i32_e32 vcc, s33, v112
	v_mov_b32_e32 v2, s71
	v_mov_b32_e32 v3, s55
	v_cndmask_b32_e32 v1, 0, v113, vcc
	v_cndmask_b32_e32 v0, v0, v112, vcc
	v_cndmask_b32_e32 v3, v2, v3, vcc
	v_mov_b32_e32 v2, s70
	v_mov_b32_e32 v114, s54
	v_cndmask_b32_e32 v2, v2, v114, vcc
	v_lshlrev_b64 v[0:1], 12, v[0:1]
	v_lshl_add_u64 v[0:1], v[2:3], 0, v[0:1]
	v_lshl_add_u64 v[114:115], v[176:177], 2, v[0:1]
	global_load_dwordx4 v[0:3], v[114:115], off
	global_load_dwordx4 v[232:235], v[114:115], off offset:64
	global_load_dwordx4 v[236:239], v[114:115], off offset:128
	global_load_dwordx4 v[240:243], v[114:115], off offset:192
	s_mov_b64 s[4:5], -1
	s_and_b64 vcc, exec, s[36:37]
	s_waitcnt vmcnt(3)
	v_pk_fma_f32 v[110:111], v[110:111], v[30:31], v[2:3]
	v_pk_fma_f32 v[108:109], v[108:109], v[28:29], v[0:1]
	global_store_dwordx4 v[114:115], v[108:111], off sc1
	s_cbranch_vccz .LBB0_210
	s_nop 1
	s_mov_b64 s[4:5], 0
	s_waitcnt vmcnt(3)
	v_pk_fma_f32 v[2:3], v[106:107], v[22:23], v[234:235]
	v_pk_fma_f32 v[0:1], v[104:105], v[20:21], v[232:233]
	global_store_dwordx4 v[114:115], v[0:3], off offset:64 sc1
	s_nop 1
	s_waitcnt vmcnt(3)
	v_pk_fma_f32 v[2:3], v[102:103], v[14:15], v[238:239]
	v_pk_fma_f32 v[0:1], v[100:101], v[12:13], v[236:237]
	global_store_dwordx4 v[114:115], v[0:3], off offset:128 sc1
	s_nop 1
	s_waitcnt vmcnt(3)
	v_pk_fma_f32 v[2:3], v[98:99], v[6:7], v[242:243]
	v_pk_fma_f32 v[0:1], v[96:97], v[4:5], v[240:241]
	global_store_dwordx4 v[114:115], v[0:3], off offset:192 sc1
.LBB0_210:
	s_andn2_b64 vcc, exec, s[4:5]
	s_cbranch_vccnz .LBB0_214
	v_pk_mul_f32 v[0:1], v[166:167], v[110:111]
	v_pk_mul_f32 v[2:3], v[164:165], v[108:109]
	v_mul_f32_e32 v116, v109, v109
	v_cvt_pk_bf16_f32 v2, v2, v3
	v_cvt_pk_bf16_f32 v3, v0, v1
	v_lshlrev_b32_e32 v0, 4, v155
	v_add3_u32 v0, v146, v0, v147
	ds_write_b64 v0, v[2:3] offset:4096
	s_nop 1
	v_fmac_f32_e32 v116, v108, v108
	v_fmac_f32_e32 v116, v110, v110
	v_fmac_f32_e32 v116, v111, v111
	v_cmp_lt_i32_e32 vcc, v230, v203
	s_waitcnt vmcnt(3)
	v_pk_fma_f32 v[0:1], v[104:105], v[20:21], v[232:233]
	s_nop 0
	v_mul_f32_e32 v104, v1, v1
	v_pk_fma_f32 v[2:3], v[106:107], v[22:23], v[234:235]
	v_fmac_f32_e32 v104, v0, v0
	v_fmac_f32_e32 v104, v2, v2
	global_store_dwordx4 v[114:115], v[0:3], off offset:64 sc1
	v_fmac_f32_e32 v104, v3, v3
	v_add_f32_e32 v104, v116, v104
	v_pk_mul_f32 v[2:3], v[158:159], v[2:3]
	v_pk_mul_f32 v[0:1], v[156:157], v[0:1]
	s_nop 0
	v_cvt_pk_bf16_f32 v0, v0, v1
	v_cvt_pk_bf16_f32 v1, v2, v3
	v_lshlrev_b32_e32 v2, 4, v154
	v_add3_u32 v2, v146, v2, v147
	ds_write_b64 v2, v[0:1] offset:4096
	s_nop 1
	s_waitcnt vmcnt(3)
	v_pk_fma_f32 v[0:1], v[100:101], v[12:13], v[236:237]
	s_nop 0
	v_mul_f32_e32 v100, v1, v1
	v_pk_fma_f32 v[2:3], v[102:103], v[14:15], v[238:239]
	v_fmac_f32_e32 v100, v0, v0
	v_fmac_f32_e32 v100, v2, v2
	global_store_dwordx4 v[114:115], v[0:3], off offset:128 sc1
	v_fmac_f32_e32 v100, v3, v3
	v_add_f32_e32 v100, v104, v100
	v_pk_mul_f32 v[2:3], v[150:151], v[2:3]
	v_pk_mul_f32 v[0:1], v[148:149], v[0:1]
	s_nop 0
	v_cvt_pk_bf16_f32 v0, v0, v1
	v_cvt_pk_bf16_f32 v1, v2, v3
	v_lshlrev_b32_e32 v2, 4, v153
	v_add3_u32 v2, v146, v2, v147
	ds_write_b64 v2, v[0:1] offset:4096
	s_nop 1
	s_waitcnt vmcnt(3)
	v_pk_fma_f32 v[0:1], v[96:97], v[4:5], v[240:241]
	s_nop 0
	v_mul_f32_e32 v96, v1, v1
	v_pk_fma_f32 v[2:3], v[98:99], v[6:7], v[242:243]
	v_fmac_f32_e32 v96, v0, v0
	v_fmac_f32_e32 v96, v2, v2
	global_store_dwordx4 v[114:115], v[0:3], off offset:192 sc1
	v_fmac_f32_e32 v96, v3, v3
	v_add_f32_e32 v96, v100, v96
	v_pk_mul_f32 v[2:3], v[142:143], v[2:3]
	v_pk_mul_f32 v[0:1], v[144:145], v[0:1]
	s_nop 0
	v_cvt_pk_bf16_f32 v0, v0, v1
	v_cvt_pk_bf16_f32 v1, v2, v3
	v_lshlrev_b32_e32 v2, 4, v152
	v_add3_u32 v2, v146, v2, v147
	ds_write_b64 v2, v[0:1] offset:4096
	v_cndmask_b32_e32 v0, v202, v230, vcc
	v_lshlrev_b32_e32 v0, 2, v0
	ds_bpermute_b32 v0, v0, v96
	v_cmp_lt_i32_e32 vcc, v209, v203
	s_waitcnt lgkmcnt(0)
	v_add_f32_e32 v96, v96, v0
	v_cndmask_b32_e32 v0, v202, v209, vcc
	v_lshlrev_b32_e32 v0, 2, v0
	ds_bpermute_b32 v97, v0, v96
	v_cmp_gt_u32_e32 vcc, 16, v185
	s_and_saveexec_b64 s[4:5], vcc
	s_cbranch_execz .LBB0_213
	v_lshlrev_b64 v[0:1], 6, v[112:113]
	s_waitcnt lgkmcnt(0)
	v_add_f32_e32 v2, v96, v97
	v_lshl_add_u64 v[0:1], v[140:141], 0, v[0:1]
	global_store_dword v[0:1], v2, off sc1

; DI unsigned pk2(float a, float b) { f32x2 v = {a, b}; bf2_t r = __builtin_convertvector(v, bf2_t); return __builtin_bit_cast(unsigned, r); }
;     static DI void run(const f32x4 (&acc)[8][4], const TileCtx& tc, const Params& p, ldsp_t wb) {
;     ...
;             for (int mm = 0; mm < 4; ++mm) { __builtin_amdgcn_sched_barrier(0);
;                 const int m = h * 4 + mm;
;                 const int row = tc.brow + tc.wr * 128 + m * 16 + tc.fr;
;                 float* xr = xrow_ptr(p, row) + col0;
;                 const float* xs = (EK == 1 && tc.l == 0) ? p.x + (size_t)row * DM + col0 : xr;
;                 float part = 0.f;
; #pragma unroll
;                 for (int n = 0; n < 4; ++n) {
;                     f32x4 xv = *(const f32x4*)(xs + n * 16);
;                     xv += gv[n] * acc[m][n];
;                     *(f32x4*)(xr + n * 16) = xv;
;                     if (has_next) {
;                         part += xv[0] * xv[0] + xv[1] * xv[1] + xv[2] * xv[2] + xv[3] * xv[3];
;                         const f32x4 hv = xv * av[n];
;                         u32x2 w; w[0] = pk2(hv[0], hv[1]); w[1] = pk2(hv[2], hv[3]);
;                         wave_put(wb, mm * 16 + tc.fr, n, tc.fq, w);
;                     }
;                 }
;                 if (has_next) {
;                     part += __shfl_xor(part, 16);
;                     part += __shfl_xor(part, 32);
;                     if (tc.fq == 0) ssp[(size_t)row * 16] = part;
;                 }
.LBB0_214:
	v_add_u32_e32 v96, 48, v132
	v_add_u32_e32 v0, 0xffffc030, v132
	s_waitcnt lgkmcnt(0)
	v_ashrrev_i32_e32 v97, 31, v96
	v_cmp_gt_i32_e32 vcc, s33, v96
	v_mov_b32_e32 v2, s71
	v_mov_b32_e32 v3, s55
	v_cndmask_b32_e32 v1, 0, v97, vcc
	v_cndmask_b32_e32 v0, v0, v96, vcc
	v_cndmask_b32_e32 v3, v2, v3, vcc
	v_mov_b32_e32 v2, s70
	v_mov_b32_e32 v98, s54
	v_cndmask_b32_e32 v2, v2, v98, vcc
	v_lshlrev_b64 v[0:1], 12, v[0:1]
	v_lshl_add_u64 v[0:1], v[2:3], 0, v[0:1]
	v_lshl_add_u64 v[98:99], v[176:177], 2, v[0:1]
	global_load_dwordx4 v[0:3], v[98:99], off
	global_load_dwordx4 v[232:235], v[98:99], off offset:64
	global_load_dwordx4 v[236:239], v[98:99], off offset:128
	global_load_dwordx4 v[240:243], v[98:99], off offset:192
	s_mov_b64 s[4:5], -1
	s_and_b64 vcc, exec, s[36:37]
	s_waitcnt vmcnt(3)
	v_pk_fma_f32 v[94:95], v[94:95], v[30:31], v[2:3]
	v_pk_fma_f32 v[92:93], v[92:93], v[28:29], v[0:1]
	global_store_dwordx4 v[98:99], v[92:95], off sc1
	s_cbranch_vccz .LBB0_216
	s_nop 1
	s_mov_b64 s[4:5], 0
	s_waitcnt vmcnt(3)
	v_pk_fma_f32 v[2:3], v[90:91], v[22:23], v[234:235]
	v_pk_fma_f32 v[0:1], v[88:89], v[20:21], v[232:233]
	global_store_dwordx4 v[98:99], v[0:3], off offset:64 sc1
	s_nop 1
	s_waitcnt vmcnt(3)
	v_pk_fma_f32 v[2:3], v[86:87], v[14:15], v[238:239]
	v_pk_fma_f32 v[0:1], v[84:85], v[12:13], v[236:237]
	global_store_dwordx4 v[98:99], v[0:3], off offset:128 sc1
	s_nop 1
	s_waitcnt vmcnt(3)
	v_pk_fma_f32 v[2:3], v[82:83], v[6:7], v[242:243]
	v_pk_fma_f32 v[0:1], v[80:81], v[4:5], v[240:241]
	global_store_dwordx4 v[98:99], v[0:3], off offset:192 sc1
.LBB0_216:
	s_andn2_b64 vcc, exec, s[4:5]
	s_cbranch_vccnz .LBB0_220
	v_pk_mul_f32 v[0:1], v[166:167], v[94:95]
	v_pk_mul_f32 v[2:3], v[164:165], v[92:93]
	v_mul_f32_e32 v100, v93, v93
	v_cvt_pk_bf16_f32 v2, v2, v3
	v_cvt_pk_bf16_f32 v3, v0, v1
	v_lshlrev_b32_e32 v0, 4, v155
	v_add3_u32 v0, v146, v0, v147
	ds_write_b64 v0, v[2:3] offset:6144
	s_nop 1
	v_fmac_f32_e32 v100, v92, v92
	v_fmac_f32_e32 v100, v94, v94
	v_fmac_f32_e32 v100, v95, v95
	v_cmp_lt_i32_e32 vcc, v230, v203
	s_waitcnt vmcnt(3)
	v_pk_fma_f32 v[0:1], v[88:89], v[20:21], v[232:233]
	s_nop 0
	v_mul_f32_e32 v88, v1, v1
	v_pk_fma_f32 v[2:3], v[90:91], v[22:23], v[234:235]
	v_fmac_f32_e32 v88, v0, v0
	v_fmac_f32_e32 v88, v2, v2
	global_store_dwordx4 v[98:99], v[0:3], off offset:64 sc1
	v_fmac_f32_e32 v88, v3, v3
	v_add_f32_e32 v88, v100, v88
	v_pk_mul_f32 v[2:3], v[158:159], v[2:3]
	v_pk_mul_f32 v[0:1], v[156:157], v[0:1]
	s_nop 0
	v_cvt_pk_bf16_f32 v0, v0, v1
	v_cvt_pk_bf16_f32 v1, v2, v3
	v_lshlrev_b32_e32 v2, 4, v154
	v_add3_u32 v2, v146, v2, v147
	ds_write_b64 v2, v[0:1] offset:6144
	s_nop 1
	s_waitcnt vmcnt(3)
	v_pk_fma_f32 v[0:1], v[84:85], v[12:13], v[236:237]
	s_nop 0
	v_mul_f32_e32 v84, v1, v1
	v_pk_fma_f32 v[2:3], v[86:87], v[14:15], v[238:239]
	v_fmac_f32_e32 v84, v0, v0
	v_fmac_f32_e32 v84, v2, v2
	global_store_dwordx4 v[98:99], v[0:3], off offset:128 sc1
	v_fmac_f32_e32 v84, v3, v3
	v_add_f32_e32 v84, v88, v84
	v_pk_mul_f32 v[2:3], v[150:151], v[2:3]
	v_pk_mul_f32 v[0:1], v[148:149], v[0:1]
	s_nop 0
	v_cvt_pk_bf16_f32 v0, v0, v1
	v_cvt_pk_bf16_f32 v1, v2, v3
	v_lshlrev_b32_e32 v2, 4, v153
	v_add3_u32 v2, v146, v2, v147
	ds_write_b64 v2, v[0:1] offset:6144
	s_nop 1
	s_waitcnt vmcnt(3)
	v_pk_fma_f32 v[0:1], v[80:81], v[4:5], v[240:241]
	s_nop 0
	v_mul_f32_e32 v80, v1, v1
	v_pk_fma_f32 v[2:3], v[82:83], v[6:7], v[242:243]
	v_fmac_f32_e32 v80, v0, v0
	v_fmac_f32_e32 v80, v2, v2
	global_store_dwordx4 v[98:99], v[0:3], off offset:192 sc1
	v_fmac_f32_e32 v80, v3, v3
	v_add_f32_e32 v80, v84, v80
	v_pk_mul_f32 v[2:3], v[142:143], v[2:3]
	v_pk_mul_f32 v[0:1], v[144:145], v[0:1]
	s_nop 0
	v_cvt_pk_bf16_f32 v0, v0, v1
	v_cvt_pk_bf16_f32 v1, v2, v3
	v_lshlrev_b32_e32 v2, 4, v152
	v_add3_u32 v2, v146, v2, v147
	ds_write_b64 v2, v[0:1] offset:6144
	v_cndmask_b32_e32 v0, v202, v230, vcc
	v_lshlrev_b32_e32 v0, 2, v0
	ds_bpermute_b32 v0, v0, v80
	v_cmp_lt_i32_e32 vcc, v209, v203
	s_waitcnt lgkmcnt(0)
	v_add_f32_e32 v80, v80, v0
	v_cndmask_b32_e32 v0, v202, v209, vcc
	v_lshlrev_b32_e32 v0, 2, v0
	ds_bpermute_b32 v81, v0, v80
	v_cmp_gt_u32_e32 vcc, 16, v185
	s_and_saveexec_b64 s[4:5], vcc
	s_cbranch_execz .LBB0_219
	v_lshlrev_b64 v[0:1], 6, v[96:97]
	s_waitcnt lgkmcnt(0)
	v_add_f32_e32 v2, v80, v81
	v_lshl_add_u64 v[0:1], v[140:141], 0, v[0:1]
	global_store_dword v[0:1], v2, off sc1
; #define LDSP __attribute__((address_space(3)))
; DI unsigned pk2(float a, float b) { f32x2 v = {a, b}; bf2_t r = __builtin_convertvector(v, bf2_t); return __builtin_bit_cast(unsigned, r); }
; DI void wave_rows_store(ldsp_t wb, int lane, bf16_t* dst0, size_t ld) {
; #pragma unroll
;     for (int i = 0; i < 8; ++i) {
;         const int row = i * 8 + (lane >> 3), ch = lane & 7;
;         const u32x4 v = *(const LDSP u32x4*)(wb + row * 128 + ((ch ^ (row & 7)) << 4));
;         *(u32x4*)(dst0 + (size_t)row * ld + ch * 8) = v;
;     }
; }
;     static DI void run(const f32x4 (&acc)[8][4], const TileCtx& tc, const Params& p, ldsp_t wb) {
;     ...
;             for (int mm = 0; mm < 4; ++mm) { __builtin_amdgcn_sched_barrier(0);
;                 const int m = h * 4 + mm;
;                 const int row = tc.brow + tc.wr * 128 + m * 16 + tc.fr;
;                 float* xr = xrow_ptr(p, row) + col0;
;                 const float* xs = (EK == 1 && tc.l == 0) ? p.x + (size_t)row * DM + col0 : xr;
;                 float part = 0.f;
; #pragma unroll
;                 for (int n = 0; n < 4; ++n) {
;                     f32x4 xv = *(const f32x4*)(xs + n * 16);
;                     xv += gv[n] * acc[m][n];
;                     *(f32x4*)(xr + n * 16) = xv;
;                     if (has_next) {
;                         part += xv[0] * xv[0] + xv[1] * xv[1] + xv[2] * xv[2] + xv[3] * xv[3];
;                         const f32x4 hv = xv * av[n];
;                         u32x2 w; w[0] = pk2(hv[0], hv[1]); w[1] = pk2(hv[2], hv[3]);
;                         wave_put(wb, mm * 16 + tc.fr, n, tc.fq, w);
;                     }
;                 }
;                 if (has_next) {
;                     part += __shfl_xor(part, 16);
;                     part += __shfl_xor(part, 32);
;                     if (tc.fq == 0) ssp[(size_t)row * 16] = part;
;                 }
;             }
;             if (has_next) wave_rows_store(wb, tc.lane, p.H + (size_t)(tc.brow + tc.wr * 128 + h * 64) * DM + tc.bcol + tc.wc * 64, DM);
.LBB0_219:
	s_or_b64 exec, exec, s[4:5]
	v_lshrrev_b32_e32 v84, 3, v185
	v_ashrrev_i32_e32 v179, 31, v178
	v_xor_b32_e32 v2, v84, v185
	v_lshlrev_b64 v[0:1], 11, v[178:179]
	v_lshlrev_b32_e32 v2, 4, v2
	v_lshl_add_u64 v[0:1], s[82:83], 0, v[0:1]
	s_ashr_i32 s35, s34, 31
	v_and_b32_e32 v2, 0x70, v2
	v_lshl_add_u64 v[0:1], s[34:35], 1, v[0:1]
	v_lshlrev_b32_e32 v192, 1, v184
	v_add_u32_e32 v85, v186, v2
	v_lshlrev_b32_e32 v2, 4, v185
	v_lshl_add_u64 v[0:1], v[0:1], 0, v[192:193]
	v_and_b32_e32 v192, 0x70, v2
	s_waitcnt lgkmcnt(0)
	v_lshl_add_u64 v[80:81], v[0:1], 0, v[192:193]
	v_lshl_add_u32 v0, v84, 7, v85
	ds_read_b128 v[0:3], v0
	v_lshlrev_b32_e32 v192, 11, v84
	v_lshl_add_u64 v[82:83], v[80:81], 0, v[192:193]
	s_waitcnt lgkmcnt(0)
	global_store_dwordx4 v[82:83], v[0:3], off sc1
	v_or_b32_e32 v82, 8, v84
	s_nop 0
	v_lshl_add_u32 v0, v82, 7, v85
	ds_read_b128 v[0:3], v0
	v_lshlrev_b32_e32 v192, 11, v82
	v_lshl_add_u64 v[82:83], v[80:81], 0, v[192:193]
	s_waitcnt lgkmcnt(0)
	global_store_dwordx4 v[82:83], v[0:3], off sc1
	v_or_b32_e32 v82, 16, v84
	s_nop 0
	v_lshl_add_u32 v0, v82, 7, v85
	ds_read_b128 v[0:3], v0
	v_lshlrev_b32_e32 v192, 11, v82
	v_lshl_add_u64 v[82:83], v[80:81], 0, v[192:193]
	s_waitcnt lgkmcnt(0)
	global_store_dwordx4 v[82:83], v[0:3], off sc1
	v_or_b32_e32 v82, 24, v84
	s_nop 0
	v_lshl_add_u32 v0, v82, 7, v85
	ds_read_b128 v[0:3], v0
	v_lshlrev_b32_e32 v192, 11, v82
	v_lshl_add_u64 v[82:83], v[80:81], 0, v[192:193]
	s_waitcnt lgkmcnt(0)
	global_store_dwordx4 v[82:83], v[0:3], off sc1
	v_or_b32_e32 v82, 32, v84
	s_nop 0
	v_lshl_add_u32 v0, v82, 7, v85
	ds_read_b128 v[0:3], v0
	v_lshlrev_b32_e32 v192, 11, v82
	v_lshl_add_u64 v[82:83], v[80:81], 0, v[192:193]
	s_waitcnt lgkmcnt(0)
	global_store_dwordx4 v[82:83], v[0:3], off sc1
	v_or_b32_e32 v82, 40, v84
	s_nop 0
	v_lshl_add_u32 v0, v82, 7, v85
	ds_read_b128 v[0:3], v0
	v_lshlrev_b32_e32 v192, 11, v82
	v_lshl_add_u64 v[82:83], v[80:81], 0, v[192:193]
	s_waitcnt lgkmcnt(0)
	global_store_dwordx4 v[82:83], v[0:3], off sc1
	v_or_b32_e32 v82, 48, v84
	s_nop 0
	v_lshl_add_u32 v0, v82, 7, v85
	ds_read_b128 v[0:3], v0
	v_lshlrev_b32_e32 v192, 11, v82
	v_lshl_add_u64 v[82:83], v[80:81], 0, v[192:193]
	s_waitcnt lgkmcnt(0)
	global_store_dwordx4 v[82:83], v[0:3], off sc1
	v_or_b32_e32 v82, 56, v84
	s_nop 0
	v_lshl_add_u32 v0, v82, 7, v85
	ds_read_b128 v[0:3], v0
	v_lshlrev_b32_e32 v192, 11, v82
	v_lshl_add_u64 v[80:81], v[80:81], 0, v[192:193]
	s_waitcnt lgkmcnt(0)
	global_store_dwordx4 v[80:81], v[0:3], off sc1
.LBB0_220:
	v_add3_u32 v80, v188, s43, 64
	v_or_b32_e32 v82, v80, v187
	v_add_u32_e32 v0, 0xffffc000, v82
	v_ashrrev_i32_e32 v83, 31, v82
	v_cmp_gt_i32_e32 vcc, s33, v82
	v_mov_b32_e32 v2, s71
	v_mov_b32_e32 v3, s55
	v_cndmask_b32_e32 v1, 0, v83, vcc
	v_cndmask_b32_e32 v0, v0, v82, vcc
	v_cndmask_b32_e32 v3, v2, v3, vcc
	v_mov_b32_e32 v2, s70
	v_mov_b32_e32 v81, s54
	v_cndmask_b32_e32 v2, v2, v81, vcc
	v_lshlrev_b64 v[0:1], 12, v[0:1]
	v_lshl_add_u64 v[0:1], v[2:3], 0, v[0:1]
	v_lshl_add_u64 v[84:85], v[176:177], 2, v[0:1]
	global_load_dwordx4 v[0:3], v[84:85], off
	global_load_dwordx4 v[232:235], v[84:85], off offset:64
	global_load_dwordx4 v[236:239], v[84:85], off offset:128
	global_load_dwordx4 v[240:243], v[84:85], off offset:192
	s_mov_b64 s[4:5], -1
	s_and_b64 vcc, exec, s[36:37]
	s_waitcnt vmcnt(3)
	v_pk_fma_f32 v[78:79], v[78:79], v[30:31], v[2:3]
	v_pk_fma_f32 v[76:77], v[76:77], v[28:29], v[0:1]
	global_store_dwordx4 v[84:85], v[76:79], off sc1
	s_cbranch_vccz .LBB0_222
	s_nop 1
	s_mov_b64 s[4:5], 0
	s_waitcnt vmcnt(3)
	v_pk_fma_f32 v[2:3], v[74:75], v[22:23], v[234:235]
	v_pk_fma_f32 v[0:1], v[72:73], v[20:21], v[232:233]
	global_store_dwordx4 v[84:85], v[0:3], off offset:64 sc1
	s_nop 1
	s_waitcnt vmcnt(3)
	v_pk_fma_f32 v[2:3], v[196:197], v[14:15], v[238:239]
	v_pk_fma_f32 v[0:1], v[194:195], v[12:13], v[236:237]
	global_store_dwordx4 v[84:85], v[0:3], off offset:128 sc1
	s_nop 1
	s_waitcnt vmcnt(3)
	v_pk_fma_f32 v[2:3], v[66:67], v[6:7], v[242:243]
	v_pk_fma_f32 v[0:1], v[64:65], v[4:5], v[240:241]
	global_store_dwordx4 v[84:85], v[0:3], off offset:192 sc1
.LBB0_222:
	s_andn2_b64 vcc, exec, s[4:5]
	s_cbranch_vccnz .LBB0_226
	v_pk_mul_f32 v[0:1], v[166:167], v[78:79]
	v_pk_mul_f32 v[2:3], v[164:165], v[76:77]
	v_mul_f32_e32 v81, v77, v77
	v_cvt_pk_bf16_f32 v2, v2, v3
	v_cvt_pk_bf16_f32 v3, v0, v1
	v_lshlrev_b32_e32 v0, 4, v155
	v_add3_u32 v0, v146, v0, v147
	ds_write_b64 v0, v[2:3]
	s_nop 1
	v_fmac_f32_e32 v81, v76, v76
	v_fmac_f32_e32 v81, v78, v78
	v_fmac_f32_e32 v81, v79, v79
	v_cmp_lt_i32_e32 vcc, v230, v203
	s_waitcnt vmcnt(3)
	v_pk_fma_f32 v[0:1], v[72:73], v[20:21], v[232:233]
	s_nop 0
	v_mul_f32_e32 v72, v1, v1
	v_pk_fma_f32 v[2:3], v[74:75], v[22:23], v[234:235]
	v_fmac_f32_e32 v72, v0, v0
	v_fmac_f32_e32 v72, v2, v2
	global_store_dwordx4 v[84:85], v[0:3], off offset:64 sc1
	v_fmac_f32_e32 v72, v3, v3
	v_add_f32_e32 v72, v81, v72
	v_pk_mul_f32 v[2:3], v[158:159], v[2:3]
	v_pk_mul_f32 v[0:1], v[156:157], v[0:1]
	s_nop 0
	v_cvt_pk_bf16_f32 v0, v0, v1
	v_cvt_pk_bf16_f32 v1, v2, v3
	v_lshlrev_b32_e32 v2, 4, v154
	v_add3_u32 v2, v146, v2, v147
	ds_write_b64 v2, v[0:1]
	s_nop 1
	s_waitcnt vmcnt(3)
	v_pk_fma_f32 v[0:1], v[194:195], v[12:13], v[236:237]
	s_nop 0
	v_mul_f32_e32 v73, v1, v1
	v_pk_fma_f32 v[2:3], v[196:197], v[14:15], v[238:239]
	v_fmac_f32_e32 v73, v0, v0
	v_fmac_f32_e32 v73, v2, v2
	global_store_dwordx4 v[84:85], v[0:3], off offset:128 sc1
	v_fmac_f32_e32 v73, v3, v3
	v_add_f32_e32 v72, v72, v73
	v_pk_mul_f32 v[2:3], v[150:151], v[2:3]
	v_pk_mul_f32 v[0:1], v[148:149], v[0:1]
	s_nop 0
	v_cvt_pk_bf16_f32 v0, v0, v1
	v_cvt_pk_bf16_f32 v1, v2, v3
	v_lshlrev_b32_e32 v2, 4, v153
	v_add3_u32 v2, v146, v2, v147
	ds_write_b64 v2, v[0:1]
	s_nop 1
	s_waitcnt vmcnt(3)
	v_pk_fma_f32 v[0:1], v[64:65], v[4:5], v[240:241]
	s_nop 0
	v_mul_f32_e32 v64, v1, v1
	v_pk_fma_f32 v[2:3], v[66:67], v[6:7], v[242:243]
	v_fmac_f32_e32 v64, v0, v0
	v_fmac_f32_e32 v64, v2, v2
	global_store_dwordx4 v[84:85], v[0:3], off offset:192 sc1
	v_fmac_f32_e32 v64, v3, v3
	v_add_f32_e32 v64, v72, v64
	v_pk_mul_f32 v[2:3], v[142:143], v[2:3]
	v_pk_mul_f32 v[0:1], v[144:145], v[0:1]
	s_nop 0
	v_cvt_pk_bf16_f32 v0, v0, v1
	v_cvt_pk_bf16_f32 v1, v2, v3
	v_lshlrev_b32_e32 v2, 4, v152
	v_add3_u32 v2, v146, v2, v147
	ds_write_b64 v2, v[0:1]
	v_cndmask_b32_e32 v0, v202, v230, vcc
	v_lshlrev_b32_e32 v0, 2, v0
	ds_bpermute_b32 v0, v0, v64
	v_cmp_lt_i32_e32 vcc, v209, v203
	s_waitcnt lgkmcnt(0)
	v_add_f32_e32 v64, v64, v0
	v_cndmask_b32_e32 v0, v202, v209, vcc
	v_lshlrev_b32_e32 v0, 2, v0
	ds_bpermute_b32 v65, v0, v64
	v_cmp_gt_u32_e32 vcc, 16, v185
	s_and_saveexec_b64 s[4:5], vcc
	s_cbranch_execz .LBB0_225
	v_lshlrev_b64 v[0:1], 6, v[82:83]
	s_waitcnt lgkmcnt(0)
	v_add_f32_e32 v2, v64, v65
	v_lshl_add_u64 v[0:1], v[140:141], 0, v[0:1]
	global_store_dword v[0:1], v2, off sc1

; DI unsigned pk2(float a, float b) { f32x2 v = {a, b}; bf2_t r = __builtin_convertvector(v, bf2_t); return __builtin_bit_cast(unsigned, r); }
;     static DI void run(const f32x4 (&acc)[8][4], const TileCtx& tc, const Params& p, ldsp_t wb) {
;     ...
;             for (int mm = 0; mm < 4; ++mm) { __builtin_amdgcn_sched_barrier(0);
;                 const int m = h * 4 + mm;
;                 const int row = tc.brow + tc.wr * 128 + m * 16 + tc.fr;
;                 float* xr = xrow_ptr(p, row) + col0;
;                 const float* xs = (EK == 1 && tc.l == 0) ? p.x + (size_t)row * DM + col0 : xr;
;                 float part = 0.f;
; #pragma unroll
;                 for (int n = 0; n < 4; ++n) {
;                     f32x4 xv = *(const f32x4*)(xs + n * 16);
;                     xv += gv[n] * acc[m][n];
;                     *(f32x4*)(xr + n * 16) = xv;
;                     if (has_next) {
;                         part += xv[0] * xv[0] + xv[1] * xv[1] + xv[2] * xv[2] + xv[3] * xv[3];
;                         const f32x4 hv = xv * av[n];
;                         u32x2 w; w[0] = pk2(hv[0], hv[1]); w[1] = pk2(hv[2], hv[3]);
;                         wave_put(wb, mm * 16 + tc.fr, n, tc.fq, w);
;                     }
;                 }
;                 if (has_next) {
;                     part += __shfl_xor(part, 16);
;                     part += __shfl_xor(part, 32);
;                     if (tc.fq == 0) ssp[(size_t)row * 16] = part;
;                 }
.LBB0_226:
	v_add_u32_e32 v64, 0x50, v132
	v_add_u32_e32 v0, 0xffffc050, v132
	s_waitcnt lgkmcnt(0)
	v_ashrrev_i32_e32 v65, 31, v64
	v_cmp_gt_i32_e32 vcc, s33, v64
	v_mov_b32_e32 v2, s71
	v_mov_b32_e32 v3, s55
	v_cndmask_b32_e32 v1, 0, v65, vcc
	v_cndmask_b32_e32 v0, v0, v64, vcc
	v_cndmask_b32_e32 v3, v2, v3, vcc
	v_mov_b32_e32 v2, s70
	v_mov_b32_e32 v66, s54
	v_cndmask_b32_e32 v2, v2, v66, vcc
	v_lshlrev_b64 v[0:1], 12, v[0:1]
	v_lshl_add_u64 v[0:1], v[2:3], 0, v[0:1]
	v_lshl_add_u64 v[66:67], v[176:177], 2, v[0:1]
	global_load_dwordx4 v[0:3], v[66:67], off
	global_load_dwordx4 v[232:235], v[66:67], off offset:64
	global_load_dwordx4 v[236:239], v[66:67], off offset:128
	global_load_dwordx4 v[240:243], v[66:67], off offset:192
	s_mov_b64 s[4:5], -1
	s_and_b64 vcc, exec, s[36:37]
	s_waitcnt vmcnt(3)
	v_pk_fma_f32 v[62:63], v[62:63], v[30:31], v[2:3]
	v_pk_fma_f32 v[60:61], v[60:61], v[28:29], v[0:1]
	global_store_dwordx4 v[66:67], v[60:63], off sc1
	s_cbranch_vccz .LBB0_228
	s_nop 1
	s_mov_b64 s[4:5], 0
	s_waitcnt vmcnt(3)
	v_pk_fma_f32 v[2:3], v[58:59], v[22:23], v[234:235]
	v_pk_fma_f32 v[0:1], v[56:57], v[20:21], v[232:233]
	global_store_dwordx4 v[66:67], v[0:3], off offset:64 sc1
	s_nop 1
	s_waitcnt vmcnt(3)
	v_pk_fma_f32 v[2:3], v[54:55], v[14:15], v[238:239]
	v_pk_fma_f32 v[0:1], v[52:53], v[12:13], v[236:237]
	global_store_dwordx4 v[66:67], v[0:3], off offset:128 sc1
	s_nop 1
	s_waitcnt vmcnt(3)
	v_pk_fma_f32 v[2:3], v[50:51], v[6:7], v[242:243]
	v_pk_fma_f32 v[0:1], v[48:49], v[4:5], v[240:241]
	global_store_dwordx4 v[66:67], v[0:3], off offset:192 sc1
.LBB0_228:
	s_andn2_b64 vcc, exec, s[4:5]
	s_cbranch_vccnz .LBB0_232
	v_pk_mul_f32 v[0:1], v[166:167], v[62:63]
	v_pk_mul_f32 v[2:3], v[164:165], v[60:61]
	v_mul_f32_e32 v72, v61, v61
	v_cvt_pk_bf16_f32 v2, v2, v3
	v_cvt_pk_bf16_f32 v3, v0, v1
	v_lshlrev_b32_e32 v0, 4, v155
	v_add3_u32 v0, v146, v0, v147
	ds_write_b64 v0, v[2:3] offset:2048
	s_nop 1
	v_fmac_f32_e32 v72, v60, v60
	v_fmac_f32_e32 v72, v62, v62
	v_fmac_f32_e32 v72, v63, v63
	v_cmp_lt_i32_e32 vcc, v230, v203
	s_waitcnt vmcnt(3)
	v_pk_fma_f32 v[0:1], v[56:57], v[20:21], v[232:233]
	s_nop 0
	v_mul_f32_e32 v56, v1, v1
	v_pk_fma_f32 v[2:3], v[58:59], v[22:23], v[234:235]
	v_fmac_f32_e32 v56, v0, v0
	v_fmac_f32_e32 v56, v2, v2
	global_store_dwordx4 v[66:67], v[0:3], off offset:64 sc1
	v_fmac_f32_e32 v56, v3, v3
	v_add_f32_e32 v56, v72, v56
	v_pk_mul_f32 v[2:3], v[158:159], v[2:3]
	v_pk_mul_f32 v[0:1], v[156:157], v[0:1]
	s_nop 0
	v_cvt_pk_bf16_f32 v0, v0, v1
	v_cvt_pk_bf16_f32 v1, v2, v3
	v_lshlrev_b32_e32 v2, 4, v154
	v_add3_u32 v2, v146, v2, v147
	ds_write_b64 v2, v[0:1] offset:2048
	s_nop 1
	s_waitcnt vmcnt(3)
	v_pk_fma_f32 v[0:1], v[52:53], v[12:13], v[236:237]
	s_nop 0
	v_mul_f32_e32 v52, v1, v1
	v_pk_fma_f32 v[2:3], v[54:55], v[14:15], v[238:239]
	v_fmac_f32_e32 v52, v0, v0
	v_fmac_f32_e32 v52, v2, v2
	global_store_dwordx4 v[66:67], v[0:3], off offset:128 sc1
	v_fmac_f32_e32 v52, v3, v3
	v_add_f32_e32 v52, v56, v52
	v_pk_mul_f32 v[2:3], v[150:151], v[2:3]
	v_pk_mul_f32 v[0:1], v[148:149], v[0:1]
	s_nop 0
	v_cvt_pk_bf16_f32 v0, v0, v1
	v_cvt_pk_bf16_f32 v1, v2, v3
	v_lshlrev_b32_e32 v2, 4, v153
	v_add3_u32 v2, v146, v2, v147
	ds_write_b64 v2, v[0:1] offset:2048
	s_nop 1
	s_waitcnt vmcnt(3)
	v_pk_fma_f32 v[0:1], v[48:49], v[4:5], v[240:241]
	s_nop 0
	v_mul_f32_e32 v48, v1, v1
	v_pk_fma_f32 v[2:3], v[50:51], v[6:7], v[242:243]
	v_fmac_f32_e32 v48, v0, v0
	v_fmac_f32_e32 v48, v2, v2
	global_store_dwordx4 v[66:67], v[0:3], off offset:192 sc1
	v_fmac_f32_e32 v48, v3, v3
	v_add_f32_e32 v48, v52, v48
	v_pk_mul_f32 v[2:3], v[142:143], v[2:3]
	v_pk_mul_f32 v[0:1], v[144:145], v[0:1]
	s_nop 0
	v_cvt_pk_bf16_f32 v0, v0, v1
	v_cvt_pk_bf16_f32 v1, v2, v3
	v_lshlrev_b32_e32 v2, 4, v152
	v_add3_u32 v2, v146, v2, v147
	ds_write_b64 v2, v[0:1] offset:2048
	v_cndmask_b32_e32 v0, v202, v230, vcc
	v_lshlrev_b32_e32 v0, 2, v0
	ds_bpermute_b32 v0, v0, v48
	v_cmp_lt_i32_e32 vcc, v209, v203
	s_waitcnt lgkmcnt(0)
	v_add_f32_e32 v48, v48, v0
	v_cndmask_b32_e32 v0, v202, v209, vcc
	v_lshlrev_b32_e32 v0, 2, v0
	ds_bpermute_b32 v49, v0, v48
	v_cmp_gt_u32_e32 vcc, 16, v185
	s_and_saveexec_b64 s[4:5], vcc
	s_cbranch_execz .LBB0_231
	v_lshlrev_b64 v[0:1], 6, v[64:65]
	s_waitcnt lgkmcnt(0)
	v_add_f32_e32 v2, v48, v49
	v_lshl_add_u64 v[0:1], v[140:141], 0, v[0:1]
	global_store_dword v[0:1], v2, off sc1

; DI unsigned pk2(float a, float b) { f32x2 v = {a, b}; bf2_t r = __builtin_convertvector(v, bf2_t); return __builtin_bit_cast(unsigned, r); }
;     static DI void run(const f32x4 (&acc)[8][4], const TileCtx& tc, const Params& p, ldsp_t wb) {
;     ...
;             for (int mm = 0; mm < 4; ++mm) { __builtin_amdgcn_sched_barrier(0);
;                 const int m = h * 4 + mm;
;                 const int row = tc.brow + tc.wr * 128 + m * 16 + tc.fr;
;                 float* xr = xrow_ptr(p, row) + col0;
;                 const float* xs = (EK == 1 && tc.l == 0) ? p.x + (size_t)row * DM + col0 : xr;
;                 float part = 0.f;
; #pragma unroll
;                 for (int n = 0; n < 4; ++n) {
;                     f32x4 xv = *(const f32x4*)(xs + n * 16);
;                     xv += gv[n] * acc[m][n];
;                     *(f32x4*)(xr + n * 16) = xv;
;                     if (has_next) {
;                         part += xv[0] * xv[0] + xv[1] * xv[1] + xv[2] * xv[2] + xv[3] * xv[3];
;                         const f32x4 hv = xv * av[n];
;                         u32x2 w; w[0] = pk2(hv[0], hv[1]); w[1] = pk2(hv[2], hv[3]);
;                         wave_put(wb, mm * 16 + tc.fr, n, tc.fq, w);
;                     }
;                 }
;                 if (has_next) {
;                     part += __shfl_xor(part, 16);
;                     part += __shfl_xor(part, 32);
;                     if (tc.fq == 0) ssp[(size_t)row * 16] = part;
;                 }
.LBB0_232:
	v_add_u32_e32 v48, 0x60, v132
	v_add_u32_e32 v0, 0xffffc060, v132
	s_waitcnt lgkmcnt(0)
	v_ashrrev_i32_e32 v49, 31, v48
	v_cmp_gt_i32_e32 vcc, s33, v48
	v_mov_b32_e32 v2, s71
	v_mov_b32_e32 v3, s55
	v_cndmask_b32_e32 v1, 0, v49, vcc
	v_cndmask_b32_e32 v0, v0, v48, vcc
	v_cndmask_b32_e32 v3, v2, v3, vcc
	v_mov_b32_e32 v2, s70
	v_mov_b32_e32 v50, s54
	v_cndmask_b32_e32 v2, v2, v50, vcc
	v_lshlrev_b64 v[0:1], 12, v[0:1]
	v_lshl_add_u64 v[0:1], v[2:3], 0, v[0:1]
	v_lshl_add_u64 v[50:51], v[176:177], 2, v[0:1]
	global_load_dwordx4 v[0:3], v[50:51], off
	global_load_dwordx4 v[232:235], v[50:51], off offset:64
	global_load_dwordx4 v[236:239], v[50:51], off offset:128
	global_load_dwordx4 v[240:243], v[50:51], off offset:192
	s_mov_b64 s[4:5], -1
	s_and_b64 vcc, exec, s[36:37]
	s_waitcnt vmcnt(3)
	v_pk_fma_f32 v[46:47], v[46:47], v[30:31], v[2:3]
	v_pk_fma_f32 v[44:45], v[44:45], v[28:29], v[0:1]
	global_store_dwordx4 v[50:51], v[44:47], off sc1
	s_cbranch_vccz .LBB0_234
	s_nop 1
	s_mov_b64 s[4:5], 0
	s_waitcnt vmcnt(3)
	v_pk_fma_f32 v[2:3], v[42:43], v[22:23], v[234:235]
	v_pk_fma_f32 v[0:1], v[40:41], v[20:21], v[232:233]
	global_store_dwordx4 v[50:51], v[0:3], off offset:64 sc1
	s_nop 1
	s_waitcnt vmcnt(3)
	v_pk_fma_f32 v[2:3], v[38:39], v[14:15], v[238:239]
	v_pk_fma_f32 v[0:1], v[36:37], v[12:13], v[236:237]
	global_store_dwordx4 v[50:51], v[0:3], off offset:128 sc1
	s_nop 1
	s_waitcnt vmcnt(3)
	v_pk_fma_f32 v[2:3], v[34:35], v[6:7], v[242:243]
	v_pk_fma_f32 v[0:1], v[32:33], v[4:5], v[240:241]
	global_store_dwordx4 v[50:51], v[0:3], off offset:192 sc1
.LBB0_234:
	s_andn2_b64 vcc, exec, s[4:5]
	s_cbranch_vccnz .LBB0_238
	v_pk_mul_f32 v[0:1], v[166:167], v[46:47]
	v_pk_mul_f32 v[2:3], v[164:165], v[44:45]
	v_mul_f32_e32 v52, v45, v45
	v_cvt_pk_bf16_f32 v2, v2, v3
	v_cvt_pk_bf16_f32 v3, v0, v1
	v_lshlrev_b32_e32 v0, 4, v155
	v_add3_u32 v0, v146, v0, v147
	ds_write_b64 v0, v[2:3] offset:4096
	s_nop 1
	v_fmac_f32_e32 v52, v44, v44
	v_fmac_f32_e32 v52, v46, v46
	v_fmac_f32_e32 v52, v47, v47
	v_cmp_lt_i32_e32 vcc, v230, v203
	s_waitcnt vmcnt(3)
	v_pk_fma_f32 v[0:1], v[40:41], v[20:21], v[232:233]
	s_nop 0
	v_mul_f32_e32 v40, v1, v1
	v_pk_fma_f32 v[2:3], v[42:43], v[22:23], v[234:235]
	v_fmac_f32_e32 v40, v0, v0
	v_fmac_f32_e32 v40, v2, v2
	global_store_dwordx4 v[50:51], v[0:3], off offset:64 sc1
	v_fmac_f32_e32 v40, v3, v3
	v_add_f32_e32 v40, v52, v40
	v_pk_mul_f32 v[2:3], v[158:159], v[2:3]
	v_pk_mul_f32 v[0:1], v[156:157], v[0:1]
	s_nop 0
	v_cvt_pk_bf16_f32 v0, v0, v1
	v_cvt_pk_bf16_f32 v1, v2, v3
	v_lshlrev_b32_e32 v2, 4, v154
	v_add3_u32 v2, v146, v2, v147
	ds_write_b64 v2, v[0:1] offset:4096
	s_nop 1
	s_waitcnt vmcnt(3)
	v_pk_fma_f32 v[0:1], v[36:37], v[12:13], v[236:237]
	s_nop 0
	v_mul_f32_e32 v36, v1, v1
	v_pk_fma_f32 v[2:3], v[38:39], v[14:15], v[238:239]
	v_fmac_f32_e32 v36, v0, v0
	v_fmac_f32_e32 v36, v2, v2
	global_store_dwordx4 v[50:51], v[0:3], off offset:128 sc1
	v_fmac_f32_e32 v36, v3, v3
	v_add_f32_e32 v36, v40, v36
	v_pk_mul_f32 v[2:3], v[150:151], v[2:3]
	v_pk_mul_f32 v[0:1], v[148:149], v[0:1]
	s_nop 0
	v_cvt_pk_bf16_f32 v0, v0, v1
	v_cvt_pk_bf16_f32 v1, v2, v3
	v_lshlrev_b32_e32 v2, 4, v153
	v_add3_u32 v2, v146, v2, v147
	ds_write_b64 v2, v[0:1] offset:4096
	s_nop 1
	s_waitcnt vmcnt(3)
	v_pk_fma_f32 v[0:1], v[32:33], v[4:5], v[240:241]
	s_nop 0
	v_mul_f32_e32 v32, v1, v1
	v_pk_fma_f32 v[2:3], v[34:35], v[6:7], v[242:243]
	v_fmac_f32_e32 v32, v0, v0
	v_fmac_f32_e32 v32, v2, v2
	global_store_dwordx4 v[50:51], v[0:3], off offset:192 sc1
	v_fmac_f32_e32 v32, v3, v3
	v_add_f32_e32 v32, v36, v32
	v_pk_mul_f32 v[2:3], v[142:143], v[2:3]
	v_pk_mul_f32 v[0:1], v[144:145], v[0:1]
	s_nop 0
	v_cvt_pk_bf16_f32 v0, v0, v1
	v_cvt_pk_bf16_f32 v1, v2, v3
	v_lshlrev_b32_e32 v2, 4, v152
	v_add3_u32 v2, v146, v2, v147
	ds_write_b64 v2, v[0:1] offset:4096
	v_cndmask_b32_e32 v0, v202, v230, vcc
	v_lshlrev_b32_e32 v0, 2, v0
	ds_bpermute_b32 v0, v0, v32
	v_cmp_lt_i32_e32 vcc, v209, v203
	s_waitcnt lgkmcnt(0)
	v_add_f32_e32 v32, v32, v0
	v_cndmask_b32_e32 v0, v202, v209, vcc
	v_lshlrev_b32_e32 v0, 2, v0
	ds_bpermute_b32 v33, v0, v32
	v_cmp_gt_u32_e32 vcc, 16, v185
	s_and_saveexec_b64 s[4:5], vcc
	s_cbranch_execz .LBB0_237
	v_lshlrev_b64 v[0:1], 6, v[48:49]
	s_waitcnt lgkmcnt(0)
	v_add_f32_e32 v2, v32, v33
	v_lshl_add_u64 v[0:1], v[140:141], 0, v[0:1]
	global_store_dword v[0:1], v2, off sc1

; DI unsigned pk2(float a, float b) { f32x2 v = {a, b}; bf2_t r = __builtin_convertvector(v, bf2_t); return __builtin_bit_cast(unsigned, r); }
;     static DI void run(const f32x4 (&acc)[8][4], const TileCtx& tc, const Params& p, ldsp_t wb) {
;     ...
;             for (int mm = 0; mm < 4; ++mm) { __builtin_amdgcn_sched_barrier(0);
;                 const int m = h * 4 + mm;
;                 const int row = tc.brow + tc.wr * 128 + m * 16 + tc.fr;
;                 float* xr = xrow_ptr(p, row) + col0;
;                 const float* xs = (EK == 1 && tc.l == 0) ? p.x + (size_t)row * DM + col0 : xr;
;                 float part = 0.f;
; #pragma unroll
;                 for (int n = 0; n < 4; ++n) {
;                     f32x4 xv = *(const f32x4*)(xs + n * 16);
;                     xv += gv[n] * acc[m][n];
;                     *(f32x4*)(xr + n * 16) = xv;
;                     if (has_next) {
;                         part += xv[0] * xv[0] + xv[1] * xv[1] + xv[2] * xv[2] + xv[3] * xv[3];
;                         const f32x4 hv = xv * av[n];
;                         u32x2 w; w[0] = pk2(hv[0], hv[1]); w[1] = pk2(hv[2], hv[3]);
;                         wave_put(wb, mm * 16 + tc.fr, n, tc.fq, w);
;                     }
;                 }
;                 if (has_next) {
;                     part += __shfl_xor(part, 16);
;                     part += __shfl_xor(part, 32);
;                     if (tc.fq == 0) ssp[(size_t)row * 16] = part;
;                 }
.LBB0_238:
	v_add_u32_e32 v32, 0x70, v132
	v_add_u32_e32 v0, 0xffffc070, v132
	s_waitcnt lgkmcnt(0)
	v_ashrrev_i32_e32 v33, 31, v32
	v_cmp_gt_i32_e32 vcc, s33, v32
	v_mov_b32_e32 v2, s71
	v_mov_b32_e32 v3, s55
	v_cndmask_b32_e32 v1, 0, v33, vcc
	v_cndmask_b32_e32 v0, v0, v32, vcc
	v_cndmask_b32_e32 v3, v2, v3, vcc
	v_mov_b32_e32 v2, s70
	v_mov_b32_e32 v34, s54
	v_cndmask_b32_e32 v2, v2, v34, vcc
	v_lshlrev_b64 v[0:1], 12, v[0:1]
	v_lshl_add_u64 v[0:1], v[2:3], 0, v[0:1]
	v_lshl_add_u64 v[34:35], v[176:177], 2, v[0:1]
	global_load_dwordx4 v[0:3], v[34:35], off
	global_load_dwordx4 v[232:235], v[34:35], off offset:64
	global_load_dwordx4 v[236:239], v[34:35], off offset:128
	global_load_dwordx4 v[240:243], v[34:35], off offset:192
	s_mov_b64 s[4:5], -1
	s_and_b64 vcc, exec, s[36:37]
	s_waitcnt vmcnt(3)
	v_pk_fma_f32 v[26:27], v[26:27], v[30:31], v[2:3]
	v_pk_fma_f32 v[24:25], v[24:25], v[28:29], v[0:1]
	global_store_dwordx4 v[34:35], v[24:27], off sc1
	s_cbranch_vccz .LBB0_240
	s_nop 1
	s_mov_b64 s[4:5], 0
	s_waitcnt vmcnt(3)
	v_pk_fma_f32 v[2:3], v[18:19], v[22:23], v[234:235]
	v_pk_fma_f32 v[0:1], v[16:17], v[20:21], v[232:233]
	global_store_dwordx4 v[34:35], v[0:3], off offset:64 sc1
	s_nop 1
	s_waitcnt vmcnt(3)
	v_pk_fma_f32 v[2:3], v[10:11], v[14:15], v[238:239]
	v_pk_fma_f32 v[0:1], v[8:9], v[12:13], v[236:237]
	global_store_dwordx4 v[34:35], v[0:3], off offset:128 sc1
	s_nop 1
	s_waitcnt vmcnt(3)
	v_pk_fma_f32 v[2:3], v[70:71], v[6:7], v[242:243]
	v_pk_fma_f32 v[0:1], v[68:69], v[4:5], v[240:241]
	global_store_dwordx4 v[34:35], v[0:3], off offset:192 sc1
.LBB0_240:
	s_andn2_b64 vcc, exec, s[4:5]
	s_cbranch_vccnz .LBB0_183
	v_pk_mul_f32 v[0:1], v[166:167], v[26:27]
	v_pk_mul_f32 v[2:3], v[164:165], v[24:25]
	v_mul_f32_e32 v28, v25, v25
	v_cvt_pk_bf16_f32 v2, v2, v3
	v_cvt_pk_bf16_f32 v3, v0, v1
	v_lshlrev_b32_e32 v0, 4, v155
	v_add3_u32 v0, v146, v0, v147
	ds_write_b64 v0, v[2:3] offset:6144
	s_nop 1
	v_fmac_f32_e32 v28, v24, v24
	v_fmac_f32_e32 v28, v26, v26
	v_fmac_f32_e32 v28, v27, v27
	v_cmp_lt_i32_e32 vcc, v230, v203
	s_waitcnt vmcnt(3)
	v_pk_fma_f32 v[0:1], v[16:17], v[20:21], v[232:233]
	s_nop 0
	v_mul_f32_e32 v16, v1, v1
	v_pk_fma_f32 v[2:3], v[18:19], v[22:23], v[234:235]
	v_fmac_f32_e32 v16, v0, v0
	v_fmac_f32_e32 v16, v2, v2
	global_store_dwordx4 v[34:35], v[0:3], off offset:64 sc1
	v_fmac_f32_e32 v16, v3, v3
	v_add_f32_e32 v16, v28, v16
	v_pk_mul_f32 v[2:3], v[158:159], v[2:3]
	v_pk_mul_f32 v[0:1], v[156:157], v[0:1]
	s_nop 0
	v_cvt_pk_bf16_f32 v0, v0, v1
	v_cvt_pk_bf16_f32 v1, v2, v3
	v_lshlrev_b32_e32 v2, 4, v154
	v_add3_u32 v2, v146, v2, v147
	ds_write_b64 v2, v[0:1] offset:6144
	s_nop 1
	s_waitcnt vmcnt(3)
	v_pk_fma_f32 v[0:1], v[8:9], v[12:13], v[236:237]
	s_nop 0
	v_mul_f32_e32 v8, v1, v1
	v_pk_fma_f32 v[2:3], v[10:11], v[14:15], v[238:239]
	v_fmac_f32_e32 v8, v0, v0
	v_fmac_f32_e32 v8, v2, v2
	global_store_dwordx4 v[34:35], v[0:3], off offset:128 sc1
	v_fmac_f32_e32 v8, v3, v3
	v_add_f32_e32 v8, v16, v8
	v_pk_mul_f32 v[2:3], v[150:151], v[2:3]
	v_pk_mul_f32 v[0:1], v[148:149], v[0:1]
	s_nop 0
	v_cvt_pk_bf16_f32 v0, v0, v1
	v_cvt_pk_bf16_f32 v1, v2, v3
	v_lshlrev_b32_e32 v2, 4, v153
	v_add3_u32 v2, v146, v2, v147
	ds_write_b64 v2, v[0:1] offset:6144
	s_nop 1
	s_waitcnt vmcnt(3)
	v_pk_fma_f32 v[0:1], v[68:69], v[4:5], v[240:241]
	s_nop 0
	v_mul_f32_e32 v4, v1, v1
	v_pk_fma_f32 v[2:3], v[70:71], v[6:7], v[242:243]
	v_fmac_f32_e32 v4, v0, v0
	v_fmac_f32_e32 v4, v2, v2
	global_store_dwordx4 v[34:35], v[0:3], off offset:192 sc1
	v_fmac_f32_e32 v4, v3, v3
	v_add_f32_e32 v4, v8, v4
	v_pk_mul_f32 v[2:3], v[142:143], v[2:3]
	v_pk_mul_f32 v[0:1], v[144:145], v[0:1]
	s_nop 0
	v_cvt_pk_bf16_f32 v0, v0, v1
	v_cvt_pk_bf16_f32 v1, v2, v3
	v_lshlrev_b32_e32 v2, 4, v152
	v_add3_u32 v2, v146, v2, v147
	ds_write_b64 v2, v[0:1] offset:6144
	v_cndmask_b32_e32 v0, v202, v230, vcc
	v_lshlrev_b32_e32 v0, 2, v0
	ds_bpermute_b32 v0, v0, v4
	v_cmp_lt_i32_e32 vcc, v209, v203
	s_waitcnt lgkmcnt(0)
	v_add_f32_e32 v0, v4, v0
	v_cndmask_b32_e32 v1, v202, v209, vcc
	v_lshlrev_b32_e32 v1, 2, v1
	ds_bpermute_b32 v1, v1, v0
	v_cmp_gt_u32_e32 vcc, 16, v185
	s_and_saveexec_b64 s[4:5], vcc
	s_cbranch_execz .LBB0_182
	s_waitcnt lgkmcnt(0)
	v_add_f32_e32 v2, v0, v1
	v_lshlrev_b64 v[0:1], 6, v[32:33]
	v_lshl_add_u64 v[0:1], v[140:141], 0, v[0:1]
	global_store_dword v[0:1], v2, off sc1
	s_branch .LBB0_182

; #define LDSP __attribute__((address_space(3)))
; #define WAIT_V0() asm volatile("s_waitcnt vmcnt(0)" ::: "memory")
; template <int EK, int TS, int KS>
; DI void ctx_tiles(const Params& p, int l, const bf16_t* __restrict__ A, const bf16_t* __restrict__ Bt, int N, int K, ldsp_t shm) {
;     ...
;         for (int t = 0; t < nt; ++t) {
;             const int cur = t & 1;
;             if (t + 1 < nt) C_STAGE(cur ^ 1, t + 1);
;             ldsp_t sa = shm + cur * 2 * TILE_A, sb = sa + TILE_A;
; #pragma unroll
;             for (int ks = 0; ks < KS; ++ks) {
;                 bf16x8 At[MT], Bf[NT];
; #pragma unroll
;                 for (int m = 0; m < MT; ++m) At[m] = *(const LDSP bf16x8*)(sa + aoff + m * (KS * 1024) + ks * 1024);
; #pragma unroll
;                 for (int n = 0; n < NT; ++n) Bf[n] = *(const LDSP bf16x8*)(sb + boff + n * (KS * 1024) + ks * 1024);
; #pragma unroll
;                 for (int m = 0; m < MT; ++m)
; #pragma unroll
;                     for (int n = 0; n < NT; ++n) acc[m][n] = __builtin_amdgcn_mfma_f32_16x16x32_bf16(Bf[n], At[m], acc[m][n], 0, 0, 0);
;             }
;             WAIT_V0(); __syncthreads();
;         }
; #pragma unroll
;         for (int m = 0; m < MT; ++m)
; #pragma unroll
;             for (int n = 0; n < NT; ++n) {
;                 const int row = wr * WM + m * 16 + fr, ch = (wc * WN + n * 16 + fq * 4) >> 2;
;                 *(LDSP f32x4*)(shm + row * (TS * 4) + ((ch ^ (row & 15)) << 4)) = acc[m][n];
.Lctxring_skip:
	ds_read_b128 v[34:37], v46 offset:4096
	ds_read_b128 v[38:41], v46 offset:12288
	ds_read_b128 v[42:45], v33 offset:36864
	s_waitcnt lgkmcnt(0)
	v_mfma_f32_16x16x32_bf16 v[0:3], v[42:45], v[34:37], v[0:3]
	v_mfma_f32_16x16x32_bf16 v[4:7], v[42:45], v[38:41], v[4:7]
	ds_read_b128 v[34:37], v46 offset:5120
	ds_read_b128 v[38:41], v46 offset:13312
	ds_read_b128 v[42:45], v33 offset:37888
	s_waitcnt lgkmcnt(0)
	v_mfma_f32_16x16x32_bf16 v[0:3], v[42:45], v[34:37], v[0:3]
	v_mfma_f32_16x16x32_bf16 v[4:7], v[42:45], v[38:41], v[4:7]
	ds_read_b128 v[34:37], v46 offset:6144
	ds_read_b128 v[38:41], v46 offset:14336
	ds_read_b128 v[42:45], v33 offset:38912
	s_waitcnt lgkmcnt(0)
	v_mfma_f32_16x16x32_bf16 v[0:3], v[42:45], v[34:37], v[0:3]
	v_mfma_f32_16x16x32_bf16 v[4:7], v[42:45], v[38:41], v[4:7]
	ds_read_b128 v[34:37], v46 offset:7168
	ds_read_b128 v[38:41], v46 offset:15360
	ds_read_b128 v[42:45], v33 offset:39936
	s_waitcnt lgkmcnt(0)
	v_mfma_f32_16x16x32_bf16 v[0:3], v[42:45], v[34:37], v[0:3]
	v_mfma_f32_16x16x32_bf16 v[4:7], v[42:45], v[38:41], v[4:7]
	s_add_i32 s5, s5, 0x10000
	s_add_u32 s42, s42, 0x200
	s_addc_u32 s43, s43, 0
	s_cmpk_eq_i32 s42, 0x1e00
	s_waitcnt vmcnt(8)
	s_barrier
	s_cbranch_scc0 .LBB0_247
	s_waitcnt vmcnt(0)
	s_barrier
	v_add3_u32 v29, v32, v30, s13
	v_add3_u32 v30, v31, v30, s30
	ds_read_b128 v[8:11], v29 offset:1024
	ds_read_b128 v[12:15], v30
	ds_read_b128 v[16:19], v29 offset:8192
	ds_read_b128 v[20:23], v29
	s_waitcnt lgkmcnt(1)
	v_mfma_f32_16x16x32_bf16 v[4:7], v[12:15], v[16:19], v[4:7]
	s_waitcnt lgkmcnt(0)
	v_mfma_f32_16x16x32_bf16 v[0:3], v[12:15], v[20:23], v[0:3]
	ds_read_b128 v[12:15], v29 offset:9216
	ds_read_b128 v[16:19], v30 offset:1024
	s_waitcnt lgkmcnt(0)
	v_mfma_f32_16x16x32_bf16 v[0:3], v[16:19], v[8:11], v[0:3]
	v_mfma_f32_16x16x32_bf16 v[4:7], v[16:19], v[12:15], v[4:7]
	ds_read_b128 v[8:11], v29 offset:2048
	ds_read_b128 v[12:15], v29 offset:10240
	ds_read_b128 v[16:19], v30 offset:2048
	s_waitcnt lgkmcnt(0)
	v_mfma_f32_16x16x32_bf16 v[0:3], v[16:19], v[8:11], v[0:3]
	v_mfma_f32_16x16x32_bf16 v[4:7], v[16:19], v[12:15], v[4:7]
	ds_read_b128 v[8:11], v29 offset:3072
	ds_read_b128 v[12:15], v29 offset:11264
	ds_read_b128 v[16:19], v30 offset:3072
	s_waitcnt lgkmcnt(0)
	v_mfma_f32_16x16x32_bf16 v[0:3], v[16:19], v[8:11], v[0:3]
	v_mfma_f32_16x16x32_bf16 v[4:7], v[16:19], v[12:15], v[4:7]
	ds_read_b128 v[8:11], v29 offset:4096
	ds_read_b128 v[12:15], v29 offset:12288
	ds_read_b128 v[16:19], v30 offset:4096
	s_waitcnt lgkmcnt(0)
	v_mfma_f32_16x16x32_bf16 v[0:3], v[16:19], v[8:11], v[0:3]
	v_mfma_f32_16x16x32_bf16 v[4:7], v[16:19], v[12:15], v[4:7]
	ds_read_b128 v[8:11], v29 offset:5120
	ds_read_b128 v[12:15], v29 offset:13312
	ds_read_b128 v[16:19], v30 offset:5120
	s_waitcnt lgkmcnt(0)
	v_mfma_f32_16x16x32_bf16 v[0:3], v[16:19], v[8:11], v[0:3]
	v_mfma_f32_16x16x32_bf16 v[4:7], v[16:19], v[12:15], v[4:7]
	ds_read_b128 v[8:11], v29 offset:6144
	ds_read_b128 v[12:15], v29 offset:14336
	ds_read_b128 v[16:19], v30 offset:6144
	s_waitcnt lgkmcnt(0)
	v_mfma_f32_16x16x32_bf16 v[0:3], v[16:19], v[8:11], v[0:3]
	v_mfma_f32_16x16x32_bf16 v[4:7], v[16:19], v[12:15], v[4:7]
	ds_read_b128 v[8:11], v29 offset:7168
	ds_read_b128 v[12:15], v29 offset:15360
	ds_read_b128 v[16:19], v30 offset:7168
	s_waitcnt vmcnt(0)
	s_waitcnt lgkmcnt(0)
	v_mfma_f32_16x16x32_bf16 v[0:3], v[16:19], v[8:11], v[0:3]
	v_lshrrev_b32_e32 v8, 4, v27
	v_lshrrev_b32_e32 v9, 2, v28
	v_bitop3_b32 v8, v9, v25, v8 bitop3:0x36
	v_mfma_f32_16x16x32_bf16 v[4:7], v[16:19], v[12:15], v[4:7]
	v_lshlrev_b32_e32 v9, 8, v26
	v_lshl_or_b32 v8, v8, 4, v9
	s_barrier
; template <int EK>
; DI void ctx_item(const Params& p, int l, int grow, int gcol, int slot, f32x4 s0, f32x4 s1, bool lead) {
;     ...
;         const float* gate = p.mod + ((size_t)l * 5 + 4) * 6144 + (EK == 1 ? 2 : 5) * DM + gcol;
;         float* xr = p.xc + (size_t)grow * DM + gcol;
;         const float* xs = (EK == 1 && l == 0) ? p.ctx + (size_t)grow * DM + gcol : xr;
;         const f32x4 g0 = *(const f32x4*)gate, g1 = *(const f32x4*)(gate + 4);
;         f32x4 x0 = *(const f32x4*)xs, x1 = *(const f32x4*)(xs + 4);
;         x0 += g0 * s0; x1 += g1 * s1;
;         *(f32x4*)xr = x0; *(f32x4*)(xr + 4) = x1;
;         const int ln = EK == 1 ? l : l + 1;
;         const float* gnx = (EK == 1 ? p.norm2_g : p.norm1_g) + (size_t)ln * DM + gcol;
;         const float* scn = p.mod + ((size_t)ln * 5 + 4) * 6144 + (EK == 1 ? 4 : 1) * DM + gcol;
;         const f32x4 a0 = *(const f32x4*)gnx * (1.f + *(const f32x4*)scn), a1 = *(const f32x4*)(gnx + 4) * (1.f + *(const f32x4*)(scn + 4));
;         const f32x4 y0 = x0 * a0, y1 = x1 * a1;
;         u32x4 w; w[0] = pk2(y0[0], y0[1]); w[1] = pk2(y0[2], y0[3]); w[2] = pk2(y1[0], y1[1]); w[3] = pk2(y1[2], y1[3]);
;         *(u32x4*)(p.H + (size_t)(NLAT + grow) * DM + gcol) = w;
;         float part = x0[0] * x0[0] + x0[1] * x0[1] + x0[2] * x0[2] + x0[3] * x0[3] + x1[0] * x1[0] + x1[1] * x1[1] + x1[2] * x1[2] + x1[3] * x1[3];
; template <int EK, int TS, int KS>
; DI void ctx_tiles(const Params& p, int l, const bf16_t* __restrict__ A, const bf16_t* __restrict__ Bt, int N, int K, ldsp_t shm) {
;     ...
;         for (int m = 0; m < MT; ++m)
; #pragma unroll
;             for (int n = 0; n < NT; ++n) {
;                 const int row = wr * WM + m * 16 + fr, ch = (wc * WN + n * 16 + fq * 4) >> 2;
;                 *(LDSP f32x4*)(shm + row * (TS * 4) + ((ch ^ (row & 15)) << 4)) = acc[m][n];
;             }
;         __syncthreads();
; #pragma unroll
;         for (int it = 0; it < (TS * TS / 8) / 512; ++it) {
;             const int item = it * 512 + tid, row = item / (TS / 8), c8 = item % (TS / 8);
;             const f32x4 s0 = *(const LDSP f32x4*)(shm + row * (TS * 4) + (((2 * c8) ^ (row & 15)) << 4));
;             const f32x4 s1 = *(const LDSP f32x4*)(shm + row * (TS * 4) + (((2 * c8 + 1) ^ (row & 15)) << 4));
;             ctx_item<EK>(p, l, tm * TS + row, tn * TS + c8 * 8, tn, s0, s1, c8 == 0);
	s_nop 0
	ds_write_b128 v8, v[0:3]
	s_nop 2
	ds_write_b128 v8, v[4:7] offset:4096
	v_ashrrev_i32_e32 v0, 31, v24
	v_lshrrev_b32_e32 v0, 29, v0
	v_add_u32_e32 v0, v24, v0
	v_ashrrev_i32_e32 v1, 3, v0
	v_and_b32_e32 v0, -8, v0
	v_sub_u32_e32 v0, v24, v0
	v_lshlrev_b32_e32 v3, 1, v0
	v_and_b32_e32 v4, 15, v1
	v_bitop3_b32 v5, v3, v1, 15 bitop3:0x78
	v_bitop3_b32 v3, v3, v4, 1 bitop3:0x36
	v_lshl_add_u32 v4, s4, 6, v1
	s_lshl_b32 s4, s40, 6
	v_lshl_add_u32 v26, v0, 3, s4
	v_cmp_lt_i32_e64 s[4:5], v134, v203
	v_cmp_eq_u32_e32 vcc, 0, v0
	v_lshlrev_b32_e32 v2, 8, v1
	v_cndmask_b32_e64 v0, v202, v134, s[4:5]
	v_cmp_lt_i32_e64 s[4:5], v135, v203
	v_lshlrev_b32_e32 v34, 2, v0
	v_lshl_add_u32 v6, v5, 4, v2
	v_cndmask_b32_e64 v0, v202, v135, s[4:5]
	v_ashrrev_i32_e32 v27, 31, v26
	v_ashrrev_i32_e32 v5, 31, v4
	v_lshlrev_b32_e32 v35, 2, v0
	v_xor_b32_e32 v0, 4, v202
	v_lshlrev_b64 v[10:11], 12, v[4:5]
	v_cmp_lt_i32_e64 s[4:5], v0, v203
	v_lshlrev_b64 v[30:31], 2, v[26:27]
	v_lshl_add_u32 v7, v3, 4, v2
	v_cndmask_b32_e64 v0, v202, v0, s[4:5]
	v_lshl_add_u64 v[14:15], s[34:35], 0, v[30:31]
	v_lshl_add_u64 v[10:11], s[70:71], 0, v[10:11]
	s_waitcnt lgkmcnt(0)
	s_barrier
	v_lshlrev_b32_e32 v36, 2, v0
	ds_read_b128 v[0:3], v6
	ds_read_b128 v[6:9], v7
	v_lshl_add_u64 v[32:33], v[10:11], 0, v[30:31]
	global_load_dwordx4 v[10:13], v[14:15], off offset:16
	s_nop 0
	global_load_dwordx4 v[14:17], v[14:15], off
	s_nop 0
	global_load_dwordx4 v[18:21], v[32:33], off offset:16
	global_load_dwordx4 v[22:25], v[32:33], off
	v_lshlrev_b64 v[28:29], 11, v[4:5]
	s_waitcnt vmcnt(0) lgkmcnt(1)
	v_pk_fma_f32 v[16:17], v[2:3], v[16:17], v[24:25]
	v_pk_fma_f32 v[14:15], v[0:1], v[14:15], v[22:23]
	s_waitcnt lgkmcnt(0)
	v_pk_fma_f32 v[2:3], v[8:9], v[12:13], v[20:21]
	v_pk_fma_f32 v[0:1], v[6:7], v[10:11], v[18:19]
	global_store_dwordx4 v[32:33], v[14:17], off sc1
	global_store_dwordx4 v[32:33], v[0:3], off offset:16 sc1
	v_lshl_add_u64 v[10:11], s[36:37], 0, v[30:31]
	v_lshl_add_u64 v[22:23], s[38:39], 0, v[30:31]
	global_load_dwordx4 v[6:9], v[10:11], off offset:16
	s_nop 0
	global_load_dwordx4 v[10:13], v[10:11], off
	s_nop 0
	global_load_dwordx4 v[18:21], v[22:23], off offset:16
	s_nop 0
	global_load_dwordx4 v[22:25], v[22:23], off
	s_waitcnt vmcnt(1)
	v_pk_add_f32 v[20:21], v[20:21], 1.0 op_sel_hi:[1,0]
	s_waitcnt vmcnt(0)
	v_pk_add_f32 v[22:23], v[22:23], 1.0 op_sel_hi:[1,0]
	v_pk_add_f32 v[18:19], v[18:19], 1.0 op_sel_hi:[1,0]
	v_pk_mul_f32 v[10:11], v[10:11], v[22:23]
	v_pk_mul_f32 v[8:9], v[8:9], v[20:21]
	v_pk_mul_f32 v[6:7], v[6:7], v[18:19]
	v_pk_mul_f32 v[10:11], v[14:15], v[10:11]
	v_pk_add_f32 v[24:25], v[24:25], 1.0 op_sel_hi:[1,0]
	v_pk_mul_f32 v[18:19], v[2:3], v[8:9]
	v_pk_mul_f32 v[8:9], v[0:1], v[6:7]
	v_cvt_pk_bf16_f32 v6, v10, v11
	v_lshl_add_u64 v[10:11], s[82:83], 0, v[28:29]
	v_pk_mul_f32 v[12:13], v[12:13], v[24:25]
	v_lshl_add_u64 v[10:11], v[26:27], 1, v[10:11]
	v_pk_mul_f32 v[12:13], v[16:17], v[12:13]
	v_add_co_u32_e64 v10, s[4:5], s14, v10
	v_cvt_pk_bf16_f32 v7, v12, v13
	v_cvt_pk_bf16_f32 v8, v8, v9
	v_cvt_pk_bf16_f32 v9, v18, v19
	v_addc_co_u32_e64 v11, s[4:5], 0, v11, s[4:5]
	global_store_dwordx4 v[10:11], v[6:9], off sc1
	s_nop 1
	v_mul_f32_e32 v6, v15, v15
	v_fmac_f32_e32 v6, v14, v14
	v_fmac_f32_e32 v6, v16, v16
	v_fmac_f32_e32 v6, v17, v17
	v_fmac_f32_e32 v6, v0, v0
	v_fmac_f32_e32 v6, v1, v1
	v_fmac_f32_e32 v6, v2, v2
	v_fmac_f32_e32 v6, v3, v3
	ds_bpermute_b32 v0, v34, v6
	s_waitcnt lgkmcnt(0)
	v_add_f32_e32 v0, v6, v0
	ds_bpermute_b32 v1, v35, v0
	s_waitcnt lgkmcnt(0)
	v_add_f32_e32 v0, v0, v1
	ds_bpermute_b32 v1, v36, v0
	s_and_saveexec_b64 s[4:5], vcc
	s_cbranch_execz .LBB0_245
	v_lshl_add_u64 v[2:3], s[6:7], 0, v[4:5]
	v_lshlrev_b64 v[2:3], 6, v[2:3]
	v_lshl_add_u64 v[2:3], s[74:75], 0, v[2:3]
	v_lshl_add_u64 v[2:3], s[40:41], 2, v[2:3]
	s_waitcnt lgkmcnt(0)
	v_add_f32_e32 v0, v0, v1
	global_store_dword v[2:3], v0, off sc1
	s_branch .LBB0_245

; #define LDSP __attribute__((address_space(3)))
; DI void wave_rows_store(ldsp_t wb, int lane, bf16_t* dst0, size_t ld) {
; #pragma unroll
;     for (int i = 0; i < 8; ++i) {
;         const int row = i * 8 + (lane >> 3), ch = lane & 7;
;         const u32x4 v = *(const LDSP u32x4*)(wb + row * 128 + ((ch ^ (row & 7)) << 4));
;         *(u32x4*)(dst0 + (size_t)row * ld + ch * 8) = v;
;     }
; }
;     static DI void run(const f32x4 (&acc)[8][4], const TileCtx& tc, const Params& p, ldsp_t wb) {
;     ...
;                 const int row0 = tc.brow + tc.wr * 128 + h * 64;
;                 bf16_t* dst0;
;                 if (lat) {
;                     const int b = row0 >> 12, t0 = row0 & 4095;
;                     dst0 = isq ? p.Q + ((size_t)(b * 8 + head) * SEQ + t0) * 64 : p.K + ((size_t)(b * 2 + head) * NKEY + CTXL + t0) * 64;
;                 } else {
;                     const int r2 = row0 - NLAT, b = r2 >> 8, t0 = r2 & 255;
;                     dst0 = isq ? p.Qc + ((size_t)(b * 8 + head) * CTXL + t0) * 64 : p.K + ((size_t)(b * 2 + head) * NKEY + t0) * 64;
;                 }
;                 wave_rows_store(wb, tc.lane, dst0, 64);
.LBB0_255:
	v_and_b32_e32 v1, -8, v1
	v_add_u32_e32 v2, v1, v94
	v_ashrrev_i32_e32 v3, 31, v2
	v_lshlrev_b64 v[2:3], s6, v[2:3]
	v_lshl_add_u64 v[2:3], s[4:5], 0, v[2:3]
	s_lshl_b32 s4, s7, 1
	v_lshlrev_b32_e32 v0, 7, v0
	v_and_b32_e32 v0, s4, v0
	v_mov_b32_e32 v1, v193
	v_lshl_add_u64 v[0:1], v[2:3], 0, v[0:1]
	v_mov_b32_e32 v41, v193
	v_add_u32_e32 v8, v95, v192
	v_lshl_add_u64 v[4:5], v[0:1], 0, v[40:41]
	ds_read_b128 v[0:3], v8
	v_lshl_add_u64 v[6:7], v[4:5], 0, v[192:193]
	s_waitcnt lgkmcnt(0)
	global_store_dwordx4 v[6:7], v[0:3], off sc1
	ds_read_b128 v[0:3], v8 offset:1024
	s_waitcnt lgkmcnt(0)
	global_store_dwordx4 v[6:7], v[0:3], off offset:1024 sc1
	ds_read_b128 v[0:3], v8 offset:2048
	s_waitcnt lgkmcnt(0)
	global_store_dwordx4 v[6:7], v[0:3], off offset:2048 sc1
	ds_read_b128 v[0:3], v8 offset:3072
	s_waitcnt lgkmcnt(0)
	global_store_dwordx4 v[6:7], v[0:3], off offset:3072 sc1
	ds_read_b128 v[0:3], v8 offset:4096
	v_lshl_add_u64 v[6:7], v[4:5], 0, v[38:39]
	s_waitcnt lgkmcnt(0)
	global_store_dwordx4 v[6:7], v[0:3], off sc1
	ds_read_b128 v[0:3], v8 offset:5120
	v_lshl_add_u64 v[6:7], v[4:5], 0, v[88:89]
	s_waitcnt lgkmcnt(0)
	global_store_dwordx4 v[6:7], v[0:3], off sc1
	ds_read_b128 v[0:3], v8 offset:6144
	v_lshl_add_u64 v[6:7], v[4:5], 0, v[90:91]
	v_lshl_add_u64 v[4:5], v[4:5], 0, v[42:43]
	s_waitcnt lgkmcnt(0)
	global_store_dwordx4 v[6:7], v[0:3], off sc1
	ds_read_b128 v[0:3], v8 offset:7168
	s_waitcnt lgkmcnt(0)
	global_store_dwordx4 v[4:5], v[0:3], off sc1

; #define WAIT_V0() asm volatile("s_waitcnt vmcnt(0)" ::: "memory")
; #define G_STAGE_A(Ap, buf, kt) do { const char* ab_ = (const char*)(Ap) + (size_t)(kt) * 128; \
;       _Pragma("unroll") for (int i = 0; i < 4; ++i) \
;         __builtin_amdgcn_global_load_lds((const unsigned*)(ab_ + soff[i]), (LDSP unsigned*)(G_SA(buf) + wid * 1024 + i * 8192), 16, 0, 0); } while (0)
; #define G_STAGE_B(Bp, buf, kt) do { const char* bb_ = (const char*)(Bp) + (size_t)(kt) * 128; \
;       _Pragma("unroll") for (int i = 0; i < 4; ++i) \
;         __builtin_amdgcn_global_load_lds((const unsigned*)(bb_ + soff[i]), (LDSP unsigned*)(G_SB(buf) + wid * 1024 + i * 8192), 16, 0, 0); } while (0)
; #define G_RDA(AF, buf, ks, mh) do { _Pragma("unroll") for (int m = 0; m < 4; ++m) AF[m] = *(const LDSP bf16x8*)(G_SA(buf) + aoff + ((mh) * 4 + m) * 2048 + (ks) * 1024); } while (0)
; #define G_RDB(BF, buf, ks) do { _Pragma("unroll") for (int n = 0; n < 4; ++n) BF[n] = *(const LDSP bf16x8*)(G_SB(buf) + boff + n * 2048 + (ks) * 1024); } while (0)
; #define G_SB0() __builtin_amdgcn_sched_barrier(0)
; template <int EK>
; DI void gemm_stream(const Params& p, int l, const bf16_t* __restrict__ A, const bf16_t* __restrict__ Bt, int M, int N, int K, ldsp_t shm) {
;     ...
;         for (int t = 0; t < nt; ++t) {
;             const int cur = t & 1;
;             G_RDA(Aa, cur, 0, 0); G_RDB(Bk0, cur, 0);
;             if (t + 1 < nt) G_STAGE_B(Bb, cur ^ 1, t + 1);
;             else if (has_next) G_STAGE_B(Bb2, cur ^ 1, 0);
;             G_SB0();
;             if (t > 0) G_MMA(Ab_, Bk1, 1);
;             G_SB0();
;             if (t + 1 < nt) G_STAGE_A(Ab, cur ^ 1, t + 1);
;             else if (has_next) G_STAGE_A(Ab2, cur ^ 1, 0);
;             G_RDA(Ab_, cur, 0, 1);
;             G_MMA(Aa, Bk0, 0); G_SB0();
;             G_RDA(Aa, cur, 1, 0); G_RDB(Bk1, cur, 1);
;             G_MMA(Ab_, Bk0, 1); G_SB0();
;             G_RDA(Ab_, cur, 1, 1);
;             G_MMA(Aa, Bk1, 0); G_SB0();
;             asm volatile("s_waitcnt lgkmcnt(0)" ::: "memory");
;             WAIT_V0(); __syncthreads();
;         }
;         G_MMA(Ab_, Bk1, 1);
.LBB0_269:
	v_add_u32_e32 v80, 0x12000, v218
	v_add_u32_e32 v132, 0x12800, v218
	v_add_u32_e32 v136, 0x13000, v218
	v_add_u32_e32 v140, 0x13800, v218
	ds_read_b128 v[80:83], v80
	ds_read_b128 v[132:135], v132
	ds_read_b128 v[136:139], v136
	ds_read_b128 v[140:143], v140
	s_setprio 1
	s_waitcnt lgkmcnt(0)
	v_mfma_f32_16x16x32_bf16 v[20:23], v[164:167], v[180:183], v[20:23]
	v_mfma_f32_16x16x32_bf16 v[24:27], v[168:171], v[180:183], v[24:27]
	v_mfma_f32_16x16x32_bf16 v[28:31], v[172:175], v[180:183], v[28:31]
	v_mfma_f32_16x16x32_bf16 v[44:47], v[172:175], v[184:187], v[44:47]
	v_mfma_f32_16x16x32_bf16 v[48:51], v[160:163], v[176:179], v[48:51]
	v_mfma_f32_16x16x32_bf16 v[52:55], v[164:167], v[176:179], v[52:55]
	v_mfma_f32_16x16x32_bf16 v[56:59], v[168:171], v[176:179], v[56:59]
	v_mfma_f32_16x16x32_bf16 v[60:63], v[172:175], v[176:179], v[60:63]
	v_mfma_f32_16x16x32_bf16 v[0:3], v[160:163], v[188:191], v[0:3]
	v_mfma_f32_16x16x32_bf16 v[4:7], v[164:167], v[188:191], v[4:7]
	v_mfma_f32_16x16x32_bf16 v[8:11], v[168:171], v[188:191], v[8:11]
	v_mfma_f32_16x16x32_bf16 v[12:15], v[172:175], v[188:191], v[12:15]
	v_mfma_f32_16x16x32_bf16 v[16:19], v[160:163], v[180:183], v[16:19]
	v_mfma_f32_16x16x32_bf16 v[32:35], v[160:163], v[184:187], v[32:35]
	v_mfma_f32_16x16x32_bf16 v[36:39], v[164:167], v[184:187], v[36:39]
	v_mfma_f32_16x16x32_bf16 v[40:43], v[168:171], v[184:187], v[40:43]
	s_setprio 0
	v_add_u32_e32 v144, 0x10400, v218
	v_add_u32_e32 v148, 0x10c00, v218
	v_add_u32_e32 v152, 0x11400, v218
	v_add_u32_e32 v156, 0x11c00, v218
	v_add_u32_e32 v176, 0x18400, v219
	v_add_u32_e32 v180, 0x18c00, v219
	v_add_u32_e32 v184, 0x19400, v219
	v_add_u32_e32 v188, 0x19c00, v219
	ds_read_b128 v[144:147], v144
	ds_read_b128 v[148:151], v148
	ds_read_b128 v[152:155], v152
	ds_read_b128 v[156:159], v156
	ds_read_b128 v[176:179], v176
	ds_read_b128 v[180:183], v180
	ds_read_b128 v[184:187], v184
	ds_read_b128 v[188:191], v188
	s_setprio 1
	v_mfma_f32_16x16x32_bf16 v[128:131], v[160:163], v[80:83], v[128:131]
	v_mfma_f32_16x16x32_bf16 v[124:127], v[164:167], v[80:83], v[124:127]
	v_mfma_f32_16x16x32_bf16 v[120:123], v[168:171], v[80:83], v[120:123]
	v_mfma_f32_16x16x32_bf16 v[116:119], v[172:175], v[80:83], v[116:119]
	v_mfma_f32_16x16x32_bf16 v[112:115], v[160:163], v[132:135], v[112:115]
	v_mfma_f32_16x16x32_bf16 v[194:197], v[164:167], v[132:135], v[108:111]
	v_mfma_f32_16x16x32_bf16 v[214:217], v[168:171], v[132:135], v[104:107]
	v_mfma_f32_16x16x32_bf16 v[132:135], v[172:175], v[132:135], v[100:103]
	v_mfma_f32_16x16x32_bf16 v[220:223], v[160:163], v[136:139], v[96:99]
	v_mfma_f32_16x16x32_bf16 v[224:227], v[164:167], v[136:139], v[92:95]
	v_mfma_f32_16x16x32_bf16 v[228:231], v[168:171], v[136:139], v[88:91]
	v_mfma_f32_16x16x32_bf16 v[136:139], v[172:175], v[136:139], v[84:87]
	v_mfma_f32_16x16x32_bf16 v[160:163], v[160:163], v[140:143], v[64:67]
	v_mfma_f32_16x16x32_bf16 v[164:167], v[164:167], v[140:143], v[68:71]
	v_mfma_f32_16x16x32_bf16 v[168:171], v[168:171], v[140:143], v[76:79]
	v_mfma_f32_16x16x32_bf16 v[140:143], v[172:175], v[140:143], v[72:75]
	s_setprio 0
	v_add_u32_e32 v64, 0x12400, v218
	v_add_u32_e32 v68, 0x12c00, v218
	ds_read_b128 v[64:67], v64
	ds_read_b128 v[172:175], v68
	v_add_u32_e32 v68, 0x13400, v218
	v_add_u32_e32 v69, 0x13c00, v218
	ds_read_b128 v[232:235], v68
	ds_read_b128 v[236:239], v69
	s_setprio 1
	s_waitcnt lgkmcnt(0)
	v_mfma_f32_16x16x32_bf16 v[240:243], v[176:179], v[144:147], v[0:3]
	v_mfma_f32_16x16x32_bf16 v[244:247], v[180:183], v[144:147], v[4:7]
	v_mfma_f32_16x16x32_bf16 v[248:251], v[184:187], v[144:147], v[8:11]
	v_mfma_f32_16x16x32_bf16 v[144:147], v[188:191], v[144:147], v[12:15]
	v_mfma_f32_16x16x32_bf16 v[108:111], v[176:179], v[152:155], v[32:35]
	v_mfma_f32_16x16x32_bf16 v[104:107], v[180:183], v[152:155], v[36:39]
	v_mfma_f32_16x16x32_bf16 v[100:103], v[184:187], v[152:155], v[40:43]
	v_mfma_f32_16x16x32_bf16 v[96:99], v[188:191], v[152:155], v[44:47]
	v_mfma_f32_16x16x32_bf16 v[92:95], v[176:179], v[156:159], v[48:51]
	v_mfma_f32_16x16x32_bf16 v[88:91], v[180:183], v[156:159], v[52:55]
	v_mfma_f32_16x16x32_bf16 v[84:87], v[184:187], v[156:159], v[56:59]
	v_mfma_f32_16x16x32_bf16 v[80:83], v[188:191], v[156:159], v[60:63]
	v_mfma_f32_16x16x32_bf16 v[210:213], v[176:179], v[148:151], v[16:19]
	v_mfma_f32_16x16x32_bf16 v[204:207], v[180:183], v[148:151], v[20:23]
	v_mfma_f32_16x16x32_bf16 v[198:201], v[184:187], v[148:151], v[24:27]
	v_mfma_f32_16x16x32_bf16 v[148:151], v[188:191], v[148:151], v[28:31]
	s_setprio 0
	s_waitcnt lgkmcnt(0)
	s_waitcnt vmcnt(0)
	s_waitcnt vmcnt(0)
	s_barrier
; #define G_STAGE_B(Bp, buf, kt) do { const char* bb_ = (const char*)(Bp) + (size_t)(kt) * 128; \
;       _Pragma("unroll") for (int i = 0; i < 4; ++i) \
;         __builtin_amdgcn_global_load_lds((const unsigned*)(bb_ + soff[i]), (LDSP unsigned*)(G_SB(buf) + wid * 1024 + i * 8192), 16, 0, 0); } while (0)
; #define G_MMA(AF, BF, mh) do { __builtin_amdgcn_s_setprio(1); \
;             _Pragma("unroll") for (int m = 0; m < 4; ++m) _Pragma("unroll") for (int n = 0; n < 4; ++n) \
;                 acc[(mh) * 4 + m][n] = __builtin_amdgcn_mfma_f32_16x16x32_bf16(BF[n], AF[m], acc[(mh) * 4 + m][n], 0, 0, 0); \
;             __builtin_amdgcn_s_setprio(0); } while (0)
; template <int EK>
; DI void gemm_stream(const Params& p, int l, const bf16_t* __restrict__ A, const bf16_t* __restrict__ Bt, int M, int N, int K, ldsp_t shm) {
;     ...
;         G_MMA(Ab_, Bk1, 1);
;         G_SB0();
;         {
;             int tid2 = threadIdx.x, pme = pm, pne = pn;
;             asm volatile("" : "+v"(tid2), "+s"(pme), "+s"(pne));
;             TileCtx tc;
;             tc.wid = tid2 >> 6; tc.lane = tid2 & 63; tc.wr = tc.wid >> 2; tc.wc = tc.wid & 3; tc.fr = tc.lane & 15; tc.fq = tc.lane >> 4; tc.l = l;
;             tc.brow = pme * 256; tc.bcol = pne * 256; tc.pn = pne;
;             ldsp_t ex = shm + G_STAGE_B + tc.wid * 8192;
;             if (EK == 0 || EK == 2) {
;                 const int cond = tc.brow < NLAT ? (tc.brow >> 12) : 4;
;                 const float* ssp = p.ss + ((size_t)(l * 2 + (EK == 0 ? 0 : 1)) * NTOK + tc.brow + tc.wr * 128 + tc.fr) * 16 + tc.fq * 4;
;                 const float* shw = (EK == 0 ? p.shw_in + ((size_t)l * 5 + cond) * IN_DIM : p.shw_ff1 + ((size_t)l * 5 + cond) * FF) + tc.bcol + tc.wc * 64 + tc.fq * 4;
;                 f32x4 shv[4];
; #pragma unroll
;                 for (int n = 0; n < 4; ++n) shv[n] = *(const f32x4*)(shw + n * 16);
; #pragma unroll
;                 for (int m = 0; m < 8; ++m) {
;                     const f32x4 pp = *(const f32x4*)(ssp + m * 256);
;                     float sq = pp[0] + pp[1] + pp[2] + pp[3];
;                     sq += __shfl_xor(sq, 16);
;                     sq += __shfl_xor(sq, 32);
;                     const float rstd = rsqrtf(sq * (1.f / DM) + EPS);
; #pragma unroll
;                     for (int n = 0; n < 4; ++n) acc[m][n] = acc[m][n] * rstd + shv[n];
;                 }
	s_setprio 1
	v_mfma_f32_16x16x32_bf16 v[76:79], v[176:179], v[64:67], v[128:131]
	v_mfma_f32_16x16x32_bf16 v[72:75], v[180:183], v[64:67], v[124:127]
	v_mfma_f32_16x16x32_bf16 v[68:71], v[184:187], v[64:67], v[120:123]
	v_mfma_f32_16x16x32_bf16 v[64:67], v[188:191], v[64:67], v[116:119]
	v_mfma_f32_16x16x32_bf16 v[60:63], v[176:179], v[172:175], v[112:115]
	v_mfma_f32_16x16x32_bf16 v[56:59], v[180:183], v[172:175], v[194:197]
	v_mfma_f32_16x16x32_bf16 v[52:55], v[184:187], v[172:175], v[214:217]
	v_mfma_f32_16x16x32_bf16 v[48:51], v[188:191], v[172:175], v[132:135]
	v_mfma_f32_16x16x32_bf16 v[28:31], v[176:179], v[232:235], v[220:223]
	v_mfma_f32_16x16x32_bf16 v[24:27], v[180:183], v[232:235], v[224:227]
	v_mfma_f32_16x16x32_bf16 v[20:23], v[184:187], v[232:235], v[228:231]
	v_mfma_f32_16x16x32_bf16 v[16:19], v[188:191], v[232:235], v[136:139]
	v_mfma_f32_16x16x32_bf16 v[12:15], v[176:179], v[236:239], v[160:163]
	v_mfma_f32_16x16x32_bf16 v[8:11], v[180:183], v[236:239], v[164:167]
	v_mfma_f32_16x16x32_bf16 v[4:7], v[184:187], v[236:239], v[168:171]
	v_mfma_f32_16x16x32_bf16 v[0:3], v[188:191], v[236:239], v[140:143]
	s_setprio 0
	v_mov_b32_e32 v172, v252
	s_lshl_b32 s41, s31, 8
	s_min_i32 s4, s41, 0x4000
	s_lshl_b32 s6, s98, 8
	s_ashr_i32 s4, s4, 12
	s_ashr_i32 s5, s41, 31
	s_add_u32 s7, s45, s41
	v_ashrrev_i32_e32 v174, 1, v172
	v_and_b32_e32 v169, 15, v172
	s_addc_u32 s5, s48, s5
	v_and_b32_e32 v112, 0xffffff80, v174
	v_ashrrev_i32_e32 v113, 31, v112
	v_or_b32_e32 v32, s7, v169
	v_mov_b32_e32 v33, s5
	s_ashr_i32 s5, s4, 31
	v_lshl_add_u64 v[32:33], v[32:33], 0, v[112:113]
	s_add_u32 s4, s44, s4
	v_lshlrev_b64 v[114:115], 6, v[32:33]
	s_addc_u32 s5, s49, s5
	v_mov_b64_e32 v[32:33], s[76:77]
	v_mov_b32_e32 v34, 0x1c00
	s_mul_i32 s7, s5, 0x1c00
	v_mad_u64_u32 v[32:33], s[4:5], s4, v34, v[32:33]
	v_ashrrev_i32_e32 v166, 6, v172
	v_add_u32_e32 v33, s7, v33
	s_ashr_i32 s7, s6, 31
	v_and_b32_e32 v171, 3, v166
	s_lshl_b64 s[4:5], s[6:7], 2
	v_xor_b32_e32 v230, 16, v202
	v_lshl_add_u64 v[32:33], v[32:33], 0, s[4:5]
	v_lshlrev_b32_e32 v192, 8, v171
	v_cmp_lt_i32_e32 vcc, v230, v203
	v_lshl_add_u64 v[32:33], v[32:33], 0, v[192:193]
	v_and_b32_e32 v192, 48, v172
	v_lshl_add_u64 v[114:115], s[74:75], 0, v[114:115]
	v_cndmask_b32_e32 v113, v202, v230, vcc
	v_cmp_lt_i32_e32 vcc, v209, v203
	v_lshl_add_u64 v[32:33], v[32:33], 0, v[192:193]
	v_lshl_add_u64 v[164:165], v[114:115], 0, v[192:193]
	v_cndmask_b32_e32 v114, v202, v209, vcc
	global_load_dwordx4 v[44:47], v[32:33], off
	global_load_dwordx4 v[40:43], v[32:33], off offset:64
	global_load_dwordx4 v[36:39], v[32:33], off offset:128
	s_nop 0
	global_load_dwordx4 v[32:35], v[32:33], off offset:192
	v_lshlrev_b32_e32 v168, 2, v114
	global_load_dwordx4 v[114:117], v[164:165], off
	global_load_dwordx4 v[118:121], v[164:165], off offset:1024
	global_load_dwordx4 v[178:181], v[164:165], off offset:2048
	global_load_dwordx4 v[130:133], v[164:165], off offset:3072
	v_mov_b32_e32 v190, s29
	v_mov_b32_e32 v191, 0
	v_lshl_add_u64 v[190:191], v[164:165], 0, v[190:191]
	global_load_dwordx4 v[182:185], v[190:191], off
	global_load_dwordx4 v[186:189], v[190:191], off offset:1024
	global_load_dwordx4 v[232:235], v[190:191], off offset:2048
	global_load_dwordx4 v[236:239], v[190:191], off offset:3072
	v_lshlrev_b32_e32 v113, 2, v113
	s_mov_b32 s4, 0x358637bd
	v_mov_b64_e32 v[162:163], s[4:5]
	s_mov_b32 s8, 0x3a800000
	v_bfe_u32 v173, v172, 4, 2
	v_and_b32_e32 v170, 63, v172
	v_lshlrev_b32_e32 v175, 2, v173
	s_cmp_gt_i32 s98, 1
	s_waitcnt vmcnt(7)
	v_mov_b32_e32 v123, v114
	s_waitcnt vmcnt(6)
	v_mov_b32_e32 v122, v118
	v_mov_b32_e32 v114, v119
	v_pk_add_f32 v[114:115], v[122:123], v[114:115]
	v_mov_b32_e32 v118, v120
	v_mov_b32_e32 v119, v116
	v_pk_add_f32 v[114:115], v[118:119], v[114:115]
	v_mov_b32_e32 v116, v121
	v_pk_add_f32 v[114:115], v[116:117], v[114:115]
	ds_bpermute_b32 v117, v113, v115
	ds_bpermute_b32 v116, v113, v114
	s_waitcnt lgkmcnt(0)
	v_pk_add_f32 v[114:115], v[114:115], v[116:117]
	ds_bpermute_b32 v117, v168, v115
	ds_bpermute_b32 v116, v168, v114
	s_waitcnt lgkmcnt(0)
	v_pk_add_f32 v[114:115], v[114:115], v[116:117]
	s_nop 0
	v_pk_fma_f32 v[114:115], v[114:115], s[8:9], v[162:163] op_sel_hi:[1,0,0]
	s_nop 0
	v_mul_f32_e32 v116, 0x4b800000, v115
	v_cmp_gt_f32_e64 s[4:5], s92, v115
	v_cmp_gt_f32_e32 vcc, s92, v114
	s_nop 0
	v_cndmask_b32_e64 v115, v115, v116, s[4:5]
	v_rsq_f32_e32 v115, v115
	s_nop 0
	v_mul_f32_e32 v116, 0x45800000, v115
	v_cndmask_b32_e64 v116, v115, v116, s[4:5]
	v_mul_f32_e32 v115, 0x4b800000, v114
	v_cndmask_b32_e32 v114, v114, v115, vcc
	v_rsq_f32_e32 v114, v114
	v_pk_fma_f32 v[158:159], v[242:243], v[116:117], v[46:47] op_sel_hi:[1,0,1]
	v_pk_fma_f32 v[160:161], v[240:241], v[116:117], v[44:45] op_sel_hi:[1,0,1]
	v_pk_fma_f32 v[154:155], v[246:247], v[116:117], v[42:43] op_sel_hi:[1,0,1]
	v_mul_f32_e32 v115, 0x45800000, v114
	v_cndmask_b32_e32 v114, v114, v115, vcc
	v_pk_fma_f32 v[156:157], v[244:245], v[116:117], v[40:41] op_sel_hi:[1,0,1]
	v_pk_fma_f32 v[216:217], v[250:251], v[116:117], v[38:39] op_sel_hi:[1,0,1]
	v_pk_fma_f32 v[152:153], v[248:249], v[116:117], v[36:37] op_sel_hi:[1,0,1]
	v_pk_fma_f32 v[146:147], v[146:147], v[116:117], v[34:35] op_sel_hi:[1,0,1]
	v_pk_fma_f32 v[214:215], v[144:145], v[116:117], v[32:33] op_sel_hi:[1,0,1]
	v_pk_fma_f32 v[140:141], v[212:213], v[114:115], v[46:47] op_sel_hi:[1,0,1]
	v_pk_fma_f32 v[144:145], v[210:211], v[114:115], v[44:45] op_sel_hi:[1,0,1]
	v_pk_fma_f32 v[138:139], v[206:207], v[114:115], v[42:43] op_sel_hi:[1,0,1]
	v_pk_fma_f32 v[142:143], v[204:205], v[114:115], v[40:41] op_sel_hi:[1,0,1]
	v_pk_fma_f32 v[126:127], v[200:201], v[114:115], v[38:39] op_sel_hi:[1,0,1]
	v_pk_fma_f32 v[128:129], v[198:199], v[114:115], v[36:37] op_sel_hi:[1,0,1]
	v_pk_fma_f32 v[120:121], v[150:151], v[114:115], v[34:35] op_sel_hi:[1,0,1]
	v_pk_fma_f32 v[124:125], v[148:149], v[114:115], v[32:33] op_sel_hi:[1,0,1]
	s_waitcnt vmcnt(4)
; template <int EK>
; DI void gemm_stream(const Params& p, int l, const bf16_t* __restrict__ A, const bf16_t* __restrict__ Bt, int M, int N, int K, ldsp_t shm) {
;     ...
; #pragma unroll
;                 for (int m = 0; m < 8; ++m) {
;                     const f32x4 pp = *(const f32x4*)(ssp + m * 256);
;                     float sq = pp[0] + pp[1] + pp[2] + pp[3];
;                     sq += __shfl_xor(sq, 16);
;                     sq += __shfl_xor(sq, 32);
;                     const float rstd = rsqrtf(sq * (1.f / DM) + EPS);
; #pragma unroll
;                     for (int n = 0; n < 4; ++n) acc[m][n] = acc[m][n] * rstd + shv[n];
;                 }
	v_mov_b64_e32 v[114:115], v[178:179]
	v_mov_b64_e32 v[116:117], v[180:181]
	v_mov_b32_e32 v119, v114
	v_mov_b32_e32 v118, v130
	v_mov_b32_e32 v114, v131
	v_pk_add_f32 v[114:115], v[118:119], v[114:115]
	v_mov_b32_e32 v118, v132
	v_mov_b32_e32 v119, v116
	v_pk_add_f32 v[114:115], v[118:119], v[114:115]
	v_mov_b32_e32 v116, v133
	v_pk_add_f32 v[114:115], v[116:117], v[114:115]
	ds_bpermute_b32 v117, v113, v115
	ds_bpermute_b32 v116, v113, v114
	s_waitcnt lgkmcnt(0)
	v_pk_add_f32 v[114:115], v[114:115], v[116:117]
	ds_bpermute_b32 v117, v168, v115
	ds_bpermute_b32 v116, v168, v114
	s_waitcnt lgkmcnt(0)
	v_pk_add_f32 v[114:115], v[114:115], v[116:117]
	s_nop 0
	v_pk_fma_f32 v[148:149], v[114:115], s[8:9], v[162:163] op_sel_hi:[1,0,0]
	s_nop 0
	v_mul_f32_e32 v114, 0x4b800000, v149
	v_cmp_gt_f32_e64 s[4:5], s92, v149
	v_cmp_gt_f32_e32 vcc, s92, v148
	s_nop 0
	v_cndmask_b32_e64 v114, v149, v114, s[4:5]
	v_rsq_f32_e32 v114, v114
	s_nop 0
	v_mul_f32_e32 v115, 0x45800000, v114
	v_cndmask_b32_e64 v116, v114, v115, s[4:5]
	v_pk_fma_f32 v[132:133], v[110:111], v[116:117], v[46:47] op_sel_hi:[1,0,1]
	v_pk_fma_f32 v[136:137], v[108:109], v[116:117], v[44:45] op_sel_hi:[1,0,1]
	v_pk_fma_f32 v[130:131], v[106:107], v[116:117], v[42:43] op_sel_hi:[1,0,1]
	v_pk_fma_f32 v[134:135], v[104:105], v[116:117], v[40:41] op_sel_hi:[1,0,1]
	v_pk_fma_f32 v[118:119], v[102:103], v[116:117], v[38:39] op_sel_hi:[1,0,1]
	v_pk_fma_f32 v[122:123], v[100:101], v[116:117], v[36:37] op_sel_hi:[1,0,1]
	v_pk_fma_f32 v[114:115], v[98:99], v[116:117], v[34:35] op_sel_hi:[1,0,1]
	v_pk_fma_f32 v[116:117], v[96:97], v[116:117], v[32:33] op_sel_hi:[1,0,1]
	v_mul_f32_e32 v96, 0x4b800000, v148
	v_cndmask_b32_e32 v96, v148, v96, vcc
	v_rsq_f32_e32 v96, v96
	s_nop 0
	v_mul_f32_e32 v97, 0x45800000, v96
	v_cndmask_b32_e32 v104, v96, v97, vcc
	v_pk_fma_f32 v[98:99], v[94:95], v[104:105], v[46:47] op_sel_hi:[1,0,1]
	v_pk_fma_f32 v[102:103], v[92:93], v[104:105], v[44:45] op_sel_hi:[1,0,1]
	v_pk_fma_f32 v[96:97], v[90:91], v[104:105], v[42:43] op_sel_hi:[1,0,1]
	v_pk_fma_f32 v[100:101], v[88:89], v[104:105], v[40:41] op_sel_hi:[1,0,1]
	v_pk_fma_f32 v[92:93], v[86:87], v[104:105], v[38:39] op_sel_hi:[1,0,1]
	v_pk_fma_f32 v[94:95], v[84:85], v[104:105], v[36:37] op_sel_hi:[1,0,1]
	v_pk_fma_f32 v[88:89], v[82:83], v[104:105], v[34:35] op_sel_hi:[1,0,1]
	v_pk_fma_f32 v[90:91], v[80:81], v[104:105], v[32:33] op_sel_hi:[1,0,1]
	v_add_co_u32_e32 v104, vcc, s29, v164
	s_nop 1
	v_addc_co_u32_e32 v105, vcc, 0, v165, vcc
	s_waitcnt vmcnt(2)
	v_mov_b64_e32 v[80:81], v[182:183]
	v_mov_b64_e32 v[82:83], v[184:185]
	v_mov_b64_e32 v[84:85], v[186:187]
	v_mov_b64_e32 v[86:87], v[188:189]
	v_mov_b32_e32 v107, v80
	v_mov_b32_e32 v106, v84
	v_mov_b32_e32 v80, v85
	v_pk_add_f32 v[80:81], v[106:107], v[80:81]
	v_mov_b32_e32 v84, v86
	v_mov_b32_e32 v85, v82
	v_pk_add_f32 v[80:81], v[84:85], v[80:81]
	v_mov_b32_e32 v82, v87
	v_pk_add_f32 v[80:81], v[82:83], v[80:81]
	ds_bpermute_b32 v83, v113, v81
	ds_bpermute_b32 v82, v113, v80
	s_waitcnt lgkmcnt(0)
	v_pk_add_f32 v[80:81], v[80:81], v[82:83]
	ds_bpermute_b32 v83, v168, v81
	ds_bpermute_b32 v82, v168, v80
	s_waitcnt lgkmcnt(0)
	v_pk_add_f32 v[80:81], v[80:81], v[82:83]
	s_nop 0
	v_pk_fma_f32 v[106:107], v[80:81], s[8:9], v[162:163] op_sel_hi:[1,0,0]
	s_nop 0
	v_mul_f32_e32 v80, 0x4b800000, v107
	v_cmp_gt_f32_e64 s[4:5], s92, v107
	v_cmp_gt_f32_e32 vcc, s92, v106
	s_nop 0
	v_cndmask_b32_e64 v80, v107, v80, s[4:5]
	v_rsq_f32_e32 v80, v80
	s_nop 0
	v_mul_f32_e32 v81, 0x45800000, v80
	v_cndmask_b32_e64 v108, v80, v81, s[4:5]
	v_pk_fma_f32 v[80:81], v[74:75], v[108:109], v[42:43] op_sel_hi:[1,0,1]
	v_pk_fma_f32 v[74:75], v[64:65], v[108:109], v[32:33] op_sel_hi:[1,0,1]
	v_mul_f32_e32 v64, 0x4b800000, v106
	v_cndmask_b32_e32 v64, v106, v64, vcc
	v_rsq_f32_e32 v64, v64
	v_pk_fma_f32 v[82:83], v[78:79], v[108:109], v[46:47] op_sel_hi:[1,0,1]
	v_pk_fma_f32 v[86:87], v[76:77], v[108:109], v[44:45] op_sel_hi:[1,0,1]
	v_pk_fma_f32 v[84:85], v[72:73], v[108:109], v[40:41] op_sel_hi:[1,0,1]
	v_mul_f32_e32 v65, 0x45800000, v64
	v_cndmask_b32_e32 v106, v64, v65, vcc
	v_pk_fma_f32 v[76:77], v[70:71], v[108:109], v[38:39] op_sel_hi:[1,0,1]
	v_pk_fma_f32 v[78:79], v[68:69], v[108:109], v[36:37] op_sel_hi:[1,0,1]
	v_pk_fma_f32 v[72:73], v[66:67], v[108:109], v[34:35] op_sel_hi:[1,0,1]
	v_pk_fma_f32 v[68:69], v[62:63], v[106:107], v[46:47] op_sel_hi:[1,0,1]
	v_pk_fma_f32 v[70:71], v[60:61], v[106:107], v[44:45] op_sel_hi:[1,0,1]
	v_pk_fma_f32 v[64:65], v[58:59], v[106:107], v[42:43] op_sel_hi:[1,0,1]
	v_pk_fma_f32 v[66:67], v[56:57], v[106:107], v[40:41] op_sel_hi:[1,0,1]
	v_pk_fma_f32 v[60:61], v[54:55], v[106:107], v[38:39] op_sel_hi:[1,0,1]
	v_pk_fma_f32 v[62:63], v[52:53], v[106:107], v[36:37] op_sel_hi:[1,0,1]
	v_pk_fma_f32 v[56:57], v[50:51], v[106:107], v[34:35] op_sel_hi:[1,0,1]
	v_pk_fma_f32 v[58:59], v[48:49], v[106:107], v[32:33] op_sel_hi:[1,0,1]
	s_waitcnt vmcnt(0)
	v_mov_b64_e32 v[48:49], v[232:233]
	v_mov_b64_e32 v[50:51], v[234:235]
	v_mov_b64_e32 v[52:53], v[236:237]
	v_mov_b64_e32 v[54:55], v[238:239]
	v_mov_b32_e32 v105, v48
	v_mov_b32_e32 v104, v52
	v_mov_b32_e32 v48, v53
	v_pk_add_f32 v[48:49], v[104:105], v[48:49]
	v_mov_b32_e32 v52, v54
	v_mov_b32_e32 v53, v50
	v_pk_add_f32 v[48:49], v[52:53], v[48:49]
	v_mov_b32_e32 v50, v55
	v_pk_add_f32 v[48:49], v[50:51], v[48:49]
	ds_bpermute_b32 v51, v113, v49
	ds_bpermute_b32 v50, v113, v48
	s_waitcnt lgkmcnt(0)
	v_pk_add_f32 v[48:49], v[48:49], v[50:51]
	ds_bpermute_b32 v51, v168, v49
	ds_bpermute_b32 v50, v168, v48
	s_waitcnt lgkmcnt(0)
; DI unsigned pk2(float a, float b) { f32x2 v = {a, b}; bf2_t r = __builtin_convertvector(v, bf2_t); return __builtin_bit_cast(unsigned, r); }
;     static DI void run(const f32x4 (&acc)[8][4], const TileCtx& tc, const Params& p, ldsp_t wb) {
;     ...
;         } else if (BRK == 2) {
; #pragma unroll
;             for (int h = 0; h < 2; ++h) {
; #pragma unroll
;                 for (int mm = 0; mm < 4; ++mm) {
;                     const int m = h * 4 + mm;
; #pragma unroll
;                     for (int n = 0; n < 4; ++n) {
;                         u32x2 w; w[0] = pk2(gelu_tanh(acc[m][n][0]), gelu_tanh(acc[m][n][1])); w[1] = pk2(gelu_tanh(acc[m][n][2]), gelu_tanh(acc[m][n][3]));
;                         wave_put(wb, mm * 16 + fr, n, fq, w);
;                     }
; template <int EK>
; DI void gemm_stream(const Params& p, int l, const bf16_t* __restrict__ A, const bf16_t* __restrict__ Bt, int M, int N, int K, ldsp_t shm) {
;     ...
; #pragma unroll
;                 for (int m = 0; m < 8; ++m) {
;                     const f32x4 pp = *(const f32x4*)(ssp + m * 256);
;                     float sq = pp[0] + pp[1] + pp[2] + pp[3];
;                     sq += __shfl_xor(sq, 16);
;                     sq += __shfl_xor(sq, 32);
;                     const float rstd = rsqrtf(sq * (1.f / DM) + EPS);
; #pragma unroll
;                     for (int n = 0; n < 4; ++n) acc[m][n] = acc[m][n] * rstd + shv[n];
;                 }
;             }
;             if (EK == 0) {
;                 if (pne < 2) EpiIn<0>::run(acc, tc, p, ex);
;                 else if (pne == 2) EpiIn<1>::run(acc, tc, p, ex);
;                 else EpiIn<2>::run(acc, tc, p, ex);
	v_pk_add_f32 v[48:49], v[48:49], v[50:51]
	s_nop 0
	v_pk_fma_f32 v[148:149], v[48:49], s[8:9], v[162:163] op_sel_hi:[1,0,0]
	s_nop 0
	v_mul_f32_e32 v48, 0x4b800000, v149
	v_cmp_gt_f32_e64 s[4:5], s92, v149
	v_cmp_gt_f32_e32 vcc, s92, v148
	s_nop 0
	v_cndmask_b32_e64 v48, v149, v48, s[4:5]
	v_rsq_f32_e32 v48, v48
	s_nop 0
	v_mul_f32_e32 v49, 0x45800000, v48
	v_cndmask_b32_e64 v50, v48, v49, s[4:5]
	v_pk_fma_f32 v[108:109], v[30:31], v[50:51], v[46:47] op_sel_hi:[1,0,1]
	v_pk_fma_f32 v[110:111], v[28:29], v[50:51], v[44:45] op_sel_hi:[1,0,1]
	v_pk_fma_f32 v[104:105], v[26:27], v[50:51], v[42:43] op_sel_hi:[1,0,1]
	v_pk_fma_f32 v[106:107], v[24:25], v[50:51], v[40:41] op_sel_hi:[1,0,1]
	v_pk_fma_f32 v[52:53], v[22:23], v[50:51], v[38:39] op_sel_hi:[1,0,1]
	v_pk_fma_f32 v[54:55], v[20:21], v[50:51], v[36:37] op_sel_hi:[1,0,1]
	v_pk_fma_f32 v[48:49], v[18:19], v[50:51], v[34:35] op_sel_hi:[1,0,1]
	v_pk_fma_f32 v[50:51], v[16:17], v[50:51], v[32:33] op_sel_hi:[1,0,1]
	v_mul_f32_e32 v16, 0x4b800000, v148
	v_cndmask_b32_e32 v16, v148, v16, vcc
	v_rsq_f32_e32 v16, v16
	s_mov_b64 s[4:5], -1
	v_mul_f32_e32 v17, 0x45800000, v16
	v_cndmask_b32_e32 v16, v16, v17, vcc
	v_pk_fma_f32 v[22:23], v[0:1], v[16:17], v[32:33] op_sel_hi:[1,0,1]
	v_mov_b32_e32 v0, 0x10000
	v_pk_fma_f32 v[46:47], v[14:15], v[16:17], v[46:47] op_sel_hi:[1,0,1]
	v_pk_fma_f32 v[44:45], v[12:13], v[16:17], v[44:45] op_sel_hi:[1,0,1]
	v_pk_fma_f32 v[28:29], v[10:11], v[16:17], v[42:43] op_sel_hi:[1,0,1]
	v_pk_fma_f32 v[30:31], v[8:9], v[16:17], v[40:41] op_sel_hi:[1,0,1]
	v_pk_fma_f32 v[24:25], v[6:7], v[16:17], v[38:39] op_sel_hi:[1,0,1]
	v_pk_fma_f32 v[26:27], v[4:5], v[16:17], v[36:37] op_sel_hi:[1,0,1]
	v_pk_fma_f32 v[20:21], v[2:3], v[16:17], v[34:35] op_sel_hi:[1,0,1]
	v_lshl_add_u32 v176, v166, 13, v0
	s_cbranch_scc0 .LBB0_327
	s_cmp_lg_u32 s98, 2
	s_cbranch_scc0 .LBB0_272
	v_mov_b32_e32 v191, 0xc0135761
	v_lshlrev_b32_e32 v3, 3, v173
	v_lshlrev_b32_e32 v2, 7, v169
	v_and_b32_e32 v3, 8, v3
	v_add3_u32 v7, v176, v2, v3
	v_mul_f32_e32 v2, v160, v160
	v_mul_f32_e32 v3, v161, v161
	v_fmamk_f32 v2, v2, 0xbdd2d3e7, v191
	v_fmamk_f32 v3, v3, 0xbdd2d3e7, v191
	v_mul_f32_e32 v2, v160, v2
	v_mul_f32_e32 v3, v161, v3
	s_nop 0
	s_nop 0
	s_nop 0
	s_nop 0
	v_exp_f32_e32 v2, v2
	v_exp_f32_e32 v3, v3
	v_lshrrev_b32_e32 v1, 5, v170
	v_and_b32_e32 v6, 7, v172
	v_add_f32_e32 v2, 1.0, v2
	v_add_f32_e32 v3, 1.0, v3
	v_rcp_f32_e32 v2, v2
	v_rcp_f32_e32 v3, v3
	v_add_u32_e32 v10, s41, v112
	s_add_i32 s4, s6, 0xfffffd00
	v_ashrrev_i32_e32 v11, 31, v10
	v_pk_mul_f32 v[2:3], v[160:161], v[2:3]
	s_ashr_i32 s5, s4, 31
	v_cvt_pk_bf16_f32 v2, v2, v3
	v_mul_f32_e32 v3, v158, v158
	v_fmamk_f32 v3, v3, 0xbdd2d3e7, v191
	v_mul_f32_e32 v3, v158, v3
	s_nop 0
	s_nop 0
	v_exp_f32_e32 v3, v3
	v_lshlrev_b32_e32 v0, 6, v171
	s_lshl_b64 s[4:5], s[4:5], 1
	v_lshlrev_b32_e32 v192, 1, v0
	v_add_f32_e32 v3, 1.0, v3
	v_rcp_f32_e32 v4, v3
	v_mul_f32_e32 v3, v159, v159
	v_fmamk_f32 v3, v3, 0xbdd2d3e7, v191
	v_mul_f32_e32 v3, v159, v3
	s_nop 0
	s_nop 0
	v_exp_f32_e32 v3, v3
	v_mov_b32_e32 v19, v193
	v_mov_b32_e32 v17, v193
	v_mov_b32_e32 v15, v193
	v_add_f32_e32 v3, 1.0, v3
	v_rcp_f32_e32 v5, v3
	v_mov_b32_e32 v13, v193
	v_mov_b32_e32 v9, v193
	v_pk_mul_f32 v[4:5], v[158:159], v[4:5]
	s_nop 0
	v_cvt_pk_bf16_f32 v3, v4, v5
	v_bitop3_b32 v4, v1, v172, 7 bitop3:0x78
	v_lshl_add_u32 v32, v4, 4, v7
	ds_write_b64 v32, v[2:3]
	v_mul_f32_e32 v2, v156, v156
	v_mul_f32_e32 v3, v157, v157
	v_fmamk_f32 v2, v2, 0xbdd2d3e7, v191
	v_fmamk_f32 v3, v3, 0xbdd2d3e7, v191
	v_mul_f32_e32 v2, v156, v2
	v_mul_f32_e32 v3, v157, v3
	s_nop 0
	s_nop 0
	s_nop 0
	s_nop 0
	v_exp_f32_e32 v2, v2
	v_exp_f32_e32 v3, v3
	v_add_f32_e32 v2, 1.0, v2
	v_add_f32_e32 v3, 1.0, v3
	v_rcp_f32_e32 v2, v2
	v_rcp_f32_e32 v3, v3
	s_nop 0
	v_pk_mul_f32 v[2:3], v[156:157], v[2:3]
	s_nop 0
	v_cvt_pk_bf16_f32 v2, v2, v3
	v_mul_f32_e32 v3, v154, v154
	v_fmamk_f32 v3, v3, 0xbdd2d3e7, v191
	v_mul_f32_e32 v3, v154, v3
	s_nop 0
	s_nop 0
	v_exp_f32_e32 v3, v3
	s_nop 0
	v_add_f32_e32 v3, 1.0, v3
	v_rcp_f32_e32 v4, v3
	v_mul_f32_e32 v3, v155, v155
	v_fmamk_f32 v3, v3, 0xbdd2d3e7, v191
	v_mul_f32_e32 v3, v155, v3
	s_nop 0
	s_nop 0
	v_exp_f32_e32 v3, v3
	s_nop 0
	v_add_f32_e32 v3, 1.0, v3
	v_rcp_f32_e32 v5, v3
	s_nop 0
	v_pk_mul_f32 v[4:5], v[154:155], v[4:5]
	s_nop 0
	v_cvt_pk_bf16_f32 v3, v4, v5
	v_bitop3_b32 v4, v1, v6, 2 bitop3:0x36
	v_lshl_add_u32 v33, v4, 4, v7
	ds_write_b64 v33, v[2:3]
	v_mul_f32_e32 v2, v152, v152
	v_mul_f32_e32 v3, v153, v153
	v_fmamk_f32 v2, v2, 0xbdd2d3e7, v191
	v_fmamk_f32 v3, v3, 0xbdd2d3e7, v191
	v_mul_f32_e32 v2, v152, v2
	v_mul_f32_e32 v3, v153, v3
	s_nop 0
	s_nop 0
	s_nop 0
	s_nop 0
	v_exp_f32_e32 v2, v2
	v_exp_f32_e32 v3, v3
	v_add_f32_e32 v2, 1.0, v2
	v_add_f32_e32 v3, 1.0, v3
	v_rcp_f32_e32 v2, v2
	v_rcp_f32_e32 v3, v3
	s_nop 0
	v_pk_mul_f32 v[2:3], v[152:153], v[2:3]
	s_nop 0
	v_cvt_pk_bf16_f32 v2, v2, v3
	v_mul_f32_e32 v3, v216, v216
	v_fmamk_f32 v3, v3, 0xbdd2d3e7, v191
	v_mul_f32_e32 v3, v216, v3
	s_nop 0
	s_nop 0
	v_exp_f32_e32 v3, v3
	s_nop 0
	v_add_f32_e32 v3, 1.0, v3
	v_rcp_f32_e32 v4, v3
	v_mul_f32_e32 v3, v217, v217
	v_fmamk_f32 v3, v3, 0xbdd2d3e7, v191
	v_mul_f32_e32 v3, v217, v3
	s_nop 0
	s_nop 0
	v_exp_f32_e32 v3, v3
	s_nop 0
	v_add_f32_e32 v3, 1.0, v3
	v_rcp_f32_e32 v5, v3
	s_nop 0
	v_pk_mul_f32 v[4:5], v[216:217], v[4:5]
	s_nop 0
	v_cvt_pk_bf16_f32 v3, v4, v5
	v_bitop3_b32 v4, v1, v6, 4 bitop3:0x36
	v_lshl_add_u32 v34, v4, 4, v7
	ds_write_b64 v34, v[2:3]
	v_mul_f32_e32 v2, v214, v214
	v_mul_f32_e32 v3, v215, v215
	v_fmamk_f32 v2, v2, 0xbdd2d3e7, v191
	v_fmamk_f32 v3, v3, 0xbdd2d3e7, v191
	v_mul_f32_e32 v2, v214, v2
	v_mul_f32_e32 v3, v215, v3
; DI unsigned pk2(float a, float b) { f32x2 v = {a, b}; bf2_t r = __builtin_convertvector(v, bf2_t); return __builtin_bit_cast(unsigned, r); }
; DI float fexp2(float x) { return __builtin_amdgcn_exp2f(x); }
; DI float gelu_tanh(float x) {
;     const float y = 0.7978845608028654f * (x + 0.044715f * x * x * x);
;     return x * __builtin_amdgcn_rcpf(1.f + fexp2(-2.f * LOG2E * y));
; }
;     static DI void run(const f32x4 (&acc)[8][4], const TileCtx& tc, const Params& p, ldsp_t wb) {
;     ...
;         } else if (BRK == 2) {
; #pragma unroll
;             for (int h = 0; h < 2; ++h) {
; #pragma unroll
;                 for (int mm = 0; mm < 4; ++mm) {
;                     const int m = h * 4 + mm;
; #pragma unroll
;                     for (int n = 0; n < 4; ++n) {
;                         u32x2 w; w[0] = pk2(gelu_tanh(acc[m][n][0]), gelu_tanh(acc[m][n][1])); w[1] = pk2(gelu_tanh(acc[m][n][2]), gelu_tanh(acc[m][n][3]));
;                         wave_put(wb, mm * 16 + fr, n, fq, w);
;                     }
	s_nop 0
	s_nop 0
	s_nop 0
	s_nop 0
	v_exp_f32_e32 v2, v2
	v_exp_f32_e32 v3, v3
	v_bitop3_b32 v1, v1, v6, 6 bitop3:0x36
	v_lshl_add_u32 v35, v1, 4, v7
	v_add_f32_e32 v2, 1.0, v2
	v_add_f32_e32 v3, 1.0, v3
	v_rcp_f32_e32 v2, v2
	v_rcp_f32_e32 v3, v3
	v_mul_f32_e32 v1, v144, v144
	v_fmamk_f32 v1, v1, 0xbdd2d3e7, v191
	v_mul_f32_e32 v1, v144, v1
	v_pk_mul_f32 v[2:3], v[214:215], v[2:3]
	s_nop 0
	v_cvt_pk_bf16_f32 v2, v2, v3
	v_mul_f32_e32 v3, v146, v146
	v_fmamk_f32 v3, v3, 0xbdd2d3e7, v191
	v_mul_f32_e32 v3, v146, v3
	s_nop 0
	s_nop 0
	v_exp_f32_e32 v3, v3
	s_nop 0
	v_exp_f32_e32 v1, v1
	v_add_f32_e32 v3, 1.0, v3
	v_rcp_f32_e32 v4, v3
	v_mul_f32_e32 v3, v147, v147
	v_fmamk_f32 v3, v3, 0xbdd2d3e7, v191
	v_mul_f32_e32 v3, v147, v3
	s_nop 0
	s_nop 0
	v_exp_f32_e32 v3, v3
	v_add_f32_e32 v1, 1.0, v1
	v_add_f32_e32 v3, 1.0, v3
	v_rcp_f32_e32 v5, v3
	s_nop 0
	v_pk_mul_f32 v[4:5], v[146:147], v[4:5]
	s_nop 0
	v_cvt_pk_bf16_f32 v3, v4, v5
	ds_write_b64 v35, v[2:3]
	v_rcp_f32_e32 v2, v1
	v_mul_f32_e32 v1, v145, v145
	v_fmamk_f32 v1, v1, 0xbdd2d3e7, v191
	v_mul_f32_e32 v1, v145, v1
	s_nop 0
	s_nop 0
	v_exp_f32_e32 v1, v1
	s_nop 0
	v_add_f32_e32 v1, 1.0, v1
	v_rcp_f32_e32 v3, v1
	v_mul_f32_e32 v1, v140, v140
	v_fmamk_f32 v1, v1, 0xbdd2d3e7, v191
	v_mul_f32_e32 v1, v140, v1
	s_nop 0
	s_nop 0
	v_exp_f32_e32 v1, v1
	v_pk_mul_f32 v[2:3], v[144:145], v[2:3]
	v_add_f32_e32 v1, 1.0, v1
	v_rcp_f32_e32 v4, v1
	v_mul_f32_e32 v1, v141, v141
	v_fmamk_f32 v1, v1, 0xbdd2d3e7, v191
	v_mul_f32_e32 v1, v141, v1
	s_nop 0
	s_nop 0
	v_exp_f32_e32 v1, v1
	v_cvt_pk_bf16_f32 v2, v2, v3
	v_add_f32_e32 v1, 1.0, v1
	v_rcp_f32_e32 v5, v1
	v_mul_f32_e32 v1, v142, v142
	v_fmamk_f32 v1, v1, 0xbdd2d3e7, v191
	v_mul_f32_e32 v1, v142, v1
	s_nop 0
	s_nop 0
	v_exp_f32_e32 v1, v1
	v_pk_mul_f32 v[4:5], v[140:141], v[4:5]
	v_add_f32_e32 v1, 1.0, v1
	v_cvt_pk_bf16_f32 v3, v4, v5
	ds_write_b64 v32, v[2:3] offset:2048
	v_rcp_f32_e32 v2, v1
	v_mul_f32_e32 v1, v143, v143
	v_fmamk_f32 v1, v1, 0xbdd2d3e7, v191
	v_mul_f32_e32 v1, v143, v1
	s_nop 0
	s_nop 0
	v_exp_f32_e32 v1, v1
	s_nop 0
	v_add_f32_e32 v1, 1.0, v1
	v_rcp_f32_e32 v3, v1
	v_mul_f32_e32 v1, v138, v138
	v_fmamk_f32 v1, v1, 0xbdd2d3e7, v191
	v_mul_f32_e32 v1, v138, v1
	s_nop 0
	s_nop 0
	v_exp_f32_e32 v1, v1
	v_pk_mul_f32 v[2:3], v[142:143], v[2:3]
	v_add_f32_e32 v1, 1.0, v1
	v_rcp_f32_e32 v4, v1
	v_mul_f32_e32 v1, v139, v139
	v_fmamk_f32 v1, v1, 0xbdd2d3e7, v191
	v_mul_f32_e32 v1, v139, v1
	s_nop 0
	s_nop 0
	v_exp_f32_e32 v1, v1
	v_cvt_pk_bf16_f32 v2, v2, v3
	v_add_f32_e32 v1, 1.0, v1
	v_rcp_f32_e32 v5, v1
	v_mul_f32_e32 v1, v128, v128
	v_fmamk_f32 v1, v1, 0xbdd2d3e7, v191
	v_mul_f32_e32 v1, v128, v1
	s_nop 0
	s_nop 0
	v_exp_f32_e32 v1, v1
	v_pk_mul_f32 v[4:5], v[138:139], v[4:5]
	v_add_f32_e32 v1, 1.0, v1
	v_cvt_pk_bf16_f32 v3, v4, v5
	ds_write_b64 v33, v[2:3] offset:2048
	v_rcp_f32_e32 v2, v1
	v_mul_f32_e32 v1, v129, v129
	v_fmamk_f32 v1, v1, 0xbdd2d3e7, v191
	v_mul_f32_e32 v1, v129, v1
	s_nop 0
	s_nop 0
	v_exp_f32_e32 v1, v1
	s_nop 0
	v_add_f32_e32 v1, 1.0, v1
	v_rcp_f32_e32 v3, v1
	v_mul_f32_e32 v1, v126, v126
	v_fmamk_f32 v1, v1, 0xbdd2d3e7, v191
	v_mul_f32_e32 v1, v126, v1
	s_nop 0
	s_nop 0
	v_exp_f32_e32 v1, v1
	v_pk_mul_f32 v[2:3], v[128:129], v[2:3]
	v_add_f32_e32 v1, 1.0, v1
	v_rcp_f32_e32 v4, v1
	v_mul_f32_e32 v1, v127, v127
	v_fmamk_f32 v1, v1, 0xbdd2d3e7, v191
	v_mul_f32_e32 v1, v127, v1
	s_nop 0
	s_nop 0
	v_exp_f32_e32 v1, v1
	v_cvt_pk_bf16_f32 v2, v2, v3
	v_add_f32_e32 v1, 1.0, v1
	v_rcp_f32_e32 v5, v1
	v_mul_f32_e32 v1, v124, v124
	v_fmamk_f32 v1, v1, 0xbdd2d3e7, v191
	v_mul_f32_e32 v1, v124, v1
	s_nop 0
	s_nop 0
	v_exp_f32_e32 v1, v1
	v_pk_mul_f32 v[4:5], v[126:127], v[4:5]
	v_add_f32_e32 v1, 1.0, v1
	v_cvt_pk_bf16_f32 v3, v4, v5
	ds_write_b64 v34, v[2:3] offset:2048
	v_rcp_f32_e32 v2, v1
	v_mul_f32_e32 v1, v125, v125
	v_fmamk_f32 v1, v1, 0xbdd2d3e7, v191
	v_mul_f32_e32 v1, v125, v1
	s_nop 0
	s_nop 0
	v_exp_f32_e32 v1, v1
	s_nop 0
	v_add_f32_e32 v1, 1.0, v1
	v_rcp_f32_e32 v3, v1
	v_mul_f32_e32 v1, v120, v120
	v_fmamk_f32 v1, v1, 0xbdd2d3e7, v191
	v_mul_f32_e32 v1, v120, v1
	s_nop 0
	s_nop 0
	v_exp_f32_e32 v1, v1
	v_pk_mul_f32 v[2:3], v[124:125], v[2:3]
	v_add_f32_e32 v1, 1.0, v1
	v_rcp_f32_e32 v4, v1
	v_mul_f32_e32 v1, v121, v121
	v_fmamk_f32 v1, v1, 0xbdd2d3e7, v191
	v_mul_f32_e32 v1, v121, v1
	s_nop 0
	s_nop 0
	v_exp_f32_e32 v1, v1
	v_cvt_pk_bf16_f32 v2, v2, v3
	v_add_f32_e32 v1, 1.0, v1
	v_rcp_f32_e32 v5, v1
	v_mul_f32_e32 v1, v136, v136
	v_fmamk_f32 v1, v1, 0xbdd2d3e7, v191
	v_mul_f32_e32 v1, v136, v1
	s_nop 0
	s_nop 0
	v_exp_f32_e32 v1, v1
	v_pk_mul_f32 v[4:5], v[120:121], v[4:5]
	v_add_f32_e32 v1, 1.0, v1
	v_cvt_pk_bf16_f32 v3, v4, v5
	ds_write_b64 v35, v[2:3] offset:2048
	v_rcp_f32_e32 v2, v1
	v_mul_f32_e32 v1, v137, v137
	v_fmamk_f32 v1, v1, 0xbdd2d3e7, v191
	v_mul_f32_e32 v1, v137, v1
	s_nop 0
	s_nop 0
	v_exp_f32_e32 v1, v1
	s_nop 0
	v_add_f32_e32 v1, 1.0, v1
	v_rcp_f32_e32 v3, v1
	v_mul_f32_e32 v1, v132, v132
	v_fmamk_f32 v1, v1, 0xbdd2d3e7, v191
	v_mul_f32_e32 v1, v132, v1
	s_nop 0
	s_nop 0
	v_exp_f32_e32 v1, v1
	v_pk_mul_f32 v[2:3], v[136:137], v[2:3]
	v_add_f32_e32 v1, 1.0, v1
	v_rcp_f32_e32 v4, v1
	v_mul_f32_e32 v1, v133, v133
	v_fmamk_f32 v1, v1, 0xbdd2d3e7, v191
	v_mul_f32_e32 v1, v133, v1
	s_nop 0
	s_nop 0
	v_exp_f32_e32 v1, v1
	v_cvt_pk_bf16_f32 v2, v2, v3
	v_add_f32_e32 v1, 1.0, v1
	v_rcp_f32_e32 v5, v1
	v_mul_f32_e32 v1, v134, v134
	v_fmamk_f32 v1, v1, 0xbdd2d3e7, v191
	v_mul_f32_e32 v1, v134, v1
	s_nop 0
	s_nop 0
	v_exp_f32_e32 v1, v1
	v_pk_mul_f32 v[4:5], v[132:133], v[4:5]
	v_add_f32_e32 v1, 1.0, v1
	v_cvt_pk_bf16_f32 v3, v4, v5
	ds_write_b64 v32, v[2:3] offset:4096
	v_rcp_f32_e32 v2, v1
; #define LDSP __attribute__((address_space(3)))
; DI unsigned pk2(float a, float b) { f32x2 v = {a, b}; bf2_t r = __builtin_convertvector(v, bf2_t); return __builtin_bit_cast(unsigned, r); }
; DI void wave_rows_store(ldsp_t wb, int lane, bf16_t* dst0, size_t ld) {
; #pragma unroll
;     for (int i = 0; i < 8; ++i) {
;         const int row = i * 8 + (lane >> 3), ch = lane & 7;
;         const u32x4 v = *(const LDSP u32x4*)(wb + row * 128 + ((ch ^ (row & 7)) << 4));
;         *(u32x4*)(dst0 + (size_t)row * ld + ch * 8) = v;
;     }
; }
;     static DI void run(const f32x4 (&acc)[8][4], const TileCtx& tc, const Params& p, ldsp_t wb) {
;     ...
;         } else if (BRK == 2) {
; #pragma unroll
;             for (int h = 0; h < 2; ++h) {
; #pragma unroll
;                 for (int mm = 0; mm < 4; ++mm) {
;                     const int m = h * 4 + mm;
; #pragma unroll
;                     for (int n = 0; n < 4; ++n) {
;                         u32x2 w; w[0] = pk2(gelu_tanh(acc[m][n][0]), gelu_tanh(acc[m][n][1])); w[1] = pk2(gelu_tanh(acc[m][n][2]), gelu_tanh(acc[m][n][3]));
;                         wave_put(wb, mm * 16 + fr, n, fq, w);
;                     }
;                 }
;                 wave_rows_store(wb, tc.lane, p.U + (size_t)(tc.brow + tc.wr * 128 + h * 64) * 1024 + (pn - 3) * 256 + wc * 64, 1024);
	v_mul_f32_e32 v1, v135, v135
	v_fmamk_f32 v1, v1, 0xbdd2d3e7, v191
	v_mul_f32_e32 v1, v135, v1
	s_nop 0
	s_nop 0
	v_exp_f32_e32 v1, v1
	s_nop 0
	v_add_f32_e32 v1, 1.0, v1
	v_rcp_f32_e32 v3, v1
	v_mul_f32_e32 v1, v130, v130
	v_fmamk_f32 v1, v1, 0xbdd2d3e7, v191
	v_mul_f32_e32 v1, v130, v1
	s_nop 0
	s_nop 0
	v_exp_f32_e32 v1, v1
	v_pk_mul_f32 v[2:3], v[134:135], v[2:3]
	v_add_f32_e32 v1, 1.0, v1
	v_rcp_f32_e32 v4, v1
	v_mul_f32_e32 v1, v131, v131
	v_fmamk_f32 v1, v1, 0xbdd2d3e7, v191
	v_mul_f32_e32 v1, v131, v1
	s_nop 0
	s_nop 0
	v_exp_f32_e32 v1, v1
	v_cvt_pk_bf16_f32 v2, v2, v3
	v_add_f32_e32 v1, 1.0, v1
	v_rcp_f32_e32 v5, v1
	v_mul_f32_e32 v1, v122, v122
	v_fmamk_f32 v1, v1, 0xbdd2d3e7, v191
	v_mul_f32_e32 v1, v122, v1
	s_nop 0
	s_nop 0
	v_exp_f32_e32 v1, v1
	v_pk_mul_f32 v[4:5], v[130:131], v[4:5]
	v_add_f32_e32 v1, 1.0, v1
	v_cvt_pk_bf16_f32 v3, v4, v5
	ds_write_b64 v33, v[2:3] offset:4096
	v_rcp_f32_e32 v2, v1
	v_mul_f32_e32 v1, v123, v123
	v_fmamk_f32 v1, v1, 0xbdd2d3e7, v191
	v_mul_f32_e32 v1, v123, v1
	s_nop 0
	s_nop 0
	v_exp_f32_e32 v1, v1
	s_nop 0
	v_add_f32_e32 v1, 1.0, v1
	v_rcp_f32_e32 v3, v1
	v_mul_f32_e32 v1, v118, v118
	v_fmamk_f32 v1, v1, 0xbdd2d3e7, v191
	v_mul_f32_e32 v1, v118, v1
	s_nop 0
	s_nop 0
	v_exp_f32_e32 v1, v1
	v_pk_mul_f32 v[2:3], v[122:123], v[2:3]
	v_add_f32_e32 v1, 1.0, v1
	v_rcp_f32_e32 v4, v1
	v_mul_f32_e32 v1, v119, v119
	v_fmamk_f32 v1, v1, 0xbdd2d3e7, v191
	v_mul_f32_e32 v1, v119, v1
	s_nop 0
	s_nop 0
	v_exp_f32_e32 v1, v1
	v_cvt_pk_bf16_f32 v2, v2, v3
	v_add_f32_e32 v1, 1.0, v1
	v_rcp_f32_e32 v5, v1
	v_mul_f32_e32 v1, v116, v116
	v_fmamk_f32 v1, v1, 0xbdd2d3e7, v191
	v_mul_f32_e32 v1, v116, v1
	s_nop 0
	s_nop 0
	v_exp_f32_e32 v1, v1
	v_pk_mul_f32 v[4:5], v[118:119], v[4:5]
	v_add_f32_e32 v1, 1.0, v1
	v_cvt_pk_bf16_f32 v3, v4, v5
	ds_write_b64 v34, v[2:3] offset:4096
	v_rcp_f32_e32 v2, v1
	v_mul_f32_e32 v1, v117, v117
	v_fmamk_f32 v1, v1, 0xbdd2d3e7, v191
	v_mul_f32_e32 v1, v117, v1
	s_nop 0
	s_nop 0
	v_exp_f32_e32 v1, v1
	s_nop 0
	v_add_f32_e32 v1, 1.0, v1
	v_rcp_f32_e32 v3, v1
	v_mul_f32_e32 v1, v114, v114
	v_fmamk_f32 v1, v1, 0xbdd2d3e7, v191
	v_mul_f32_e32 v1, v114, v1
	s_nop 0
	s_nop 0
	v_exp_f32_e32 v1, v1
	v_pk_mul_f32 v[2:3], v[116:117], v[2:3]
	v_add_f32_e32 v1, 1.0, v1
	v_rcp_f32_e32 v4, v1
	v_mul_f32_e32 v1, v115, v115
	v_fmamk_f32 v1, v1, 0xbdd2d3e7, v191
	v_mul_f32_e32 v1, v115, v1
	s_nop 0
	s_nop 0
	v_exp_f32_e32 v1, v1
	v_cvt_pk_bf16_f32 v2, v2, v3
	v_add_f32_e32 v1, 1.0, v1
	v_rcp_f32_e32 v5, v1
	v_mul_f32_e32 v1, v102, v102
	v_fmamk_f32 v1, v1, 0xbdd2d3e7, v191
	v_mul_f32_e32 v1, v102, v1
	s_nop 0
	s_nop 0
	v_exp_f32_e32 v1, v1
	v_pk_mul_f32 v[4:5], v[114:115], v[4:5]
	v_add_f32_e32 v1, 1.0, v1
	v_cvt_pk_bf16_f32 v3, v4, v5
	ds_write_b64 v35, v[2:3] offset:4096
	v_rcp_f32_e32 v2, v1
	v_mul_f32_e32 v1, v103, v103
	v_fmamk_f32 v1, v1, 0xbdd2d3e7, v191
	v_mul_f32_e32 v1, v103, v1
	s_nop 0
	s_nop 0
	v_exp_f32_e32 v1, v1
	s_nop 0
	v_add_f32_e32 v1, 1.0, v1
	v_rcp_f32_e32 v3, v1
	v_mul_f32_e32 v1, v98, v98
	v_fmamk_f32 v1, v1, 0xbdd2d3e7, v191
	v_mul_f32_e32 v1, v98, v1
	s_nop 0
	s_nop 0
	v_exp_f32_e32 v1, v1
	v_pk_mul_f32 v[2:3], v[102:103], v[2:3]
	v_add_f32_e32 v1, 1.0, v1
	v_rcp_f32_e32 v4, v1
	v_mul_f32_e32 v1, v99, v99
	v_fmamk_f32 v1, v1, 0xbdd2d3e7, v191
	v_mul_f32_e32 v1, v99, v1
	s_nop 0
	s_nop 0
	v_exp_f32_e32 v1, v1
	v_cvt_pk_bf16_f32 v2, v2, v3
	v_add_f32_e32 v1, 1.0, v1
	v_rcp_f32_e32 v5, v1
	v_mul_f32_e32 v1, v100, v100
	v_fmamk_f32 v1, v1, 0xbdd2d3e7, v191
	v_mul_f32_e32 v1, v100, v1
	s_nop 0
	s_nop 0
	v_exp_f32_e32 v1, v1
	v_pk_mul_f32 v[4:5], v[98:99], v[4:5]
	v_add_f32_e32 v1, 1.0, v1
	v_cvt_pk_bf16_f32 v3, v4, v5
	ds_write_b64 v32, v[2:3] offset:6144
	v_rcp_f32_e32 v2, v1
	v_mul_f32_e32 v1, v101, v101
	v_fmamk_f32 v1, v1, 0xbdd2d3e7, v191
	v_mul_f32_e32 v1, v101, v1
	s_nop 0
	s_nop 0
	v_exp_f32_e32 v1, v1
	s_nop 0
	v_add_f32_e32 v1, 1.0, v1
	v_rcp_f32_e32 v3, v1
	v_mul_f32_e32 v1, v96, v96
	v_fmamk_f32 v1, v1, 0xbdd2d3e7, v191
	v_mul_f32_e32 v1, v96, v1
	s_nop 0
	s_nop 0
	v_exp_f32_e32 v1, v1
	v_pk_mul_f32 v[2:3], v[100:101], v[2:3]
	v_add_f32_e32 v1, 1.0, v1
	v_rcp_f32_e32 v4, v1
	v_mul_f32_e32 v1, v97, v97
	v_fmamk_f32 v1, v1, 0xbdd2d3e7, v191
	v_mul_f32_e32 v1, v97, v1
	s_nop 0
	s_nop 0
	v_exp_f32_e32 v1, v1
	v_cvt_pk_bf16_f32 v2, v2, v3
	v_add_f32_e32 v1, 1.0, v1
	v_rcp_f32_e32 v5, v1
	v_mul_f32_e32 v1, v94, v94
	v_fmamk_f32 v1, v1, 0xbdd2d3e7, v191
	v_mul_f32_e32 v1, v94, v1
	s_nop 0
	s_nop 0
	v_exp_f32_e32 v1, v1
	v_pk_mul_f32 v[4:5], v[96:97], v[4:5]
	v_add_f32_e32 v1, 1.0, v1
	v_cvt_pk_bf16_f32 v3, v4, v5
	ds_write_b64 v33, v[2:3] offset:6144
	v_rcp_f32_e32 v2, v1
	v_mul_f32_e32 v1, v95, v95
	v_fmamk_f32 v1, v1, 0xbdd2d3e7, v191
	v_mul_f32_e32 v1, v95, v1
	s_nop 0
	s_nop 0
	v_exp_f32_e32 v1, v1
	s_nop 0
	v_add_f32_e32 v1, 1.0, v1
	v_rcp_f32_e32 v3, v1
	v_mul_f32_e32 v1, v92, v92
	v_fmamk_f32 v1, v1, 0xbdd2d3e7, v191
	v_mul_f32_e32 v1, v92, v1
	s_nop 0
	s_nop 0
	v_exp_f32_e32 v1, v1
	v_pk_mul_f32 v[2:3], v[94:95], v[2:3]
	v_add_f32_e32 v1, 1.0, v1
	v_rcp_f32_e32 v4, v1
	v_mul_f32_e32 v1, v93, v93
	v_fmamk_f32 v1, v1, 0xbdd2d3e7, v191
	v_mul_f32_e32 v1, v93, v1
	s_nop 0
	s_nop 0
	v_exp_f32_e32 v1, v1
	v_cvt_pk_bf16_f32 v2, v2, v3
	v_add_f32_e32 v1, 1.0, v1
	v_rcp_f32_e32 v5, v1
	v_mul_f32_e32 v1, v90, v90
	v_fmamk_f32 v1, v1, 0xbdd2d3e7, v191
	v_mul_f32_e32 v1, v90, v1
	s_nop 0
	s_nop 0
	v_exp_f32_e32 v1, v1
	v_pk_mul_f32 v[4:5], v[92:93], v[4:5]
	v_add_f32_e32 v1, 1.0, v1
	v_cvt_pk_bf16_f32 v3, v4, v5
	ds_write_b64 v34, v[2:3] offset:6144
	v_rcp_f32_e32 v2, v1
	v_mul_f32_e32 v1, v91, v91
	v_fmamk_f32 v1, v1, 0xbdd2d3e7, v191
	v_mul_f32_e32 v1, v91, v1
	s_nop 0
	s_nop 0
	v_exp_f32_e32 v1, v1
	s_nop 0
	v_add_f32_e32 v1, 1.0, v1
	v_rcp_f32_e32 v3, v1
	v_mul_f32_e32 v1, v88, v88
	v_fmamk_f32 v1, v1, 0xbdd2d3e7, v191
	v_mul_f32_e32 v1, v88, v1
	s_nop 0
	s_nop 0
	v_exp_f32_e32 v1, v1
	v_pk_mul_f32 v[2:3], v[90:91], v[2:3]
	v_add_f32_e32 v1, 1.0, v1
	v_rcp_f32_e32 v4, v1
	v_mul_f32_e32 v1, v89, v89
	v_fmamk_f32 v1, v1, 0xbdd2d3e7, v191
	v_mul_f32_e32 v1, v89, v1
	s_nop 0
	s_nop 0
	v_exp_f32_e32 v1, v1
	v_cvt_pk_bf16_f32 v2, v2, v3
	v_add_f32_e32 v1, 1.0, v1
	v_rcp_f32_e32 v5, v1
	s_nop 0
	v_pk_mul_f32 v[4:5], v[88:89], v[4:5]
	s_nop 0
	v_cvt_pk_bf16_f32 v3, v4, v5
	ds_write_b64 v35, v[2:3] offset:6144
	v_lshlrev_b64 v[2:3], 11, v[10:11]
	v_lshl_add_u64 v[2:3], s[16:17], 0, v[2:3]
	v_lshl_add_u64 v[2:3], v[2:3], 0, s[4:5]
	v_lshrrev_b32_e32 v11, 3, v170
	v_lshl_add_u64 v[0:1], v[2:3], 0, v[192:193]
	v_xor_b32_e32 v2, v11, v170
	v_lshlrev_b32_e32 v2, 4, v2
	v_and_b32_e32 v2, 0x70, v2
	v_add_u32_e32 v43, v176, v2
	v_lshlrev_b32_e32 v2, 4, v170
	v_and_b32_e32 v18, 0x70, v2
	v_lshl_add_u32 v42, v11, 7, v43
	v_lshl_add_u64 v[162:163], v[0:1], 0, v[18:19]
	ds_read_b128 v[0:3], v42
	v_lshlrev_b32_e32 v16, 11, v11
	v_lshl_add_u64 v[4:5], v[162:163], 0, v[16:17]
	s_waitcnt lgkmcnt(0)
; #define LDSP __attribute__((address_space(3)))
; DI unsigned pk2(float a, float b) { f32x2 v = {a, b}; bf2_t r = __builtin_convertvector(v, bf2_t); return __builtin_bit_cast(unsigned, r); }
; DI void wave_rows_store(ldsp_t wb, int lane, bf16_t* dst0, size_t ld) {
; #pragma unroll
;     for (int i = 0; i < 8; ++i) {
;         const int row = i * 8 + (lane >> 3), ch = lane & 7;
;         const u32x4 v = *(const LDSP u32x4*)(wb + row * 128 + ((ch ^ (row & 7)) << 4));
;         *(u32x4*)(dst0 + (size_t)row * ld + ch * 8) = v;
;     }
; }
;     static DI void run(const f32x4 (&acc)[8][4], const TileCtx& tc, const Params& p, ldsp_t wb) {
;     ...
;         } else if (BRK == 2) {
; #pragma unroll
;             for (int h = 0; h < 2; ++h) {
; #pragma unroll
;                 for (int mm = 0; mm < 4; ++mm) {
;                     const int m = h * 4 + mm;
; #pragma unroll
;                     for (int n = 0; n < 4; ++n) {
;                         u32x2 w; w[0] = pk2(gelu_tanh(acc[m][n][0]), gelu_tanh(acc[m][n][1])); w[1] = pk2(gelu_tanh(acc[m][n][2]), gelu_tanh(acc[m][n][3]));
;                         wave_put(wb, mm * 16 + fr, n, fq, w);
;                     }
	global_store_dwordx4 v[4:5], v[0:3], off sc1
	v_or_b32_e32 v4, 8, v11
	v_lshl_add_u32 v41, v4, 7, v43
	ds_read_b128 v[0:3], v41
	v_lshlrev_b32_e32 v14, 11, v4
	v_lshl_add_u64 v[4:5], v[162:163], 0, v[14:15]
	s_waitcnt lgkmcnt(0)
	global_store_dwordx4 v[4:5], v[0:3], off sc1
	v_or_b32_e32 v4, 16, v11
	v_lshl_add_u32 v40, v4, 7, v43
	ds_read_b128 v[0:3], v40
	v_lshlrev_b32_e32 v12, 11, v4
	v_lshl_add_u64 v[4:5], v[162:163], 0, v[12:13]
	s_waitcnt lgkmcnt(0)
	global_store_dwordx4 v[4:5], v[0:3], off sc1
	v_or_b32_e32 v4, 24, v11
	v_lshl_add_u32 v39, v4, 7, v43
	ds_read_b128 v[0:3], v39
	v_lshlrev_b32_e32 v8, 11, v4
	v_lshl_add_u64 v[4:5], v[162:163], 0, v[8:9]
	s_waitcnt lgkmcnt(0)
	global_store_dwordx4 v[4:5], v[0:3], off sc1
	s_nop 1
	v_or_b32_e32 v0, 32, v11
	v_lshl_add_u32 v38, v0, 7, v43
	ds_read_b128 v[4:7], v38
	v_lshlrev_b32_e32 v2, 11, v0
	v_mov_b32_e32 v3, v193
	v_lshl_add_u64 v[0:1], v[162:163], 0, v[2:3]
	s_waitcnt lgkmcnt(0)
	global_store_dwordx4 v[0:1], v[4:7], off sc1
	v_or_b32_e32 v0, 40, v11
	v_lshl_add_u32 v37, v0, 7, v43
	ds_read_b128 v[148:151], v37
	v_lshlrev_b32_e32 v6, 11, v0
	v_mov_b32_e32 v7, v193
	v_lshl_add_u64 v[0:1], v[162:163], 0, v[6:7]
	v_mov_b32_e32 v5, v193
	s_waitcnt lgkmcnt(0)
	global_store_dwordx4 v[0:1], v[148:151], off sc1
	v_or_b32_e32 v0, 48, v11
	v_lshl_add_u32 v36, v0, 7, v43
	ds_read_b128 v[148:151], v36
	v_lshlrev_b32_e32 v4, 11, v0
	v_lshl_add_u64 v[0:1], v[162:163], 0, v[4:5]
	s_waitcnt lgkmcnt(0)
	global_store_dwordx4 v[0:1], v[148:151], off sc1
	v_or_b32_e32 v0, 56, v11
	v_lshl_add_u32 v11, v0, 7, v43
	v_mul_f32_e32 v43, v86, v86
	v_fmamk_f32 v43, v43, 0xbdd2d3e7, v191
	v_mul_f32_e32 v43, v86, v43
	s_nop 0
	s_nop 0
	ds_read_b128 v[148:151], v11
	v_exp_f32_e32 v43, v43
	v_lshlrev_b32_e32 v0, 11, v0
	v_mov_b32_e32 v1, v193
	v_lshl_add_u64 v[162:163], v[162:163], 0, v[0:1]
	v_add_f32_e32 v43, 1.0, v43
	s_waitcnt lgkmcnt(0)
	global_store_dwordx4 v[162:163], v[148:151], off sc1
	s_nop 1
	v_rcp_f32_e32 v148, v43
	v_mul_f32_e32 v43, v87, v87
	v_fmamk_f32 v43, v43, 0xbdd2d3e7, v191
	v_mul_f32_e32 v43, v87, v43
	s_nop 0
	s_nop 0
	v_exp_f32_e32 v43, v43
	s_nop 0
	v_add_f32_e32 v43, 1.0, v43
	v_rcp_f32_e32 v149, v43
	v_mul_f32_e32 v43, v82, v82
	v_fmamk_f32 v43, v43, 0xbdd2d3e7, v191
	v_mul_f32_e32 v43, v82, v43
	s_nop 0
	s_nop 0
	v_exp_f32_e32 v43, v43
	v_pk_mul_f32 v[148:149], v[86:87], v[148:149]
	v_add_f32_e32 v43, 1.0, v43
	v_rcp_f32_e32 v150, v43
	v_mul_f32_e32 v43, v83, v83
	v_fmamk_f32 v43, v43, 0xbdd2d3e7, v191
	v_mul_f32_e32 v43, v83, v43
	s_nop 0
	s_nop 0
	v_exp_f32_e32 v43, v43
	v_cvt_pk_bf16_f32 v148, v148, v149
	v_add_f32_e32 v43, 1.0, v43
	v_rcp_f32_e32 v151, v43
	v_mul_f32_e32 v43, v84, v84
	v_fmamk_f32 v43, v43, 0xbdd2d3e7, v191
	v_mul_f32_e32 v43, v84, v43
	s_nop 0
	s_nop 0
	v_exp_f32_e32 v43, v43
	v_pk_mul_f32 v[150:151], v[82:83], v[150:151]
	v_add_f32_e32 v43, 1.0, v43
	v_cvt_pk_bf16_f32 v149, v150, v151
	ds_write_b64 v32, v[148:149]
	v_rcp_f32_e32 v148, v43
	v_mul_f32_e32 v43, v85, v85
	v_fmamk_f32 v43, v43, 0xbdd2d3e7, v191
	v_mul_f32_e32 v43, v85, v43
	s_nop 0
	s_nop 0
	v_exp_f32_e32 v43, v43
	s_nop 0
	v_add_f32_e32 v43, 1.0, v43
	v_rcp_f32_e32 v149, v43
	v_mul_f32_e32 v43, v80, v80
	v_fmamk_f32 v43, v43, 0xbdd2d3e7, v191
	v_mul_f32_e32 v43, v80, v43
	s_nop 0
	s_nop 0
	v_exp_f32_e32 v43, v43
	v_pk_mul_f32 v[148:149], v[84:85], v[148:149]
	v_add_f32_e32 v43, 1.0, v43
	v_rcp_f32_e32 v150, v43
	v_mul_f32_e32 v43, v81, v81
	v_fmamk_f32 v43, v43, 0xbdd2d3e7, v191
	v_mul_f32_e32 v43, v81, v43
	s_nop 0
	s_nop 0
	v_exp_f32_e32 v43, v43
	v_cvt_pk_bf16_f32 v148, v148, v149
	v_add_f32_e32 v43, 1.0, v43
	v_rcp_f32_e32 v151, v43
	v_mul_f32_e32 v43, v78, v78
	v_fmamk_f32 v43, v43, 0xbdd2d3e7, v191
	v_mul_f32_e32 v43, v78, v43
	s_nop 0
	s_nop 0
	v_exp_f32_e32 v43, v43
	v_pk_mul_f32 v[150:151], v[80:81], v[150:151]
	v_add_f32_e32 v43, 1.0, v43
	v_cvt_pk_bf16_f32 v149, v150, v151
	ds_write_b64 v33, v[148:149]
	v_rcp_f32_e32 v148, v43
	v_mul_f32_e32 v43, v79, v79
	v_fmamk_f32 v43, v43, 0xbdd2d3e7, v191
	v_mul_f32_e32 v43, v79, v43
	s_nop 0
	s_nop 0
	v_exp_f32_e32 v43, v43
	s_nop 0
	v_add_f32_e32 v43, 1.0, v43
	v_rcp_f32_e32 v149, v43
	v_mul_f32_e32 v43, v76, v76
	v_fmamk_f32 v43, v43, 0xbdd2d3e7, v191
	v_mul_f32_e32 v43, v76, v43
	s_nop 0
	s_nop 0
	v_exp_f32_e32 v43, v43
	v_pk_mul_f32 v[148:149], v[78:79], v[148:149]
	v_add_f32_e32 v43, 1.0, v43
	v_rcp_f32_e32 v150, v43
	v_mul_f32_e32 v43, v77, v77
	v_fmamk_f32 v43, v43, 0xbdd2d3e7, v191
	v_mul_f32_e32 v43, v77, v43
	s_nop 0
	s_nop 0
	v_exp_f32_e32 v43, v43
	v_cvt_pk_bf16_f32 v148, v148, v149
	v_add_f32_e32 v43, 1.0, v43
	v_rcp_f32_e32 v151, v43
	v_mul_f32_e32 v43, v74, v74
	v_fmamk_f32 v43, v43, 0xbdd2d3e7, v191
	v_mul_f32_e32 v43, v74, v43
	s_nop 0
	s_nop 0
	v_exp_f32_e32 v43, v43
	v_pk_mul_f32 v[150:151], v[76:77], v[150:151]
	v_add_f32_e32 v43, 1.0, v43
	v_cvt_pk_bf16_f32 v149, v150, v151
	ds_write_b64 v34, v[148:149]
	v_rcp_f32_e32 v148, v43
	v_mul_f32_e32 v43, v75, v75
	v_fmamk_f32 v43, v43, 0xbdd2d3e7, v191
	v_mul_f32_e32 v43, v75, v43
	s_nop 0
	s_nop 0
	v_exp_f32_e32 v43, v43
	s_nop 0
	v_add_f32_e32 v43, 1.0, v43
	v_rcp_f32_e32 v149, v43
	v_mul_f32_e32 v43, v72, v72
	v_fmamk_f32 v43, v43, 0xbdd2d3e7, v191
	v_mul_f32_e32 v43, v72, v43
	s_nop 0
	s_nop 0
	v_exp_f32_e32 v43, v43
	v_pk_mul_f32 v[148:149], v[74:75], v[148:149]
	v_add_f32_e32 v43, 1.0, v43
	v_rcp_f32_e32 v150, v43
	v_mul_f32_e32 v43, v73, v73
	v_fmamk_f32 v43, v43, 0xbdd2d3e7, v191
	v_mul_f32_e32 v43, v73, v43
	s_nop 0
	s_nop 0
	v_exp_f32_e32 v43, v43
	v_cvt_pk_bf16_f32 v148, v148, v149
	v_add_f32_e32 v43, 1.0, v43
	v_rcp_f32_e32 v151, v43
	v_mul_f32_e32 v43, v70, v70
; DI unsigned pk2(float a, float b) { f32x2 v = {a, b}; bf2_t r = __builtin_convertvector(v, bf2_t); return __builtin_bit_cast(unsigned, r); }
; DI float fexp2(float x) { return __builtin_amdgcn_exp2f(x); }
; DI float gelu_tanh(float x) {
;     const float y = 0.7978845608028654f * (x + 0.044715f * x * x * x);
;     return x * __builtin_amdgcn_rcpf(1.f + fexp2(-2.f * LOG2E * y));
; }
;     static DI void run(const f32x4 (&acc)[8][4], const TileCtx& tc, const Params& p, ldsp_t wb) {
;     ...
;         } else if (BRK == 2) {
; #pragma unroll
;             for (int h = 0; h < 2; ++h) {
; #pragma unroll
;                 for (int mm = 0; mm < 4; ++mm) {
;                     const int m = h * 4 + mm;
; #pragma unroll
;                     for (int n = 0; n < 4; ++n) {
;                         u32x2 w; w[0] = pk2(gelu_tanh(acc[m][n][0]), gelu_tanh(acc[m][n][1])); w[1] = pk2(gelu_tanh(acc[m][n][2]), gelu_tanh(acc[m][n][3]));
;                         wave_put(wb, mm * 16 + fr, n, fq, w);
;                     }
	v_fmamk_f32 v43, v43, 0xbdd2d3e7, v191
	v_mul_f32_e32 v43, v70, v43
	s_nop 0
	s_nop 0
	v_exp_f32_e32 v43, v43
	v_pk_mul_f32 v[150:151], v[72:73], v[150:151]
	v_add_f32_e32 v43, 1.0, v43
	v_cvt_pk_bf16_f32 v149, v150, v151
	ds_write_b64 v35, v[148:149]
	v_rcp_f32_e32 v148, v43
	v_mul_f32_e32 v43, v71, v71
	v_fmamk_f32 v43, v43, 0xbdd2d3e7, v191
	v_mul_f32_e32 v43, v71, v43
	s_nop 0
	s_nop 0
	v_exp_f32_e32 v43, v43
	s_nop 0
	v_add_f32_e32 v43, 1.0, v43
	v_rcp_f32_e32 v149, v43
	v_mul_f32_e32 v43, v68, v68
	v_fmamk_f32 v43, v43, 0xbdd2d3e7, v191
	v_mul_f32_e32 v43, v68, v43
	s_nop 0
	s_nop 0
	v_exp_f32_e32 v43, v43
	v_pk_mul_f32 v[148:149], v[70:71], v[148:149]
	v_add_f32_e32 v43, 1.0, v43
	v_rcp_f32_e32 v150, v43
	v_mul_f32_e32 v43, v69, v69
	v_fmamk_f32 v43, v43, 0xbdd2d3e7, v191
	v_mul_f32_e32 v43, v69, v43
	s_nop 0
	s_nop 0
	v_exp_f32_e32 v43, v43
	v_cvt_pk_bf16_f32 v148, v148, v149
	v_add_f32_e32 v43, 1.0, v43
	v_rcp_f32_e32 v151, v43
	v_mul_f32_e32 v43, v66, v66
	v_fmamk_f32 v43, v43, 0xbdd2d3e7, v191
	v_mul_f32_e32 v43, v66, v43
	s_nop 0
	s_nop 0
	v_exp_f32_e32 v43, v43
	v_pk_mul_f32 v[150:151], v[68:69], v[150:151]
	v_add_f32_e32 v43, 1.0, v43
	v_cvt_pk_bf16_f32 v149, v150, v151
	ds_write_b64 v32, v[148:149] offset:2048
	v_rcp_f32_e32 v148, v43
	v_mul_f32_e32 v43, v67, v67
	v_fmamk_f32 v43, v43, 0xbdd2d3e7, v191
	v_mul_f32_e32 v43, v67, v43
	s_nop 0
	s_nop 0
	v_exp_f32_e32 v43, v43
	s_nop 0
	v_add_f32_e32 v43, 1.0, v43
	v_rcp_f32_e32 v149, v43
	v_mul_f32_e32 v43, v64, v64
	v_fmamk_f32 v43, v43, 0xbdd2d3e7, v191
	v_mul_f32_e32 v43, v64, v43
	s_nop 0
	s_nop 0
	v_exp_f32_e32 v43, v43
	v_pk_mul_f32 v[148:149], v[66:67], v[148:149]
	v_add_f32_e32 v43, 1.0, v43
	v_rcp_f32_e32 v150, v43
	v_mul_f32_e32 v43, v65, v65
	v_fmamk_f32 v43, v43, 0xbdd2d3e7, v191
	v_mul_f32_e32 v43, v65, v43
	s_nop 0
	s_nop 0
	v_exp_f32_e32 v43, v43
	v_cvt_pk_bf16_f32 v148, v148, v149
	v_add_f32_e32 v43, 1.0, v43
	v_rcp_f32_e32 v151, v43
	v_mul_f32_e32 v43, v62, v62
	v_fmamk_f32 v43, v43, 0xbdd2d3e7, v191
	v_mul_f32_e32 v43, v62, v43
	s_nop 0
	s_nop 0
	v_exp_f32_e32 v43, v43
	v_pk_mul_f32 v[150:151], v[64:65], v[150:151]
	v_add_f32_e32 v43, 1.0, v43
	v_cvt_pk_bf16_f32 v149, v150, v151
	ds_write_b64 v33, v[148:149] offset:2048
	v_rcp_f32_e32 v148, v43
	v_mul_f32_e32 v43, v63, v63
	v_fmamk_f32 v43, v43, 0xbdd2d3e7, v191
	v_mul_f32_e32 v43, v63, v43
	s_nop 0
	s_nop 0
	v_exp_f32_e32 v43, v43
	s_nop 0
	v_add_f32_e32 v43, 1.0, v43
	v_rcp_f32_e32 v149, v43
	v_mul_f32_e32 v43, v60, v60
	v_fmamk_f32 v43, v43, 0xbdd2d3e7, v191
	v_mul_f32_e32 v43, v60, v43
	s_nop 0
	s_nop 0
	v_exp_f32_e32 v43, v43
	v_pk_mul_f32 v[148:149], v[62:63], v[148:149]
	v_add_f32_e32 v43, 1.0, v43
	v_rcp_f32_e32 v150, v43
	v_mul_f32_e32 v43, v61, v61
	v_fmamk_f32 v43, v43, 0xbdd2d3e7, v191
	v_mul_f32_e32 v43, v61, v43
	s_nop 0
	s_nop 0
	v_exp_f32_e32 v43, v43
	v_cvt_pk_bf16_f32 v148, v148, v149
	v_add_f32_e32 v43, 1.0, v43
	v_rcp_f32_e32 v151, v43
	v_mul_f32_e32 v43, v58, v58
	v_fmamk_f32 v43, v43, 0xbdd2d3e7, v191
	v_mul_f32_e32 v43, v58, v43
	s_nop 0
	s_nop 0
	v_exp_f32_e32 v43, v43
	v_pk_mul_f32 v[150:151], v[60:61], v[150:151]
	v_add_f32_e32 v43, 1.0, v43
	v_cvt_pk_bf16_f32 v149, v150, v151
	ds_write_b64 v34, v[148:149] offset:2048
	v_rcp_f32_e32 v148, v43
	v_mul_f32_e32 v43, v59, v59
	v_fmamk_f32 v43, v43, 0xbdd2d3e7, v191
	v_mul_f32_e32 v43, v59, v43
	s_nop 0
	s_nop 0
	v_exp_f32_e32 v43, v43
	s_nop 0
	v_add_f32_e32 v43, 1.0, v43
	v_rcp_f32_e32 v149, v43
	v_mul_f32_e32 v43, v56, v56
	v_fmamk_f32 v43, v43, 0xbdd2d3e7, v191
	v_mul_f32_e32 v43, v56, v43
	s_nop 0
	s_nop 0
	v_exp_f32_e32 v43, v43
	v_pk_mul_f32 v[148:149], v[58:59], v[148:149]
	v_add_f32_e32 v43, 1.0, v43
	v_rcp_f32_e32 v150, v43
	v_mul_f32_e32 v43, v57, v57
	v_fmamk_f32 v43, v43, 0xbdd2d3e7, v191
	v_mul_f32_e32 v43, v57, v43
	s_nop 0
	s_nop 0
	v_exp_f32_e32 v43, v43
	v_cvt_pk_bf16_f32 v148, v148, v149
	v_add_f32_e32 v43, 1.0, v43
	v_rcp_f32_e32 v151, v43
	v_mul_f32_e32 v43, v110, v110
	v_fmamk_f32 v43, v43, 0xbdd2d3e7, v191
	v_mul_f32_e32 v43, v110, v43
	s_nop 0
	s_nop 0
	v_exp_f32_e32 v43, v43
	v_pk_mul_f32 v[150:151], v[56:57], v[150:151]
	v_add_f32_e32 v43, 1.0, v43
	v_cvt_pk_bf16_f32 v149, v150, v151
	ds_write_b64 v35, v[148:149] offset:2048
	v_rcp_f32_e32 v148, v43
	v_mul_f32_e32 v43, v111, v111
	v_fmamk_f32 v43, v43, 0xbdd2d3e7, v191
	v_mul_f32_e32 v43, v111, v43
	s_nop 0
	s_nop 0
	v_exp_f32_e32 v43, v43
	s_nop 0
	v_add_f32_e32 v43, 1.0, v43
	v_rcp_f32_e32 v149, v43
	v_mul_f32_e32 v43, v108, v108
	v_fmamk_f32 v43, v43, 0xbdd2d3e7, v191
	v_mul_f32_e32 v43, v108, v43
	s_nop 0
	s_nop 0
	v_exp_f32_e32 v43, v43
	v_pk_mul_f32 v[148:149], v[110:111], v[148:149]
	v_add_f32_e32 v43, 1.0, v43
	v_rcp_f32_e32 v150, v43
	v_mul_f32_e32 v43, v109, v109
	v_fmamk_f32 v43, v43, 0xbdd2d3e7, v191
	v_mul_f32_e32 v43, v109, v43
	s_nop 0
	s_nop 0
	v_exp_f32_e32 v43, v43
	v_cvt_pk_bf16_f32 v148, v148, v149
	v_add_f32_e32 v43, 1.0, v43
	v_rcp_f32_e32 v151, v43
	v_mul_f32_e32 v43, v106, v106
	v_fmamk_f32 v43, v43, 0xbdd2d3e7, v191
	v_mul_f32_e32 v43, v106, v43
	s_nop 0
	s_nop 0
	v_exp_f32_e32 v43, v43
	v_pk_mul_f32 v[150:151], v[108:109], v[150:151]
	v_add_f32_e32 v43, 1.0, v43
	v_cvt_pk_bf16_f32 v149, v150, v151
	ds_write_b64 v32, v[148:149] offset:4096
	v_rcp_f32_e32 v148, v43
	v_mul_f32_e32 v43, v107, v107
	v_fmamk_f32 v43, v43, 0xbdd2d3e7, v191
	v_mul_f32_e32 v43, v107, v43
	s_nop 0
	s_nop 0
	v_exp_f32_e32 v43, v43
	s_nop 0
	v_add_f32_e32 v43, 1.0, v43
	v_rcp_f32_e32 v149, v43
	v_mul_f32_e32 v43, v104, v104
	v_fmamk_f32 v43, v43, 0xbdd2d3e7, v191
	v_mul_f32_e32 v43, v104, v43
	s_nop 0
	s_nop 0
	v_exp_f32_e32 v43, v43
	v_pk_mul_f32 v[148:149], v[106:107], v[148:149]
; DI unsigned pk2(float a, float b) { f32x2 v = {a, b}; bf2_t r = __builtin_convertvector(v, bf2_t); return __builtin_bit_cast(unsigned, r); }
;     static DI void run(const f32x4 (&acc)[8][4], const TileCtx& tc, const Params& p, ldsp_t wb) {
;     ...
;         } else if (BRK == 2) {
; #pragma unroll
;             for (int h = 0; h < 2; ++h) {
; #pragma unroll
;                 for (int mm = 0; mm < 4; ++mm) {
;                     const int m = h * 4 + mm;
; #pragma unroll
;                     for (int n = 0; n < 4; ++n) {
;                         u32x2 w; w[0] = pk2(gelu_tanh(acc[m][n][0]), gelu_tanh(acc[m][n][1])); w[1] = pk2(gelu_tanh(acc[m][n][2]), gelu_tanh(acc[m][n][3]));
;                         wave_put(wb, mm * 16 + fr, n, fq, w);
;                     }
;                 }
;                 wave_rows_store(wb, tc.lane, p.U + (size_t)(tc.brow + tc.wr * 128 + h * 64) * 1024 + (pn - 3) * 256 + wc * 64, 1024);
	v_add_f32_e32 v43, 1.0, v43
	v_rcp_f32_e32 v150, v43
	v_mul_f32_e32 v43, v105, v105
	v_fmamk_f32 v43, v43, 0xbdd2d3e7, v191
	v_mul_f32_e32 v43, v105, v43
	s_nop 0
	s_nop 0
	v_exp_f32_e32 v43, v43
	v_cvt_pk_bf16_f32 v148, v148, v149
	v_add_f32_e32 v43, 1.0, v43
	v_rcp_f32_e32 v151, v43
	v_mul_f32_e32 v43, v54, v54
	v_fmamk_f32 v43, v43, 0xbdd2d3e7, v191
	v_mul_f32_e32 v43, v54, v43
	s_nop 0
	s_nop 0
	v_exp_f32_e32 v43, v43
	v_pk_mul_f32 v[150:151], v[104:105], v[150:151]
	v_add_f32_e32 v43, 1.0, v43
	v_cvt_pk_bf16_f32 v149, v150, v151
	ds_write_b64 v33, v[148:149] offset:4096
	v_rcp_f32_e32 v148, v43
	v_mul_f32_e32 v43, v55, v55
	v_fmamk_f32 v43, v43, 0xbdd2d3e7, v191
	v_mul_f32_e32 v43, v55, v43
	s_nop 0
	s_nop 0
	v_exp_f32_e32 v43, v43
	s_nop 0
	v_add_f32_e32 v43, 1.0, v43
	v_rcp_f32_e32 v149, v43
	v_mul_f32_e32 v43, v52, v52
	v_fmamk_f32 v43, v43, 0xbdd2d3e7, v191
	v_mul_f32_e32 v43, v52, v43
	s_nop 0
	s_nop 0
	v_exp_f32_e32 v43, v43
	v_pk_mul_f32 v[148:149], v[54:55], v[148:149]
	v_add_f32_e32 v43, 1.0, v43
	v_rcp_f32_e32 v150, v43
	v_mul_f32_e32 v43, v53, v53
	v_fmamk_f32 v43, v43, 0xbdd2d3e7, v191
	v_mul_f32_e32 v43, v53, v43
	s_nop 0
	s_nop 0
	v_exp_f32_e32 v43, v43
	v_cvt_pk_bf16_f32 v148, v148, v149
	v_add_f32_e32 v43, 1.0, v43
	v_rcp_f32_e32 v151, v43
	v_mul_f32_e32 v43, v50, v50
	v_fmamk_f32 v43, v43, 0xbdd2d3e7, v191
	v_mul_f32_e32 v43, v50, v43
	s_nop 0
	s_nop 0
	v_exp_f32_e32 v43, v43
	v_pk_mul_f32 v[150:151], v[52:53], v[150:151]
	v_add_f32_e32 v43, 1.0, v43
	v_cvt_pk_bf16_f32 v149, v150, v151
	ds_write_b64 v34, v[148:149] offset:4096
	v_rcp_f32_e32 v148, v43
	v_mul_f32_e32 v43, v51, v51
	v_fmamk_f32 v43, v43, 0xbdd2d3e7, v191
	v_mul_f32_e32 v43, v51, v43
	s_nop 0
	s_nop 0
	v_exp_f32_e32 v43, v43
	s_nop 0
	v_add_f32_e32 v43, 1.0, v43
	v_rcp_f32_e32 v149, v43
	v_mul_f32_e32 v43, v48, v48
	v_fmamk_f32 v43, v43, 0xbdd2d3e7, v191
	v_mul_f32_e32 v43, v48, v43
	s_nop 0
	s_nop 0
	v_exp_f32_e32 v43, v43
	v_pk_mul_f32 v[148:149], v[50:51], v[148:149]
	v_add_f32_e32 v43, 1.0, v43
	v_rcp_f32_e32 v150, v43
	v_mul_f32_e32 v43, v49, v49
	v_fmamk_f32 v43, v43, 0xbdd2d3e7, v191
	v_mul_f32_e32 v43, v49, v43
	s_nop 0
	s_nop 0
	v_exp_f32_e32 v43, v43
	v_cvt_pk_bf16_f32 v148, v148, v149
	v_add_f32_e32 v43, 1.0, v43
	v_rcp_f32_e32 v151, v43
	v_mul_f32_e32 v43, v44, v44
	v_fmamk_f32 v43, v43, 0xbdd2d3e7, v191
	v_mul_f32_e32 v43, v44, v43
	s_nop 0
	s_nop 0
	v_exp_f32_e32 v43, v43
	v_pk_mul_f32 v[150:151], v[48:49], v[150:151]
	v_add_f32_e32 v43, 1.0, v43
	v_cvt_pk_bf16_f32 v149, v150, v151
	ds_write_b64 v35, v[148:149] offset:4096
	v_rcp_f32_e32 v148, v43
	v_mul_f32_e32 v43, v45, v45
	v_fmamk_f32 v43, v43, 0xbdd2d3e7, v191
	v_mul_f32_e32 v43, v45, v43
	s_nop 0
	s_nop 0
	v_exp_f32_e32 v43, v43
	s_nop 0
	v_add_f32_e32 v43, 1.0, v43
	v_rcp_f32_e32 v149, v43
	v_mul_f32_e32 v43, v46, v46
	v_fmamk_f32 v43, v43, 0xbdd2d3e7, v191
	v_mul_f32_e32 v43, v46, v43
	s_nop 0
	s_nop 0
	v_exp_f32_e32 v43, v43
	v_pk_mul_f32 v[148:149], v[44:45], v[148:149]
	v_add_f32_e32 v43, 1.0, v43
	v_rcp_f32_e32 v150, v43
	v_mul_f32_e32 v43, v47, v47
	v_fmamk_f32 v43, v43, 0xbdd2d3e7, v191
	v_mul_f32_e32 v43, v47, v43
	s_nop 0
	s_nop 0
	v_exp_f32_e32 v43, v43
	v_cvt_pk_bf16_f32 v148, v148, v149
	v_add_f32_e32 v43, 1.0, v43
	v_rcp_f32_e32 v151, v43
	s_nop 0
	v_pk_mul_f32 v[150:151], v[46:47], v[150:151]
	s_nop 0
	v_cvt_pk_bf16_f32 v149, v150, v151
	ds_write_b64 v32, v[148:149] offset:6144
	v_mul_f32_e32 v32, v30, v30
	v_fmamk_f32 v32, v32, 0xbdd2d3e7, v191
	v_mul_f32_e32 v32, v30, v32
	s_nop 0
	s_nop 0
	v_exp_f32_e32 v32, v32
	s_nop 0
	v_add_f32_e32 v32, 1.0, v32
	v_rcp_f32_e32 v148, v32
	v_mul_f32_e32 v32, v31, v31
	v_fmamk_f32 v32, v32, 0xbdd2d3e7, v191
	v_mul_f32_e32 v32, v31, v32
	s_nop 0
	s_nop 0
	v_exp_f32_e32 v32, v32
	s_nop 0
	v_add_f32_e32 v32, 1.0, v32
	v_rcp_f32_e32 v149, v32
	v_mul_f32_e32 v32, v28, v28
	v_fmamk_f32 v32, v32, 0xbdd2d3e7, v191
	v_mul_f32_e32 v32, v28, v32
	s_nop 0
	s_nop 0
	v_exp_f32_e32 v32, v32
	v_pk_mul_f32 v[148:149], v[30:31], v[148:149]
	v_add_f32_e32 v32, 1.0, v32
	v_rcp_f32_e32 v150, v32
	v_mul_f32_e32 v32, v29, v29
	v_fmamk_f32 v32, v32, 0xbdd2d3e7, v191
	v_mul_f32_e32 v32, v29, v32
	s_nop 0
	s_nop 0
	v_exp_f32_e32 v32, v32
	v_cvt_pk_bf16_f32 v148, v148, v149
	v_add_f32_e32 v32, 1.0, v32
	v_rcp_f32_e32 v151, v32
	v_mul_f32_e32 v32, v26, v26
	v_fmamk_f32 v32, v32, 0xbdd2d3e7, v191
	v_mul_f32_e32 v32, v26, v32
	v_pk_mul_f32 v[150:151], v[28:29], v[150:151]
	s_nop 0
	v_cvt_pk_bf16_f32 v149, v150, v151
	ds_write_b64 v33, v[148:149] offset:6144
	v_mul_f32_e32 v33, v27, v27
	v_fmamk_f32 v33, v33, 0xbdd2d3e7, v191
	v_mul_f32_e32 v33, v27, v33
	s_nop 0
	s_nop 0
	s_nop 0
	v_exp_f32_e32 v32, v32
	v_exp_f32_e32 v33, v33
	v_add_f32_e32 v32, 1.0, v32
	v_add_f32_e32 v33, 1.0, v33
	v_rcp_f32_e32 v32, v32
	v_rcp_f32_e32 v33, v33
	s_nop 0
	v_pk_mul_f32 v[32:33], v[26:27], v[32:33]
	s_nop 0
	v_cvt_pk_bf16_f32 v32, v32, v33
	v_mul_f32_e32 v33, v24, v24
	v_fmamk_f32 v33, v33, 0xbdd2d3e7, v191
	v_mul_f32_e32 v33, v24, v33
	s_nop 0
	s_nop 0
	v_exp_f32_e32 v33, v33
	s_nop 0
	v_add_f32_e32 v33, 1.0, v33
	v_rcp_f32_e32 v148, v33
	v_mul_f32_e32 v33, v25, v25
	v_fmamk_f32 v33, v33, 0xbdd2d3e7, v191
	v_mul_f32_e32 v33, v25, v33
	s_nop 0
	s_nop 0
	v_exp_f32_e32 v33, v33
	s_nop 0
	v_add_f32_e32 v33, 1.0, v33
	v_rcp_f32_e32 v149, v33
	s_nop 0
	v_pk_mul_f32 v[148:149], v[24:25], v[148:149]
	s_nop 0
	v_cvt_pk_bf16_f32 v33, v148, v149
	ds_write_b64 v34, v[32:33] offset:6144
	v_mul_f32_e32 v32, v22, v22
	v_mul_f32_e32 v33, v23, v23
	v_fmamk_f32 v32, v32, 0xbdd2d3e7, v191
	v_fmamk_f32 v33, v33, 0xbdd2d3e7, v191
	v_mul_f32_e32 v32, v22, v32
	v_mul_f32_e32 v33, v23, v33
	s_nop 0
	s_nop 0
	s_nop 0
	s_nop 0
	v_exp_f32_e32 v32, v32
	v_exp_f32_e32 v33, v33
	v_add_f32_e32 v32, 1.0, v32
	v_add_f32_e32 v33, 1.0, v33
	v_rcp_f32_e32 v32, v32
	v_rcp_f32_e32 v33, v33
	s_nop 0
	v_pk_mul_f32 v[32:33], v[22:23], v[32:33]
	s_nop 0
	v_cvt_pk_bf16_f32 v32, v32, v33
	v_mul_f32_e32 v33, v20, v20
	v_fmamk_f32 v33, v33, 0xbdd2d3e7, v191
	v_mul_f32_e32 v33, v20, v33
	s_nop 0
	s_nop 0
	v_exp_f32_e32 v33, v33
	s_nop 0
	v_add_f32_e32 v33, 1.0, v33
	v_rcp_f32_e32 v148, v33
	v_mul_f32_e32 v33, v21, v21
	v_fmamk_f32 v33, v33, 0xbdd2d3e7, v191
	v_mul_f32_e32 v33, v21, v33
	s_nop 0
	s_nop 0
	v_exp_f32_e32 v33, v33
	s_nop 0
	v_add_f32_e32 v33, 1.0, v33
	v_rcp_f32_e32 v149, v33
	s_nop 0
	v_pk_mul_f32 v[148:149], v[20:21], v[148:149]
	s_nop 0
	v_cvt_pk_bf16_f32 v33, v148, v149
	ds_write_b64 v35, v[32:33] offset:6144
	v_or_b32_e32 v32, 64, v10
	v_ashrrev_i32_e32 v33, 31, v32
	v_lshlrev_b64 v[32:33], 11, v[32:33]
	v_lshl_add_u64 v[32:33], s[16:17], 0, v[32:33]
	v_lshl_add_u64 v[32:33], v[32:33], 0, s[4:5]
	v_lshl_add_u64 v[32:33], v[32:33], 0, v[192:193]
	v_lshl_add_u64 v[148:149], v[32:33], 0, v[18:19]
	ds_read_b128 v[32:35], v42
	v_lshl_add_u64 v[16:17], v[148:149], 0, v[16:17]
	v_lshl_add_u64 v[14:15], v[148:149], 0, v[14:15]
	v_lshl_add_u64 v[12:13], v[148:149], 0, v[12:13]
	v_lshl_add_u64 v[8:9], v[148:149], 0, v[8:9]
	s_waitcnt lgkmcnt(0)
; #define LDSP __attribute__((address_space(3)))
; DI bf16_t f2bf(float a) { return (bf16_t)(pk2(a, 0.f) & 0xffffu); }
; DI void wave_rows_store(ldsp_t wb, int lane, bf16_t* dst0, size_t ld) {
; #pragma unroll
;     for (int i = 0; i < 8; ++i) {
;         const int row = i * 8 + (lane >> 3), ch = lane & 7;
;         const u32x4 v = *(const LDSP u32x4*)(wb + row * 128 + ((ch ^ (row & 7)) << 4));
;         *(u32x4*)(dst0 + (size_t)row * ld + ch * 8) = v;
;     }
; }
;     static DI void run(const f32x4 (&acc)[8][4], const TileCtx& tc, const Params& p, ldsp_t wb) {
;     ...
;         } else if (BRK == 1) {
;             const int kvh = wc - 2;
; #pragma unroll
;             for (int h = 0; h < 2; ++h) {
; #pragma unroll
;                 for (int mm = 0; mm < 4; ++mm) {
;                     const int m = h * 4 + mm;
;                     const int key = mm * 16 + fr, k16 = key & 15;
;                     const int kp = (key & ~15) | ((((k16 >> 2) & 1) << 3) + (k16 & 3) + ((k16 >> 3) << 2));
; #pragma unroll
;                     for (int n = 0; n < 4; ++n)
; #pragma unroll
;                         for (int j = 0; j < 4; ++j) {
;                             const int d = n * 16 + fq * 4 + j;
;                             *(LDSP bf16_t*)(wb + d * 128 + (((kp >> 3) ^ (d & 7)) << 4) + (kp & 7) * 2) = f2bf(acc[m][n][j]);
;                         }
;                 }
	global_store_dwordx4 v[16:17], v[32:35], off sc1
	ds_read_b128 v[16:19], v41
	v_lshl_add_u64 v[2:3], v[148:149], 0, v[2:3]
	v_lshl_add_u64 v[0:1], v[148:149], 0, v[0:1]
	s_mov_b64 s[4:5], 0
	s_waitcnt lgkmcnt(0)
	global_store_dwordx4 v[14:15], v[16:19], off sc1
	ds_read_b128 v[14:17], v40
	s_waitcnt lgkmcnt(0)
	global_store_dwordx4 v[12:13], v[14:17], off sc1
	ds_read_b128 v[12:15], v39
	s_waitcnt lgkmcnt(0)
	global_store_dwordx4 v[8:9], v[12:15], off sc1
	ds_read_b128 v[12:15], v38
	s_waitcnt lgkmcnt(0)
	global_store_dwordx4 v[2:3], v[12:15], off sc1
	ds_read_b128 v[12:15], v37
	v_lshl_add_u64 v[2:3], v[148:149], 0, v[6:7]
	ds_read_b128 v[6:9], v36
	s_waitcnt lgkmcnt(1)
	global_store_dwordx4 v[2:3], v[12:15], off sc1
	v_lshl_add_u64 v[2:3], v[148:149], 0, v[4:5]
	s_waitcnt lgkmcnt(0)
	global_store_dwordx4 v[2:3], v[6:9], off sc1
	ds_read_b128 v[2:5], v11
	s_waitcnt lgkmcnt(0)
	global_store_dwordx4 v[0:1], v[2:5], off sc1
.LBB0_272:
	s_andn2_b64 vcc, exec, s[4:5]
	s_cbranch_vccnz .LBB0_326
	v_cmp_lt_u32_e32 vcc, 1, v171
	s_and_saveexec_b64 s[4:5], vcc
	s_xor_b64 s[4:5], exec, s[4:5]
	s_cbranch_execz .LBB0_283
	v_bfe_u32 v2, v172, 2, 1
	v_and_b32_e32 v5, 4, v175
	v_or_b32_e32 v6, v5, v2
	v_lshlrev_b32_e32 v0, 1, v169
	v_and_b32_e32 v1, 8, v172
	v_lshl_add_u32 v4, v173, 9, v176
	v_lshlrev_b32_e32 v6, 4, v6
	v_and_b32_e32 v0, 6, v0
	v_add3_u32 v6, v4, v6, v1
	v_cvt_pk_bf16_f32 v3, v160, s0
	v_add_u32_e32 v10, v6, v0
	ds_write_b16 v10, v3
	v_or_b32_e32 v3, 1, v175
	v_bitop3_b32 v8, v3, v2, 5 bitop3:0x6c
	v_lshl_add_u32 v7, v3, 7, v176
	v_lshlrev_b32_e32 v8, 4, v8
	v_add3_u32 v8, v7, v8, v1
	v_cvt_pk_bf16_f32 v6, v161, s0
	v_add_u32_e32 v11, v8, v0
	v_bitop3_b32 v12, v175, 6, 2 bitop3:0xc8
	ds_write_b16 v11, v6
	v_or_b32_e32 v6, 2, v175
	v_or_b32_e32 v12, v12, v2
	v_lshl_add_u32 v9, v6, 7, v176
	v_lshlrev_b32_e32 v12, 4, v12
	v_add3_u32 v12, v9, v12, v1
	v_cvt_pk_bf16_f32 v8, v158, s0
	v_add_u32_e32 v12, v12, v0
	ds_write_b16 v12, v8
	v_or_b32_e32 v8, 3, v175
	v_bitop3_b32 v13, v8, v2, 7 bitop3:0x6c
	v_lshl_add_u32 v148, v8, 7, v176
	v_lshlrev_b32_e32 v13, 4, v13
	v_add3_u32 v13, v148, v13, v1
	v_cvt_pk_bf16_f32 v14, v159, s0
	v_add_u32_e32 v13, v13, v0
	ds_write_b16 v13, v14
	v_cvt_pk_bf16_f32 v14, v156, s0
	v_or_b32_e32 v149, 17, v175
	ds_write_b16 v10, v14 offset:2048
	v_bitop3_b32 v14, v149, v2, 5 bitop3:0x6c
	v_lshl_add_u32 v150, v149, 7, v176
	v_lshlrev_b32_e32 v14, 4, v14
	v_add3_u32 v14, v150, v14, v1
	v_cvt_pk_bf16_f32 v15, v157, s0
	v_add_u32_e32 v14, v14, v0
	ds_write_b16 v14, v15
	v_bitop3_b32 v15, v175, 6, 18 bitop3:0xc8
	v_or_b32_e32 v151, 18, v175
	v_or_b32_e32 v15, v15, v2
	v_lshl_add_u32 v192, v151, 7, v176
	v_lshlrev_b32_e32 v15, 4, v15
	v_add3_u32 v15, v192, v15, v1
	v_cvt_pk_bf16_f32 v16, v154, s0
	v_add_u32_e32 v15, v15, v0
	v_or_b32_e32 v196, 19, v175
	ds_write_b16 v15, v16
	v_bitop3_b32 v16, v196, v2, 7 bitop3:0x6c
	v_lshl_add_u32 v197, v196, 7, v176
	v_lshlrev_b32_e32 v16, 4, v16
	v_add3_u32 v16, v197, v16, v1
	v_cvt_pk_bf16_f32 v17, v155, s0
	v_add_u32_e32 v16, v16, v0
	ds_write_b16 v16, v17
	v_cvt_pk_bf16_f32 v17, v152, s0
	v_or_b32_e32 v198, 33, v175
	ds_write_b16 v10, v17 offset:4096
	v_bitop3_b32 v17, v198, v2, 5 bitop3:0x6c
	v_lshl_add_u32 v199, v198, 7, v176
	v_lshlrev_b32_e32 v17, 4, v17
	v_add3_u32 v17, v199, v17, v1
	v_cvt_pk_bf16_f32 v18, v153, s0
	v_add_u32_e32 v17, v17, v0
	ds_write_b16 v17, v18
	v_bitop3_b32 v18, v175, 6, 34 bitop3:0xc8
	v_or_b32_e32 v200, 34, v175
	v_or_b32_e32 v18, v18, v2
	v_lshl_add_u32 v201, v200, 7, v176
	v_lshlrev_b32_e32 v18, 4, v18
	v_add3_u32 v18, v201, v18, v1
	v_cvt_pk_bf16_f32 v19, v216, s0
	v_add_u32_e32 v18, v18, v0
	v_or_b32_e32 v204, 35, v175
	ds_write_b16 v18, v19
	v_bitop3_b32 v19, v204, v2, 7 bitop3:0x6c
	v_lshl_add_u32 v205, v204, 7, v176
	v_lshlrev_b32_e32 v19, 4, v19
	v_or_b32_e32 v206, 49, v175
	v_add3_u32 v19, v205, v19, v1
	v_bitop3_b32 v33, v206, v2, 5 bitop3:0x6c
	v_bitop3_b32 v34, v175, 6, 50 bitop3:0xc8
	v_cvt_pk_bf16_f32 v32, v217, s0
	v_add_u32_e32 v19, v19, v0
	v_lshl_add_u32 v207, v206, 7, v176
	v_lshlrev_b32_e32 v33, 4, v33
	v_or_b32_e32 v210, 50, v175
	v_or_b32_e32 v34, v34, v2
	v_or_b32_e32 v212, 51, v175
	v_lshrrev_b32_e32 v219, 2, v169
	ds_write_b16 v19, v32
	v_cvt_pk_bf16_f32 v32, v214, s0
	v_add3_u32 v33, v207, v33, v1
	v_lshl_add_u32 v211, v210, 7, v176
	v_lshlrev_b32_e32 v34, 4, v34
	v_bitop3_b32 v35, v212, v2, 7 bitop3:0x6c
	v_or_b32_e32 v43, 2, v219
	ds_write_b16 v10, v32 offset:6144
	v_cvt_pk_bf16_f32 v32, v215, s0
	v_add_u32_e32 v33, v33, v0
	v_add3_u32 v34, v211, v34, v1
	v_lshl_add_u32 v213, v212, 7, v176
	v_lshlrev_b32_e32 v35, 4, v35
	v_or_b32_e32 v5, v5, v43
	ds_write_b16 v33, v32
	v_cvt_pk_bf16_f32 v32, v146, s0
	v_add_u32_e32 v34, v34, v0
	v_add3_u32 v35, v213, v35, v1
	v_lshlrev_b32_e32 v5, 4, v5
	ds_write_b16 v34, v32
	v_cvt_pk_bf16_f32 v32, v147, s0
	v_add_u32_e32 v35, v35, v0
	v_add3_u32 v5, v4, v5, v1
	ds_write_b16 v35, v32
	v_cvt_pk_bf16_f32 v36, v144, s0
	v_add_u32_e32 v32, v5, v0
	ds_write_b16 v32, v36
	v_bitop3_b32 v36, v3, v43, 5 bitop3:0x6c
	v_lshlrev_b32_e32 v36, 4, v36
	v_bitop3_b32 v37, v6, v43, 6 bitop3:0x6c
	v_add3_u32 v36, v7, v36, v1
	v_lshlrev_b32_e32 v37, 4, v37
	v_bitop3_b32 v38, v8, v43, 7 bitop3:0x6c
	v_cvt_pk_bf16_f32 v5, v145, s0
	v_add_u32_e32 v36, v36, v0
	v_add3_u32 v37, v9, v37, v1
	v_lshlrev_b32_e32 v38, 4, v38
	ds_write_b16 v36, v5
	v_cvt_pk_bf16_f32 v5, v140, s0
	v_add_u32_e32 v37, v37, v0
	v_add3_u32 v38, v148, v38, v1
	v_bitop3_b32 v39, v149, v43, 5 bitop3:0x6c
	ds_write_b16 v37, v5
	v_cvt_pk_bf16_f32 v5, v141, s0
	v_add_u32_e32 v38, v38, v0
	v_lshlrev_b32_e32 v39, 4, v39
	v_bitop3_b32 v40, v151, v43, 6 bitop3:0x6c
; #define LDSP __attribute__((address_space(3)))
; DI bf16_t f2bf(float a) { return (bf16_t)(pk2(a, 0.f) & 0xffffu); }
;     static DI void run(const f32x4 (&acc)[8][4], const TileCtx& tc, const Params& p, ldsp_t wb) {
;     ...
;                 for (int mm = 0; mm < 4; ++mm) {
;                     const int m = h * 4 + mm;
;                     const int key = mm * 16 + fr, k16 = key & 15;
;                     const int kp = (key & ~15) | ((((k16 >> 2) & 1) << 3) + (k16 & 3) + ((k16 >> 3) << 2));
; #pragma unroll
;                     for (int n = 0; n < 4; ++n)
; #pragma unroll
;                         for (int j = 0; j < 4; ++j) {
;                             const int d = n * 16 + fq * 4 + j;
;                             *(LDSP bf16_t*)(wb + d * 128 + (((kp >> 3) ^ (d & 7)) << 4) + (kp & 7) * 2) = f2bf(acc[m][n][j]);
;                         }
;                 }
	ds_write_b16 v38, v5
	v_cvt_pk_bf16_f32 v5, v142, s0
	v_add3_u32 v39, v150, v39, v1
	v_lshlrev_b32_e32 v40, 4, v40
	v_bitop3_b32 v41, v196, v43, 7 bitop3:0x6c
	ds_write_b16 v32, v5 offset:2048
	v_cvt_pk_bf16_f32 v5, v143, s0
	v_add_u32_e32 v39, v39, v0
	v_add3_u32 v40, v192, v40, v1
	v_lshlrev_b32_e32 v41, 4, v41
	ds_write_b16 v39, v5
	v_cvt_pk_bf16_f32 v5, v138, s0
	v_add_u32_e32 v40, v40, v0
	v_add3_u32 v41, v197, v41, v1
	v_bitop3_b32 v42, v198, v43, 5 bitop3:0x6c
	ds_write_b16 v40, v5
	v_cvt_pk_bf16_f32 v5, v139, s0
	v_add_u32_e32 v41, v41, v0
	v_lshlrev_b32_e32 v42, 4, v42
	v_bitop3_b32 v162, v200, v43, 6 bitop3:0x6c
	ds_write_b16 v41, v5
	v_cvt_pk_bf16_f32 v5, v128, s0
	v_add3_u32 v42, v199, v42, v1
	v_lshlrev_b32_e32 v162, 4, v162
	v_bitop3_b32 v163, v204, v43, 7 bitop3:0x6c
	ds_write_b16 v32, v5 offset:4096
	v_cvt_pk_bf16_f32 v5, v129, s0
	v_add_u32_e32 v42, v42, v0
	v_add3_u32 v162, v201, v162, v1
	v_lshlrev_b32_e32 v163, 4, v163
	ds_write_b16 v42, v5
	v_cvt_pk_bf16_f32 v5, v126, s0
	v_add_u32_e32 v162, v162, v0
	v_add3_u32 v163, v205, v163, v1
	v_bitop3_b32 v164, v206, v43, 5 bitop3:0x6c
	ds_write_b16 v162, v5
	v_cvt_pk_bf16_f32 v5, v127, s0
	v_add_u32_e32 v163, v163, v0
	v_lshlrev_b32_e32 v164, 4, v164
	v_bitop3_b32 v165, v210, v43, 6 bitop3:0x6c
	ds_write_b16 v163, v5
	v_cvt_pk_bf16_f32 v5, v124, s0
	v_add3_u32 v164, v207, v164, v1
	v_lshlrev_b32_e32 v165, 4, v165
	v_bitop3_b32 v43, v212, v43, 7 bitop3:0x6c
	ds_write_b16 v32, v5 offset:6144
	v_cvt_pk_bf16_f32 v5, v125, s0
	v_add_u32_e32 v164, v164, v0
	v_add3_u32 v165, v211, v165, v1
	v_lshlrev_b32_e32 v43, 4, v43
	ds_write_b16 v164, v5
	v_cvt_pk_bf16_f32 v5, v120, s0
	v_add_u32_e32 v165, v165, v0
	v_add3_u32 v43, v213, v43, v1
	ds_write_b16 v165, v5
	v_cvt_pk_bf16_f32 v5, v121, s0
	v_add_u32_e32 v166, v43, v0
	ds_write_b16 v166, v5
	v_or_b32_e32 v5, 4, v2
	v_bitop3_b32 v2, v175, v2, 4 bitop3:0x4e
	v_lshlrev_b32_e32 v2, 4, v2
	v_add3_u32 v2, v4, v2, v1
	v_cvt_pk_bf16_f32 v167, v136, s0
	v_add_u32_e32 v43, v2, v0
	ds_write_b16 v43, v167
	v_bitop3_b32 v167, v3, v5, 5 bitop3:0x6c
	v_lshlrev_b32_e32 v167, 4, v167
	v_bitop3_b32 v177, v6, v5, 6 bitop3:0x6c
	v_add3_u32 v167, v7, v167, v1
	v_lshlrev_b32_e32 v177, 4, v177
	v_bitop3_b32 v178, v8, v5, 7 bitop3:0x6c
	v_cvt_pk_bf16_f32 v2, v137, s0
	v_add_u32_e32 v167, v167, v0
	v_add3_u32 v177, v9, v177, v1
	v_lshlrev_b32_e32 v178, 4, v178
	ds_write_b16 v167, v2
	v_cvt_pk_bf16_f32 v2, v132, s0
	v_add_u32_e32 v177, v177, v0
	v_add3_u32 v178, v148, v178, v1
	v_bitop3_b32 v179, v149, v5, 5 bitop3:0x6c
	v_bitop3_b32 v183, v200, v5, 6 bitop3:0x6c
	ds_write_b16 v177, v2
	v_cvt_pk_bf16_f32 v2, v133, s0
	v_add_u32_e32 v178, v178, v0
	v_lshlrev_b32_e32 v179, 4, v179
	v_bitop3_b32 v180, v151, v5, 6 bitop3:0x6c
	v_lshlrev_b32_e32 v183, 4, v183
	ds_write_b16 v178, v2
	v_cvt_pk_bf16_f32 v2, v134, s0
	v_add3_u32 v179, v150, v179, v1
	v_lshlrev_b32_e32 v180, 4, v180
	v_bitop3_b32 v181, v196, v5, 7 bitop3:0x6c
	v_add3_u32 v183, v201, v183, v1
	ds_write_b16 v43, v2 offset:2048
	v_cvt_pk_bf16_f32 v2, v135, s0
	v_add_u32_e32 v179, v179, v0
	v_add3_u32 v180, v192, v180, v1
	v_lshlrev_b32_e32 v181, 4, v181
	v_add_u32_e32 v184, v183, v0
	v_bitop3_b32 v183, v204, v5, 7 bitop3:0x6c
	ds_write_b16 v179, v2
	v_cvt_pk_bf16_f32 v2, v130, s0
	v_add_u32_e32 v180, v180, v0
	v_add3_u32 v181, v197, v181, v1
	v_bitop3_b32 v182, v198, v5, 5 bitop3:0x6c
	v_lshlrev_b32_e32 v183, 4, v183
	ds_write_b16 v180, v2
	v_cvt_pk_bf16_f32 v2, v131, s0
	v_add_u32_e32 v181, v181, v0
	v_lshlrev_b32_e32 v182, 4, v182
	v_add3_u32 v183, v205, v183, v1
	ds_write_b16 v181, v2
	v_cvt_pk_bf16_f32 v2, v122, s0
	v_add3_u32 v182, v199, v182, v1
	v_add_u32_e32 v185, v183, v0
	v_bitop3_b32 v183, v206, v5, 5 bitop3:0x6c
	ds_write_b16 v43, v2 offset:4096
	v_cvt_pk_bf16_f32 v2, v123, s0
	v_add_u32_e32 v182, v182, v0
	v_lshlrev_b32_e32 v183, 4, v183
	ds_write_b16 v182, v2
	v_cvt_pk_bf16_f32 v2, v118, s0
	v_add3_u32 v183, v207, v183, v1
	ds_write_b16 v184, v2
	v_cvt_pk_bf16_f32 v2, v119, s0
	v_add_u32_e32 v186, v183, v0
	v_bitop3_b32 v183, v210, v5, 6 bitop3:0x6c
	ds_write_b16 v185, v2
	v_cvt_pk_bf16_f32 v2, v116, s0
	v_lshlrev_b32_e32 v183, 4, v183
	v_bitop3_b32 v5, v212, v5, 7 bitop3:0x6c
	ds_write_b16 v43, v2 offset:6144
	v_cvt_pk_bf16_f32 v2, v117, s0
	v_add3_u32 v183, v211, v183, v1
	v_lshlrev_b32_e32 v5, 4, v5
	ds_write_b16 v186, v2
	v_cvt_pk_bf16_f32 v2, v114, s0
	v_add_u32_e32 v187, v183, v0
	v_add3_u32 v5, v213, v5, v1
	ds_write_b16 v187, v2
	v_cvt_pk_bf16_f32 v2, v115, s0
	v_add_u32_e32 v188, v5, v0
	ds_write_b16 v188, v2
	v_or_b32_e32 v2, 6, v219
	v_bitop3_b32 v183, v175, v2, 4 bitop3:0x6c
	v_bitop3_b32 v3, v3, v2, 5 bitop3:0x6c
	v_lshlrev_b32_e32 v183, 4, v183
	v_lshlrev_b32_e32 v3, 4, v3
	v_add3_u32 v4, v4, v183, v1
	v_add3_u32 v3, v7, v3, v1
	v_cvt_pk_bf16_f32 v5, v102, s0
	v_add_u32_e32 v183, v4, v0
	v_cvt_pk_bf16_f32 v4, v103, s0
	v_add_u32_e32 v189, v3, v0
	ds_write_b16 v183, v5
	ds_write_b16 v189, v4
	v_bitop3_b32 v4, v6, v219, 6 bitop3:0x4e
	v_lshlrev_b32_e32 v4, 4, v4
	v_add3_u32 v4, v9, v4, v1
	v_add_u32_e32 v190, v4, v0
	v_bitop3_b32 v4, v8, v2, 7 bitop3:0x6c
	v_lshlrev_b32_e32 v4, 4, v4
	v_add3_u32 v4, v148, v4, v1
	v_add_u32_e32 v191, v4, v0
	v_bitop3_b32 v4, v149, v2, 5 bitop3:0x6c
	v_lshlrev_b32_e32 v4, 4, v4
	v_add3_u32 v4, v150, v4, v1
	v_add_u32_e32 v194, v4, v0
	v_bitop3_b32 v4, v151, v219, 6 bitop3:0x4e
	v_lshlrev_b32_e32 v4, 4, v4
	v_add3_u32 v4, v192, v4, v1
	v_add_u32_e32 v195, v4, v0
	v_bitop3_b32 v4, v196, v2, 7 bitop3:0x6c
	v_lshlrev_b32_e32 v4, 4, v4
	v_add3_u32 v4, v197, v4, v1
	v_add_u32_e32 v196, v4, v0
	v_bitop3_b32 v4, v198, v2, 5 bitop3:0x6c
	v_lshlrev_b32_e32 v4, 4, v4
; #define LDSP __attribute__((address_space(3)))
; DI bf16_t f2bf(float a) { return (bf16_t)(pk2(a, 0.f) & 0xffffu); }
; DI void wave_rows_store(ldsp_t wb, int lane, bf16_t* dst0, size_t ld) {
; #pragma unroll
;     for (int i = 0; i < 8; ++i) {
;         const int row = i * 8 + (lane >> 3), ch = lane & 7;
;         const u32x4 v = *(const LDSP u32x4*)(wb + row * 128 + ((ch ^ (row & 7)) << 4));
;         *(u32x4*)(dst0 + (size_t)row * ld + ch * 8) = v;
;     }
; }
;     static DI void run(const f32x4 (&acc)[8][4], const TileCtx& tc, const Params& p, ldsp_t wb) {
;     ...
;                 for (int mm = 0; mm < 4; ++mm) {
;                     const int m = h * 4 + mm;
;                     const int key = mm * 16 + fr, k16 = key & 15;
;                     const int kp = (key & ~15) | ((((k16 >> 2) & 1) << 3) + (k16 & 3) + ((k16 >> 3) << 2));
; #pragma unroll
;                     for (int n = 0; n < 4; ++n)
; #pragma unroll
;                         for (int j = 0; j < 4; ++j) {
;                             const int d = n * 16 + fq * 4 + j;
;                             *(LDSP bf16_t*)(wb + d * 128 + (((kp >> 3) ^ (d & 7)) << 4) + (kp & 7) * 2) = f2bf(acc[m][n][j]);
;                         }
;                 }
;                 const int row0 = tc.brow + tc.wr * 128 + h * 64;
;                 int b, pos0;
;                 if (row0 < NLAT) { b = row0 >> 12; pos0 = CTXL + (row0 & 4095); } else { const int r2 = row0 - NLAT; b = r2 >> 8; pos0 = r2 & 255; }
;                 wave_rows_store(wb, tc.lane, p.Vt + (size_t)(b * 2 + kvh) * 64 * NKEY + pos0, NKEY);
	v_add3_u32 v4, v199, v4, v1
	v_cvt_pk_bf16_f32 v3, v98, s0
	v_add_u32_e32 v197, v4, v0
	v_bitop3_b32 v4, v200, v219, 6 bitop3:0x4e
	ds_write_b16 v190, v3
	v_cvt_pk_bf16_f32 v3, v99, s0
	v_lshlrev_b32_e32 v4, 4, v4
	ds_write_b16 v191, v3
	v_cvt_pk_bf16_f32 v3, v100, s0
	v_add3_u32 v4, v201, v4, v1
	ds_write_b16 v183, v3 offset:2048
	v_cvt_pk_bf16_f32 v3, v101, s0
	v_add_u32_e32 v198, v4, v0
	v_bitop3_b32 v4, v204, v2, 7 bitop3:0x6c
	ds_write_b16 v194, v3
	v_cvt_pk_bf16_f32 v3, v96, s0
	v_lshlrev_b32_e32 v4, 4, v4
	ds_write_b16 v195, v3
	v_cvt_pk_bf16_f32 v3, v97, s0
	v_add3_u32 v4, v205, v4, v1
	ds_write_b16 v196, v3
	v_cvt_pk_bf16_f32 v3, v94, s0
	v_add_u32_e32 v199, v4, v0
	v_bitop3_b32 v4, v206, v2, 5 bitop3:0x6c
	ds_write_b16 v183, v3 offset:4096
	v_cvt_pk_bf16_f32 v3, v95, s0
	v_lshlrev_b32_e32 v4, 4, v4
	ds_write_b16 v197, v3
	v_cvt_pk_bf16_f32 v3, v92, s0
	v_add3_u32 v4, v207, v4, v1
	ds_write_b16 v198, v3
	v_cvt_pk_bf16_f32 v3, v93, s0
	v_add_u32_e32 v218, v4, v0
	v_bitop3_b32 v4, v210, v219, 6 bitop3:0x4e
	v_bitop3_b32 v2, v212, v2, 7 bitop3:0x6c
	ds_write_b16 v199, v3
	v_cvt_pk_bf16_f32 v3, v90, s0
	v_lshlrev_b32_e32 v4, 4, v4
	v_lshlrev_b32_e32 v2, 4, v2
	ds_write_b16 v183, v3 offset:6144
	v_cvt_pk_bf16_f32 v3, v91, s0
	v_add3_u32 v4, v211, v4, v1
	v_add3_u32 v1, v213, v2, v1
	ds_write_b16 v218, v3
	v_cvt_pk_bf16_f32 v3, v88, s0
	v_add_u32_e32 v220, v4, v0
	v_add_u32_e32 v223, v1, v0
	v_add_u32_e32 v1, s41, v112
	s_movk_i32 s6, 0x3fff
	ds_write_b16 v220, v3
	v_cvt_pk_bf16_f32 v3, v89, s0
	v_cmp_lt_i32_e32 vcc, s6, v1
	ds_write_b16 v223, v3
	s_and_saveexec_b64 s[6:7], vcc
	s_xor_b64 s[6:7], exec, s[6:7]
	v_add_u32_e32 v0, 0xffffc000, v1
	v_lshrrev_b32_e32 v0, 8, v0
	v_and_b32_e32 v192, 0x80, v174
	s_andn2_saveexec_b64 s[6:7], s[6:7]
	v_ashrrev_i32_e32 v0, 12, v1
	v_and_b32_e32 v1, 0xf80, v1
	v_add_u32_e32 v192, 0x100, v1
	s_or_b64 exec, exec, s[6:7]
	v_add_u32_e32 v225, -2, v171
	v_lshl_add_u32 v2, v0, 1, v225
	v_mov_b64_e32 v[0:1], s[26:27]
	s_mov_b32 s6, 0x88000
	v_lshrrev_b32_e32 v204, 3, v170
	v_mad_i64_i32 v[0:1], s[6:7], v2, s6, v[0:1]
	v_xor_b32_e32 v2, v204, v170
	v_lshlrev_b32_e32 v2, 4, v2
	v_and_b32_e32 v2, 0x70, v2
	v_add_u32_e32 v205, v176, v2
	v_lshlrev_b32_e32 v2, 3, v170
	v_and_b32_e32 v2, 56, v2
	v_lshl_add_u64 v[0:1], v[192:193], 1, v[0:1]
	v_lshlrev_b32_e32 v8, 1, v2
	v_mov_b32_e32 v9, v193
	v_lshl_add_u64 v[200:201], v[0:1], 0, v[8:9]
	v_lshlrev_b32_e32 v9, 7, v204
	v_add_u32_e32 v226, v205, v9
	ds_read_b128 v[0:3], v226
	v_mul_u32_u24_e32 v192, 0x2200, v204
	v_lshl_add_u64 v[4:5], v[200:201], 0, v[192:193]
	s_mov_b32 s6, 0x11000
	v_add_co_u32_e32 v6, vcc, s6, v4
	s_waitcnt lgkmcnt(0)
	global_store_dwordx4 v[4:5], v[0:3], off sc1
	v_addc_co_u32_e32 v7, vcc, 0, v5, vcc
	s_nop 0
	v_or_b32_e32 v0, 0x400, v9
	v_add_u32_e32 v227, v205, v0
	ds_read_b128 v[0:3], v227
	s_mov_b32 s6, 0x22000
	s_movk_i32 s91, 0x2200
	s_waitcnt lgkmcnt(0)
	global_store_dwordx4 v[6:7], v[0:3], off sc1
	s_nop 1
	v_or_b32_e32 v0, 0x800, v9
	v_add_u32_e32 v228, v205, v0
	ds_read_b128 v[0:3], v228
	v_add_co_u32_e32 v6, vcc, s6, v4
	s_mov_b32 s6, 0x33000
	s_nop 0
	v_addc_co_u32_e32 v7, vcc, 0, v5, vcc
	s_waitcnt lgkmcnt(0)
	global_store_dwordx4 v[6:7], v[0:3], off sc1
	v_add_co_u32_e32 v4, vcc, s6, v4
	s_nop 0
	v_or_b32_e32 v0, 0xc00, v9
	v_add_u32_e32 v229, v205, v0
	ds_read_b128 v[0:3], v229
	v_addc_co_u32_e32 v5, vcc, 0, v5, vcc
	s_movk_i32 s6, 0x2200
	s_waitcnt lgkmcnt(0)
	global_store_dwordx4 v[4:5], v[0:3], off sc1
	s_nop 1
	v_or_b32_e32 v0, 0x1000, v9
	v_add_u32_e32 v224, v205, v0
	ds_read_b128 v[4:7], v224
	v_mov_b32_e32 v0, 0x44000
	v_mad_u32_u24 v2, v204, s6, v0
	v_mov_b32_e32 v3, v193
	v_lshl_add_u64 v[0:1], v[200:201], 0, v[2:3]
	s_waitcnt lgkmcnt(0)
	global_store_dwordx4 v[0:1], v[4:7], off sc1
	v_or_b32_e32 v0, 0x1400, v9
	v_add_u32_e32 v222, v205, v0
	ds_read_b128 v[148:151], v222
	v_mov_b32_e32 v0, 0x55000
	v_mad_u32_u24 v6, v204, s6, v0
	v_mov_b32_e32 v7, v193
	v_lshl_add_u64 v[0:1], v[200:201], 0, v[6:7]
	s_waitcnt lgkmcnt(0)
	global_store_dwordx4 v[0:1], v[148:151], off sc1
	v_or_b32_e32 v0, 0x1800, v9
	v_add_u32_e32 v221, v205, v0
	ds_read_b128 v[148:151], v221
	v_mov_b32_e32 v0, 0x66000
	v_mad_u32_u24 v4, v204, s6, v0
	v_mov_b32_e32 v5, v193
	v_lshl_add_u64 v[0:1], v[200:201], 0, v[4:5]
	s_waitcnt lgkmcnt(0)
; #define LDSP __attribute__((address_space(3)))
; DI bf16_t f2bf(float a) { return (bf16_t)(pk2(a, 0.f) & 0xffffu); }
; DI void wave_rows_store(ldsp_t wb, int lane, bf16_t* dst0, size_t ld) {
; #pragma unroll
;     for (int i = 0; i < 8; ++i) {
;         const int row = i * 8 + (lane >> 3), ch = lane & 7;
;         const u32x4 v = *(const LDSP u32x4*)(wb + row * 128 + ((ch ^ (row & 7)) << 4));
;         *(u32x4*)(dst0 + (size_t)row * ld + ch * 8) = v;
;     }
; }
;     static DI void run(const f32x4 (&acc)[8][4], const TileCtx& tc, const Params& p, ldsp_t wb) {
;     ...
;                 for (int mm = 0; mm < 4; ++mm) {
;                     const int m = h * 4 + mm;
;                     const int key = mm * 16 + fr, k16 = key & 15;
;                     const int kp = (key & ~15) | ((((k16 >> 2) & 1) << 3) + (k16 & 3) + ((k16 >> 3) << 2));
; #pragma unroll
;                     for (int n = 0; n < 4; ++n)
; #pragma unroll
;                         for (int j = 0; j < 4; ++j) {
;                             const int d = n * 16 + fq * 4 + j;
;                             *(LDSP bf16_t*)(wb + d * 128 + (((kp >> 3) ^ (d & 7)) << 4) + (kp & 7) * 2) = f2bf(acc[m][n][j]);
;                         }
;                 }
;                 const int row0 = tc.brow + tc.wr * 128 + h * 64;
;                 int b, pos0;
;                 if (row0 < NLAT) { b = row0 >> 12; pos0 = CTXL + (row0 & 4095); } else { const int r2 = row0 - NLAT; b = r2 >> 8; pos0 = r2 & 255; }
;                 wave_rows_store(wb, tc.lane, p.Vt + (size_t)(b * 2 + kvh) * 64 * NKEY + pos0, NKEY);
	global_store_dwordx4 v[0:1], v[148:151], off sc1
	v_or_b32_e32 v0, 0x1c00, v9
	v_cvt_pk_bf16_f32 v9, v86, s0
	ds_write_b16 v10, v9
	v_cvt_pk_bf16_f32 v9, v87, s0
	ds_write_b16 v11, v9
	v_cvt_pk_bf16_f32 v9, v82, s0
	ds_write_b16 v12, v9
	v_cvt_pk_bf16_f32 v9, v83, s0
	ds_write_b16 v13, v9
	v_cvt_pk_bf16_f32 v9, v84, s0
	ds_write_b16 v10, v9 offset:2048
	v_cvt_pk_bf16_f32 v9, v85, s0
	ds_write_b16 v14, v9
	v_cvt_pk_bf16_f32 v9, v80, s0
	ds_write_b16 v15, v9
	v_cvt_pk_bf16_f32 v9, v81, s0
	ds_write_b16 v16, v9
	v_cvt_pk_bf16_f32 v9, v78, s0
	ds_write_b16 v10, v9 offset:4096
	v_cvt_pk_bf16_f32 v9, v79, s0
	ds_write_b16 v17, v9
	v_cvt_pk_bf16_f32 v9, v76, s0
	ds_write_b16 v18, v9
	v_cvt_pk_bf16_f32 v9, v77, s0
	v_add_u32_e32 v219, v205, v0
	ds_write_b16 v19, v9
	v_cvt_pk_bf16_f32 v9, v74, s0
	ds_read_b128 v[148:151], v219
	ds_write_b16 v10, v9 offset:6144
	v_cvt_pk_bf16_f32 v9, v75, s0
	ds_write_b16 v33, v9
	v_cvt_pk_bf16_f32 v9, v72, s0
	ds_write_b16 v34, v9
	v_cvt_pk_bf16_f32 v9, v73, s0
	ds_write_b16 v35, v9
	v_cvt_pk_bf16_f32 v9, v70, s0
	ds_write_b16 v32, v9
	v_cvt_pk_bf16_f32 v9, v71, s0
	ds_write_b16 v36, v9
	v_cvt_pk_bf16_f32 v9, v68, s0
	ds_write_b16 v37, v9
	v_cvt_pk_bf16_f32 v9, v69, s0
	ds_write_b16 v38, v9
	v_cvt_pk_bf16_f32 v9, v66, s0
	ds_write_b16 v32, v9 offset:2048
	v_cvt_pk_bf16_f32 v9, v67, s0
	ds_write_b16 v39, v9
	v_cvt_pk_bf16_f32 v9, v64, s0
	ds_write_b16 v40, v9
	v_cvt_pk_bf16_f32 v9, v65, s0
	ds_write_b16 v41, v9
	v_cvt_pk_bf16_f32 v9, v62, s0
	ds_write_b16 v32, v9 offset:4096
	v_cvt_pk_bf16_f32 v9, v63, s0
	ds_write_b16 v42, v9
	v_cvt_pk_bf16_f32 v9, v60, s0
	ds_write_b16 v162, v9
	v_cvt_pk_bf16_f32 v9, v61, s0
	ds_write_b16 v163, v9
	v_cvt_pk_bf16_f32 v9, v58, s0
	ds_write_b16 v32, v9 offset:6144
	v_cvt_pk_bf16_f32 v9, v59, s0
	ds_write_b16 v164, v9
	v_cvt_pk_bf16_f32 v9, v56, s0
	ds_write_b16 v165, v9
	v_cvt_pk_bf16_f32 v9, v57, s0
	ds_write_b16 v166, v9
	v_cvt_pk_bf16_f32 v9, v110, s0
	ds_write_b16 v43, v9
	v_cvt_pk_bf16_f32 v9, v111, s0
	ds_write_b16 v167, v9
	v_cvt_pk_bf16_f32 v9, v108, s0
	ds_write_b16 v177, v9
	v_cvt_pk_bf16_f32 v9, v109, s0
	ds_write_b16 v178, v9
	v_cvt_pk_bf16_f32 v9, v106, s0
	ds_write_b16 v43, v9 offset:2048
	v_cvt_pk_bf16_f32 v9, v107, s0
	ds_write_b16 v179, v9
	v_cvt_pk_bf16_f32 v9, v104, s0
	ds_write_b16 v180, v9
	v_cvt_pk_bf16_f32 v9, v105, s0
	ds_write_b16 v181, v9
	v_cvt_pk_bf16_f32 v9, v54, s0
	ds_write_b16 v43, v9 offset:4096
	v_cvt_pk_bf16_f32 v9, v55, s0
	ds_write_b16 v182, v9
	v_cvt_pk_bf16_f32 v9, v52, s0
	ds_write_b16 v184, v9
	v_cvt_pk_bf16_f32 v9, v53, s0
	ds_write_b16 v185, v9
	v_cvt_pk_bf16_f32 v9, v50, s0
	ds_write_b16 v43, v9 offset:6144
	v_cvt_pk_bf16_f32 v9, v51, s0
	ds_write_b16 v186, v9
	v_cvt_pk_bf16_f32 v9, v48, s0
	ds_write_b16 v187, v9
	v_cvt_pk_bf16_f32 v9, v49, s0
	ds_write_b16 v188, v9
	v_cvt_pk_bf16_f32 v9, v44, s0
	ds_write_b16 v183, v9
	v_cvt_pk_bf16_f32 v9, v45, s0
	ds_write_b16 v189, v9
	v_cvt_pk_bf16_f32 v9, v46, s0
	ds_write_b16 v190, v9
	v_cvt_pk_bf16_f32 v9, v47, s0
	ds_write_b16 v191, v9
	v_cvt_pk_bf16_f32 v9, v30, s0
	ds_write_b16 v183, v9 offset:2048
	v_cvt_pk_bf16_f32 v9, v31, s0
	ds_write_b16 v194, v9
	v_cvt_pk_bf16_f32 v9, v28, s0
	ds_write_b16 v195, v9
	v_cvt_pk_bf16_f32 v9, v29, s0
	ds_write_b16 v196, v9
	v_cvt_pk_bf16_f32 v9, v26, s0
	ds_write_b16 v183, v9 offset:4096
	v_cvt_pk_bf16_f32 v9, v27, s0
	ds_write_b16 v197, v9
	v_cvt_pk_bf16_f32 v9, v24, s0
	ds_write_b16 v198, v9
	v_cvt_pk_bf16_f32 v9, v25, s0
	ds_write_b16 v199, v9
	v_cvt_pk_bf16_f32 v9, v22, s0
	v_mov_b32_e32 v0, 0x77000
	ds_write_b16 v183, v9 offset:6144
	v_cvt_pk_bf16_f32 v9, v23, s0
	v_mad_u32_u24 v0, v204, s6, v0
	v_mov_b32_e32 v1, v193
	ds_write_b16 v218, v9
	v_cvt_pk_bf16_f32 v9, v20, s0
	v_add3_u32 v11, v112, s41, 64
	s_movk_i32 s6, 0x3fff
	v_lshl_add_u64 v[200:201], v[200:201], 0, v[0:1]
	ds_write_b16 v220, v9
	v_cvt_pk_bf16_f32 v9, v21, s0
	v_cmp_lt_i32_e32 vcc, s6, v11
	s_waitcnt lgkmcnt(14)
	global_store_dwordx4 v[200:201], v[148:151], off sc1
	ds_write_b16 v223, v9
	s_and_saveexec_b64 s[6:7], vcc
	s_xor_b64 s[6:7], exec, s[6:7]
	v_add_u32_e32 v9, 0xffffc000, v11
	v_lshrrev_b32_e32 v9, 8, v9
	v_and_b32_e32 v10, 0xc0, v11
	s_andn2_saveexec_b64 s[6:7], s[6:7]
	v_and_b32_e32 v10, 0xfc0, v11
	v_ashrrev_i32_e32 v9, 12, v11
	v_add_u32_e32 v10, 0x100, v10
	s_or_b64 exec, exec, s[6:7]
	v_lshl_add_u32 v9, v9, 1, v225
	v_mov_b64_e32 v[12:13], s[26:27]
	s_mov_b32 s6, 0x88000
	v_mad_i64_i32 v[12:13], s[6:7], v9, s6, v[12:13]
	v_mov_b32_e32 v11, v193
	v_lshl_add_u64 v[10:11], v[10:11], 1, v[12:13]
	v_mov_b32_e32 v9, v193
	v_lshl_add_u64 v[12:13], v[10:11], 0, v[8:9]
	ds_read_b128 v[8:11], v226
	v_lshl_add_u64 v[14:15], v[12:13], 0, v[192:193]
	s_mov_b32 s6, 0x11000
	v_add_co_u32_e32 v16, vcc, s6, v14
	s_waitcnt lgkmcnt(0)
	global_store_dwordx4 v[14:15], v[8:11], off sc1
	ds_read_b128 v[8:11], v227
	v_addc_co_u32_e32 v17, vcc, 0, v15, vcc
	s_mov_b32 s6, 0x22000
	v_lshl_add_u64 v[2:3], v[12:13], 0, v[2:3]
	s_waitcnt lgkmcnt(0)
	global_store_dwordx4 v[16:17], v[8:11], off sc1
	ds_read_b128 v[8:11], v228
	v_add_co_u32_e32 v16, vcc, s6, v14
	s_mov_b32 s6, 0x33000
	s_nop 0
	v_addc_co_u32_e32 v17, vcc, 0, v15, vcc
	s_waitcnt lgkmcnt(0)
	global_store_dwordx4 v[16:17], v[8:11], off sc1
	ds_read_b128 v[8:11], v229
	v_add_co_u32_e32 v14, vcc, s6, v14
	v_lshl_add_u64 v[0:1], v[12:13], 0, v[0:1]
	s_nop 0
	v_addc_co_u32_e32 v15, vcc, 0, v15, vcc
	s_waitcnt lgkmcnt(0)
	global_store_dwordx4 v[14:15], v[8:11], off sc1
	ds_read_b128 v[8:11], v224
	s_waitcnt lgkmcnt(0)
	global_store_dwordx4 v[2:3], v[8:11], off sc1
	ds_read_b128 v[8:11], v222
	v_lshl_add_u64 v[2:3], v[12:13], 0, v[6:7]
	s_waitcnt lgkmcnt(0)
	global_store_dwordx4 v[2:3], v[8:11], off sc1
	ds_read_b128 v[6:9], v221
	v_lshl_add_u64 v[2:3], v[12:13], 0, v[4:5]
	s_waitcnt lgkmcnt(0)
	global_store_dwordx4 v[2:3], v[6:9], off sc1
	ds_read_b128 v[2:5], v219
	s_waitcnt lgkmcnt(0)
	global_store_dwordx4 v[0:1], v[2:5], off sc1

;     static DI void run(const f32x4 (&acc)[8][4], const TileCtx& tc, const Params& p, ldsp_t wb) {
;     ...
;                     float ss = 0.f;
; #pragma unroll
;                     for (int n = 0; n < 4; ++n)
; #pragma unroll
;                         for (int j = 0; j < 4; ++j) ss += acc[m][n][j] * acc[m][n][j];
;                     ss += __shfl_xor(ss, 16);
;                     ss += __shfl_xor(ss, 32);
;                     const float rstd = rsqrtf(ss * (1.f / 64.f) + EPS) * osc;
;                     const int t = row & 4095;
; #pragma unroll
;                     for (int ax = 0; ax < 2; ++ax) {
;                         f32x4 x1 = acc[m][2 * ax] * rstd * gv[2 * ax], x2 = acc[m][2 * ax + 1] * rstd * gv[2 * ax + 1];
;                         if (lat) {
;                             const int pos = ax == 0 ? (t >> 6) : (t & 63);
;                             const f32x4 cs = *(const f32x4*)(p.rope + pos * 16 + fq * 4), sn = *(const f32x4*)(p.rope + 1024 + pos * 16 + fq * 4);
;                             const f32x4 o1 = x1 * cs - x2 * sn, o2 = x2 * cs + x1 * sn;
;                             x1 = o1; x2 = o2;
;     ...
;                 const int row0 = tc.brow + tc.wr * 128 + h * 64;
;                 bf16_t* dst0;
;                 if (lat) {
;                     const int b = row0 >> 12, t0 = row0 & 4095;
;                     dst0 = isq ? p.Q + ((size_t)(b * 8 + head) * SEQ + t0) * 64 : p.K + ((size_t)(b * 2 + head) * NKEY + CTXL + t0) * 64;
;                 } else {
;                     const int r2 = row0 - NLAT, b = r2 >> 8, t0 = r2 & 255;
;                     dst0 = isq ? p.Qc + ((size_t)(b * 8 + head) * CTXL + t0) * 64 : p.K + ((size_t)(b * 2 + head) * NKEY + t0) * 64;
;                 }
;                 wave_rows_store(wb, tc.lane, dst0, 64);
.LBB0_304:
	v_lshrrev_b32_e32 v18, 3, v170
	v_xor_b32_e32 v19, v18, v170
	v_lshlrev_b32_e32 v19, 4, v19
	v_and_b32_e32 v19, 0x70, v19
	v_add_u32_e32 v181, v176, v19
	v_lshlrev_b32_e32 v19, 3, v170
	v_lshlrev_b64 v[16:17], 7, v[16:17]
	v_and_b32_e32 v19, 56, v19
	v_lshlrev_b32_e32 v192, 7, v18
	v_lshl_add_u64 v[16:17], s[24:25], 0, v[16:17]
	v_lshlrev_b32_e32 v36, 1, v19
	v_mov_b32_e32 v37, v193
	v_add_u32_e32 v33, v181, v192
	v_lshl_add_u64 v[148:149], v[16:17], 0, v[36:37]
	ds_read_b128 v[16:19], v33
	v_lshl_add_u64 v[34:35], v[148:149], 0, v[192:193]
	v_or_b32_e32 v40, 0x1400, v192
	v_mov_b32_e32 v41, v193
	v_or_b32_e32 v42, 0x1800, v192
	s_waitcnt lgkmcnt(0)
	global_store_dwordx4 v[34:35], v[16:19], off sc1
	ds_read_b128 v[16:19], v33 offset:1024
	v_mov_b32_e32 v43, v193
	s_waitcnt lgkmcnt(0)
	global_store_dwordx4 v[34:35], v[16:19], off offset:1024 sc1
	ds_read_b128 v[16:19], v33 offset:2048
	s_waitcnt lgkmcnt(0)
	global_store_dwordx4 v[34:35], v[16:19], off offset:2048 sc1
	ds_read_b128 v[16:19], v33 offset:3072
	s_waitcnt lgkmcnt(0)
	global_store_dwordx4 v[34:35], v[16:19], off offset:3072 sc1
	ds_read_b128 v[16:19], v33 offset:4096
	v_or_b32_e32 v34, 0x1000, v192
	v_mov_b32_e32 v35, v193
	v_lshl_add_u64 v[38:39], v[148:149], 0, v[34:35]
	s_waitcnt lgkmcnt(0)
	global_store_dwordx4 v[38:39], v[16:19], off sc1
	ds_read_b128 v[16:19], v33 offset:5120
	v_lshl_add_u64 v[38:39], v[148:149], 0, v[40:41]
	s_waitcnt lgkmcnt(0)
	global_store_dwordx4 v[38:39], v[16:19], off sc1
	ds_read_b128 v[16:19], v33 offset:6144
	v_lshl_add_u64 v[38:39], v[148:149], 0, v[42:43]
	s_waitcnt lgkmcnt(0)
	global_store_dwordx4 v[38:39], v[16:19], off sc1
	ds_read_b128 v[16:19], v33 offset:7168
	v_or_b32_e32 v38, 0x1c00, v192
	v_mov_b32_e32 v39, v193
	v_lshl_add_u64 v[148:149], v[148:149], 0, v[38:39]
	s_waitcnt lgkmcnt(0)
	global_store_dwordx4 v[148:149], v[16:19], off sc1
	v_mul_f32_e32 v33, v87, v87
	v_fmac_f32_e32 v33, v86, v86
	v_fmac_f32_e32 v33, v82, v82
	v_fmac_f32_e32 v33, v83, v83
	v_fmac_f32_e32 v33, v84, v84
	v_fmac_f32_e32 v33, v85, v85
	v_fmac_f32_e32 v33, v80, v80
	v_fmac_f32_e32 v33, v81, v81
	v_pk_mul_f32 v[18:19], v[78:79], v[78:79]
	v_pk_mul_f32 v[16:17], v[76:77], v[76:77]
	v_add_f32_e32 v18, v18, v33
	v_add_f32_e32 v18, v19, v18
	v_add_f32_e32 v16, v16, v18
	v_add_f32_e32 v33, v17, v16
	v_pk_mul_f32 v[18:19], v[74:75], v[74:75]
	v_pk_mul_f32 v[16:17], v[72:73], v[72:73]
	v_add_f32_e32 v18, v18, v33
	v_add_f32_e32 v18, v19, v18
	v_add_f32_e32 v16, v16, v18
	v_add_f32_e32 v16, v17, v16
	ds_bpermute_b32 v17, v113, v16
	s_waitcnt lgkmcnt(0)
	v_add_f32_e32 v16, v16, v17
	ds_bpermute_b32 v17, v168, v16
	s_waitcnt lgkmcnt(0)
	v_add_f32_e32 v16, v16, v17
	v_fmamk_f32 v16, v16, 0x3c800000, v208
	v_cmp_gt_f32_e32 vcc, s92, v16
	v_mul_f32_e32 v17, 0x4b800000, v16
	s_nop 0
	v_cndmask_b32_e32 v16, v16, v17, vcc
	v_rsq_f32_e32 v16, v16
	s_nop 0
	v_mul_f32_e32 v17, 0x45800000, v16
	v_cndmask_b32_e32 v162, v16, v17, vcc
	v_pk_mul_f32 v[16:17], v[86:87], v[162:163] op_sel_hi:[1,0]
	v_pk_mul_f32 v[18:19], v[82:83], v[162:163] op_sel_hi:[1,0]
	v_pk_mul_f32 v[148:149], v[84:85], v[162:163] op_sel_hi:[1,0]
	v_pk_mul_f32 v[150:151], v[80:81], v[162:163] op_sel_hi:[1,0]
	v_pk_mul_f32 v[18:19], v[14:15], v[18:19]
	v_pk_mul_f32 v[16:17], v[12:13], v[16:17]
	v_pk_mul_f32 v[164:165], v[10:11], v[150:151]
	v_pk_mul_f32 v[166:167], v[8:9], v[148:149]
	s_and_b64 vcc, exec, s[4:5]
	s_cbranch_vccnz .LBB0_306
	v_add_u32_e32 v33, s41, v174
	v_and_b32_e32 v182, 0xf80, v33
	v_mov_b32_e32 v33, v193
	v_lshl_add_u64 v[148:149], s[18:19], 0, v[32:33]
	v_or_b32_e32 v150, 64, v182
	v_mov_b32_e32 v151, v193
	v_mov_b32_e32 v183, v193
	v_lshl_add_u64 v[148:149], v[148:149], 0, v[150:151]
	v_lshl_add_u64 v[182:183], s[68:69], 0, v[182:183]
	global_load_dwordx4 v[148:151], v[148:149], off
	v_lshl_add_u64 v[182:183], v[182:183], 0, v[32:33]
	global_load_dwordx4 v[182:185], v[182:183], off offset:64
	s_waitcnt vmcnt(1)
	v_pk_mul_f32 v[186:187], v[164:165], v[150:151]
	v_pk_mul_f32 v[188:189], v[166:167], v[148:149]
	v_pk_mul_f32 v[150:151], v[18:19], v[150:151]
	v_pk_mul_f32 v[148:149], v[16:17], v[148:149]
	s_waitcnt vmcnt(0)
	v_pk_fma_f32 v[18:19], v[18:19], v[184:185], v[186:187] neg_lo:[0,0,1] neg_hi:[0,0,1]
	v_pk_fma_f32 v[16:17], v[16:17], v[182:183], v[188:189] neg_lo:[0,0,1] neg_hi:[0,0,1]
	v_pk_fma_f32 v[164:165], v[164:165], v[184:185], v[150:151]
	v_pk_fma_f32 v[166:167], v[166:167], v[182:183], v[148:149]

; #define LDSP __attribute__((address_space(3)))
; DI void wave_rows_store(ldsp_t wb, int lane, bf16_t* dst0, size_t ld) {
; #pragma unroll
;     for (int i = 0; i < 8; ++i) {
;         const int row = i * 8 + (lane >> 3), ch = lane & 7;
;         const u32x4 v = *(const LDSP u32x4*)(wb + row * 128 + ((ch ^ (row & 7)) << 4));
;         *(u32x4*)(dst0 + (size_t)row * ld + ch * 8) = v;
;     }
; }
.LBB0_324:
	v_lshlrev_b64 v[0:1], 7, v[0:1]
	v_lshl_add_u64 v[0:1], s[24:25], 0, v[0:1]
	v_mov_b32_e32 v37, v193
	v_add_u32_e32 v8, v181, v192
	v_lshl_add_u64 v[4:5], v[0:1], 0, v[36:37]
	ds_read_b128 v[0:3], v8
	v_lshl_add_u64 v[6:7], v[4:5], 0, v[192:193]
	s_waitcnt lgkmcnt(0)
	global_store_dwordx4 v[6:7], v[0:3], off sc1
	ds_read_b128 v[0:3], v8 offset:1024
	s_waitcnt lgkmcnt(0)
	global_store_dwordx4 v[6:7], v[0:3], off offset:1024 sc1
	ds_read_b128 v[0:3], v8 offset:2048
	s_waitcnt lgkmcnt(0)
	global_store_dwordx4 v[6:7], v[0:3], off offset:2048 sc1
	ds_read_b128 v[0:3], v8 offset:3072
	s_waitcnt lgkmcnt(0)
	global_store_dwordx4 v[6:7], v[0:3], off offset:3072 sc1
	ds_read_b128 v[0:3], v8 offset:4096
	v_lshl_add_u64 v[6:7], v[4:5], 0, v[34:35]
	s_waitcnt lgkmcnt(0)
	global_store_dwordx4 v[6:7], v[0:3], off sc1
	ds_read_b128 v[0:3], v8 offset:5120
	v_lshl_add_u64 v[6:7], v[4:5], 0, v[40:41]
	s_waitcnt lgkmcnt(0)
	global_store_dwordx4 v[6:7], v[0:3], off sc1
	ds_read_b128 v[0:3], v8 offset:6144
	v_lshl_add_u64 v[6:7], v[4:5], 0, v[42:43]
	v_lshl_add_u64 v[4:5], v[4:5], 0, v[38:39]
	s_waitcnt lgkmcnt(0)
	global_store_dwordx4 v[6:7], v[0:3], off sc1
	ds_read_b128 v[0:3], v8 offset:7168
	s_waitcnt lgkmcnt(0)
	global_store_dwordx4 v[4:5], v[0:3], off sc1

; DI unsigned pk2(float a, float b) { f32x2 v = {a, b}; bf2_t r = __builtin_convertvector(v, bf2_t); return __builtin_bit_cast(unsigned, r); }
;     static DI void run(const f32x4 (&acc)[8][4], const TileCtx& tc, const Params& p, ldsp_t wb) {
;     ...
;                     float ss = 0.f;
; #pragma unroll
;                     for (int n = 0; n < 4; ++n)
; #pragma unroll
;                         for (int j = 0; j < 4; ++j) ss += acc[m][n][j] * acc[m][n][j];
;                     ss += __shfl_xor(ss, 16);
;                     ss += __shfl_xor(ss, 32);
;                     const float rstd = rsqrtf(ss * (1.f / 64.f) + EPS) * osc;
;                     const int t = row & 4095;
; #pragma unroll
;                     for (int ax = 0; ax < 2; ++ax) {
;                         f32x4 x1 = acc[m][2 * ax] * rstd * gv[2 * ax], x2 = acc[m][2 * ax + 1] * rstd * gv[2 * ax + 1];
;                         if (lat) {
;                             const int pos = ax == 0 ? (t >> 6) : (t & 63);
;                             const f32x4 cs = *(const f32x4*)(p.rope + pos * 16 + fq * 4), sn = *(const f32x4*)(p.rope + 1024 + pos * 16 + fq * 4);
;                             const f32x4 o1 = x1 * cs - x2 * sn, o2 = x2 * cs + x1 * sn;
;                             x1 = o1; x2 = o2;
;                         }
;                         u32x2 w; w[0] = pk2(x1[0], x1[1]); w[1] = pk2(x1[2], x1[3]);
;                         wave_put(wb, mm * 16 + fr, 2 * ax, fq, w);
;                         w[0] = pk2(x2[0], x2[1]); w[1] = pk2(x2[2], x2[3]);
;                         wave_put(wb, mm * 16 + fr, 2 * ax + 1, fq, w);
;                     }
;                 }
;                 const int row0 = tc.brow + tc.wr * 128 + h * 64;
;                 bf16_t* dst0;
;                 if (lat) {
;                     const int b = row0 >> 12, t0 = row0 & 4095;
;                     dst0 = isq ? p.Q + ((size_t)(b * 8 + head) * SEQ + t0) * 64 : p.K + ((size_t)(b * 2 + head) * NKEY + CTXL + t0) * 64;
;                 } else {
;                     const int r2 = row0 - NLAT, b = r2 >> 8, t0 = r2 & 255;
;                     dst0 = isq ? p.Qc + ((size_t)(b * 8 + head) * CTXL + t0) * 64 : p.K + ((size_t)(b * 2 + head) * NKEY + t0) * 64;
;                 }
;                 wave_rows_store(wb, tc.lane, dst0, 64);
.LBB0_349:
	v_lshl_or_b32 v94, s98, 2, v171
	v_and_b32_e32 v17, -8, v17
	v_add_u32_e32 v18, v17, v94
	v_ashrrev_i32_e32 v19, 31, v18
	v_lshlrev_b64 v[18:19], s8, v[18:19]
	v_lshl_add_u64 v[18:19], s[6:7], 0, v[18:19]
	s_lshl_b32 s6, s9, 1
	v_lshlrev_b32_e32 v16, 7, v16
	v_and_b32_e32 v192, s6, v16
	v_lshl_add_u64 v[16:17], v[18:19], 0, v[192:193]
	v_lshrrev_b32_e32 v18, 3, v170
	v_xor_b32_e32 v19, v18, v170
	v_lshlrev_b32_e32 v19, 4, v19
	v_and_b32_e32 v19, 0x70, v19
	v_add_u32_e32 v95, v176, v19
	v_lshlrev_b32_e32 v19, 3, v170
	v_and_b32_e32 v19, 56, v19
	v_lshlrev_b32_e32 v192, 7, v18
	v_lshlrev_b32_e32 v40, 1, v19
	v_mov_b32_e32 v41, v193
	v_add_u32_e32 v33, v95, v192
	v_lshl_add_u64 v[92:93], v[16:17], 0, v[40:41]
	ds_read_b128 v[16:19], v33
	v_lshl_add_u64 v[38:39], v[92:93], 0, v[192:193]
	v_or_b32_e32 v88, 0x1400, v192
	v_mov_b32_e32 v89, v193
	v_or_b32_e32 v90, 0x1800, v192
	s_waitcnt lgkmcnt(0)
	global_store_dwordx4 v[38:39], v[16:19], off sc1
	ds_read_b128 v[16:19], v33 offset:1024
	v_mov_b32_e32 v91, v193
	s_waitcnt lgkmcnt(0)
	global_store_dwordx4 v[38:39], v[16:19], off offset:1024 sc1
	ds_read_b128 v[16:19], v33 offset:2048
	s_waitcnt lgkmcnt(0)
	global_store_dwordx4 v[38:39], v[16:19], off offset:2048 sc1
	ds_read_b128 v[16:19], v33 offset:3072
	s_waitcnt lgkmcnt(0)
	global_store_dwordx4 v[38:39], v[16:19], off offset:3072 sc1
	ds_read_b128 v[16:19], v33 offset:4096
	v_or_b32_e32 v38, 0x1000, v192
	v_mov_b32_e32 v39, v193
	v_lshl_add_u64 v[42:43], v[92:93], 0, v[38:39]
	s_waitcnt lgkmcnt(0)
	global_store_dwordx4 v[42:43], v[16:19], off sc1
	ds_read_b128 v[16:19], v33 offset:5120
	v_lshl_add_u64 v[42:43], v[92:93], 0, v[88:89]
	s_waitcnt lgkmcnt(0)
	global_store_dwordx4 v[42:43], v[16:19], off sc1
	ds_read_b128 v[16:19], v33 offset:6144
	v_lshl_add_u64 v[42:43], v[92:93], 0, v[90:91]
	s_waitcnt lgkmcnt(0)
	global_store_dwordx4 v[42:43], v[16:19], off sc1
	ds_read_b128 v[16:19], v33 offset:7168
	v_or_b32_e32 v42, 0x1c00, v192
	v_mov_b32_e32 v43, v193
	v_lshl_add_u64 v[92:93], v[92:93], 0, v[42:43]
	s_waitcnt lgkmcnt(0)
	global_store_dwordx4 v[92:93], v[16:19], off sc1
	v_mul_f32_e32 v33, v87, v87
	v_fmac_f32_e32 v33, v86, v86
	v_fmac_f32_e32 v33, v82, v82
	v_fmac_f32_e32 v33, v83, v83
	v_fmac_f32_e32 v33, v84, v84
	v_fmac_f32_e32 v33, v85, v85
	v_fmac_f32_e32 v33, v80, v80
	v_fmac_f32_e32 v33, v81, v81
	v_pk_mul_f32 v[18:19], v[78:79], v[78:79]
	v_pk_mul_f32 v[16:17], v[76:77], v[76:77]
	v_add_f32_e32 v18, v18, v33
	v_add_f32_e32 v18, v19, v18
	v_add_f32_e32 v16, v16, v18
	v_add_f32_e32 v33, v17, v16
	v_pk_mul_f32 v[18:19], v[74:75], v[74:75]
	v_pk_mul_f32 v[16:17], v[72:73], v[72:73]
	v_add_f32_e32 v18, v18, v33
	v_add_f32_e32 v18, v19, v18
	v_add_f32_e32 v16, v16, v18
	v_add_f32_e32 v16, v17, v16
	ds_bpermute_b32 v17, v113, v16
	s_and_b64 vcc, exec, s[4:5]
	s_waitcnt lgkmcnt(0)
	v_add_f32_e32 v16, v16, v17
	ds_bpermute_b32 v17, v168, v16
	s_waitcnt lgkmcnt(0)
	v_add_f32_e32 v16, v16, v17
	v_fmamk_f32 v16, v16, 0x3c800000, v208
	v_mul_f32_e32 v17, 0x4b800000, v16
	v_cmp_gt_f32_e64 s[6:7], s92, v16
	s_nop 1
	v_cndmask_b32_e64 v16, v16, v17, s[6:7]
	v_rsq_f32_e32 v16, v16
	s_nop 0
	v_mul_f32_e32 v17, 0x45800000, v16
	v_cndmask_b32_e64 v16, v16, v17, s[6:7]
	v_mul_f32_e32 v92, 0x3e38aa3b, v16
	v_pk_mul_f32 v[16:17], v[86:87], v[92:93] op_sel_hi:[1,0]
	v_pk_mul_f32 v[18:19], v[82:83], v[92:93] op_sel_hi:[1,0]
	v_pk_mul_f32 v[82:83], v[84:85], v[92:93] op_sel_hi:[1,0]
	v_pk_mul_f32 v[80:81], v[80:81], v[92:93] op_sel_hi:[1,0]
	v_pk_mul_f32 v[18:19], v[14:15], v[18:19]
	v_pk_mul_f32 v[16:17], v[12:13], v[16:17]
	v_pk_mul_f32 v[80:81], v[10:11], v[80:81]
	v_pk_mul_f32 v[82:83], v[8:9], v[82:83]
	s_cbranch_vccnz .LBB0_351
	v_mov_b32_e32 v33, v193
	v_lshl_add_u64 v[84:85], s[18:19], 0, v[32:33]
	v_or_b32_e32 v86, 64, v34
	v_mov_b32_e32 v87, v193
	v_mov_b32_e32 v35, v193
	v_lshl_add_u64 v[84:85], v[84:85], 0, v[86:87]
	v_lshl_add_u64 v[34:35], s[68:69], 0, v[34:35]
	v_lshl_add_u64 v[34:35], v[34:35], 0, v[32:33]
	v_mov_b64_e32 v[84:85], v[204:205]
	v_mov_b64_e32 v[86:87], v[206:207]
	v_pk_mul_f32 v[34:35], v[80:81], v[86:87]
	v_pk_mul_f32 v[100:101], v[82:83], v[84:85]
	v_pk_mul_f32 v[86:87], v[18:19], v[86:87]
	v_pk_mul_f32 v[84:85], v[16:17], v[84:85]
	v_mov_b64_e32 v[96:97], v[210:211]
	v_mov_b64_e32 v[98:99], v[212:213]
	v_pk_fma_f32 v[18:19], v[18:19], v[98:99], v[34:35] neg_lo:[0,0,1] neg_hi:[0,0,1]
	v_pk_fma_f32 v[16:17], v[16:17], v[96:97], v[100:101] neg_lo:[0,0,1] neg_hi:[0,0,1]
	v_pk_fma_f32 v[80:81], v[80:81], v[98:99], v[86:87]
	v_pk_fma_f32 v[82:83], v[82:83], v[96:97], v[84:85]

; DI void grid_barrier(unsigned* bar, unsigned k) {
;     asm volatile("s_waitcnt vmcnt(0)" ::: "memory");
;     __syncthreads();
;     if (threadIdx.x == 0) {
;         __builtin_amdgcn_fence(__ATOMIC_RELEASE, "agent");
;         asm volatile("s_waitcnt vmcnt(0)" ::: "memory");
;         const unsigned j = blockIdx.x & 7u, G = gridDim.x;
;         const unsigned nsub = (G - j + 7u) >> 3, ngrp = G < 8u ? G : 8u;
;         const unsigned old = __hip_atomic_fetch_add(bar + 64 * (1 + j), 1u, __ATOMIC_RELAXED, __HIP_MEMORY_SCOPE_AGENT);
; template <bool COOP>
; __global__ void __launch_bounds__(512) mk_kernel(Params p, int ph_lo, int ph_hi) {
;     ...
;         if (COOP && ph + 1 < ph_hi) {
;             if (ph == 0) cg::this_grid().sync();
;             else grid_barrier(p.bar, (unsigned)ph);
.LBB0_372:
	v_readlane_b32 s4, v253, 1
	v_readlane_b32 s5, v253, 2
	s_add_i32 s4, s93, 1
	v_writelane_b32 v253, s4, 1
	s_cmp_ge_i32 s4, s5
	s_nop 0
	v_writelane_b32 v253, s5, 2
	s_mov_b64 s[4:5], -1
	s_cbranch_scc1 .LBB0_5
	s_cmp_lg_u32 s93, 0
	s_cbranch_scc0 .LBB0_433
	s_waitcnt vmcnt(0)
	s_waitcnt lgkmcnt(0)
	s_barrier
	s_mov_b64 s[4:5], exec
	v_readlane_b32 s6, v253, 59
	v_readlane_b32 s7, v253, 60
	s_and_b64 s[6:7], s[4:5], s[6:7]
	s_mov_b64 exec, s[6:7]
	s_cbranch_execz .LBB0_432
	s_nop 0
	s_waitcnt vmcnt(0)
	s_waitcnt vmcnt(0)
	s_load_dword s10, s[88:89], 0x0
	s_mov_b64 s[6:7], exec
	v_mbcnt_lo_u32_b32 v0, s6, 0
	v_mbcnt_hi_u32_b32 v0, s7, v0
	v_cmp_eq_u32_e32 vcc, 0, v0
	s_and_saveexec_b64 s[8:9], vcc
	s_cbranch_execz .LBB0_377
	s_bcnt1_i32_b64 s6, s[6:7]
	v_mov_b32_e32 v1, s6
	v_readlane_b32 s6, v253, 41
	v_readlane_b32 s7, v253, 42
	s_nop 4
	global_atomic_add v1, v193, v1, s[6:7] offset:256 sc0

; DI unsigned pk2(float a, float b) { f32x2 v = {a, b}; bf2_t r = __builtin_convertvector(v, bf2_t); return __builtin_bit_cast(unsigned, r); }
; DI void phase0(const Params& p, ldsp_t smem) {
;     ...
;         if (v < U_WS) {
;             int tw = threadIdx.x;
;             asm volatile("" : "+v"(tw));
;             const size_t i = ((size_t)v * 512 + tw) * 8;
;             const f32x4 a = *(const f32x4*)(p.w_spatial + i), b = *(const f32x4*)(p.w_spatial + i + 4);
;             u32x4 w; w[0] = pk2(a[0], a[1]); w[1] = pk2(a[2], a[3]); w[2] = pk2(b[0], b[1]); w[3] = pk2(b[2], b[3]);
;             *(u32x4*)(p.ws_bf + i) = w;
;             continue;
;         }
;         int ti = threadIdx.x;
;         asm volatile("" : "+v"(ti));
;         if (ti >= 64 && ti < 64 + 9) p.bar[(ti - 64) * 64] = 0u;
.LBB0_392:
	s_cmpk_gt_u32 s10, 0xc3f
	s_cbranch_scc0 .LBB0_407
	s_cmpk_eq_i32 s10, 0xc80
	s_cbranch_scc1 .LBB0_395
	s_add_i32 s98, s10, 0xfffff3c0
	v_mov_b32_e32 v0, v252
	s_lshl_b64 s[4:5], s[98:99], 12
	v_ashrrev_i32_e32 v1, 31, v0
	v_readlane_b32 s12, v253, 3
	s_waitcnt lgkmcnt(3)
	v_lshl_add_u64 v[8:9], v[0:1], 3, s[4:5]
	v_readlane_b32 s18, v253, 9
	v_readlane_b32 s19, v253, 10
	v_readlane_b32 s13, v253, 4
	v_readlane_b32 s14, v253, 5
	s_waitcnt lgkmcnt(0)
	v_lshl_add_u64 v[4:5], v[8:9], 2, s[18:19]
	global_load_dwordx4 v[0:3], v[4:5], off
	s_nop 0
	global_load_dwordx4 v[4:7], v[4:5], off offset:16
	v_readlane_b32 s15, v253, 6
	v_readlane_b32 s16, v253, 7
	v_readlane_b32 s17, v253, 8
	v_readlane_b32 s20, v253, 11
	v_readlane_b32 s21, v253, 12
	v_readlane_b32 s22, v253, 13
	v_readlane_b32 s23, v253, 14
	v_readlane_b32 s24, v253, 15
	v_readlane_b32 s25, v253, 16
	v_readlane_b32 s26, v253, 17
	v_readlane_b32 s27, v253, 18
	v_readlane_b32 s12, v254, 50
	v_readlane_b32 s13, v254, 51
	v_readlane_b32 s14, v254, 52
	v_readlane_b32 s15, v254, 53
	v_readlane_b32 s16, v254, 54
	v_readlane_b32 s17, v254, 55
	v_readlane_b32 s18, v254, 56
	v_readlane_b32 s19, v254, 57
	v_readlane_b32 s20, v254, 58
	v_readlane_b32 s21, v254, 59
	v_readlane_b32 s22, v254, 60
	v_readlane_b32 s23, v254, 61
	v_readlane_b32 s24, v254, 62
	v_readlane_b32 s25, v254, 63
	v_readlane_b32 s26, v255, 0
	v_readlane_b32 s27, v255, 1
	v_lshl_add_u64 v[8:9], v[8:9], 1, s[64:65]
	s_mov_b64 s[4:5], 0
	s_waitcnt vmcnt(1)
	v_cvt_pk_bf16_f32 v0, v0, v1
	v_cvt_pk_bf16_f32 v1, v2, v3
	s_waitcnt vmcnt(0)
	v_cvt_pk_bf16_f32 v2, v4, v5
	v_cvt_pk_bf16_f32 v3, v6, v7
	global_store_dwordx4 v[8:9], v[0:3], off sc1
.LBB0_395:
	s_andn2_b64 vcc, exec, s[4:5]
	s_cbranch_vccnz .LBB0_406
	v_mov_b32_e32 v0, v252
	s_nop 0
	v_subrev_u32_e32 v1, 64, v0
	v_cmp_gt_u32_e32 vcc, 9, v1
	v_lshlrev_b32_e32 v192, 6, v0
	s_and_saveexec_b64 s[4:5], vcc
	s_cbranch_execz .LBB0_398
	v_lshl_add_u64 v[2:3], v[192:193], 2, s[80:81]
	v_add_co_u32_e32 v2, vcc, 0xffffc000, v2
	s_nop 1
	v_addc_co_u32_e32 v3, vcc, -1, v3, vcc
	global_store_dword v[2:3], v193, off sc1

; DI void phase0(const Params& p, ldsp_t smem) {
;     ...
;         if (ti < DEPTH) {
;             float mq = 0.f, mk = 0.f;
;             for (int i = 0; i < 64; ++i) { mq = fmaxf(mq, fabsf(p.q_norm_g[ti * 64 + i])); mk = fmaxf(mk, fabsf(p.k_norm_g[ti * 64 + i])); }
;             p.smax[ti] = 8.f * mq * mk;
;         }
.LBB0_400:
	v_lshl_add_u64 v[16:17], v[2:3], 0, s[6:7]
	v_lshl_add_u64 v[20:21], v[4:5], 0, s[6:7]
	global_load_dwordx4 v[8:11], v[16:17], off
	global_load_dwordx4 v[12:15], v[20:21], off
	s_nop 0
	global_load_dwordx4 v[16:19], v[16:17], off offset:16
	s_nop 0
	global_load_dwordx4 v[20:23], v[20:21], off offset:16
	s_add_u32 s6, s6, 32
	s_addc_u32 s7, s7, 0
	s_cmpk_eq_i32 s6, 0x100
	s_waitcnt vmcnt(3)
	v_max3_f32 v6, v6, |v8|, |v9|
	s_waitcnt vmcnt(2)
	v_max3_f32 v1, v1, |v12|, |v13|
	v_max3_f32 v6, v6, |v10|, |v11|
	v_max3_f32 v1, v1, |v14|, |v15|
	s_waitcnt vmcnt(1)
	v_max3_f32 v6, v6, |v16|, |v17|
	s_waitcnt vmcnt(0)
	v_max3_f32 v1, v1, |v20|, |v21|
	v_max3_f32 v6, v6, |v18|, |v19|
	v_max3_f32 v1, v1, |v22|, |v23|
	s_cbranch_scc0 .LBB0_400
	v_mul_f32_e32 v2, 0x41000000, v6
	v_mul_f32_e32 v4, v2, v1
	v_ashrrev_i32_e32 v1, 31, v0
	v_lshl_add_u64 v[2:3], v[0:1], 2, s[72:73]
	global_store_dword v[2:3], v4, off sc1

; DI float fexp2(float x) { return __builtin_amdgcn_exp2f(x); }
; DI void phase0(const Params& p, ldsp_t smem) {
;     ...
;         for (int i = ti; i < 1024; i += 512) {
;             const int pos = i >> 4, f = i & 15;
;             const float inv = fexp2(-(float)f * (13.287712379549449f / 16.f));
;             const float rev = (float)pos * inv * 0.15915494309189535f;
;             p.rope[i] = __builtin_amdgcn_cosf(rev);
;             p.rope[1024 + i] = __builtin_amdgcn_sinf(rev);
;         }
.LBB0_404:
	v_ashrrev_i32_e32 v1, 4, v0
	v_cvt_f32_i32_e32 v1, v1
	s_movk_i32 s8, 0x1ff
	v_cmp_lt_i32_e32 vcc, s8, v0
	s_or_b64 s[6:7], vcc, s[6:7]
	v_mul_f32_e32 v1, v4, v1
	v_mul_f32_e32 v1, 0.15915494, v1
	s_waitcnt lgkmcnt(0)
	v_cos_f32_e32 v5, v1
	v_sin_f32_e32 v1, v1
	global_store_dword v[2:3], v5, off offset:-4096 sc1
	global_store_dword v[2:3], v1, off sc1
	v_add_u32_e32 v1, 0x200, v0
	v_lshl_add_u64 v[2:3], v[2:3], 0, s[94:95]
	v_mov_b32_e32 v0, v1
	s_andn2_b64 exec, exec, s[6:7]
	s_cbranch_execnz .LBB0_404

; #define LDSP __attribute__((address_space(3)))
; DI unsigned pk2(float a, float b) { f32x2 v = {a, b}; bf2_t r = __builtin_convertvector(v, bf2_t); return __builtin_bit_cast(unsigned, r); }
; DI void transpose_tile(const float* __restrict__ src, bf16_t* __restrict__ dst, int K, int N, int tk, int tn, ldsp_t smem) {
;     LDSP float* t = (LDSP float*)smem;
;     int tid = threadIdx.x;
;     asm volatile("" : "+v"(tid));
;     const int k0 = tk * 64, n0 = tn * 256;
;     f32x4 v[8];
; #pragma unroll
;     for (int i = 0; i < 8; ++i) v[i] = *(const f32x4*)(src + (size_t)(k0 + (tid >> 6) + 8 * i) * N + n0 + (tid & 63) * 4);
; #pragma unroll
;     for (int i = 0; i < 8; ++i) {
;         const int k = (tid >> 6) + 8 * i, n4 = (tid & 63) * 4;
;         t[k * 257 + n4 + 0] = v[i][0]; t[k * 257 + n4 + 1] = v[i][1]; t[k * 257 + n4 + 2] = v[i][2]; t[k * 257 + n4 + 3] = v[i][3];
;     }
;     __syncthreads();
; #pragma unroll
;     for (int j = 0; j < 4; ++j) {
;         const int n = (tid >> 3) + 64 * j, k8 = (tid & 7) * 8;
;         u32x4 w;
;         w[0] = pk2(t[(k8 + 0) * 257 + n], t[(k8 + 1) * 257 + n]);
;         w[1] = pk2(t[(k8 + 2) * 257 + n], t[(k8 + 3) * 257 + n]);
;         w[2] = pk2(t[(k8 + 4) * 257 + n], t[(k8 + 5) * 257 + n]);
;         w[3] = pk2(t[(k8 + 6) * 257 + n], t[(k8 + 7) * 257 + n]);
;         *(u32x4*)(dst + (size_t)(n0 + n) * K + k0 + k8) = w;
;     }
;     __syncthreads();
; }
.LBB0_407:
	s_andn2_b64 vcc, exec, s[4:5]
	s_cbranch_vccnz .LBB0_420
	s_add_i32 s4, s10, 0xfe80
	s_and_b32 s5, s4, 0xffff
	s_mul_i32 s5, s5, 0xbe83
	s_lshr_b32 s7, s5, 25
	s_mul_i32 s5, s7, 0x2b0
	s_sub_i32 s4, s4, s5
	s_and_b32 s6, s4, 0xffff
	s_cmpk_gt_u32 s6, 0x6f
	s_mov_b64 s[4:5], -1
	s_cbranch_scc0 .LBB0_418
	s_cmpk_gt_u32 s6, 0xaf
	s_cbranch_scc0 .LBB0_415
	s_lshl_b32 s11, s7, 24
	s_lshl_b32 s9, s7, 23
	s_lshl_b32 s8, s6, 8
	s_cmpk_gt_u32 s6, 0x1af
	s_cbranch_scc0 .LBB0_412
	s_add_u32 s34, s52, s11
	s_addc_u32 s35, s53, 0
	s_add_u32 s5, s62, s9
	s_addc_u32 s31, s63, 0
	s_lshl_b32 s4, s6, 4
	s_and_b32 s4, s4, 0x3fc0
	v_mov_b32_e32 v34, v252
	s_add_i32 s98, s4, 0xffffe500
	s_and_b32 s4, s8, 0x300
	s_lshl_b32 s36, s4, 2
	v_ashrrev_i32_e32 v32, 6, v34
	v_add_u32_e32 v0, s98, v32
	s_add_u32 s34, s34, s36
	v_lshlrev_b32_e32 v1, 4, v34
	s_addc_u32 s35, s35, 0
	v_and_b32_e32 v192, 0x3f0, v1
	v_ashrrev_i32_e32 v1, 31, v0
	v_lshl_add_u64 v[2:3], s[34:35], 0, v[192:193]
	v_lshlrev_b64 v[0:1], 12, v[0:1]
	v_lshl_add_u64 v[28:29], v[2:3], 0, v[0:1]
	s_mov_b32 s34, 0x8000
	s_waitcnt lgkmcnt(5)
	v_add_co_u32_e32 v4, vcc, s34, v28
	global_load_dwordx4 v[0:3], v[28:29], off
	s_waitcnt lgkmcnt(0)
	v_addc_co_u32_e32 v5, vcc, 0, v29, vcc
	s_mov_b32 s34, 0x10000
	global_load_dwordx4 v[4:7], v[4:5], off
	v_add_co_u32_e32 v8, vcc, s34, v28
	s_mov_b32 s34, 0x20000
	s_nop 0
	v_addc_co_u32_e32 v9, vcc, 0, v29, vcc
	global_load_dwordx4 v[8:11], v[8:9], off
	v_add_co_u32_e32 v12, vcc, s30, v28
	s_movk_i32 s36, 0x404
	s_nop 0
	v_addc_co_u32_e32 v13, vcc, 0, v29, vcc
	global_load_dwordx4 v[12:15], v[12:13], off
	v_add_co_u32_e32 v16, vcc, s34, v28
	s_mov_b32 s34, 0x28000
	s_nop 0
	v_addc_co_u32_e32 v17, vcc, 0, v29, vcc
	global_load_dwordx4 v[16:19], v[16:17], off
	v_add_co_u32_e32 v20, vcc, s34, v28
	s_mov_b32 s34, 0x30000
	s_nop 0
	v_addc_co_u32_e32 v21, vcc, 0, v29, vcc
	global_load_dwordx4 v[20:23], v[20:21], off
	v_add_co_u32_e32 v24, vcc, s34, v28
	s_mov_b32 s34, 0x38000
	s_nop 0
	v_addc_co_u32_e32 v25, vcc, 0, v29, vcc
	global_load_dwordx4 v[24:27], v[24:25], off
	v_add_co_u32_e32 v28, vcc, s34, v28
	v_mad_u64_u32 v[32:33], s[34:35], v32, s36, v[192:193]
	s_nop 0
	v_addc_co_u32_e32 v29, vcc, 0, v29, vcc
	global_load_dwordx4 v[28:31], v[28:29], off
	s_lshl_b64 s[34:35], s[98:99], 1
	s_add_u32 s34, s5, s34
	s_addc_u32 s35, s31, s35
	s_waitcnt vmcnt(7)
	ds_write2_b32 v32, v0, v1 offset1:1
	ds_write2_b32 v32, v2, v3 offset0:2 offset1:3
	v_add_u32_e32 v0, 0x2020, v32
	s_waitcnt vmcnt(6)
	ds_write2_b32 v0, v4, v5 offset1:1
	v_add_u32_e32 v0, 0x2028, v32
	ds_write2_b32 v0, v6, v7 offset1:1
	v_add_u32_e32 v0, 0x4040, v32
	s_waitcnt vmcnt(5)
	ds_write2_b32 v0, v8, v9 offset1:1
	v_add_u32_e32 v0, 0x4048, v32
	ds_write2_b32 v0, v10, v11 offset1:1
	v_add_u32_e32 v0, 0x6060, v32
	s_waitcnt vmcnt(4)
	ds_write2_b32 v0, v12, v13 offset1:1
	v_add_u32_e32 v0, 0x6068, v32
	ds_write2_b32 v0, v14, v15 offset1:1
	v_add_u32_e32 v0, 0x8080, v32
	s_waitcnt vmcnt(3)
	ds_write2_b32 v0, v16, v17 offset1:1
	v_add_u32_e32 v0, 0x8088, v32
	ds_write2_b32 v0, v18, v19 offset1:1
	v_add_u32_e32 v0, 0xa0a0, v32
	s_waitcnt vmcnt(2)
	ds_write2_b32 v0, v20, v21 offset1:1
	v_add_u32_e32 v0, 0xa0a8, v32
	ds_write2_b32 v0, v22, v23 offset1:1
	v_add_u32_e32 v0, 0xc0c0, v32
	v_ashrrev_i32_e32 v22, 3, v34
	v_lshlrev_b32_e32 v1, 2, v22
	s_waitcnt vmcnt(1)
	ds_write2_b32 v0, v24, v25 offset1:1
	v_add_u32_e32 v0, 0xc0c8, v32
	ds_write2_b32 v0, v26, v27 offset1:1
	v_add_u32_e32 v0, 0xe0e0, v32
	v_add_u32_e32 v22, s4, v22
	v_ashrrev_i32_e32 v23, 31, v22
	v_lshlrev_b64 v[24:25], 13, v[22:23]
	s_waitcnt vmcnt(0)
	ds_write2_b32 v0, v28, v29 offset1:1
	v_add_u32_e32 v0, 0xe0e8, v32
	ds_write2_b32 v0, v30, v31 offset1:1
	v_lshlrev_b32_e32 v0, 3, v34
	v_and_b32_e32 v0, 56, v0
	v_mad_u32_u24 v26, v0, s36, v1
	v_add_u32_e32 v27, 4, v26
	v_add_u32_e32 v28, 8, v26
	v_add_u32_e32 v29, 12, v26
	v_add_u32_e32 v30, 16, v26
	v_add_u32_e32 v31, 20, v26
	v_add_u32_e32 v32, 24, v26
	v_add_u32_e32 v33, 28, v26
	s_waitcnt lgkmcnt(0)
	s_barrier
	ds_read2st64_b32 v[6:7], v26 offset1:1
	ds_read2st64_b32 v[8:9], v27 offset0:4 offset1:5
	ds_read2st64_b32 v[10:11], v28 offset0:8 offset1:9
	ds_read2st64_b32 v[12:13], v29 offset0:12 offset1:13
	ds_read2st64_b32 v[14:15], v30 offset0:16 offset1:17
	ds_read2st64_b32 v[16:17], v31 offset0:20 offset1:21
	ds_read2st64_b32 v[18:19], v32 offset0:24 offset1:25
	ds_read2st64_b32 v[20:21], v33 offset0:28 offset1:29
	v_lshlrev_b32_e32 v192, 1, v0
	v_lshl_add_u64 v[4:5], s[34:35], 0, v[192:193]
	s_waitcnt lgkmcnt(6)
	v_cvt_pk_bf16_f32 v0, v6, v8
	s_waitcnt lgkmcnt(4)
	v_cvt_pk_bf16_f32 v1, v10, v12
	s_waitcnt lgkmcnt(2)
	v_cvt_pk_bf16_f32 v2, v14, v16
	s_waitcnt lgkmcnt(0)
	v_cvt_pk_bf16_f32 v3, v18, v20
	v_lshl_add_u64 v[24:25], v[4:5], 0, v[24:25]
	v_add_u32_e32 v6, 64, v22
	global_store_dwordx4 v[24:25], v[0:3], off sc1
	v_add_u32_e32 v24, 0x80, v22
	v_ashrrev_i32_e32 v25, 31, v24
	v_cvt_pk_bf16_f32 v0, v7, v9
	v_ashrrev_i32_e32 v7, 31, v6
	v_lshlrev_b64 v[6:7], 13, v[6:7]
	v_cvt_pk_bf16_f32 v1, v11, v13
	v_cvt_pk_bf16_f32 v2, v15, v17
	v_cvt_pk_bf16_f32 v3, v19, v21
	v_lshl_add_u64 v[6:7], v[4:5], 0, v[6:7]
	global_store_dwordx4 v[6:7], v[0:3], off sc1
	ds_read2st64_b32 v[6:7], v26 offset0:2 offset1:3
	ds_read2st64_b32 v[8:9], v27 offset0:6 offset1:7
	ds_read2st64_b32 v[10:11], v28 offset0:10 offset1:11
	ds_read2st64_b32 v[12:13], v29 offset0:14 offset1:15
	ds_read2st64_b32 v[14:15], v30 offset0:18 offset1:19
	ds_read2st64_b32 v[16:17], v31 offset0:22 offset1:23
	ds_read2st64_b32 v[18:19], v32 offset0:26 offset1:27
	ds_read2st64_b32 v[20:21], v33 offset0:30 offset1:31
	v_lshlrev_b64 v[24:25], 13, v[24:25]
	s_waitcnt lgkmcnt(6)
	v_cvt_pk_bf16_f32 v0, v6, v8
	s_waitcnt lgkmcnt(4)
	v_cvt_pk_bf16_f32 v1, v10, v12
	s_waitcnt lgkmcnt(2)
	v_cvt_pk_bf16_f32 v2, v14, v16
	s_waitcnt lgkmcnt(0)
	v_cvt_pk_bf16_f32 v3, v18, v20
	v_lshl_add_u64 v[24:25], v[4:5], 0, v[24:25]
	v_add_u32_e32 v6, 0xc0, v22
	global_store_dwordx4 v[24:25], v[0:3], off sc1
	s_mov_b64 s[4:5], 0
	s_nop 0
	v_cvt_pk_bf16_f32 v0, v7, v9
	v_ashrrev_i32_e32 v7, 31, v6
	v_lshlrev_b64 v[6:7], 13, v[6:7]
	v_cvt_pk_bf16_f32 v1, v11, v13
	v_cvt_pk_bf16_f32 v2, v15, v17
	v_cvt_pk_bf16_f32 v3, v19, v21
	v_lshl_add_u64 v[4:5], v[4:5], 0, v[6:7]
	global_store_dwordx4 v[4:5], v[0:3], off sc1
	s_barrier
; #define LDSP __attribute__((address_space(3)))
; DI unsigned pk2(float a, float b) { f32x2 v = {a, b}; bf2_t r = __builtin_convertvector(v, bf2_t); return __builtin_bit_cast(unsigned, r); }
; DI void transpose_tile(const float* __restrict__ src, bf16_t* __restrict__ dst, int K, int N, int tk, int tn, ldsp_t smem) {
;     LDSP float* t = (LDSP float*)smem;
;     int tid = threadIdx.x;
;     asm volatile("" : "+v"(tid));
;     const int k0 = tk * 64, n0 = tn * 256;
;     f32x4 v[8];
; #pragma unroll
;     for (int i = 0; i < 8; ++i) v[i] = *(const f32x4*)(src + (size_t)(k0 + (tid >> 6) + 8 * i) * N + n0 + (tid & 63) * 4);
; #pragma unroll
;     for (int i = 0; i < 8; ++i) {
;         const int k = (tid >> 6) + 8 * i, n4 = (tid & 63) * 4;
;         t[k * 257 + n4 + 0] = v[i][0]; t[k * 257 + n4 + 1] = v[i][1]; t[k * 257 + n4 + 2] = v[i][2]; t[k * 257 + n4 + 3] = v[i][3];
;     }
;     __syncthreads();
; #pragma unroll
;     for (int j = 0; j < 4; ++j) {
;         const int n = (tid >> 3) + 64 * j, k8 = (tid & 7) * 8;
;         u32x4 w;
;         w[0] = pk2(t[(k8 + 0) * 257 + n], t[(k8 + 1) * 257 + n]);
;         w[1] = pk2(t[(k8 + 2) * 257 + n], t[(k8 + 3) * 257 + n]);
;         w[2] = pk2(t[(k8 + 4) * 257 + n], t[(k8 + 5) * 257 + n]);
;         w[3] = pk2(t[(k8 + 6) * 257 + n], t[(k8 + 7) * 257 + n]);
;         *(u32x4*)(dst + (size_t)(n0 + n) * K + k0 + k8) = w;
;     }
;     __syncthreads();
; }
.LBB0_412:
	s_andn2_b64 vcc, exec, s[4:5]
	s_cbranch_vccnz .LBB0_414
	v_readlane_b32 s36, v253, 3
	v_readlane_b32 s50, v253, 17
	v_readlane_b32 s51, v253, 18
	s_add_u32 s11, s50, s11
	s_addc_u32 s31, s51, 0
	s_add_u32 s5, s60, s9
	s_addc_u32 s9, s61, 0
	s_lshl_b32 s4, s6, 2
	s_and_b32 s4, s4, 0x7c0
	v_mov_b32_e32 v34, v252
	s_add_i32 s98, s4, 0xfffffd40
	s_and_b32 s4, s8, 0xf00
	s_lshl_b32 s8, s4, 2
	v_ashrrev_i32_e32 v32, 6, v34
	v_add_u32_e32 v0, s98, v32
	s_add_u32 s34, s11, s8
	v_lshlrev_b32_e32 v1, 4, v34
	s_addc_u32 s35, s31, 0
	v_and_b32_e32 v192, 0x3f0, v1
	v_ashrrev_i32_e32 v1, 31, v0
	v_lshl_add_u64 v[2:3], s[34:35], 0, v[192:193]
	v_lshlrev_b64 v[0:1], 14, v[0:1]
	v_lshl_add_u64 v[28:29], v[2:3], 0, v[0:1]
	s_mov_b32 s8, 0x20000
	s_waitcnt lgkmcnt(5)
	v_add_co_u32_e32 v4, vcc, s8, v28
	global_load_dwordx4 v[0:3], v[28:29], off
	s_waitcnt lgkmcnt(0)
	v_addc_co_u32_e32 v5, vcc, 0, v29, vcc
	s_mov_b32 s8, 0x40000
	global_load_dwordx4 v[4:7], v[4:5], off
	v_add_co_u32_e32 v8, vcc, s8, v28
	s_mov_b32 s8, 0x60000
	s_nop 0
	v_addc_co_u32_e32 v9, vcc, 0, v29, vcc
	global_load_dwordx4 v[8:11], v[8:9], off
	v_add_co_u32_e32 v12, vcc, s8, v28
	s_mov_b32 s8, 0x80000
	s_nop 0
	v_addc_co_u32_e32 v13, vcc, 0, v29, vcc
	global_load_dwordx4 v[12:15], v[12:13], off
	v_add_co_u32_e32 v16, vcc, s8, v28
	s_mov_b32 s8, 0xa0000
	s_nop 0
	v_addc_co_u32_e32 v17, vcc, 0, v29, vcc
	global_load_dwordx4 v[16:19], v[16:17], off
	v_add_co_u32_e32 v20, vcc, s8, v28
	s_mov_b32 s8, 0xc0000
	s_nop 0
	v_addc_co_u32_e32 v21, vcc, 0, v29, vcc
	global_load_dwordx4 v[20:23], v[20:21], off
	v_add_co_u32_e32 v24, vcc, s8, v28
	s_mov_b32 s8, 0xe0000
	s_nop 0
	v_addc_co_u32_e32 v25, vcc, 0, v29, vcc
	global_load_dwordx4 v[24:27], v[24:25], off
	v_add_co_u32_e32 v28, vcc, s8, v28
	s_movk_i32 s11, 0x404
	s_nop 0
	v_addc_co_u32_e32 v29, vcc, 0, v29, vcc
	global_load_dwordx4 v[28:31], v[28:29], off
	v_mad_u64_u32 v[32:33], s[34:35], v32, s11, v[192:193]
	s_lshl_b64 s[34:35], s[98:99], 1
	s_add_u32 s8, s5, s34
	s_addc_u32 s9, s9, s35
	v_readlane_b32 s37, v253, 4
	v_readlane_b32 s38, v253, 5
	v_readlane_b32 s39, v253, 6
	v_readlane_b32 s40, v253, 7
	v_readlane_b32 s41, v253, 8
	v_readlane_b32 s42, v253, 9
	v_readlane_b32 s43, v253, 10
	v_readlane_b32 s44, v253, 11
	v_readlane_b32 s45, v253, 12
	v_readlane_b32 s46, v253, 13
	v_readlane_b32 s47, v253, 14
	v_readlane_b32 s48, v253, 15
	v_readlane_b32 s49, v253, 16
	s_waitcnt vmcnt(7)
	ds_write2_b32 v32, v0, v1 offset1:1
	ds_write2_b32 v32, v2, v3 offset0:2 offset1:3
	v_add_u32_e32 v0, 0x2020, v32
	s_waitcnt vmcnt(6)
	ds_write2_b32 v0, v4, v5 offset1:1
	v_add_u32_e32 v0, 0x2028, v32
	ds_write2_b32 v0, v6, v7 offset1:1
	v_add_u32_e32 v0, 0x4040, v32
	s_waitcnt vmcnt(5)
	ds_write2_b32 v0, v8, v9 offset1:1
	v_add_u32_e32 v0, 0x4048, v32
	ds_write2_b32 v0, v10, v11 offset1:1
	v_add_u32_e32 v0, 0x6060, v32
	s_waitcnt vmcnt(4)
	ds_write2_b32 v0, v12, v13 offset1:1
	v_add_u32_e32 v0, 0x6068, v32
	ds_write2_b32 v0, v14, v15 offset1:1
	v_add_u32_e32 v0, 0x8080, v32
	s_waitcnt vmcnt(3)
	ds_write2_b32 v0, v16, v17 offset1:1
	v_add_u32_e32 v0, 0x8088, v32
	ds_write2_b32 v0, v18, v19 offset1:1
	v_add_u32_e32 v0, 0xa0a0, v32
	s_waitcnt vmcnt(2)
	ds_write2_b32 v0, v20, v21 offset1:1
	v_add_u32_e32 v0, 0xa0a8, v32
	ds_write2_b32 v0, v22, v23 offset1:1
	v_add_u32_e32 v0, 0xc0c0, v32
	v_ashrrev_i32_e32 v22, 3, v34
	v_lshlrev_b32_e32 v1, 2, v22
	s_waitcnt vmcnt(1)
	ds_write2_b32 v0, v24, v25 offset1:1
	v_add_u32_e32 v0, 0xc0c8, v32
	ds_write2_b32 v0, v26, v27 offset1:1
	v_add_u32_e32 v0, 0xe0e0, v32
	v_add_u32_e32 v22, s4, v22
	v_ashrrev_i32_e32 v23, 31, v22
	s_waitcnt vmcnt(0)
	ds_write2_b32 v0, v28, v29 offset1:1
	v_add_u32_e32 v0, 0xe0e8, v32
	ds_write2_b32 v0, v30, v31 offset1:1
	v_lshlrev_b32_e32 v0, 3, v34
	v_and_b32_e32 v0, 56, v0
	v_mad_u32_u24 v26, v0, s11, v1
	v_add_u32_e32 v27, 4, v26
	v_add_u32_e32 v28, 8, v26
	v_add_u32_e32 v29, 12, v26
	v_add_u32_e32 v30, 16, v26
	v_add_u32_e32 v31, 20, v26
	v_add_u32_e32 v32, 24, v26
	v_add_u32_e32 v33, 28, v26
	s_waitcnt lgkmcnt(0)
	s_barrier
	ds_read2st64_b32 v[6:7], v26 offset1:1
	ds_read2st64_b32 v[8:9], v27 offset0:4 offset1:5
	ds_read2st64_b32 v[10:11], v28 offset0:8 offset1:9
	ds_read2st64_b32 v[12:13], v29 offset0:12 offset1:13
	ds_read2st64_b32 v[14:15], v30 offset0:16 offset1:17
	ds_read2st64_b32 v[16:17], v31 offset0:20 offset1:21
	ds_read2st64_b32 v[18:19], v32 offset0:24 offset1:25
	ds_read2st64_b32 v[20:21], v33 offset0:28 offset1:29
	v_lshlrev_b32_e32 v192, 1, v0
	v_lshl_add_u64 v[4:5], s[8:9], 0, v[192:193]
	v_lshlrev_b64 v[24:25], 11, v[22:23]
	s_waitcnt lgkmcnt(6)
	v_cvt_pk_bf16_f32 v0, v6, v8
	s_waitcnt lgkmcnt(4)
	v_cvt_pk_bf16_f32 v1, v10, v12
	s_waitcnt lgkmcnt(2)
	v_cvt_pk_bf16_f32 v2, v14, v16
	s_waitcnt lgkmcnt(0)
	v_cvt_pk_bf16_f32 v3, v18, v20
	v_lshl_add_u64 v[24:25], v[4:5], 0, v[24:25]
	v_add_u32_e32 v6, 64, v22
	global_store_dwordx4 v[24:25], v[0:3], off sc1
	v_add_u32_e32 v24, 0x80, v22
	v_ashrrev_i32_e32 v25, 31, v24
	v_cvt_pk_bf16_f32 v0, v7, v9
	v_ashrrev_i32_e32 v7, 31, v6
	v_lshlrev_b64 v[6:7], 11, v[6:7]
	v_cvt_pk_bf16_f32 v1, v11, v13
	v_cvt_pk_bf16_f32 v2, v15, v17
	v_cvt_pk_bf16_f32 v3, v19, v21
	v_lshl_add_u64 v[6:7], v[4:5], 0, v[6:7]
	global_store_dwordx4 v[6:7], v[0:3], off sc1
	ds_read2st64_b32 v[6:7], v26 offset0:2 offset1:3
	ds_read2st64_b32 v[8:9], v27 offset0:6 offset1:7
	ds_read2st64_b32 v[10:11], v28 offset0:10 offset1:11
	ds_read2st64_b32 v[12:13], v29 offset0:14 offset1:15
	ds_read2st64_b32 v[14:15], v30 offset0:18 offset1:19
	ds_read2st64_b32 v[16:17], v31 offset0:22 offset1:23
	ds_read2st64_b32 v[18:19], v32 offset0:26 offset1:27
	ds_read2st64_b32 v[20:21], v33 offset0:30 offset1:31
	v_lshlrev_b64 v[24:25], 11, v[24:25]
	s_waitcnt lgkmcnt(6)
	v_cvt_pk_bf16_f32 v0, v6, v8
	s_waitcnt lgkmcnt(4)
	v_cvt_pk_bf16_f32 v1, v10, v12
	s_waitcnt lgkmcnt(2)
	v_cvt_pk_bf16_f32 v2, v14, v16
	s_waitcnt lgkmcnt(0)
	v_cvt_pk_bf16_f32 v3, v18, v20
	v_lshl_add_u64 v[24:25], v[4:5], 0, v[24:25]
	v_add_u32_e32 v6, 0xc0, v22
	global_store_dwordx4 v[24:25], v[0:3], off sc1
	s_nop 1
	v_cvt_pk_bf16_f32 v0, v7, v9
	v_ashrrev_i32_e32 v7, 31, v6
	v_lshlrev_b64 v[6:7], 11, v[6:7]
	v_cvt_pk_bf16_f32 v1, v11, v13
	v_cvt_pk_bf16_f32 v2, v15, v17
	v_cvt_pk_bf16_f32 v3, v19, v21
	v_lshl_add_u64 v[4:5], v[4:5], 0, v[6:7]
	global_store_dwordx4 v[4:5], v[0:3], off sc1
	s_barrier

; #define LDSP __attribute__((address_space(3)))
; DI unsigned pk2(float a, float b) { f32x2 v = {a, b}; bf2_t r = __builtin_convertvector(v, bf2_t); return __builtin_bit_cast(unsigned, r); }
; DI void transpose_tile(const float* __restrict__ src, bf16_t* __restrict__ dst, int K, int N, int tk, int tn, ldsp_t smem) {
;     LDSP float* t = (LDSP float*)smem;
;     int tid = threadIdx.x;
;     asm volatile("" : "+v"(tid));
;     const int k0 = tk * 64, n0 = tn * 256;
;     f32x4 v[8];
; #pragma unroll
;     for (int i = 0; i < 8; ++i) v[i] = *(const f32x4*)(src + (size_t)(k0 + (tid >> 6) + 8 * i) * N + n0 + (tid & 63) * 4);
; #pragma unroll
;     for (int i = 0; i < 8; ++i) {
;         const int k = (tid >> 6) + 8 * i, n4 = (tid & 63) * 4;
;         t[k * 257 + n4 + 0] = v[i][0]; t[k * 257 + n4 + 1] = v[i][1]; t[k * 257 + n4 + 2] = v[i][2]; t[k * 257 + n4 + 3] = v[i][3];
;     }
;     __syncthreads();
; #pragma unroll
;     for (int j = 0; j < 4; ++j) {
;         const int n = (tid >> 3) + 64 * j, k8 = (tid & 7) * 8;
;         u32x4 w;
;         w[0] = pk2(t[(k8 + 0) * 257 + n], t[(k8 + 1) * 257 + n]);
;         w[1] = pk2(t[(k8 + 2) * 257 + n], t[(k8 + 3) * 257 + n]);
;         w[2] = pk2(t[(k8 + 4) * 257 + n], t[(k8 + 5) * 257 + n]);
;         w[3] = pk2(t[(k8 + 6) * 257 + n], t[(k8 + 7) * 257 + n]);
;         *(u32x4*)(dst + (size_t)(n0 + n) * K + k0 + k8) = w;
;     }
;     __syncthreads();
; }
.LBB0_415:
	s_andn2_b64 vcc, exec, s[4:5]
	s_cbranch_vccnz .LBB0_417
	v_readlane_b32 s36, v253, 3
	s_lshl_b32 s4, s7, 22
	v_readlane_b32 s46, v253, 13
	v_readlane_b32 s47, v253, 14
	s_add_u32 s9, s46, s4
	s_addc_u32 s11, s47, 0
	s_lshl_b32 s4, s7, 21
	s_add_u32 s5, s58, s4
	s_addc_u32 s8, s59, 0
	s_lshl_b32 s4, s6, 4
	s_and_b32 s4, s4, 0xfc0
	s_add_i32 s98, s4, 0xfffff900
	s_lshl_b32 s4, s6, 8
	v_mov_b32_e32 v34, v252
	s_and_b32 s4, s4, 0x300
	s_lshl_b32 s31, s4, 2
	v_ashrrev_i32_e32 v32, 6, v34
	v_add_u32_e32 v0, s98, v32
	s_add_u32 s34, s9, s31
	v_lshlrev_b32_e32 v1, 4, v34
	s_addc_u32 s35, s11, 0
	v_and_b32_e32 v192, 0x3f0, v1
	v_ashrrev_i32_e32 v1, 31, v0
	v_lshl_add_u64 v[2:3], s[34:35], 0, v[192:193]
	v_lshlrev_b64 v[0:1], 12, v[0:1]
	v_lshl_add_u64 v[28:29], v[2:3], 0, v[0:1]
	s_mov_b32 s9, 0x8000
	s_waitcnt lgkmcnt(5)
	v_add_co_u32_e32 v4, vcc, s9, v28
	global_load_dwordx4 v[0:3], v[28:29], off
	s_waitcnt lgkmcnt(0)
	v_addc_co_u32_e32 v5, vcc, 0, v29, vcc
	s_mov_b32 s9, 0x10000
	global_load_dwordx4 v[4:7], v[4:5], off
	v_add_co_u32_e32 v8, vcc, s9, v28
	s_mov_b32 s9, 0x20000
	s_nop 0
	v_addc_co_u32_e32 v9, vcc, 0, v29, vcc
	global_load_dwordx4 v[8:11], v[8:9], off
	v_add_co_u32_e32 v12, vcc, s30, v28
	v_readlane_b32 s37, v253, 4
	s_nop 0
	v_addc_co_u32_e32 v13, vcc, 0, v29, vcc
	global_load_dwordx4 v[12:15], v[12:13], off
	v_add_co_u32_e32 v16, vcc, s9, v28
	s_mov_b32 s9, 0x28000
	s_nop 0
	v_addc_co_u32_e32 v17, vcc, 0, v29, vcc
	global_load_dwordx4 v[16:19], v[16:17], off
	v_add_co_u32_e32 v20, vcc, s9, v28
	s_mov_b32 s9, 0x30000
	s_nop 0
	v_addc_co_u32_e32 v21, vcc, 0, v29, vcc
	global_load_dwordx4 v[20:23], v[20:21], off
	v_add_co_u32_e32 v24, vcc, s9, v28
	s_mov_b32 s9, 0x38000
	s_nop 0
	v_addc_co_u32_e32 v25, vcc, 0, v29, vcc
	global_load_dwordx4 v[24:27], v[24:25], off
	v_add_co_u32_e32 v28, vcc, s9, v28
	s_movk_i32 s9, 0x404
	s_nop 0
	v_addc_co_u32_e32 v29, vcc, 0, v29, vcc
	global_load_dwordx4 v[28:31], v[28:29], off
	v_mad_u64_u32 v[32:33], s[34:35], v32, s9, v[192:193]
	s_lshl_b64 s[34:35], s[98:99], 1
	s_add_u32 s34, s5, s34
	s_addc_u32 s35, s8, s35
	v_readlane_b32 s38, v253, 5
	v_readlane_b32 s39, v253, 6
	v_readlane_b32 s40, v253, 7
	v_readlane_b32 s41, v253, 8
	v_readlane_b32 s42, v253, 9
	v_readlane_b32 s43, v253, 10
	v_readlane_b32 s44, v253, 11
	v_readlane_b32 s45, v253, 12
	v_readlane_b32 s48, v253, 15
	v_readlane_b32 s49, v253, 16
	v_readlane_b32 s50, v253, 17
	v_readlane_b32 s51, v253, 18
	s_waitcnt vmcnt(7)
	ds_write2_b32 v32, v0, v1 offset1:1
	ds_write2_b32 v32, v2, v3 offset0:2 offset1:3
	v_add_u32_e32 v0, 0x2020, v32
	s_waitcnt vmcnt(6)
	ds_write2_b32 v0, v4, v5 offset1:1
	v_add_u32_e32 v0, 0x2028, v32
	ds_write2_b32 v0, v6, v7 offset1:1
	v_add_u32_e32 v0, 0x4040, v32
	s_waitcnt vmcnt(5)
	ds_write2_b32 v0, v8, v9 offset1:1
	v_add_u32_e32 v0, 0x4048, v32
	ds_write2_b32 v0, v10, v11 offset1:1
	v_add_u32_e32 v0, 0x6060, v32
	s_waitcnt vmcnt(4)
	ds_write2_b32 v0, v12, v13 offset1:1
	v_add_u32_e32 v0, 0x6068, v32
	ds_write2_b32 v0, v14, v15 offset1:1
	v_add_u32_e32 v0, 0x8080, v32
	s_waitcnt vmcnt(3)
	ds_write2_b32 v0, v16, v17 offset1:1
	v_add_u32_e32 v0, 0x8088, v32
	ds_write2_b32 v0, v18, v19 offset1:1
	v_add_u32_e32 v0, 0xa0a0, v32
	s_waitcnt vmcnt(2)
	ds_write2_b32 v0, v20, v21 offset1:1
	v_add_u32_e32 v0, 0xa0a8, v32
	ds_write2_b32 v0, v22, v23 offset1:1
	v_add_u32_e32 v0, 0xc0c0, v32
	v_ashrrev_i32_e32 v22, 3, v34
	v_lshlrev_b32_e32 v1, 2, v22
	s_waitcnt vmcnt(1)
	ds_write2_b32 v0, v24, v25 offset1:1
	v_add_u32_e32 v0, 0xc0c8, v32
	ds_write2_b32 v0, v26, v27 offset1:1
	v_add_u32_e32 v0, 0xe0e0, v32
	v_add_u32_e32 v22, s4, v22
	v_ashrrev_i32_e32 v23, 31, v22
	s_waitcnt vmcnt(0)
	ds_write2_b32 v0, v28, v29 offset1:1
	v_add_u32_e32 v0, 0xe0e8, v32
	ds_write2_b32 v0, v30, v31 offset1:1
	v_lshlrev_b32_e32 v0, 3, v34
	v_and_b32_e32 v0, 56, v0
	v_mad_u32_u24 v26, v0, s9, v1
	v_add_u32_e32 v27, 4, v26
	v_add_u32_e32 v28, 8, v26
	v_add_u32_e32 v29, 12, v26
	v_add_u32_e32 v30, 16, v26
	v_add_u32_e32 v31, 20, v26
	v_add_u32_e32 v32, 24, v26
	v_add_u32_e32 v33, 28, v26
	s_waitcnt lgkmcnt(0)
	s_barrier
	ds_read2st64_b32 v[6:7], v26 offset1:1
	ds_read2st64_b32 v[8:9], v27 offset0:4 offset1:5
	ds_read2st64_b32 v[10:11], v28 offset0:8 offset1:9
	ds_read2st64_b32 v[12:13], v29 offset0:12 offset1:13
	ds_read2st64_b32 v[14:15], v30 offset0:16 offset1:17
	ds_read2st64_b32 v[16:17], v31 offset0:20 offset1:21
	ds_read2st64_b32 v[18:19], v32 offset0:24 offset1:25
	ds_read2st64_b32 v[20:21], v33 offset0:28 offset1:29
	v_lshlrev_b32_e32 v192, 1, v0
	v_lshl_add_u64 v[4:5], s[34:35], 0, v[192:193]
	v_lshlrev_b64 v[24:25], 11, v[22:23]
	s_waitcnt lgkmcnt(6)
	v_cvt_pk_bf16_f32 v0, v6, v8
	s_waitcnt lgkmcnt(4)
	v_cvt_pk_bf16_f32 v1, v10, v12
	s_waitcnt lgkmcnt(2)
	v_cvt_pk_bf16_f32 v2, v14, v16
	s_waitcnt lgkmcnt(0)
	v_cvt_pk_bf16_f32 v3, v18, v20
	v_lshl_add_u64 v[24:25], v[4:5], 0, v[24:25]
	v_add_u32_e32 v6, 64, v22
	global_store_dwordx4 v[24:25], v[0:3], off sc1
	v_add_u32_e32 v24, 0x80, v22
	v_ashrrev_i32_e32 v25, 31, v24
	v_cvt_pk_bf16_f32 v0, v7, v9
	v_ashrrev_i32_e32 v7, 31, v6
	v_lshlrev_b64 v[6:7], 11, v[6:7]
	v_cvt_pk_bf16_f32 v1, v11, v13
	v_cvt_pk_bf16_f32 v2, v15, v17
	v_cvt_pk_bf16_f32 v3, v19, v21
	v_lshl_add_u64 v[6:7], v[4:5], 0, v[6:7]
	global_store_dwordx4 v[6:7], v[0:3], off sc1
	ds_read2st64_b32 v[6:7], v26 offset0:2 offset1:3
	ds_read2st64_b32 v[8:9], v27 offset0:6 offset1:7
	ds_read2st64_b32 v[10:11], v28 offset0:10 offset1:11
	ds_read2st64_b32 v[12:13], v29 offset0:14 offset1:15
	ds_read2st64_b32 v[14:15], v30 offset0:18 offset1:19
	ds_read2st64_b32 v[16:17], v31 offset0:22 offset1:23
	ds_read2st64_b32 v[18:19], v32 offset0:26 offset1:27
	ds_read2st64_b32 v[20:21], v33 offset0:30 offset1:31
	v_lshlrev_b64 v[24:25], 11, v[24:25]
	s_waitcnt lgkmcnt(6)
	v_cvt_pk_bf16_f32 v0, v6, v8
	s_waitcnt lgkmcnt(4)
	v_cvt_pk_bf16_f32 v1, v10, v12
	s_waitcnt lgkmcnt(2)
	v_cvt_pk_bf16_f32 v2, v14, v16
	s_waitcnt lgkmcnt(0)
	v_cvt_pk_bf16_f32 v3, v18, v20
	v_lshl_add_u64 v[24:25], v[4:5], 0, v[24:25]
	v_add_u32_e32 v6, 0xc0, v22
	global_store_dwordx4 v[24:25], v[0:3], off sc1
	s_nop 1
	v_cvt_pk_bf16_f32 v0, v7, v9
	v_ashrrev_i32_e32 v7, 31, v6
	v_lshlrev_b64 v[6:7], 11, v[6:7]
	v_cvt_pk_bf16_f32 v1, v11, v13
	v_cvt_pk_bf16_f32 v2, v15, v17
	v_cvt_pk_bf16_f32 v3, v19, v21
	v_lshl_add_u64 v[4:5], v[4:5], 0, v[6:7]
	global_store_dwordx4 v[4:5], v[0:3], off sc1
	s_barrier

; #define LDSP __attribute__((address_space(3)))
; DI unsigned pk2(float a, float b) { f32x2 v = {a, b}; bf2_t r = __builtin_convertvector(v, bf2_t); return __builtin_bit_cast(unsigned, r); }
; DI void transpose_tile(const float* __restrict__ src, bf16_t* __restrict__ dst, int K, int N, int tk, int tn, ldsp_t smem) {
;     LDSP float* t = (LDSP float*)smem;
;     int tid = threadIdx.x;
;     asm volatile("" : "+v"(tid));
;     const int k0 = tk * 64, n0 = tn * 256;
;     f32x4 v[8];
; #pragma unroll
;     for (int i = 0; i < 8; ++i) v[i] = *(const f32x4*)(src + (size_t)(k0 + (tid >> 6) + 8 * i) * N + n0 + (tid & 63) * 4);
; #pragma unroll
;     for (int i = 0; i < 8; ++i) {
;         const int k = (tid >> 6) + 8 * i, n4 = (tid & 63) * 4;
;         t[k * 257 + n4 + 0] = v[i][0]; t[k * 257 + n4 + 1] = v[i][1]; t[k * 257 + n4 + 2] = v[i][2]; t[k * 257 + n4 + 3] = v[i][3];
;     }
;     __syncthreads();
; #pragma unroll
;     for (int j = 0; j < 4; ++j) {
;         const int n = (tid >> 3) + 64 * j, k8 = (tid & 7) * 8;
;         u32x4 w;
;         w[0] = pk2(t[(k8 + 0) * 257 + n], t[(k8 + 1) * 257 + n]);
;         w[1] = pk2(t[(k8 + 2) * 257 + n], t[(k8 + 3) * 257 + n]);
;         w[2] = pk2(t[(k8 + 4) * 257 + n], t[(k8 + 5) * 257 + n]);
;         w[3] = pk2(t[(k8 + 6) * 257 + n], t[(k8 + 7) * 257 + n]);
;         *(u32x4*)(dst + (size_t)(n0 + n) * K + k0 + k8) = w;
;     }
;     __syncthreads();
; }
.LBB0_418:
	s_andn2_b64 vcc, exec, s[4:5]
	s_cbranch_vccnz .LBB0_420
	s_mul_i32 s4, s7, 0x700000
	s_add_u32 s9, s26, s4
	s_addc_u32 s11, s27, 0
	s_mul_i32 s7, s7, 0x380000
	s_add_u32 s5, s56, s7
	s_addc_u32 s7, s57, 0
	s_and_b32 s4, s6, 0xff
	s_mul_i32 s4, s4, 37
	s_lshr_b32 s4, s4, 8
	s_sub_i32 s8, s6, s4
	s_bfe_u32 s8, s8, 0x70001
	s_add_i32 s8, s8, s4
	s_bfe_u32 s8, s8, 0x60002
	s_mul_i32 s4, s8, 7
	s_sub_i32 s4, s6, s4
	s_and_b32 s4, s4, 0xff
	v_mov_b32_e32 v34, v252
	s_lshl_b32 s6, s4, 10
	s_add_u32 s34, s9, s6
	v_lshlrev_b32_e32 v0, 4, v34
	v_ashrrev_i32_e32 v32, 6, v34
	s_addc_u32 s35, s11, 0
	v_and_b32_e32 v192, 0x3f0, v0
	v_lshl_add_u32 v30, s8, 6, v32
	v_lshl_add_u64 v[28:29], s[34:35], 0, v[192:193]
	s_movk_i32 s6, 0x1c00
	v_mad_i64_i32 v[0:1], s[34:35], v30, s6, v[28:29]
	s_waitcnt lgkmcnt(5)
	v_add_u32_e32 v4, 8, v30
	global_load_dwordx4 v[0:3], v[0:1], off
	s_waitcnt lgkmcnt(0)
	v_mad_i64_i32 v[4:5], s[34:35], v4, s6, v[28:29]
	global_load_dwordx4 v[4:7], v[4:5], off
	v_add_u32_e32 v8, 16, v30
	v_mad_i64_i32 v[8:9], s[34:35], v8, s6, v[28:29]
	global_load_dwordx4 v[8:11], v[8:9], off
	v_add_u32_e32 v12, 24, v30
	v_mad_i64_i32 v[12:13], s[34:35], v12, s6, v[28:29]
	global_load_dwordx4 v[12:15], v[12:13], off
	v_add_u32_e32 v16, 32, v30
	v_mad_i64_i32 v[16:17], s[34:35], v16, s6, v[28:29]
	global_load_dwordx4 v[16:19], v[16:17], off
	v_add_u32_e32 v20, 40, v30
	v_mad_i64_i32 v[20:21], s[34:35], v20, s6, v[28:29]
	global_load_dwordx4 v[20:23], v[20:21], off
	v_add_u32_e32 v24, 48, v30
	v_mad_i64_i32 v[24:25], s[34:35], v24, s6, v[28:29]
	global_load_dwordx4 v[24:27], v[24:25], off
	v_add_u32_e32 v30, 56, v30
	v_mad_i64_i32 v[28:29], s[34:35], v30, s6, v[28:29]
	global_load_dwordx4 v[28:31], v[28:29], off
	s_movk_i32 s9, 0x404
	v_mad_u64_u32 v[32:33], s[34:35], v32, s9, v[192:193]
	s_lshl_b32 s6, s8, 7
	s_add_u32 s6, s5, s6
	s_addc_u32 s7, s7, 0
	s_waitcnt vmcnt(7)
	ds_write2_b32 v32, v0, v1 offset1:1
	ds_write2_b32 v32, v2, v3 offset0:2 offset1:3
	v_add_u32_e32 v0, 0x2020, v32
	s_waitcnt vmcnt(6)
	ds_write2_b32 v0, v4, v5 offset1:1
	v_add_u32_e32 v0, 0x2028, v32
	ds_write2_b32 v0, v6, v7 offset1:1
	v_add_u32_e32 v0, 0x4040, v32
	s_waitcnt vmcnt(5)
	ds_write2_b32 v0, v8, v9 offset1:1
	v_add_u32_e32 v0, 0x4048, v32
	ds_write2_b32 v0, v10, v11 offset1:1
	v_add_u32_e32 v0, 0x6060, v32
	s_waitcnt vmcnt(4)
	ds_write2_b32 v0, v12, v13 offset1:1
	v_add_u32_e32 v0, 0x6068, v32
	ds_write2_b32 v0, v14, v15 offset1:1
	v_add_u32_e32 v0, 0x8080, v32
	s_waitcnt vmcnt(3)
	ds_write2_b32 v0, v16, v17 offset1:1
	v_add_u32_e32 v0, 0x8088, v32
	ds_write2_b32 v0, v18, v19 offset1:1
	v_add_u32_e32 v0, 0xa0a0, v32
	s_waitcnt vmcnt(2)
	ds_write2_b32 v0, v20, v21 offset1:1
	v_add_u32_e32 v0, 0xa0a8, v32
	ds_write2_b32 v0, v22, v23 offset1:1
	v_add_u32_e32 v0, 0xc0c0, v32
	s_waitcnt vmcnt(1)
	ds_write2_b32 v0, v24, v25 offset1:1
	v_add_u32_e32 v0, 0xc0c8, v32
	ds_write2_b32 v0, v26, v27 offset1:1
	v_add_u32_e32 v0, 0xe0e0, v32
	s_waitcnt vmcnt(0)
	ds_write2_b32 v0, v28, v29 offset1:1
	v_add_u32_e32 v0, 0xe0e8, v32
	ds_write2_b32 v0, v30, v31 offset1:1
	v_ashrrev_i32_e32 v22, 3, v34
	v_lshlrev_b32_e32 v0, 3, v34
	v_and_b32_e32 v2, 56, v0
	v_lshlrev_b32_e32 v3, 2, v22
	v_mad_u32_u24 v26, v2, s9, v3
	v_add_u32_e32 v27, 4, v26
	v_add_u32_e32 v28, 8, v26
	v_add_u32_e32 v29, 12, v26
	v_add_u32_e32 v30, 16, v26
	v_add_u32_e32 v31, 20, v26
	v_add_u32_e32 v32, 24, v26
	v_add_u32_e32 v33, 28, v26
	s_waitcnt lgkmcnt(0)
	s_barrier
	ds_read2st64_b32 v[6:7], v26 offset1:1
	ds_read2st64_b32 v[8:9], v27 offset0:4 offset1:5
	ds_read2st64_b32 v[10:11], v28 offset0:8 offset1:9
	ds_read2st64_b32 v[12:13], v29 offset0:12 offset1:13
	ds_read2st64_b32 v[14:15], v30 offset0:16 offset1:17
	ds_read2st64_b32 v[16:17], v31 offset0:20 offset1:21
	ds_read2st64_b32 v[18:19], v32 offset0:24 offset1:25
	ds_read2st64_b32 v[20:21], v33 offset0:28 offset1:29
	v_lshl_add_u32 v22, s4, 8, v22
	v_lshlrev_b32_e32 v192, 1, v2
	v_ashrrev_i32_e32 v23, 31, v22
	v_lshl_add_u64 v[0:1], s[6:7], 0, v[192:193]
	v_lshlrev_b64 v[24:25], 11, v[22:23]
	s_waitcnt lgkmcnt(6)
	v_cvt_pk_bf16_f32 v2, v6, v8
	s_waitcnt lgkmcnt(4)
	v_cvt_pk_bf16_f32 v3, v10, v12
	s_waitcnt lgkmcnt(2)
	v_cvt_pk_bf16_f32 v4, v14, v16
	s_waitcnt lgkmcnt(0)
	v_cvt_pk_bf16_f32 v5, v18, v20
	v_lshl_add_u64 v[24:25], v[0:1], 0, v[24:25]
	v_add_u32_e32 v6, 64, v22
	global_store_dwordx4 v[24:25], v[2:5], off sc1
	v_add_u32_e32 v24, 0x80, v22
	v_ashrrev_i32_e32 v25, 31, v24
	v_cvt_pk_bf16_f32 v2, v7, v9
	v_ashrrev_i32_e32 v7, 31, v6
	v_lshlrev_b64 v[6:7], 11, v[6:7]
	v_cvt_pk_bf16_f32 v3, v11, v13
	v_cvt_pk_bf16_f32 v4, v15, v17
	v_cvt_pk_bf16_f32 v5, v19, v21
	v_lshl_add_u64 v[6:7], v[0:1], 0, v[6:7]
	global_store_dwordx4 v[6:7], v[2:5], off sc1
	ds_read2st64_b32 v[6:7], v26 offset0:2 offset1:3
	ds_read2st64_b32 v[8:9], v27 offset0:6 offset1:7
	ds_read2st64_b32 v[10:11], v28 offset0:10 offset1:11
	ds_read2st64_b32 v[12:13], v29 offset0:14 offset1:15
	ds_read2st64_b32 v[14:15], v30 offset0:18 offset1:19
	ds_read2st64_b32 v[16:17], v31 offset0:22 offset1:23
	ds_read2st64_b32 v[18:19], v32 offset0:26 offset1:27
	ds_read2st64_b32 v[20:21], v33 offset0:30 offset1:31
	v_lshlrev_b64 v[24:25], 11, v[24:25]
	s_waitcnt lgkmcnt(6)
	v_cvt_pk_bf16_f32 v2, v6, v8
	s_waitcnt lgkmcnt(4)
	v_cvt_pk_bf16_f32 v3, v10, v12
	s_waitcnt lgkmcnt(2)
	v_cvt_pk_bf16_f32 v4, v14, v16
	s_waitcnt lgkmcnt(0)
	v_cvt_pk_bf16_f32 v5, v18, v20
	v_lshl_add_u64 v[24:25], v[0:1], 0, v[24:25]
	v_add_u32_e32 v6, 0xc0, v22
	global_store_dwordx4 v[24:25], v[2:5], off sc1
	s_nop 1
	v_cvt_pk_bf16_f32 v2, v7, v9
	v_ashrrev_i32_e32 v7, 31, v6
	v_lshlrev_b64 v[6:7], 11, v[6:7]
	v_cvt_pk_bf16_f32 v3, v11, v13
	v_cvt_pk_bf16_f32 v4, v15, v17
	v_cvt_pk_bf16_f32 v5, v19, v21
	v_lshl_add_u64 v[0:1], v[0:1], 0, v[6:7]
	global_store_dwordx4 v[0:1], v[2:5], off sc1
	s_barrier

; DI void mod_unit(const Params& p, int l, int cgi, ldsp_t smem) {
;     ...
;     const float* wp = p.w_mod + ((size_t)l * 1024 + ks * 32) * 6144 + cgi * 64 + c4 * 4;
; #pragma unroll 8
;     for (int kk = 0; kk < 32; ++kk) {
;         const f32x4 w = *(const f32x4*)(wp + (size_t)kk * 6144);
;         const int k = ks * 32 + kk;
; #pragma unroll
;         for (int q = 0; q < 5; ++q) acc[q] += w * s[q * 1024 + k];
;     }
.LBB0_428:
	v_lshl_add_u64 v[28:29], v[26:27], 0, s[8:9]
	global_load_dwordx4 v[32:35], v[28:29], off
	ds_read_b128 v[36:39], v31
	ds_read_b128 v[20:23], v31 offset:16
	s_mov_b32 s5, 0xc000
	s_add_u32 s8, s8, 0x30000
	s_addc_u32 s9, s9, 0
	s_cmp_eq_u32 s8, 0xc0000
	s_waitcnt vmcnt(0) lgkmcnt(1)
	v_pk_fma_f32 v[40:41], v[34:35], v[36:37], v[6:7] op_sel_hi:[1,0,1]
	v_pk_fma_f32 v[42:43], v[32:33], v[36:37], v[4:5] op_sel_hi:[1,0,1]
	ds_read_b128 v[4:7], v31 offset:4096
	s_waitcnt lgkmcnt(0)
	v_pk_fma_f32 v[44:45], v[34:35], v[4:5], v[10:11] op_sel_hi:[1,0,1]
	v_pk_fma_f32 v[46:47], v[32:33], v[4:5], v[8:9] op_sel_hi:[1,0,1]
	ds_read_b128 v[8:11], v31 offset:8192
	s_waitcnt lgkmcnt(0)
	v_pk_fma_f32 v[48:49], v[34:35], v[8:9], v[14:15] op_sel_hi:[1,0,1]
	v_pk_fma_f32 v[50:51], v[32:33], v[8:9], v[12:13] op_sel_hi:[1,0,1]
	ds_read_b128 v[12:15], v31 offset:12288
	s_waitcnt lgkmcnt(0)
	v_pk_fma_f32 v[52:53], v[34:35], v[12:13], v[18:19] op_sel_hi:[1,0,1]
	v_pk_fma_f32 v[54:55], v[32:33], v[12:13], v[16:17] op_sel_hi:[1,0,1]
	ds_read_b128 v[16:19], v31 offset:16384
	s_waitcnt lgkmcnt(0)
	v_pk_fma_f32 v[32:33], v[32:33], v[16:17], v[0:1] op_sel_hi:[1,0,1]
	v_add_co_u32_e32 v0, vcc, s28, v28
	v_pk_fma_f32 v[34:35], v[34:35], v[16:17], v[2:3] op_sel_hi:[1,0,1]
	s_nop 0
	v_addc_co_u32_e32 v1, vcc, 0, v29, vcc
	global_load_dwordx4 v[0:3], v[0:1], off
	s_waitcnt vmcnt(0)
	v_pk_fma_f32 v[42:43], v[0:1], v[36:37], v[42:43] op_sel:[0,1,0]
	v_pk_fma_f32 v[36:37], v[2:3], v[36:37], v[40:41] op_sel:[0,1,0]
	v_pk_fma_f32 v[40:41], v[0:1], v[4:5], v[46:47] op_sel:[0,1,0]
	v_pk_fma_f32 v[4:5], v[2:3], v[4:5], v[44:45] op_sel:[0,1,0]
	v_pk_fma_f32 v[44:45], v[0:1], v[8:9], v[50:51] op_sel:[0,1,0]
	v_pk_fma_f32 v[46:47], v[0:1], v[12:13], v[54:55] op_sel:[0,1,0]
	v_pk_fma_f32 v[32:33], v[0:1], v[16:17], v[32:33] op_sel:[0,1,0]
	v_add_co_u32_e32 v0, vcc, s5, v28
	v_pk_fma_f32 v[8:9], v[2:3], v[8:9], v[48:49] op_sel:[0,1,0]
	s_nop 0
	v_addc_co_u32_e32 v1, vcc, 0, v29, vcc
	v_pk_fma_f32 v[12:13], v[2:3], v[12:13], v[52:53] op_sel:[0,1,0]
	v_pk_fma_f32 v[16:17], v[2:3], v[16:17], v[34:35] op_sel:[0,1,0]
	global_load_dwordx4 v[0:3], v[0:1], off
	s_mov_b32 s5, 0x12000
	s_waitcnt vmcnt(0)
	v_pk_fma_f32 v[34:35], v[2:3], v[38:39], v[36:37] op_sel_hi:[1,0,1]
	v_pk_fma_f32 v[36:37], v[0:1], v[38:39], v[42:43] op_sel_hi:[1,0,1]
	v_pk_fma_f32 v[40:41], v[0:1], v[6:7], v[40:41] op_sel_hi:[1,0,1]
	v_pk_fma_f32 v[42:43], v[0:1], v[10:11], v[44:45] op_sel_hi:[1,0,1]
	v_pk_fma_f32 v[44:45], v[0:1], v[14:15], v[46:47] op_sel_hi:[1,0,1]
	v_pk_fma_f32 v[32:33], v[0:1], v[18:19], v[32:33] op_sel_hi:[1,0,1]
	v_add_co_u32_e32 v0, vcc, s5, v28
	v_pk_fma_f32 v[4:5], v[2:3], v[6:7], v[4:5] op_sel_hi:[1,0,1]
	s_nop 0
	v_addc_co_u32_e32 v1, vcc, 0, v29, vcc
	v_pk_fma_f32 v[8:9], v[2:3], v[10:11], v[8:9] op_sel_hi:[1,0,1]
	v_pk_fma_f32 v[12:13], v[2:3], v[14:15], v[12:13] op_sel_hi:[1,0,1]
	v_pk_fma_f32 v[16:17], v[2:3], v[18:19], v[16:17] op_sel_hi:[1,0,1]
	global_load_dwordx4 v[0:3], v[0:1], off
	v_mov_b32_e32 v6, v39
	s_mov_b32 s5, 0x1e000
	s_waitcnt vmcnt(0)
	v_pk_fma_f32 v[34:35], v[2:3], v[6:7], v[34:35] op_sel_hi:[1,0,1]
	v_pk_fma_f32 v[36:37], v[0:1], v[6:7], v[36:37] op_sel_hi:[1,0,1]
	v_mov_b32_e32 v6, v7
	v_pk_fma_f32 v[4:5], v[2:3], v[6:7], v[4:5] op_sel_hi:[1,0,1]
	v_pk_fma_f32 v[38:39], v[0:1], v[6:7], v[40:41] op_sel_hi:[1,0,1]
	v_mov_b32_e32 v6, v11
	v_pk_fma_f32 v[40:41], v[2:3], v[6:7], v[8:9] op_sel_hi:[1,0,1]
	v_pk_fma_f32 v[42:43], v[0:1], v[6:7], v[42:43] op_sel_hi:[1,0,1]
	v_mov_b32_e32 v6, v15
	v_pk_fma_f32 v[46:47], v[2:3], v[6:7], v[12:13] op_sel_hi:[1,0,1]
	v_pk_fma_f32 v[44:45], v[0:1], v[6:7], v[44:45] op_sel_hi:[1,0,1]
	v_mov_b32_e32 v6, v19
	v_pk_fma_f32 v[48:49], v[0:1], v[6:7], v[32:33] op_sel_hi:[1,0,1]
	v_add_co_u32_e32 v0, vcc, s30, v28
	v_pk_fma_f32 v[18:19], v[2:3], v[6:7], v[16:17] op_sel_hi:[1,0,1]
	s_nop 0
	v_addc_co_u32_e32 v1, vcc, 0, v29, vcc
	global_load_dwordx4 v[0:3], v[0:1], off
	ds_read_b128 v[6:9], v31 offset:4112
	ds_read_b128 v[10:13], v31 offset:8208
	ds_read_b128 v[14:17], v31 offset:12304
	s_waitcnt vmcnt(0)
	v_pk_fma_f32 v[50:51], v[2:3], v[20:21], v[34:35] op_sel_hi:[1,0,1]
	ds_read_b128 v[32:35], v31 offset:16400
	v_pk_fma_f32 v[36:37], v[0:1], v[20:21], v[36:37] op_sel_hi:[1,0,1]
	s_waitcnt lgkmcnt(3)
	v_pk_fma_f32 v[38:39], v[0:1], v[6:7], v[38:39] op_sel_hi:[1,0,1]
	s_waitcnt lgkmcnt(2)
	v_pk_fma_f32 v[42:43], v[0:1], v[10:11], v[42:43] op_sel_hi:[1,0,1]
	s_waitcnt lgkmcnt(1)
	v_pk_fma_f32 v[44:45], v[0:1], v[14:15], v[44:45] op_sel_hi:[1,0,1]
	s_waitcnt lgkmcnt(0)
	v_pk_fma_f32 v[48:49], v[0:1], v[32:33], v[48:49] op_sel_hi:[1,0,1]
	v_add_co_u32_e32 v0, vcc, s5, v28
	v_pk_fma_f32 v[4:5], v[2:3], v[6:7], v[4:5] op_sel_hi:[1,0,1]
	s_nop 0
	v_addc_co_u32_e32 v1, vcc, 0, v29, vcc
	v_pk_fma_f32 v[40:41], v[2:3], v[10:11], v[40:41] op_sel_hi:[1,0,1]
	v_pk_fma_f32 v[46:47], v[2:3], v[14:15], v[46:47] op_sel_hi:[1,0,1]
	v_pk_fma_f32 v[18:19], v[2:3], v[32:33], v[18:19] op_sel_hi:[1,0,1]
	global_load_dwordx4 v[0:3], v[0:1], off
	s_mov_b32 s5, 0x24000
	v_add_u32_e32 v31, 32, v31
	s_waitcnt vmcnt(0)
; DI void mod_unit(const Params& p, int l, int cgi, ldsp_t smem) {
;     ...
;     for (int kk = 0; kk < 32; ++kk) {
;         const f32x4 w = *(const f32x4*)(wp + (size_t)kk * 6144);
;         const int k = ks * 32 + kk;
; #pragma unroll
;         for (int q = 0; q < 5; ++q) acc[q] += w * s[q * 1024 + k];
;     }
; #pragma unroll
;     for (int q = 0; q < 5; ++q)
; #pragma unroll
;         for (int j = 0; j < 4; ++j) red[(ks * 5 + q) * 64 + c4 * 4 + j] = acc[q][j];
;     __syncthreads();
;     if (tid < 320) {
;         const int q = tid >> 6, col = tid & 63;
;         float a = 0.f;
;         for (int k2 = 0; k2 < 32; ++k2) a += red[(k2 * 5 + q) * 64 + col];
;         const int j = cgi * 64 + col;
;         p.mod[((size_t)l * 5 + q) * 6144 + j] = a + p.b_mod[(size_t)l * 6144 + j];
;     }
	v_pk_fma_f32 v[50:51], v[2:3], v[20:21], v[50:51] op_sel:[0,1,0]
	v_pk_fma_f32 v[20:21], v[0:1], v[20:21], v[36:37] op_sel:[0,1,0]
	v_pk_fma_f32 v[4:5], v[2:3], v[6:7], v[4:5] op_sel:[0,1,0]
	v_pk_fma_f32 v[6:7], v[0:1], v[6:7], v[38:39] op_sel:[0,1,0]
	v_pk_fma_f32 v[36:37], v[2:3], v[10:11], v[40:41] op_sel:[0,1,0]
	v_pk_fma_f32 v[10:11], v[0:1], v[10:11], v[42:43] op_sel:[0,1,0]
	v_pk_fma_f32 v[38:39], v[2:3], v[14:15], v[46:47] op_sel:[0,1,0]
	v_pk_fma_f32 v[14:15], v[0:1], v[14:15], v[44:45] op_sel:[0,1,0]
	v_pk_fma_f32 v[18:19], v[2:3], v[32:33], v[18:19] op_sel:[0,1,0]
	v_pk_fma_f32 v[32:33], v[0:1], v[32:33], v[48:49] op_sel:[0,1,0]
	v_add_co_u32_e32 v0, vcc, s5, v28
	s_mov_b32 s5, 0x2a000
	s_nop 0
	v_addc_co_u32_e32 v1, vcc, 0, v29, vcc
	global_load_dwordx4 v[0:3], v[0:1], off
	s_waitcnt vmcnt(0)
	v_pk_fma_f32 v[20:21], v[0:1], v[22:23], v[20:21] op_sel_hi:[1,0,1]
	v_pk_fma_f32 v[44:45], v[0:1], v[8:9], v[6:7] op_sel_hi:[1,0,1]
	v_pk_fma_f32 v[46:47], v[0:1], v[12:13], v[10:11] op_sel_hi:[1,0,1]
	v_pk_fma_f32 v[48:49], v[0:1], v[16:17], v[14:15] op_sel_hi:[1,0,1]
	v_pk_fma_f32 v[32:33], v[0:1], v[34:35], v[32:33] op_sel_hi:[1,0,1]
	v_add_co_u32_e32 v0, vcc, s5, v28
	v_pk_fma_f32 v[40:41], v[2:3], v[22:23], v[50:51] op_sel_hi:[1,0,1]
	s_nop 0
	v_addc_co_u32_e32 v1, vcc, 0, v29, vcc
	v_pk_fma_f32 v[42:43], v[2:3], v[8:9], v[4:5] op_sel_hi:[1,0,1]
	v_pk_fma_f32 v[36:37], v[2:3], v[12:13], v[36:37] op_sel_hi:[1,0,1]
	v_pk_fma_f32 v[38:39], v[2:3], v[16:17], v[38:39] op_sel_hi:[1,0,1]
	v_pk_fma_f32 v[50:51], v[2:3], v[34:35], v[18:19] op_sel_hi:[1,0,1]
	global_load_dwordx4 v[0:3], v[0:1], off
	v_mov_b32_e32 v4, v23
	v_mov_b32_e32 v8, v9
	v_mov_b32_e32 v12, v13
	v_mov_b32_e32 v16, v17
	s_waitcnt vmcnt(0)
	v_pk_fma_f32 v[6:7], v[2:3], v[4:5], v[40:41] op_sel_hi:[1,0,1]
	v_pk_fma_f32 v[4:5], v[0:1], v[4:5], v[20:21] op_sel_hi:[1,0,1]
	v_mov_b32_e32 v20, v35
	v_pk_fma_f32 v[10:11], v[2:3], v[8:9], v[42:43] op_sel_hi:[1,0,1]
	v_pk_fma_f32 v[8:9], v[0:1], v[8:9], v[44:45] op_sel_hi:[1,0,1]
	v_pk_fma_f32 v[14:15], v[2:3], v[12:13], v[36:37] op_sel_hi:[1,0,1]
	v_pk_fma_f32 v[12:13], v[0:1], v[12:13], v[46:47] op_sel_hi:[1,0,1]
	v_pk_fma_f32 v[18:19], v[2:3], v[16:17], v[38:39] op_sel_hi:[1,0,1]
	v_pk_fma_f32 v[16:17], v[0:1], v[16:17], v[48:49] op_sel_hi:[1,0,1]
	v_pk_fma_f32 v[2:3], v[2:3], v[20:21], v[50:51] op_sel_hi:[1,0,1]
	v_pk_fma_f32 v[0:1], v[0:1], v[20:21], v[32:33] op_sel_hi:[1,0,1]
	s_cbranch_scc0 .LBB0_428
	s_movk_i32 s5, 0x500
	v_mul_lo_u32 v20, v25, s5
	s_movk_i32 s5, 0x140
	v_lshl_or_b32 v20, v30, 2, v20
	v_cmp_gt_i32_e32 vcc, s5, v24
	ds_write_b128 v20, v[4:7] offset:20480
	ds_write_b128 v20, v[8:11] offset:20736
	ds_write_b128 v20, v[12:15] offset:20992
	ds_write_b128 v20, v[16:19] offset:21248
	ds_write_b128 v20, v[0:3] offset:21504
	s_waitcnt lgkmcnt(0)
	s_barrier
	s_and_saveexec_b64 s[8:9], vcc
	s_cbranch_execz .LBB0_388
	v_ashrrev_i32_e32 v0, 6, v24
	v_and_b32_e32 v1, 63, v24
	v_lshlrev_b32_e32 v2, 8, v0
	v_lshl_or_b32 v4, v1, 2, v2
	ds_read2st64_b32 v[2:3], v4 offset0:80 offset1:85
	s_mul_hi_i32 s5, s4, 0x6000
	s_waitcnt lgkmcnt(0)
	v_add_f32_e32 v2, 0, v2
	v_add_f32_e32 v5, v2, v3
	ds_read2st64_b32 v[2:3], v4 offset0:90 offset1:95
	s_waitcnt lgkmcnt(0)
	v_add_f32_e32 v2, v5, v2
	v_add_f32_e32 v5, v2, v3
	ds_read2st64_b32 v[2:3], v4 offset0:100 offset1:105
	s_waitcnt lgkmcnt(0)
	v_add_f32_e32 v2, v5, v2
	v_add_f32_e32 v5, v2, v3
	ds_read2st64_b32 v[2:3], v4 offset0:110 offset1:115
	s_waitcnt lgkmcnt(0)
	v_add_f32_e32 v2, v5, v2
	v_add_f32_e32 v5, v2, v3
	ds_read2st64_b32 v[2:3], v4 offset0:120 offset1:125
	s_waitcnt lgkmcnt(0)
	v_add_f32_e32 v2, v5, v2
	v_add_f32_e32 v5, v2, v3
	ds_read2st64_b32 v[2:3], v4 offset0:130 offset1:135
	s_waitcnt lgkmcnt(0)
	v_add_f32_e32 v2, v5, v2
	v_add_f32_e32 v5, v2, v3
	ds_read2st64_b32 v[2:3], v4 offset0:140 offset1:145
	s_waitcnt lgkmcnt(0)
	v_add_f32_e32 v2, v5, v2
	v_add_f32_e32 v5, v2, v3
	ds_read2st64_b32 v[2:3], v4 offset0:150 offset1:155
	s_waitcnt lgkmcnt(0)
	v_add_f32_e32 v2, v5, v2
	v_add_f32_e32 v5, v2, v3
	ds_read2st64_b32 v[2:3], v4 offset0:160 offset1:165
	s_waitcnt lgkmcnt(0)
	v_add_f32_e32 v2, v5, v2
	v_add_f32_e32 v5, v2, v3
	ds_read2st64_b32 v[2:3], v4 offset0:170 offset1:175
	s_waitcnt lgkmcnt(0)
	v_add_f32_e32 v2, v5, v2
	v_add_f32_e32 v5, v2, v3
	ds_read2st64_b32 v[2:3], v4 offset0:180 offset1:185
	s_waitcnt lgkmcnt(0)
	v_add_f32_e32 v2, v5, v2
	v_add_f32_e32 v5, v2, v3
	ds_read2st64_b32 v[2:3], v4 offset0:190 offset1:195
	s_waitcnt lgkmcnt(0)
	v_add_f32_e32 v2, v5, v2
	v_add_f32_e32 v5, v2, v3
	ds_read2st64_b32 v[2:3], v4 offset0:200 offset1:205
	s_waitcnt lgkmcnt(0)
	v_add_f32_e32 v2, v5, v2
	v_add_f32_e32 v5, v2, v3
	ds_read2st64_b32 v[2:3], v4 offset0:210 offset1:215
	s_waitcnt lgkmcnt(0)
	v_add_f32_e32 v2, v5, v2
	v_add_f32_e32 v5, v2, v3
	ds_read2st64_b32 v[2:3], v4 offset0:220 offset1:225
	s_waitcnt lgkmcnt(0)
	v_add_f32_e32 v2, v5, v2
	v_add_f32_e32 v5, v2, v3
	ds_read2st64_b32 v[2:3], v4 offset0:230 offset1:235
	s_waitcnt lgkmcnt(0)
	v_add_f32_e32 v2, v5, v2
	v_add_f32_e32 v6, v2, v3
	v_or_b32_e32 v2, s6, v1
	s_mul_i32 s6, s4, 0x6000
	v_ashrrev_i32_e32 v3, 31, v2
	s_add_u32 s6, s22, s6
	s_addc_u32 s7, s23, s5
	v_lshlrev_b64 v[2:3], 2, v[2:3]
	v_lshl_add_u64 v[4:5], s[6:7], 0, v[2:3]
	global_load_dword v1, v[4:5], off
	v_mov_b64_e32 v[4:5], s[66:67]
	s_waitcnt vmcnt(0)
	v_add_f32_e32 v6, v6, v1
	v_ashrrev_i32_e32 v1, 31, v0
	v_mad_i64_i32 v[0:1], s[4:5], s4, 5, v[0:1]
	v_mad_u64_u32 v[4:5], s[4:5], v0, s28, v[4:5]
	v_mad_i32_i24 v5, v1, s28, v5
	v_lshl_add_u64 v[0:1], v[4:5], 0, v[2:3]
	global_store_dword v[0:1], v6, off sc1
	s_branch .LBB0_388
